# v43
# baseline (speedup 1.0000x reference)
; #define PG8_STAGE(bufoff, gbase, voff) do { _Pragma("unroll") for (int _i = 0; _i < 2; ++_i) \
;         __builtin_amdgcn_global_load_lds((const unsigned*)((const char*)(gbase) + (voff)[_i]), (PG8_LAS unsigned*)(lds + (bufoff) + ldsw + _i * 8192), 16, 0, 0); } while (0)
; #define PG8_LDA(dst, b, h) do { _Pragma("unroll") for (int m = 0; m < 4; ++m) _Pragma("unroll") for (int k = 0; k < 2; ++k) dst[m][k] = *(const PG8_LAS bf16x8*)(lds + PG8_SA(b, h) + aoff + m * 2048 + k * 1024); } while (0)
; #define PG8_LDB(dst, b, h) do { _Pragma("unroll") for (int n = 0; n < 2; ++n) _Pragma("unroll") for (int k = 0; k < 2; ++k) dst[n][k] = *(const PG8_LAS bf16x8*)(lds + PG8_SB(b, h) + boff + n * 2048 + k * 1024); } while (0)
; #define PG8_MMA(ai, bj, At, Bt) do { __builtin_amdgcn_s_setprio(1); _Pragma("unroll") for (int m = 0; m < 4; ++m) _Pragma("unroll") for (int n = 0; n < 2; ++n) _Pragma("unroll") for (int k = 0; k < 2; ++k) \
;         acc[ai][bj][m][n] = __builtin_amdgcn_mfma_f32_16x16x32_bf16(Bt[n][k], At[m][k], acc[ai][bj][m][n], 0, 0, 0); __builtin_amdgcn_s_setprio(0); } while (0)
; #define PG8_BAR __builtin_amdgcn_s_barrier()
; template <class Epi, class Sched, bool ALIGN_EPI = false, bool SP2 = false>
; __device__ __forceinline__ void gemm_phase(PG8_LAS unsigned char* lds, const Gemm g, const Sched& S, const Epi& E) {
;     ...
;         const bool has_next = S.next(ui + 1, nxt);
;         const char* nA = has_next ? (const char*)g.A + (size_t)nxt.pm * tstep : cA; const char* nB = has_next ? (const char*)g.Bt + (size_t)nxt.pn * tstep : cB;
;         for (int t = 0; t < nt; t += 2) {
;             const bool last = (t == nt - 2);
;             const char* a1 = cA + (size_t)(t + 1) * kstep;
;             const char* a2 = last ? nA : cA + (size_t)(t + 2) * kstep; const char* b2 = last ? nB : cB + (size_t)(t + 2) * kstep;
;             const char* a3 = a2 + kstep; const char* b3 = b2 + kstep;
;             if (last && has_next) S.a_ready(nxt);
;             if constexpr (SP2) {
;             PG8_LDB(B0, 0, 0); PG8_LDB(B1, 0, 1); PG8_SCHED; PG8_LDA(At, 0, 0); PG8_STAGE(PG8_SA(1, 1), a1 + hstep, voffA);
;             PG8_WAIT_V(8); PG8_WAIT_L(0); PG8_BAR; PG8_MMA(0, 0, At, B0); PG8_MMA(0, 1, At, B1); PG8_BAR; PG8_SCHED;
;             PG8_LDA(At, 0, 1); PG8_STAGE(PG8_SB(0, 0), b2, voffB); PG8_STAGE(PG8_SB(0, 1), b2 + hstep, voffB); PG8_STAGE(PG8_SA(0, 0), a2, voffA);
.LBB0_168:
	s_ashr_i32 s29, s28, 31
	v_cmp_lt_i64_e32 vcc, s[30:31], v[140:141]
	s_lshl_b64 s[30:31], s[28:29], 20
	s_add_u32 s30, s6, s30
	s_addc_u32 s31, s7, s31
	s_and_b64 s[34:35], vcc, exec
	s_cselect_b32 s29, s31, s39
	s_cselect_b32 s57, s30, s38
	s_ashr_i32 s27, s26, 31
	s_lshl_b64 s[34:35], s[26:27], 20
	s_add_u32 s34, s22, s34
	s_addc_u32 s35, s23, s35
	s_and_b64 s[42:43], vcc, exec
	s_cselect_b32 s27, s35, s41
	s_cselect_b32 s58, s34, s40
	s_add_u32 s38, s38, 0x80080
	s_addc_u32 s39, s39, 0
	s_add_u32 s59, s40, 0x100
	s_addc_u32 s60, s41, 0
	s_mov_b32 s61, -2
	ds_read_b128 v[152:155], v149
	ds_read_b128 v[156:159], v149 offset:1024
	ds_read_b128 v[160:163], v149 offset:2048
	ds_read_b128 v[164:167], v149 offset:3072
	ds_read_b128 v[168:171], v150
	ds_read_b128 v[172:175], v150 offset:1024
	ds_read_b128 v[176:179], v150 offset:2048
	ds_read_b128 v[180:183], v150 offset:3072
	s_add_u32 s40, s38, 0xfff80080
	s_addc_u32 s41, s39, -1
	s_cmp_eq_u32 s61, 28
	s_cselect_b32 s43, s29, s41
	s_cselect_b32 s42, s57, s40
	s_cselect_b32 s41, s27, s60
	s_cselect_b32 s40, s58, s59
	s_add_i32 m0, s37, 0xc000
	ds_read_b128 v[184:187], v151
	ds_read_b128 v[188:191], v151 offset:1024
	ds_read_b128 v[192:195], v151 offset:2048
	ds_read_b128 v[196:199], v151 offset:3072
	ds_read_b128 v[200:203], v151 offset:4096
	ds_read_b128 v[204:207], v151 offset:5120
	ds_read_b128 v[208:211], v151 offset:6144
	ds_read_b128 v[214:217], v151 offset:7168
	global_load_lds_dwordx4 v136, s[38:39]
	s_add_i32 m0, s37, 0xe000
	s_nop 0
	global_load_lds_dwordx4 v138, s[38:39]
	s_waitcnt vmcnt(8)
	s_waitcnt lgkmcnt(0)
	s_barrier
	v_mfma_f32_16x16x32_bf16 v[124:127], v[152:155], v[184:187], 0
	v_mfma_f32_16x16x32_bf16 v[120:123], v[160:163], v[184:187], 0
	v_mfma_f32_16x16x32_bf16 v[108:111], v[152:155], v[192:195], 0
	v_mfma_f32_16x16x32_bf16 v[104:107], v[160:163], v[192:195], 0
	v_mfma_f32_16x16x32_bf16 v[92:95], v[152:155], v[200:203], 0
	v_mfma_f32_16x16x32_bf16 v[88:91], v[160:163], v[200:203], 0
	v_mfma_f32_16x16x32_bf16 v[76:79], v[152:155], v[208:211], 0
	v_mfma_f32_16x16x32_bf16 v[72:75], v[160:163], v[208:211], 0
	v_mfma_f32_16x16x32_bf16 v[124:127], v[156:159], v[188:191], v[124:127]
	v_mfma_f32_16x16x32_bf16 v[120:123], v[164:167], v[188:191], v[120:123]
	v_mfma_f32_16x16x32_bf16 v[108:111], v[156:159], v[196:199], v[108:111]
	v_mfma_f32_16x16x32_bf16 v[104:107], v[164:167], v[196:199], v[104:107]
	v_mfma_f32_16x16x32_bf16 v[92:95], v[156:159], v[204:207], v[92:95]
	v_mfma_f32_16x16x32_bf16 v[88:91], v[164:167], v[204:207], v[88:91]
	v_mfma_f32_16x16x32_bf16 v[76:79], v[156:159], v[214:217], v[76:79]
	v_mfma_f32_16x16x32_bf16 v[72:75], v[164:167], v[214:217], v[72:75]
	v_mfma_f32_16x16x32_bf16 v[116:119], v[168:171], v[184:187], 0
	v_mfma_f32_16x16x32_bf16 v[112:115], v[176:179], v[184:187], 0
	v_mfma_f32_16x16x32_bf16 v[100:103], v[168:171], v[192:195], 0
	v_mfma_f32_16x16x32_bf16 v[96:99], v[176:179], v[192:195], 0
	v_mfma_f32_16x16x32_bf16 v[84:87], v[168:171], v[200:203], 0
	v_mfma_f32_16x16x32_bf16 v[80:83], v[176:179], v[200:203], 0
	v_mfma_f32_16x16x32_bf16 v[68:71], v[168:171], v[208:211], 0
	v_mfma_f32_16x16x32_bf16 v[64:67], v[176:179], v[208:211], 0
	v_mfma_f32_16x16x32_bf16 v[116:119], v[172:175], v[188:191], v[116:119]
	v_mfma_f32_16x16x32_bf16 v[112:115], v[180:183], v[188:191], v[112:115]
	v_mfma_f32_16x16x32_bf16 v[100:103], v[172:175], v[196:199], v[100:103]
	v_mfma_f32_16x16x32_bf16 v[96:99], v[180:183], v[196:199], v[96:99]
	v_mfma_f32_16x16x32_bf16 v[84:87], v[172:175], v[204:207], v[84:87]
	v_mfma_f32_16x16x32_bf16 v[80:83], v[180:183], v[204:207], v[80:83]
	v_mfma_f32_16x16x32_bf16 v[68:71], v[172:175], v[214:217], v[68:71]
	v_mfma_f32_16x16x32_bf16 v[64:67], v[180:183], v[214:217], v[64:67]
	s_barrier
	s_add_i32 s62, s53, s24
	s_mov_b32 m0, s62
	ds_read_b128 v[184:187], v151 offset:16384
	ds_read_b128 v[188:191], v151 offset:17408
	ds_read_b128 v[192:195], v151 offset:18432
	ds_read_b128 v[196:199], v151 offset:19456
	ds_read_b128 v[200:203], v151 offset:20480
	ds_read_b128 v[204:207], v151 offset:21504
	ds_read_b128 v[208:211], v151 offset:22528
	ds_read_b128 v[214:217], v151 offset:23552
	global_load_lds_dwordx4 v132, s[40:41]
	s_add_i32 m0, s62, 0x2000
	s_add_u32 s62, s40, 0x80000
	s_addc_u32 s63, s41, 0
	s_add_i32 s64, s54, s24
	global_load_lds_dwordx4 v128, s[40:41]
	s_mov_b32 m0, s64
	s_nop 0
	global_load_lds_dwordx4 v132, s[62:63]
	s_add_i32 m0, s64, 0x2000
	s_nop 0
	global_load_lds_dwordx4 v128, s[62:63]
	s_mov_b32 m0, s37
	s_nop 0
	global_load_lds_dwordx4 v134, s[42:43]
	s_mov_b32 m0, s45
	s_nop 0
	global_load_lds_dwordx4 v130, s[42:43]
	s_waitcnt vmcnt(8)
	s_waitcnt lgkmcnt(0)
	s_barrier
; #define PG8_STAGE(bufoff, gbase, voff) do { _Pragma("unroll") for (int _i = 0; _i < 2; ++_i) \
;         __builtin_amdgcn_global_load_lds((const unsigned*)((const char*)(gbase) + (voff)[_i]), (PG8_LAS unsigned*)(lds + (bufoff) + ldsw + _i * 8192), 16, 0, 0); } while (0)
; #define PG8_LDA(dst, b, h) do { _Pragma("unroll") for (int m = 0; m < 4; ++m) _Pragma("unroll") for (int k = 0; k < 2; ++k) dst[m][k] = *(const PG8_LAS bf16x8*)(lds + PG8_SA(b, h) + aoff + m * 2048 + k * 1024); } while (0)
; #define PG8_LDB(dst, b, h) do { _Pragma("unroll") for (int n = 0; n < 2; ++n) _Pragma("unroll") for (int k = 0; k < 2; ++k) dst[n][k] = *(const PG8_LAS bf16x8*)(lds + PG8_SB(b, h) + boff + n * 2048 + k * 1024); } while (0)
; #define PG8_MMA(ai, bj, At, Bt) do { __builtin_amdgcn_s_setprio(1); _Pragma("unroll") for (int m = 0; m < 4; ++m) _Pragma("unroll") for (int n = 0; n < 2; ++n) _Pragma("unroll") for (int k = 0; k < 2; ++k) \
;         acc[ai][bj][m][n] = __builtin_amdgcn_mfma_f32_16x16x32_bf16(Bt[n][k], At[m][k], acc[ai][bj][m][n], 0, 0, 0); __builtin_amdgcn_s_setprio(0); } while (0)
; #define PG8_WAIT_V(n) asm volatile("s_waitcnt vmcnt(" #n ")" ::: "memory")
; #define PG8_WAIT_L(n) asm volatile("s_waitcnt lgkmcnt(" #n ")" ::: "memory")
; #define PG8_BAR __builtin_amdgcn_s_barrier()
; #define PG8_SCHED __builtin_amdgcn_sched_barrier(0)
; template <class Epi, class Sched, bool ALIGN_EPI = false, bool SP2 = false>
; __device__ __forceinline__ void gemm_phase(PG8_LAS unsigned char* lds, const Gemm g, const Sched& S, const Epi& E) {
;     ...
;             PG8_WAIT_V(8); PG8_WAIT_L(0); PG8_BAR; PG8_MMA(1, 0, At, B0); PG8_MMA(1, 1, At, B1); PG8_BAR; PG8_SCHED;
;             PG8_LDB(B0, 1, 0); PG8_LDB(B1, 1, 1); PG8_SCHED; PG8_LDA(At, 1, 0); PG8_STAGE(PG8_SA(0, 1), a2 + hstep, voffA);
;             PG8_WAIT_V(8); PG8_WAIT_L(0); PG8_BAR; PG8_MMA(0, 0, At, B0); PG8_MMA(0, 1, At, B1); PG8_BAR; PG8_SCHED;
	v_mfma_f32_16x16x32_bf16 v[60:63], v[152:155], v[184:187], 0
	v_mfma_f32_16x16x32_bf16 v[56:59], v[160:163], v[184:187], 0
	v_mfma_f32_16x16x32_bf16 v[44:47], v[152:155], v[192:195], 0
	v_mfma_f32_16x16x32_bf16 v[40:43], v[160:163], v[192:195], 0
	v_mfma_f32_16x16x32_bf16 v[28:31], v[152:155], v[200:203], 0
	v_mfma_f32_16x16x32_bf16 v[24:27], v[160:163], v[200:203], 0
	v_mfma_f32_16x16x32_bf16 v[12:15], v[152:155], v[208:211], 0
	v_mfma_f32_16x16x32_bf16 v[8:11], v[160:163], v[208:211], 0
	v_mfma_f32_16x16x32_bf16 v[60:63], v[156:159], v[188:191], v[60:63]
	v_mfma_f32_16x16x32_bf16 v[56:59], v[164:167], v[188:191], v[56:59]
	v_mfma_f32_16x16x32_bf16 v[44:47], v[156:159], v[196:199], v[44:47]
	v_mfma_f32_16x16x32_bf16 v[40:43], v[164:167], v[196:199], v[40:43]
	v_mfma_f32_16x16x32_bf16 v[28:31], v[156:159], v[204:207], v[28:31]
	v_mfma_f32_16x16x32_bf16 v[24:27], v[164:167], v[204:207], v[24:27]
	v_mfma_f32_16x16x32_bf16 v[12:15], v[156:159], v[214:217], v[12:15]
	v_mfma_f32_16x16x32_bf16 v[8:11], v[164:167], v[214:217], v[8:11]
	v_mfma_f32_16x16x32_bf16 v[52:55], v[168:171], v[184:187], 0
	v_mfma_f32_16x16x32_bf16 v[48:51], v[176:179], v[184:187], 0
	v_mfma_f32_16x16x32_bf16 v[36:39], v[168:171], v[192:195], 0
	v_mfma_f32_16x16x32_bf16 v[32:35], v[176:179], v[192:195], 0
	v_mfma_f32_16x16x32_bf16 v[20:23], v[168:171], v[200:203], 0
	v_mfma_f32_16x16x32_bf16 v[16:19], v[176:179], v[200:203], 0
	v_mfma_f32_16x16x32_bf16 v[4:7], v[168:171], v[208:211], 0
	v_mfma_f32_16x16x32_bf16 v[0:3], v[176:179], v[208:211], 0
	v_mfma_f32_16x16x32_bf16 v[52:55], v[172:175], v[188:191], v[52:55]
	v_mfma_f32_16x16x32_bf16 v[48:51], v[180:183], v[188:191], v[48:51]
	v_mfma_f32_16x16x32_bf16 v[36:39], v[172:175], v[196:199], v[36:39]
	v_mfma_f32_16x16x32_bf16 v[32:35], v[180:183], v[196:199], v[32:35]
	v_mfma_f32_16x16x32_bf16 v[20:23], v[172:175], v[204:207], v[20:23]
	v_mfma_f32_16x16x32_bf16 v[16:19], v[180:183], v[204:207], v[16:19]
	v_mfma_f32_16x16x32_bf16 v[4:7], v[172:175], v[214:217], v[4:7]
	v_mfma_f32_16x16x32_bf16 v[0:3], v[180:183], v[214:217], v[0:3]
	s_barrier
	s_add_i32 s62, 0, 0x18000
	s_add_i32 s63, 0, 0x1c000
	v_add_u32_e32 v164, s62, v147
	v_add_u32_e32 v180, s63, v147
	ds_read_b128 v[152:155], v164
	ds_read_b128 v[156:159], v164 offset:1024
	ds_read_b128 v[160:163], v164 offset:2048
	ds_read_b128 v[164:167], v164 offset:3072
	ds_read_b128 v[168:171], v180
	ds_read_b128 v[172:175], v180 offset:1024
	ds_read_b128 v[176:179], v180 offset:2048
	ds_read_b128 v[180:183], v180 offset:3072
	s_add_u32 s84, s42, 0x80
	s_addc_u32 s85, s43, 0
	s_add_u32 s42, s42, 0x80000
	s_addc_u32 s43, s43, 0
	s_mov_b32 m0, s46
	ds_read_b128 v[184:187], v151 offset:32768
	ds_read_b128 v[188:191], v151 offset:33792
	ds_read_b128 v[192:195], v151 offset:34816
	ds_read_b128 v[196:199], v151 offset:35840
	ds_read_b128 v[200:203], v151 offset:36864
	ds_read_b128 v[204:207], v151 offset:37888
	ds_read_b128 v[208:211], v151 offset:38912
	ds_read_b128 v[214:217], v151 offset:39936
	global_load_lds_dwordx4 v134, s[42:43]
	s_mov_b32 m0, s47
	s_nop 0
	global_load_lds_dwordx4 v130, s[42:43]
	s_waitcnt vmcnt(8)
	s_waitcnt lgkmcnt(0)
	s_barrier
	v_mfma_f32_16x16x32_bf16 v[124:127], v[152:155], v[184:187], v[124:127]
	v_mfma_f32_16x16x32_bf16 v[120:123], v[160:163], v[184:187], v[120:123]
	v_mfma_f32_16x16x32_bf16 v[108:111], v[152:155], v[192:195], v[108:111]
	v_mfma_f32_16x16x32_bf16 v[104:107], v[160:163], v[192:195], v[104:107]
	v_mfma_f32_16x16x32_bf16 v[92:95], v[152:155], v[200:203], v[92:95]
	v_mfma_f32_16x16x32_bf16 v[88:91], v[160:163], v[200:203], v[88:91]
	v_mfma_f32_16x16x32_bf16 v[76:79], v[152:155], v[208:211], v[76:79]
	v_mfma_f32_16x16x32_bf16 v[72:75], v[160:163], v[208:211], v[72:75]
	v_mfma_f32_16x16x32_bf16 v[124:127], v[156:159], v[188:191], v[124:127]
	v_mfma_f32_16x16x32_bf16 v[120:123], v[164:167], v[188:191], v[120:123]
	v_mfma_f32_16x16x32_bf16 v[108:111], v[156:159], v[196:199], v[108:111]
	v_mfma_f32_16x16x32_bf16 v[104:107], v[164:167], v[196:199], v[104:107]
	v_mfma_f32_16x16x32_bf16 v[92:95], v[156:159], v[204:207], v[92:95]
	v_mfma_f32_16x16x32_bf16 v[88:91], v[164:167], v[204:207], v[88:91]
	v_mfma_f32_16x16x32_bf16 v[76:79], v[156:159], v[214:217], v[76:79]
	v_mfma_f32_16x16x32_bf16 v[72:75], v[164:167], v[214:217], v[72:75]
	v_mfma_f32_16x16x32_bf16 v[116:119], v[168:171], v[184:187], v[116:119]
	v_mfma_f32_16x16x32_bf16 v[112:115], v[176:179], v[184:187], v[112:115]
	v_mfma_f32_16x16x32_bf16 v[100:103], v[168:171], v[192:195], v[100:103]
	v_mfma_f32_16x16x32_bf16 v[96:99], v[176:179], v[192:195], v[96:99]
	v_mfma_f32_16x16x32_bf16 v[84:87], v[168:171], v[200:203], v[84:87]
	v_mfma_f32_16x16x32_bf16 v[80:83], v[176:179], v[200:203], v[80:83]
	v_mfma_f32_16x16x32_bf16 v[68:71], v[168:171], v[208:211], v[68:71]
	v_mfma_f32_16x16x32_bf16 v[64:67], v[176:179], v[208:211], v[64:67]
	v_mfma_f32_16x16x32_bf16 v[116:119], v[172:175], v[188:191], v[116:119]
	v_mfma_f32_16x16x32_bf16 v[112:115], v[180:183], v[188:191], v[112:115]
	v_mfma_f32_16x16x32_bf16 v[100:103], v[172:175], v[196:199], v[100:103]
	v_mfma_f32_16x16x32_bf16 v[96:99], v[180:183], v[196:199], v[96:99]
	v_mfma_f32_16x16x32_bf16 v[84:87], v[172:175], v[204:207], v[84:87]
	v_mfma_f32_16x16x32_bf16 v[80:83], v[180:183], v[204:207], v[80:83]
	v_mfma_f32_16x16x32_bf16 v[68:71], v[172:175], v[214:217], v[68:71]
	v_mfma_f32_16x16x32_bf16 v[64:67], v[180:183], v[214:217], v[64:67]
	s_barrier
; #define PG8_STAGE(bufoff, gbase, voff) do { _Pragma("unroll") for (int _i = 0; _i < 2; ++_i) \
;         __builtin_amdgcn_global_load_lds((const unsigned*)((const char*)(gbase) + (voff)[_i]), (PG8_LAS unsigned*)(lds + (bufoff) + ldsw + _i * 8192), 16, 0, 0); } while (0)
; #define PG8_LDA(dst, b, h) do { _Pragma("unroll") for (int m = 0; m < 4; ++m) _Pragma("unroll") for (int k = 0; k < 2; ++k) dst[m][k] = *(const PG8_LAS bf16x8*)(lds + PG8_SA(b, h) + aoff + m * 2048 + k * 1024); } while (0)
; #define PG8_LDB(dst, b, h) do { _Pragma("unroll") for (int n = 0; n < 2; ++n) _Pragma("unroll") for (int k = 0; k < 2; ++k) dst[n][k] = *(const PG8_LAS bf16x8*)(lds + PG8_SB(b, h) + boff + n * 2048 + k * 1024); } while (0)
; #define PG8_MMA(ai, bj, At, Bt) do { __builtin_amdgcn_s_setprio(1); _Pragma("unroll") for (int m = 0; m < 4; ++m) _Pragma("unroll") for (int n = 0; n < 2; ++n) _Pragma("unroll") for (int k = 0; k < 2; ++k) \
;         acc[ai][bj][m][n] = __builtin_amdgcn_mfma_f32_16x16x32_bf16(Bt[n][k], At[m][k], acc[ai][bj][m][n], 0, 0, 0); __builtin_amdgcn_s_setprio(0); } while (0)
; #define PG8_WAIT_V(n) asm volatile("s_waitcnt vmcnt(" #n ")" ::: "memory")
; #define PG8_WAIT_L(n) asm volatile("s_waitcnt lgkmcnt(" #n ")" ::: "memory")
; #define PG8_BAR __builtin_amdgcn_s_barrier()
; #define PG8_SCHED __builtin_amdgcn_sched_barrier(0)
; template <class Epi, class Sched, bool ALIGN_EPI = false, bool SP2 = false>
; __device__ __forceinline__ void gemm_phase(PG8_LAS unsigned char* lds, const Gemm g, const Sched& S, const Epi& E) {
;     ...
;             PG8_LDB(B0, 0, 0); PG8_LDB(B1, 0, 1); PG8_SCHED; PG8_LDA(At, 0, 0); PG8_STAGE(PG8_SA(1, 1), a1 + hstep, voffA);
;             PG8_WAIT_V(8); PG8_WAIT_L(0); PG8_BAR; PG8_MMA(0, 0, At, B0); PG8_MMA(0, 1, At, B1); PG8_BAR; PG8_SCHED;
;     ...
;             PG8_LDA(At, 1, 1); PG8_STAGE(PG8_SB(1, 0), b3, voffB); PG8_STAGE(PG8_SB(1, 1), b3 + hstep, voffB); PG8_STAGE(PG8_SA(1, 0), a3, voffA);
;             PG8_WAIT_V(8); PG8_WAIT_L(0); PG8_BAR; PG8_MMA(1, 0, At, B0); PG8_MMA(1, 1, At, B1); PG8_BAR; PG8_SCHED;
	s_add_i32 s42, s62, s24
	s_add_u32 s86, s40, 0x80
	s_addc_u32 s87, s41, 0
	s_mov_b32 m0, s42
	ds_read_b128 v[184:187], v151 offset:49152
	ds_read_b128 v[188:191], v151 offset:50176
	ds_read_b128 v[192:195], v151 offset:51200
	ds_read_b128 v[196:199], v151 offset:52224
	ds_read_b128 v[200:203], v151 offset:53248
	ds_read_b128 v[204:207], v151 offset:54272
	ds_read_b128 v[208:211], v151 offset:55296
	ds_read_b128 v[214:217], v151 offset:56320
	global_load_lds_dwordx4 v132, s[86:87]
	s_add_i32 m0, s42, 0x2000
	s_add_u32 s40, s40, 0x80080
	s_addc_u32 s41, s41, 0
	s_add_i32 s42, s63, s24
	global_load_lds_dwordx4 v128, s[86:87]
	s_mov_b32 m0, s42
	s_nop 0
	global_load_lds_dwordx4 v132, s[40:41]
	s_add_i32 m0, s42, 0x2000
	s_nop 0
	global_load_lds_dwordx4 v128, s[40:41]
	s_mov_b32 m0, s49
	s_nop 0
	global_load_lds_dwordx4 v134, s[84:85]
	s_mov_b32 m0, s50
	s_nop 0
	global_load_lds_dwordx4 v130, s[84:85]
	s_waitcnt vmcnt(8)
	s_waitcnt lgkmcnt(0)
	s_barrier
	v_mfma_f32_16x16x32_bf16 v[60:63], v[152:155], v[184:187], v[60:63]
	v_mfma_f32_16x16x32_bf16 v[56:59], v[160:163], v[184:187], v[56:59]
	v_mfma_f32_16x16x32_bf16 v[44:47], v[152:155], v[192:195], v[44:47]
	v_mfma_f32_16x16x32_bf16 v[40:43], v[160:163], v[192:195], v[40:43]
	v_mfma_f32_16x16x32_bf16 v[28:31], v[152:155], v[200:203], v[28:31]
	v_mfma_f32_16x16x32_bf16 v[24:27], v[160:163], v[200:203], v[24:27]
	v_mfma_f32_16x16x32_bf16 v[12:15], v[152:155], v[208:211], v[12:15]
	v_mfma_f32_16x16x32_bf16 v[8:11], v[160:163], v[208:211], v[8:11]
	v_mfma_f32_16x16x32_bf16 v[60:63], v[156:159], v[188:191], v[60:63]
	v_mfma_f32_16x16x32_bf16 v[56:59], v[164:167], v[188:191], v[56:59]
	v_mfma_f32_16x16x32_bf16 v[44:47], v[156:159], v[196:199], v[44:47]
	v_mfma_f32_16x16x32_bf16 v[40:43], v[164:167], v[196:199], v[40:43]
	v_mfma_f32_16x16x32_bf16 v[28:31], v[156:159], v[204:207], v[28:31]
	v_mfma_f32_16x16x32_bf16 v[24:27], v[164:167], v[204:207], v[24:27]
	v_mfma_f32_16x16x32_bf16 v[12:15], v[156:159], v[214:217], v[12:15]
	v_mfma_f32_16x16x32_bf16 v[8:11], v[164:167], v[214:217], v[8:11]
	v_mfma_f32_16x16x32_bf16 v[52:55], v[168:171], v[184:187], v[52:55]
	v_mfma_f32_16x16x32_bf16 v[48:51], v[176:179], v[184:187], v[48:51]
	v_mfma_f32_16x16x32_bf16 v[36:39], v[168:171], v[192:195], v[36:39]
	v_mfma_f32_16x16x32_bf16 v[32:35], v[176:179], v[192:195], v[32:35]
	v_mfma_f32_16x16x32_bf16 v[20:23], v[168:171], v[200:203], v[20:23]
	v_mfma_f32_16x16x32_bf16 v[16:19], v[176:179], v[200:203], v[16:19]
	v_mfma_f32_16x16x32_bf16 v[4:7], v[168:171], v[208:211], v[4:7]
	v_mfma_f32_16x16x32_bf16 v[0:3], v[176:179], v[208:211], v[0:3]
	v_mfma_f32_16x16x32_bf16 v[52:55], v[172:175], v[188:191], v[52:55]
	v_mfma_f32_16x16x32_bf16 v[48:51], v[180:183], v[188:191], v[48:51]
	v_mfma_f32_16x16x32_bf16 v[36:39], v[172:175], v[196:199], v[36:39]
	v_mfma_f32_16x16x32_bf16 v[32:35], v[180:183], v[196:199], v[32:35]
	v_mfma_f32_16x16x32_bf16 v[20:23], v[172:175], v[204:207], v[20:23]
	v_mfma_f32_16x16x32_bf16 v[16:19], v[180:183], v[204:207], v[16:19]
	v_mfma_f32_16x16x32_bf16 v[4:7], v[172:175], v[214:217], v[4:7]
	v_mfma_f32_16x16x32_bf16 v[0:3], v[180:183], v[214:217], v[0:3]
	s_barrier
	s_add_i32 s61, s61, 2
	s_add_u32 s38, s38, 0x100
	s_addc_u32 s39, s39, 0
	s_add_u32 s59, s59, 0x100
	s_addc_u32 s60, s60, 0
	s_cmp_gt_u32 s61, 29
.LBB0_169:
	ds_read_b128 v[152:155], v149
	ds_read_b128 v[156:159], v149 offset:1024
	ds_read_b128 v[160:163], v149 offset:2048
	ds_read_b128 v[164:167], v149 offset:3072
	ds_read_b128 v[168:171], v150
	ds_read_b128 v[172:175], v150 offset:1024
	ds_read_b128 v[176:179], v150 offset:2048
	ds_read_b128 v[180:183], v150 offset:3072
	s_add_u32 s40, s38, 0xfff80080
	s_addc_u32 s41, s39, -1
	s_cmp_eq_u32 s61, 28
	s_cselect_b32 s43, s29, s41
	s_cselect_b32 s42, s57, s40
	s_cselect_b32 s41, s27, s60
	s_cselect_b32 s40, s58, s59
	s_add_i32 m0, s37, 0xc000
	ds_read_b128 v[184:187], v151
	ds_read_b128 v[188:191], v151 offset:1024
	ds_read_b128 v[192:195], v151 offset:2048
	ds_read_b128 v[196:199], v151 offset:3072
	ds_read_b128 v[200:203], v151 offset:4096
	ds_read_b128 v[204:207], v151 offset:5120
	ds_read_b128 v[208:211], v151 offset:6144
	ds_read_b128 v[214:217], v151 offset:7168
	global_load_lds_dwordx4 v136, s[38:39]
	s_add_i32 m0, s37, 0xe000
	s_nop 0
	global_load_lds_dwordx4 v138, s[38:39]
	s_waitcnt vmcnt(8)
	s_waitcnt lgkmcnt(0)
	s_barrier
	v_mfma_f32_16x16x32_bf16 v[124:127], v[152:155], v[184:187], v[124:127]
	v_mfma_f32_16x16x32_bf16 v[120:123], v[160:163], v[184:187], v[120:123]
	v_mfma_f32_16x16x32_bf16 v[108:111], v[152:155], v[192:195], v[108:111]
	v_mfma_f32_16x16x32_bf16 v[104:107], v[160:163], v[192:195], v[104:107]
	v_mfma_f32_16x16x32_bf16 v[92:95], v[152:155], v[200:203], v[92:95]
	v_mfma_f32_16x16x32_bf16 v[88:91], v[160:163], v[200:203], v[88:91]
	v_mfma_f32_16x16x32_bf16 v[76:79], v[152:155], v[208:211], v[76:79]
	v_mfma_f32_16x16x32_bf16 v[72:75], v[160:163], v[208:211], v[72:75]
	v_mfma_f32_16x16x32_bf16 v[124:127], v[156:159], v[188:191], v[124:127]
	v_mfma_f32_16x16x32_bf16 v[120:123], v[164:167], v[188:191], v[120:123]
	v_mfma_f32_16x16x32_bf16 v[108:111], v[156:159], v[196:199], v[108:111]
	v_mfma_f32_16x16x32_bf16 v[104:107], v[164:167], v[196:199], v[104:107]
	v_mfma_f32_16x16x32_bf16 v[92:95], v[156:159], v[204:207], v[92:95]
	v_mfma_f32_16x16x32_bf16 v[88:91], v[164:167], v[204:207], v[88:91]
	v_mfma_f32_16x16x32_bf16 v[76:79], v[156:159], v[214:217], v[76:79]
	v_mfma_f32_16x16x32_bf16 v[72:75], v[164:167], v[214:217], v[72:75]
	v_mfma_f32_16x16x32_bf16 v[116:119], v[168:171], v[184:187], v[116:119]
	v_mfma_f32_16x16x32_bf16 v[112:115], v[176:179], v[184:187], v[112:115]
	v_mfma_f32_16x16x32_bf16 v[100:103], v[168:171], v[192:195], v[100:103]
	v_mfma_f32_16x16x32_bf16 v[96:99], v[176:179], v[192:195], v[96:99]
	v_mfma_f32_16x16x32_bf16 v[84:87], v[168:171], v[200:203], v[84:87]
	v_mfma_f32_16x16x32_bf16 v[80:83], v[176:179], v[200:203], v[80:83]
	v_mfma_f32_16x16x32_bf16 v[68:71], v[168:171], v[208:211], v[68:71]
	v_mfma_f32_16x16x32_bf16 v[64:67], v[176:179], v[208:211], v[64:67]
	v_mfma_f32_16x16x32_bf16 v[116:119], v[172:175], v[188:191], v[116:119]
	v_mfma_f32_16x16x32_bf16 v[112:115], v[180:183], v[188:191], v[112:115]
	v_mfma_f32_16x16x32_bf16 v[100:103], v[172:175], v[196:199], v[100:103]
	v_mfma_f32_16x16x32_bf16 v[96:99], v[180:183], v[196:199], v[96:99]
	v_mfma_f32_16x16x32_bf16 v[84:87], v[172:175], v[204:207], v[84:87]
	v_mfma_f32_16x16x32_bf16 v[80:83], v[180:183], v[204:207], v[80:83]
	v_mfma_f32_16x16x32_bf16 v[68:71], v[172:175], v[214:217], v[68:71]
	v_mfma_f32_16x16x32_bf16 v[64:67], v[180:183], v[214:217], v[64:67]
	s_barrier
; #define PG8_STAGE(bufoff, gbase, voff) do { _Pragma("unroll") for (int _i = 0; _i < 2; ++_i) \
;         __builtin_amdgcn_global_load_lds((const unsigned*)((const char*)(gbase) + (voff)[_i]), (PG8_LAS unsigned*)(lds + (bufoff) + ldsw + _i * 8192), 16, 0, 0); } while (0)
; #define PG8_LDA(dst, b, h) do { _Pragma("unroll") for (int m = 0; m < 4; ++m) _Pragma("unroll") for (int k = 0; k < 2; ++k) dst[m][k] = *(const PG8_LAS bf16x8*)(lds + PG8_SA(b, h) + aoff + m * 2048 + k * 1024); } while (0)
; #define PG8_LDB(dst, b, h) do { _Pragma("unroll") for (int n = 0; n < 2; ++n) _Pragma("unroll") for (int k = 0; k < 2; ++k) dst[n][k] = *(const PG8_LAS bf16x8*)(lds + PG8_SB(b, h) + boff + n * 2048 + k * 1024); } while (0)
; #define PG8_MMA(ai, bj, At, Bt) do { __builtin_amdgcn_s_setprio(1); _Pragma("unroll") for (int m = 0; m < 4; ++m) _Pragma("unroll") for (int n = 0; n < 2; ++n) _Pragma("unroll") for (int k = 0; k < 2; ++k) \
;         acc[ai][bj][m][n] = __builtin_amdgcn_mfma_f32_16x16x32_bf16(Bt[n][k], At[m][k], acc[ai][bj][m][n], 0, 0, 0); __builtin_amdgcn_s_setprio(0); } while (0)
; #define PG8_WAIT_V(n) asm volatile("s_waitcnt vmcnt(" #n ")" ::: "memory")
; #define PG8_WAIT_L(n) asm volatile("s_waitcnt lgkmcnt(" #n ")" ::: "memory")
; #define PG8_BAR __builtin_amdgcn_s_barrier()
; #define PG8_SCHED __builtin_amdgcn_sched_barrier(0)
; template <class Epi, class Sched, bool ALIGN_EPI = false, bool SP2 = false>
; __device__ __forceinline__ void gemm_phase(PG8_LAS unsigned char* lds, const Gemm g, const Sched& S, const Epi& E) {
;     ...
;             PG8_LDA(At, 0, 1); PG8_STAGE(PG8_SB(0, 0), b2, voffB); PG8_STAGE(PG8_SB(0, 1), b2 + hstep, voffB); PG8_STAGE(PG8_SA(0, 0), a2, voffA);
;             PG8_WAIT_V(8); PG8_WAIT_L(0); PG8_BAR; PG8_MMA(1, 0, At, B0); PG8_MMA(1, 1, At, B1); PG8_BAR; PG8_SCHED;
;             PG8_LDB(B0, 1, 0); PG8_LDB(B1, 1, 1); PG8_SCHED; PG8_LDA(At, 1, 0); PG8_STAGE(PG8_SA(0, 1), a2 + hstep, voffA);
;             PG8_WAIT_V(8); PG8_WAIT_L(0); PG8_BAR; PG8_MMA(0, 0, At, B0); PG8_MMA(0, 1, At, B1); PG8_BAR; PG8_SCHED;
	s_add_i32 s62, s53, s24
	s_mov_b32 m0, s62
	ds_read_b128 v[184:187], v151 offset:16384
	ds_read_b128 v[188:191], v151 offset:17408
	ds_read_b128 v[192:195], v151 offset:18432
	ds_read_b128 v[196:199], v151 offset:19456
	ds_read_b128 v[200:203], v151 offset:20480
	ds_read_b128 v[204:207], v151 offset:21504
	ds_read_b128 v[208:211], v151 offset:22528
	ds_read_b128 v[214:217], v151 offset:23552
	global_load_lds_dwordx4 v132, s[40:41]
	s_add_i32 m0, s62, 0x2000
	s_add_u32 s62, s40, 0x80000
	s_addc_u32 s63, s41, 0
	s_add_i32 s64, s54, s24
	global_load_lds_dwordx4 v128, s[40:41]
	s_mov_b32 m0, s64
	s_nop 0
	global_load_lds_dwordx4 v132, s[62:63]
	s_add_i32 m0, s64, 0x2000
	s_nop 0
	global_load_lds_dwordx4 v128, s[62:63]
	s_mov_b32 m0, s37
	s_nop 0
	global_load_lds_dwordx4 v134, s[42:43]
	s_mov_b32 m0, s45
	s_nop 0
	global_load_lds_dwordx4 v130, s[42:43]
	s_waitcnt vmcnt(8)
	s_waitcnt lgkmcnt(0)
	s_barrier
	v_mfma_f32_16x16x32_bf16 v[60:63], v[152:155], v[184:187], v[60:63]
	v_mfma_f32_16x16x32_bf16 v[56:59], v[160:163], v[184:187], v[56:59]
	v_mfma_f32_16x16x32_bf16 v[44:47], v[152:155], v[192:195], v[44:47]
	v_mfma_f32_16x16x32_bf16 v[40:43], v[160:163], v[192:195], v[40:43]
	v_mfma_f32_16x16x32_bf16 v[28:31], v[152:155], v[200:203], v[28:31]
	v_mfma_f32_16x16x32_bf16 v[24:27], v[160:163], v[200:203], v[24:27]
	v_mfma_f32_16x16x32_bf16 v[12:15], v[152:155], v[208:211], v[12:15]
	v_mfma_f32_16x16x32_bf16 v[8:11], v[160:163], v[208:211], v[8:11]
	v_mfma_f32_16x16x32_bf16 v[60:63], v[156:159], v[188:191], v[60:63]
	v_mfma_f32_16x16x32_bf16 v[56:59], v[164:167], v[188:191], v[56:59]
	v_mfma_f32_16x16x32_bf16 v[44:47], v[156:159], v[196:199], v[44:47]
	v_mfma_f32_16x16x32_bf16 v[40:43], v[164:167], v[196:199], v[40:43]
	v_mfma_f32_16x16x32_bf16 v[28:31], v[156:159], v[204:207], v[28:31]
	v_mfma_f32_16x16x32_bf16 v[24:27], v[164:167], v[204:207], v[24:27]
	v_mfma_f32_16x16x32_bf16 v[12:15], v[156:159], v[214:217], v[12:15]
	v_mfma_f32_16x16x32_bf16 v[8:11], v[164:167], v[214:217], v[8:11]
	v_mfma_f32_16x16x32_bf16 v[52:55], v[168:171], v[184:187], v[52:55]
	v_mfma_f32_16x16x32_bf16 v[48:51], v[176:179], v[184:187], v[48:51]
	v_mfma_f32_16x16x32_bf16 v[36:39], v[168:171], v[192:195], v[36:39]
	v_mfma_f32_16x16x32_bf16 v[32:35], v[176:179], v[192:195], v[32:35]
	v_mfma_f32_16x16x32_bf16 v[20:23], v[168:171], v[200:203], v[20:23]
	v_mfma_f32_16x16x32_bf16 v[16:19], v[176:179], v[200:203], v[16:19]
	v_mfma_f32_16x16x32_bf16 v[4:7], v[168:171], v[208:211], v[4:7]
	v_mfma_f32_16x16x32_bf16 v[0:3], v[176:179], v[208:211], v[0:3]
	v_mfma_f32_16x16x32_bf16 v[52:55], v[172:175], v[188:191], v[52:55]
	v_mfma_f32_16x16x32_bf16 v[48:51], v[180:183], v[188:191], v[48:51]
	v_mfma_f32_16x16x32_bf16 v[36:39], v[172:175], v[196:199], v[36:39]
	v_mfma_f32_16x16x32_bf16 v[32:35], v[180:183], v[196:199], v[32:35]
	v_mfma_f32_16x16x32_bf16 v[20:23], v[172:175], v[204:207], v[20:23]
	v_mfma_f32_16x16x32_bf16 v[16:19], v[180:183], v[204:207], v[16:19]
	v_mfma_f32_16x16x32_bf16 v[4:7], v[172:175], v[214:217], v[4:7]
	v_mfma_f32_16x16x32_bf16 v[0:3], v[180:183], v[214:217], v[0:3]
	s_barrier
	s_add_i32 s62, 0, 0x18000
	s_add_i32 s63, 0, 0x1c000
	v_add_u32_e32 v164, s62, v147
	v_add_u32_e32 v180, s63, v147
	ds_read_b128 v[152:155], v164
	ds_read_b128 v[156:159], v164 offset:1024
	ds_read_b128 v[160:163], v164 offset:2048
	ds_read_b128 v[164:167], v164 offset:3072
	ds_read_b128 v[168:171], v180
	ds_read_b128 v[172:175], v180 offset:1024
	ds_read_b128 v[176:179], v180 offset:2048
	ds_read_b128 v[180:183], v180 offset:3072
	s_add_u32 s84, s42, 0x80
	s_addc_u32 s85, s43, 0
	s_add_u32 s42, s42, 0x80000
	s_addc_u32 s43, s43, 0
	s_mov_b32 m0, s46
	ds_read_b128 v[184:187], v151 offset:32768
	ds_read_b128 v[188:191], v151 offset:33792
	ds_read_b128 v[192:195], v151 offset:34816
	ds_read_b128 v[196:199], v151 offset:35840
	ds_read_b128 v[200:203], v151 offset:36864
	ds_read_b128 v[204:207], v151 offset:37888
	ds_read_b128 v[208:211], v151 offset:38912
	ds_read_b128 v[214:217], v151 offset:39936
	global_load_lds_dwordx4 v134, s[42:43]
	s_mov_b32 m0, s47
	s_nop 0
	global_load_lds_dwordx4 v130, s[42:43]
	s_waitcnt vmcnt(8)
	s_waitcnt lgkmcnt(0)
	s_barrier
	v_mfma_f32_16x16x32_bf16 v[124:127], v[152:155], v[184:187], v[124:127]
	v_mfma_f32_16x16x32_bf16 v[120:123], v[160:163], v[184:187], v[120:123]
	v_mfma_f32_16x16x32_bf16 v[108:111], v[152:155], v[192:195], v[108:111]
	v_mfma_f32_16x16x32_bf16 v[104:107], v[160:163], v[192:195], v[104:107]
	v_mfma_f32_16x16x32_bf16 v[92:95], v[152:155], v[200:203], v[92:95]
	v_mfma_f32_16x16x32_bf16 v[88:91], v[160:163], v[200:203], v[88:91]
	v_mfma_f32_16x16x32_bf16 v[76:79], v[152:155], v[208:211], v[76:79]
	v_mfma_f32_16x16x32_bf16 v[72:75], v[160:163], v[208:211], v[72:75]
	v_mfma_f32_16x16x32_bf16 v[124:127], v[156:159], v[188:191], v[124:127]
	v_mfma_f32_16x16x32_bf16 v[120:123], v[164:167], v[188:191], v[120:123]
	v_mfma_f32_16x16x32_bf16 v[108:111], v[156:159], v[196:199], v[108:111]
	v_mfma_f32_16x16x32_bf16 v[104:107], v[164:167], v[196:199], v[104:107]
	v_mfma_f32_16x16x32_bf16 v[92:95], v[156:159], v[204:207], v[92:95]
	v_mfma_f32_16x16x32_bf16 v[88:91], v[164:167], v[204:207], v[88:91]
	v_mfma_f32_16x16x32_bf16 v[76:79], v[156:159], v[214:217], v[76:79]
	v_mfma_f32_16x16x32_bf16 v[72:75], v[164:167], v[214:217], v[72:75]
	v_mfma_f32_16x16x32_bf16 v[116:119], v[168:171], v[184:187], v[116:119]
	v_mfma_f32_16x16x32_bf16 v[112:115], v[176:179], v[184:187], v[112:115]
	v_mfma_f32_16x16x32_bf16 v[100:103], v[168:171], v[192:195], v[100:103]
	v_mfma_f32_16x16x32_bf16 v[96:99], v[176:179], v[192:195], v[96:99]
	v_mfma_f32_16x16x32_bf16 v[84:87], v[168:171], v[200:203], v[84:87]
	v_mfma_f32_16x16x32_bf16 v[80:83], v[176:179], v[200:203], v[80:83]
	v_mfma_f32_16x16x32_bf16 v[68:71], v[168:171], v[208:211], v[68:71]
	v_mfma_f32_16x16x32_bf16 v[64:67], v[176:179], v[208:211], v[64:67]
	v_mfma_f32_16x16x32_bf16 v[116:119], v[172:175], v[188:191], v[116:119]
	v_mfma_f32_16x16x32_bf16 v[112:115], v[180:183], v[188:191], v[112:115]
	v_mfma_f32_16x16x32_bf16 v[100:103], v[172:175], v[196:199], v[100:103]
	v_mfma_f32_16x16x32_bf16 v[96:99], v[180:183], v[196:199], v[96:99]
	v_mfma_f32_16x16x32_bf16 v[84:87], v[172:175], v[204:207], v[84:87]
	v_mfma_f32_16x16x32_bf16 v[80:83], v[180:183], v[204:207], v[80:83]
	v_mfma_f32_16x16x32_bf16 v[68:71], v[172:175], v[214:217], v[68:71]
	v_mfma_f32_16x16x32_bf16 v[64:67], v[180:183], v[214:217], v[64:67]
	s_barrier
; __device__ __forceinline__ float fsilu(float v) { return v * fsigmoid(v); }
; __device__ __forceinline__ u32x4 pack8(const f32x4 a, const f32x4 b) { u32x4 w; w.x = cvt_pk_bf16(a[0], a[1]); w.y = cvt_pk_bf16(a[2], a[3]); w.z = cvt_pk_bf16(b[0], b[1]); w.w = cvt_pk_bf16(b[2], b[3]); return w; }
; #define PG8_STAGE(bufoff, gbase, voff) do { _Pragma("unroll") for (int _i = 0; _i < 2; ++_i) \
;         __builtin_amdgcn_global_load_lds((const unsigned*)((const char*)(gbase) + (voff)[_i]), (PG8_LAS unsigned*)(lds + (bufoff) + ldsw + _i * 8192), 16, 0, 0); } while (0)
; #define PG8_LDA(dst, b, h) do { _Pragma("unroll") for (int m = 0; m < 4; ++m) _Pragma("unroll") for (int k = 0; k < 2; ++k) dst[m][k] = *(const PG8_LAS bf16x8*)(lds + PG8_SA(b, h) + aoff + m * 2048 + k * 1024); } while (0)
; #define PG8_MMA(ai, bj, At, Bt) do { __builtin_amdgcn_s_setprio(1); _Pragma("unroll") for (int m = 0; m < 4; ++m) _Pragma("unroll") for (int n = 0; n < 2; ++n) _Pragma("unroll") for (int k = 0; k < 2; ++k) \
;         acc[ai][bj][m][n] = __builtin_amdgcn_mfma_f32_16x16x32_bf16(Bt[n][k], At[m][k], acc[ai][bj][m][n], 0, 0, 0); __builtin_amdgcn_s_setprio(0); } while (0)
; #define PG8_BAR __builtin_amdgcn_s_barrier()
;     __device__ __forceinline__ void operator()(const f32x4 (&acc)[2][2][4][2], const Unit& u, int wr, int wc, int fr, int fq) const {
;         const int row0 = u.pm * BM + wr * 64 + fr, col0 = u.pn * 128 + wc * 32 + 8 * fq;
; #pragma unroll
;         for (int ai = 0; ai < 2; ++ai)
; #pragma unroll
;             for (int m = 0; m < 4; ++m) {
;                 bf16_t* rowp = O + (size_t)(row0 + ai * HALF + m * 16) * ldc + col0;
;                 f32x4 h0, h1;
; #pragma unroll
;                 for (int j = 0; j < 4; ++j) { h0[j] = fsilu(acc[ai][0][m][0][j]) * acc[ai][1][m][0][j]; h1[j] = fsilu(acc[ai][0][m][1][j]) * acc[ai][1][m][1][j]; }
;                 *(u32x4*)rowp = pack8(h0, h1);
; template <class Epi, class Sched, bool ALIGN_EPI = false, bool SP2 = false>
; __device__ __forceinline__ void gemm_phase(PG8_LAS unsigned char* lds, const Gemm g, const Sched& S, const Epi& E) {
;     ...
;             PG8_LDA(At, 1, 1); PG8_STAGE(PG8_SB(1, 0), b3, voffB); PG8_STAGE(PG8_SB(1, 1), b3 + hstep, voffB); PG8_STAGE(PG8_SA(1, 0), a3, voffA);
;             PG8_WAIT_V(8); PG8_WAIT_L(0); PG8_BAR; PG8_MMA(1, 0, At, B0); PG8_MMA(1, 1, At, B1); PG8_BAR; PG8_SCHED;
	s_add_i32 s42, s62, s24
	s_add_u32 s86, s40, 0x80
	s_addc_u32 s87, s41, 0
	s_mov_b32 m0, s42
	ds_read_b128 v[184:187], v151 offset:49152
	ds_read_b128 v[188:191], v151 offset:50176
	ds_read_b128 v[192:195], v151 offset:51200
	ds_read_b128 v[196:199], v151 offset:52224
	ds_read_b128 v[200:203], v151 offset:53248
	ds_read_b128 v[204:207], v151 offset:54272
	ds_read_b128 v[208:211], v151 offset:55296
	ds_read_b128 v[214:217], v151 offset:56320
	global_load_lds_dwordx4 v132, s[86:87]
	s_add_i32 m0, s42, 0x2000
	s_add_u32 s40, s40, 0x80080
	s_addc_u32 s41, s41, 0
	s_add_i32 s42, s63, s24
	global_load_lds_dwordx4 v128, s[86:87]
	s_mov_b32 m0, s42
	s_nop 0
	global_load_lds_dwordx4 v132, s[40:41]
	s_add_i32 m0, s42, 0x2000
	s_nop 0
	global_load_lds_dwordx4 v128, s[40:41]
	s_mov_b32 m0, s49
	s_nop 0
	global_load_lds_dwordx4 v134, s[84:85]
	s_mov_b32 m0, s50
	s_nop 0
	global_load_lds_dwordx4 v130, s[84:85]
	s_waitcnt vmcnt(8)
	s_waitcnt lgkmcnt(0)
	s_barrier
	v_mfma_f32_16x16x32_bf16 v[60:63], v[152:155], v[184:187], v[60:63]
	v_mfma_f32_16x16x32_bf16 v[56:59], v[160:163], v[184:187], v[56:59]
	v_mfma_f32_16x16x32_bf16 v[44:47], v[152:155], v[192:195], v[44:47]
	v_mfma_f32_16x16x32_bf16 v[40:43], v[160:163], v[192:195], v[40:43]
	v_mfma_f32_16x16x32_bf16 v[28:31], v[152:155], v[200:203], v[28:31]
	v_mfma_f32_16x16x32_bf16 v[24:27], v[160:163], v[200:203], v[24:27]
	v_mfma_f32_16x16x32_bf16 v[12:15], v[152:155], v[208:211], v[12:15]
	v_mfma_f32_16x16x32_bf16 v[8:11], v[160:163], v[208:211], v[8:11]
	v_mfma_f32_16x16x32_bf16 v[60:63], v[156:159], v[188:191], v[60:63]
	v_mfma_f32_16x16x32_bf16 v[56:59], v[164:167], v[188:191], v[56:59]
	v_mfma_f32_16x16x32_bf16 v[44:47], v[156:159], v[196:199], v[44:47]
	v_mfma_f32_16x16x32_bf16 v[40:43], v[164:167], v[196:199], v[40:43]
	v_mfma_f32_16x16x32_bf16 v[28:31], v[156:159], v[204:207], v[28:31]
	v_mfma_f32_16x16x32_bf16 v[24:27], v[164:167], v[204:207], v[24:27]
	v_mfma_f32_16x16x32_bf16 v[12:15], v[156:159], v[214:217], v[12:15]
	v_mfma_f32_16x16x32_bf16 v[8:11], v[164:167], v[214:217], v[8:11]
	v_mfma_f32_16x16x32_bf16 v[52:55], v[168:171], v[184:187], v[52:55]
	v_mfma_f32_16x16x32_bf16 v[48:51], v[176:179], v[184:187], v[48:51]
	v_mfma_f32_16x16x32_bf16 v[36:39], v[168:171], v[192:195], v[36:39]
	v_mfma_f32_16x16x32_bf16 v[32:35], v[176:179], v[192:195], v[32:35]
	v_mfma_f32_16x16x32_bf16 v[20:23], v[168:171], v[200:203], v[20:23]
	v_mfma_f32_16x16x32_bf16 v[16:19], v[176:179], v[200:203], v[16:19]
	v_mfma_f32_16x16x32_bf16 v[4:7], v[168:171], v[208:211], v[4:7]
	v_mfma_f32_16x16x32_bf16 v[0:3], v[176:179], v[208:211], v[0:3]
	v_mfma_f32_16x16x32_bf16 v[52:55], v[172:175], v[188:191], v[52:55]
	v_mfma_f32_16x16x32_bf16 v[48:51], v[180:183], v[188:191], v[48:51]
	v_mfma_f32_16x16x32_bf16 v[36:39], v[172:175], v[196:199], v[36:39]
	v_mfma_f32_16x16x32_bf16 v[32:35], v[180:183], v[196:199], v[32:35]
	v_mfma_f32_16x16x32_bf16 v[20:23], v[172:175], v[204:207], v[20:23]
	v_mfma_f32_16x16x32_bf16 v[16:19], v[180:183], v[204:207], v[16:19]
	v_mfma_f32_16x16x32_bf16 v[4:7], v[172:175], v[214:217], v[4:7]
	v_mfma_f32_16x16x32_bf16 v[0:3], v[180:183], v[214:217], v[0:3]
	s_barrier
	s_add_i32 s61, s61, 2
	s_add_u32 s38, s38, 0x100
	s_addc_u32 s39, s39, 0
	s_add_u32 s59, s59, 0x100
	s_addc_u32 s60, s60, 0
	s_cmp_gt_u32 s61, 29
	s_cbranch_scc0 .LBB0_169
	v_mul_f32_e32 v153, 0xbfb8aa3b, v124
	v_mul_f32_e32 v158, 0xbfb8aa3b, v120
	v_exp_f32_e32 v153, v153
	v_exp_f32_e32 v159, v158
	v_mul_f32_e32 v158, 0xbfb8aa3b, v125
	v_exp_f32_e32 v160, v158
	v_add_f32_e32 v153, 1.0, v153
	v_rcp_f32_e32 v158, v153
	v_add_f32_e32 v153, 1.0, v159
	v_add_f32_e32 v159, 1.0, v160
	v_rcp_f32_e32 v159, v159
	v_mul_f32_e32 v160, 0xbfb8aa3b, v121
	v_exp_f32_e32 v161, v160
	v_rcp_f32_e32 v160, v153
	v_pk_mul_f32 v[124:125], v[124:125], v[158:159]
	v_mul_f32_e32 v153, 0xbfb8aa3b, v127
	v_pk_mul_f32 v[116:117], v[124:125], v[116:117]
	v_add_f32_e32 v124, 1.0, v161
	v_mul_f32_e32 v125, 0xbfb8aa3b, v122
	v_rcp_f32_e32 v161, v124
	v_mul_f32_e32 v124, 0xbfb8aa3b, v126
	v_exp_f32_e32 v125, v125
	v_exp_f32_e32 v124, v124
	v_exp_f32_e32 v153, v153
	v_mul_f32_e32 v158, 0xbfb8aa3b, v123
	v_exp_f32_e32 v159, v158
	v_add_f32_e32 v125, 1.0, v125
	v_add_f32_e32 v124, 1.0, v124
	v_rcp_f32_e32 v158, v125
	v_add_f32_e32 v125, 1.0, v153
	v_rcp_f32_e32 v124, v124
	v_rcp_f32_e32 v125, v125
	v_add_f32_e32 v153, 1.0, v159
	v_rcp_f32_e32 v159, v153
	v_pk_mul_f32 v[120:121], v[120:121], v[160:161]
	v_lshl_or_b32 v154, s56, 7, v148
	v_pk_mul_f32 v[120:121], v[120:121], v[112:113]
	v_pk_mul_f32 v[112:113], v[126:127], v[124:125]
	v_lshl_add_u32 v152, s36, 8, v146
	v_ashrrev_i32_e32 v155, 31, v154
	v_mov_b64_e32 v[144:145], s[10:11]
	v_pk_mul_f32 v[118:119], v[112:113], v[118:119]
	v_pk_mul_f32 v[112:113], v[122:123], v[158:159]
	v_mad_i64_i32 v[156:157], s[38:39], v152, s55, v[144:145]
	v_pk_mul_f32 v[122:123], v[112:113], v[114:115]
	v_lshlrev_b64 v[112:113], 1, v[154:155]
	v_lshl_add_u64 v[124:125], v[156:157], 0, v[112:113]
	v_cvt_pk_bf16_f32 v114, v116, v117
	v_cvt_pk_bf16_f32 v115, v118, v119
	v_cvt_pk_bf16_f32 v116, v120, v121
	v_cvt_pk_bf16_f32 v117, v122, v123
	global_store_dwordx4 v[124:125], v[114:117], off
	v_mul_f32_e32 v118, 0xbfb8aa3b, v109
	v_exp_f32_e32 v118, v118
	v_mul_f32_e32 v116, 0xbfb8aa3b, v108
	v_mul_f32_e32 v117, 0xbfb8aa3b, v104
	v_exp_f32_e32 v116, v116
	v_exp_f32_e32 v117, v117
	v_or_b32_e32 v114, 16, v152
	v_mad_i64_i32 v[114:115], s[38:39], v114, s55, v[144:145]
	v_add_f32_e32 v116, 1.0, v116
	v_add_f32_e32 v119, 1.0, v117
	v_add_f32_e32 v117, 1.0, v118
	v_rcp_f32_e32 v116, v116
	v_rcp_f32_e32 v117, v117
	v_mul_f32_e32 v118, 0xbfb8aa3b, v105
; __device__ __forceinline__ float fsilu(float v) { return v * fsigmoid(v); }
; __device__ __forceinline__ u32x4 pack8(const f32x4 a, const f32x4 b) { u32x4 w; w.x = cvt_pk_bf16(a[0], a[1]); w.y = cvt_pk_bf16(a[2], a[3]); w.z = cvt_pk_bf16(b[0], b[1]); w.w = cvt_pk_bf16(b[2], b[3]); return w; }
;     __device__ __forceinline__ void operator()(const f32x4 (&acc)[2][2][4][2], const Unit& u, int wr, int wc, int fr, int fq) const {
;         const int row0 = u.pm * BM + wr * 64 + fr, col0 = u.pn * 128 + wc * 32 + 8 * fq;
; #pragma unroll
;         for (int ai = 0; ai < 2; ++ai)
; #pragma unroll
;             for (int m = 0; m < 4; ++m) {
;                 bf16_t* rowp = O + (size_t)(row0 + ai * HALF + m * 16) * ldc + col0;
;                 f32x4 h0, h1;
; #pragma unroll
;                 for (int j = 0; j < 4; ++j) { h0[j] = fsilu(acc[ai][0][m][0][j]) * acc[ai][1][m][0][j]; h1[j] = fsilu(acc[ai][0][m][1][j]) * acc[ai][1][m][1][j]; }
;                 *(u32x4*)rowp = pack8(h0, h1);
	v_exp_f32_e32 v120, v118
	v_rcp_f32_e32 v118, v119
	v_pk_mul_f32 v[108:109], v[108:109], v[116:117]
	v_mul_f32_e32 v116, 0xbfb8aa3b, v111
	v_pk_mul_f32 v[100:101], v[108:109], v[100:101]
	v_add_f32_e32 v108, 1.0, v120
	v_rcp_f32_e32 v119, v108
	v_mul_f32_e32 v109, 0xbfb8aa3b, v106
	v_mul_f32_e32 v108, 0xbfb8aa3b, v110
	v_exp_f32_e32 v109, v109
	v_exp_f32_e32 v108, v108
	v_exp_f32_e32 v117, v116
	v_mul_f32_e32 v116, 0xbfb8aa3b, v107
	v_pk_mul_f32 v[104:105], v[104:105], v[118:119]
	v_exp_f32_e32 v118, v116
	v_add_f32_e32 v109, 1.0, v109
	v_add_f32_e32 v108, 1.0, v108
	v_rcp_f32_e32 v116, v109
	v_add_f32_e32 v109, 1.0, v117
	v_rcp_f32_e32 v108, v108
	v_rcp_f32_e32 v109, v109
	v_add_f32_e32 v117, 1.0, v118
	v_rcp_f32_e32 v117, v117
	v_pk_mul_f32 v[104:105], v[104:105], v[96:97]
	v_pk_mul_f32 v[96:97], v[110:111], v[108:109]
	v_lshl_add_u64 v[108:109], v[114:115], 0, v[112:113]
	v_pk_mul_f32 v[102:103], v[96:97], v[102:103]
	v_pk_mul_f32 v[96:97], v[106:107], v[116:117]
	s_and_b64 vcc, exec, s[8:9]
	v_pk_mul_f32 v[106:107], v[96:97], v[98:99]
	v_cvt_pk_bf16_f32 v96, v100, v101
	v_cvt_pk_bf16_f32 v97, v102, v103
	v_cvt_pk_bf16_f32 v98, v104, v105
	v_cvt_pk_bf16_f32 v99, v106, v107
	global_store_dwordx4 v[108:109], v[96:99], off
	v_mul_f32_e32 v100, 0xbfb8aa3b, v93
	v_exp_f32_e32 v100, v100
	v_mul_f32_e32 v98, 0xbfb8aa3b, v92
	v_mul_f32_e32 v99, 0xbfb8aa3b, v88
	v_exp_f32_e32 v98, v98
	v_exp_f32_e32 v99, v99
	v_or_b32_e32 v96, 32, v152
	v_mad_i64_i32 v[96:97], s[38:39], v96, s55, v[144:145]
	v_add_f32_e32 v98, 1.0, v98
	v_add_f32_e32 v101, 1.0, v99
	v_add_f32_e32 v99, 1.0, v100
	v_rcp_f32_e32 v98, v98
	v_rcp_f32_e32 v99, v99
	v_mul_f32_e32 v100, 0xbfb8aa3b, v89
	v_exp_f32_e32 v102, v100
	v_rcp_f32_e32 v100, v101
	v_pk_mul_f32 v[92:93], v[92:93], v[98:99]
	v_mul_f32_e32 v98, 0xbfb8aa3b, v95
	v_pk_mul_f32 v[84:85], v[92:93], v[84:85]
	v_add_f32_e32 v92, 1.0, v102
	v_rcp_f32_e32 v101, v92
	v_mul_f32_e32 v93, 0xbfb8aa3b, v90
	v_mul_f32_e32 v92, 0xbfb8aa3b, v94
	v_exp_f32_e32 v93, v93
	v_exp_f32_e32 v92, v92
	v_exp_f32_e32 v99, v98
	v_mul_f32_e32 v98, 0xbfb8aa3b, v91
	v_pk_mul_f32 v[88:89], v[88:89], v[100:101]
	v_exp_f32_e32 v100, v98
	v_add_f32_e32 v93, 1.0, v93
	v_add_f32_e32 v92, 1.0, v92
	v_rcp_f32_e32 v98, v93
	v_add_f32_e32 v93, 1.0, v99
	v_rcp_f32_e32 v92, v92
	v_rcp_f32_e32 v93, v93
	v_add_f32_e32 v99, 1.0, v100
	v_rcp_f32_e32 v99, v99
	v_pk_mul_f32 v[88:89], v[88:89], v[80:81]
	v_pk_mul_f32 v[80:81], v[94:95], v[92:93]
	v_lshl_add_u64 v[92:93], v[96:97], 0, v[112:113]
	v_pk_mul_f32 v[86:87], v[80:81], v[86:87]
	v_pk_mul_f32 v[80:81], v[90:91], v[98:99]
	s_mov_b32 s56, s26
	v_pk_mul_f32 v[90:91], v[80:81], v[82:83]
	v_cvt_pk_bf16_f32 v80, v84, v85
	v_cvt_pk_bf16_f32 v81, v86, v87
	v_cvt_pk_bf16_f32 v82, v88, v89
	v_cvt_pk_bf16_f32 v83, v90, v91
	global_store_dwordx4 v[92:93], v[80:83], off
	v_mul_f32_e32 v84, 0xbfb8aa3b, v77
	v_exp_f32_e32 v84, v84
	v_mul_f32_e32 v82, 0xbfb8aa3b, v76
	v_mul_f32_e32 v83, 0xbfb8aa3b, v72
	v_exp_f32_e32 v82, v82
	v_exp_f32_e32 v83, v83
	v_or_b32_e32 v80, 48, v152
	v_mad_i64_i32 v[80:81], s[38:39], v80, s55, v[144:145]
	v_add_f32_e32 v82, 1.0, v82
	v_add_f32_e32 v85, 1.0, v83
	v_add_f32_e32 v83, 1.0, v84
	v_rcp_f32_e32 v82, v82
	v_rcp_f32_e32 v83, v83
	v_mul_f32_e32 v84, 0xbfb8aa3b, v73
	v_exp_f32_e32 v86, v84
	v_rcp_f32_e32 v84, v85
	v_pk_mul_f32 v[76:77], v[76:77], v[82:83]
	v_mul_f32_e32 v82, 0xbfb8aa3b, v79
	v_pk_mul_f32 v[68:69], v[76:77], v[68:69]
	v_add_f32_e32 v76, 1.0, v86
	v_rcp_f32_e32 v85, v76
	v_mul_f32_e32 v77, 0xbfb8aa3b, v74
	v_mul_f32_e32 v76, 0xbfb8aa3b, v78
	v_exp_f32_e32 v77, v77
	v_exp_f32_e32 v76, v76
	v_exp_f32_e32 v83, v82
	v_mul_f32_e32 v82, 0xbfb8aa3b, v75
	v_pk_mul_f32 v[72:73], v[72:73], v[84:85]
	v_exp_f32_e32 v84, v82
	v_add_f32_e32 v77, 1.0, v77
	v_add_f32_e32 v76, 1.0, v76
	v_rcp_f32_e32 v82, v77
	v_add_f32_e32 v77, 1.0, v83
	v_rcp_f32_e32 v76, v76
	v_rcp_f32_e32 v77, v77
	v_add_f32_e32 v83, 1.0, v84
	v_rcp_f32_e32 v83, v83
	v_pk_mul_f32 v[72:73], v[72:73], v[64:65]
	v_pk_mul_f32 v[64:65], v[78:79], v[76:77]
	v_lshl_add_u64 v[76:77], v[80:81], 0, v[112:113]
	v_pk_mul_f32 v[70:71], v[64:65], v[70:71]
	v_pk_mul_f32 v[64:65], v[74:75], v[82:83]
	s_mov_b32 s36, s28
	v_pk_mul_f32 v[74:75], v[64:65], v[66:67]
	v_cvt_pk_bf16_f32 v64, v68, v69
	v_cvt_pk_bf16_f32 v65, v70, v71
	v_cvt_pk_bf16_f32 v66, v72, v73
	v_cvt_pk_bf16_f32 v67, v74, v75
	global_store_dwordx4 v[76:77], v[64:67], off
	v_mul_f32_e32 v68, 0xbfb8aa3b, v61
	v_exp_f32_e32 v68, v68
	v_mul_f32_e32 v66, 0xbfb8aa3b, v60
	v_mul_f32_e32 v67, 0xbfb8aa3b, v56
	v_exp_f32_e32 v66, v66
	v_exp_f32_e32 v67, v67
	v_add_u32_e32 v64, 0x80, v152
	v_mad_i64_i32 v[64:65], s[38:39], v64, s55, v[144:145]
	v_add_f32_e32 v66, 1.0, v66
	v_add_f32_e32 v69, 1.0, v67
	v_add_f32_e32 v67, 1.0, v68
	v_rcp_f32_e32 v66, v66
	v_rcp_f32_e32 v67, v67
	v_mul_f32_e32 v68, 0xbfb8aa3b, v57
	v_exp_f32_e32 v70, v68
	v_rcp_f32_e32 v68, v69
	v_pk_mul_f32 v[60:61], v[60:61], v[66:67]
	v_mul_f32_e32 v66, 0xbfb8aa3b, v63
	v_pk_mul_f32 v[52:53], v[60:61], v[52:53]
	v_add_f32_e32 v60, 1.0, v70
	v_rcp_f32_e32 v69, v60
	v_mul_f32_e32 v61, 0xbfb8aa3b, v58
	v_mul_f32_e32 v60, 0xbfb8aa3b, v62
	v_exp_f32_e32 v61, v61
	v_exp_f32_e32 v60, v60
	v_exp_f32_e32 v67, v66
	v_mul_f32_e32 v66, 0xbfb8aa3b, v59
	v_pk_mul_f32 v[56:57], v[56:57], v[68:69]
	v_exp_f32_e32 v68, v66
	v_add_f32_e32 v61, 1.0, v61
	v_add_f32_e32 v60, 1.0, v60
	v_rcp_f32_e32 v66, v61
; __device__ __forceinline__ float fsilu(float v) { return v * fsigmoid(v); }
; __device__ __forceinline__ u32x4 pack8(const f32x4 a, const f32x4 b) { u32x4 w; w.x = cvt_pk_bf16(a[0], a[1]); w.y = cvt_pk_bf16(a[2], a[3]); w.z = cvt_pk_bf16(b[0], b[1]); w.w = cvt_pk_bf16(b[2], b[3]); return w; }
; #define PG8_WAIT_V(n) asm volatile("s_waitcnt vmcnt(" #n ")" ::: "memory")
; #define PG8_BAR __builtin_amdgcn_s_barrier()
;     __device__ __forceinline__ void operator()(const f32x4 (&acc)[2][2][4][2], const Unit& u, int wr, int wc, int fr, int fq) const {
;         const int row0 = u.pm * BM + wr * 64 + fr, col0 = u.pn * 128 + wc * 32 + 8 * fq;
; #pragma unroll
;         for (int ai = 0; ai < 2; ++ai)
; #pragma unroll
;             for (int m = 0; m < 4; ++m) {
;                 bf16_t* rowp = O + (size_t)(row0 + ai * HALF + m * 16) * ldc + col0;
;                 f32x4 h0, h1;
; #pragma unroll
;                 for (int j = 0; j < 4; ++j) { h0[j] = fsilu(acc[ai][0][m][0][j]) * acc[ai][1][m][0][j]; h1[j] = fsilu(acc[ai][0][m][1][j]) * acc[ai][1][m][1][j]; }
;                 *(u32x4*)rowp = pack8(h0, h1);
; template <class Epi, class Sched, bool ALIGN_EPI = false, bool SP2 = false>
; __device__ __forceinline__ void gemm_phase(PG8_LAS unsigned char* lds, const Gemm g, const Sched& S, const Epi& E) {
;     ...
;         if constexpr (!Epi::AFTER_DRAIN) { E(acc, cur, wr, wc, fr, fq); S.done(cur); }
;         if (!has_next) break;
; #pragma unroll
;         for (int a = 0; a < 2; ++a)
; #pragma unroll
;             for (int b = 0; b < 2; ++b)
; #pragma unroll
;                 for (int m = 0; m < 4; ++m)
; #pragma unroll
;                     for (int n = 0; n < 2; ++n) acc[a][b][m][n] = (f32x4){0.f, 0.f, 0.f, 0.f};
;         cur = nxt; cA = nA; cB = nB; ++ui;
;         if constexpr (ALIGN_EPI) { if (wr == 1) PG8_BAR; }
;     }
;     PG8_WAIT_V(0);
;     if constexpr (!ALIGN_EPI) { if (wr == 0) PG8_BAR; }
	v_add_f32_e32 v61, 1.0, v67
	v_rcp_f32_e32 v60, v60
	v_rcp_f32_e32 v61, v61
	v_add_f32_e32 v67, 1.0, v68
	v_rcp_f32_e32 v67, v67
	v_pk_mul_f32 v[56:57], v[56:57], v[48:49]
	v_pk_mul_f32 v[48:49], v[62:63], v[60:61]
	v_lshl_add_u64 v[60:61], v[64:65], 0, v[112:113]
	v_pk_mul_f32 v[54:55], v[48:49], v[54:55]
	v_pk_mul_f32 v[48:49], v[58:59], v[66:67]
	s_mov_b64 s[40:41], s[34:35]
	v_pk_mul_f32 v[58:59], v[48:49], v[50:51]
	v_cvt_pk_bf16_f32 v48, v52, v53
	v_cvt_pk_bf16_f32 v49, v54, v55
	v_cvt_pk_bf16_f32 v50, v56, v57
	v_cvt_pk_bf16_f32 v51, v58, v59
	global_store_dwordx4 v[60:61], v[48:51], off
	v_mul_f32_e32 v52, 0xbfb8aa3b, v45
	v_exp_f32_e32 v52, v52
	v_mul_f32_e32 v50, 0xbfb8aa3b, v44
	v_mul_f32_e32 v51, 0xbfb8aa3b, v40
	v_exp_f32_e32 v50, v50
	v_exp_f32_e32 v51, v51
	v_add_u32_e32 v48, 0x90, v152
	v_mad_i64_i32 v[48:49], s[38:39], v48, s55, v[144:145]
	v_add_f32_e32 v50, 1.0, v50
	v_add_f32_e32 v53, 1.0, v51
	v_add_f32_e32 v51, 1.0, v52
	v_rcp_f32_e32 v50, v50
	v_rcp_f32_e32 v51, v51
	v_mul_f32_e32 v52, 0xbfb8aa3b, v41
	v_exp_f32_e32 v54, v52
	v_rcp_f32_e32 v52, v53
	v_pk_mul_f32 v[44:45], v[44:45], v[50:51]
	v_mul_f32_e32 v50, 0xbfb8aa3b, v47
	v_pk_mul_f32 v[36:37], v[44:45], v[36:37]
	v_add_f32_e32 v44, 1.0, v54
	v_rcp_f32_e32 v53, v44
	v_mul_f32_e32 v45, 0xbfb8aa3b, v42
	v_mul_f32_e32 v44, 0xbfb8aa3b, v46
	v_exp_f32_e32 v45, v45
	v_exp_f32_e32 v44, v44
	v_exp_f32_e32 v51, v50
	v_mul_f32_e32 v50, 0xbfb8aa3b, v43
	v_pk_mul_f32 v[40:41], v[40:41], v[52:53]
	v_exp_f32_e32 v52, v50
	v_add_f32_e32 v45, 1.0, v45
	v_add_f32_e32 v44, 1.0, v44
	v_rcp_f32_e32 v50, v45
	v_add_f32_e32 v45, 1.0, v51
	v_rcp_f32_e32 v44, v44
	v_rcp_f32_e32 v45, v45
	v_add_f32_e32 v51, 1.0, v52
	v_rcp_f32_e32 v51, v51
	v_pk_mul_f32 v[40:41], v[40:41], v[32:33]
	v_pk_mul_f32 v[32:33], v[46:47], v[44:45]
	v_lshl_add_u64 v[44:45], v[48:49], 0, v[112:113]
	v_pk_mul_f32 v[38:39], v[32:33], v[38:39]
	v_pk_mul_f32 v[32:33], v[42:43], v[50:51]
	s_nop 0
	v_pk_mul_f32 v[42:43], v[32:33], v[34:35]
	v_cvt_pk_bf16_f32 v32, v36, v37
	v_cvt_pk_bf16_f32 v33, v38, v39
	v_cvt_pk_bf16_f32 v34, v40, v41
	v_cvt_pk_bf16_f32 v35, v42, v43
	global_store_dwordx4 v[44:45], v[32:35], off
	v_mul_f32_e32 v36, 0xbfb8aa3b, v29
	v_exp_f32_e32 v36, v36
	v_mul_f32_e32 v34, 0xbfb8aa3b, v28
	v_mul_f32_e32 v35, 0xbfb8aa3b, v24
	v_exp_f32_e32 v34, v34
	v_exp_f32_e32 v35, v35
	v_add_u32_e32 v32, 0xa0, v152
	v_mad_i64_i32 v[32:33], s[38:39], v32, s55, v[144:145]
	v_add_f32_e32 v34, 1.0, v34
	v_add_f32_e32 v37, 1.0, v35
	v_add_f32_e32 v35, 1.0, v36
	v_rcp_f32_e32 v34, v34
	v_rcp_f32_e32 v35, v35
	v_mul_f32_e32 v36, 0xbfb8aa3b, v25
	v_exp_f32_e32 v38, v36
	v_rcp_f32_e32 v36, v37
	v_pk_mul_f32 v[28:29], v[28:29], v[34:35]
	v_mul_f32_e32 v34, 0xbfb8aa3b, v31
	v_pk_mul_f32 v[20:21], v[28:29], v[20:21]
	v_add_f32_e32 v28, 1.0, v38
	v_rcp_f32_e32 v37, v28
	v_mul_f32_e32 v29, 0xbfb8aa3b, v26
	v_mul_f32_e32 v28, 0xbfb8aa3b, v30
	v_exp_f32_e32 v29, v29
	v_exp_f32_e32 v28, v28
	v_exp_f32_e32 v35, v34
	v_mul_f32_e32 v34, 0xbfb8aa3b, v27
	v_pk_mul_f32 v[24:25], v[24:25], v[36:37]
	v_exp_f32_e32 v36, v34
	v_add_f32_e32 v29, 1.0, v29
	v_add_f32_e32 v28, 1.0, v28
	v_rcp_f32_e32 v34, v29
	v_add_f32_e32 v29, 1.0, v35
	v_rcp_f32_e32 v28, v28
	v_rcp_f32_e32 v29, v29
	v_add_f32_e32 v35, 1.0, v36
	v_rcp_f32_e32 v35, v35
	v_pk_mul_f32 v[24:25], v[24:25], v[16:17]
	v_pk_mul_f32 v[16:17], v[30:31], v[28:29]
	v_lshl_add_u64 v[28:29], v[32:33], 0, v[112:113]
	v_pk_mul_f32 v[22:23], v[16:17], v[22:23]
	v_pk_mul_f32 v[16:17], v[26:27], v[34:35]
	s_nop 0
	v_pk_mul_f32 v[26:27], v[16:17], v[18:19]
	v_cvt_pk_bf16_f32 v16, v20, v21
	v_cvt_pk_bf16_f32 v17, v22, v23
	v_cvt_pk_bf16_f32 v18, v24, v25
	v_cvt_pk_bf16_f32 v19, v26, v27
	global_store_dwordx4 v[28:29], v[16:19], off
	v_mul_f32_e32 v20, 0xbfb8aa3b, v13
	v_exp_f32_e32 v20, v20
	v_mul_f32_e32 v18, 0xbfb8aa3b, v12
	v_mul_f32_e32 v19, 0xbfb8aa3b, v8
	v_exp_f32_e32 v18, v18
	v_exp_f32_e32 v19, v19
	v_add_u32_e32 v16, 0xb0, v152
	v_mad_i64_i32 v[16:17], s[38:39], v16, s55, v[144:145]
	v_add_f32_e32 v18, 1.0, v18
	v_add_f32_e32 v21, 1.0, v19
	v_add_f32_e32 v19, 1.0, v20
	v_rcp_f32_e32 v18, v18
	v_rcp_f32_e32 v19, v19
	v_mul_f32_e32 v20, 0xbfb8aa3b, v9
	v_exp_f32_e32 v22, v20
	v_rcp_f32_e32 v20, v21
	v_pk_mul_f32 v[12:13], v[12:13], v[18:19]
	v_mul_f32_e32 v18, 0xbfb8aa3b, v15
	v_pk_mul_f32 v[4:5], v[12:13], v[4:5]
	v_add_f32_e32 v12, 1.0, v22
	v_rcp_f32_e32 v21, v12
	v_mul_f32_e32 v13, 0xbfb8aa3b, v10
	v_mul_f32_e32 v12, 0xbfb8aa3b, v14
	v_exp_f32_e32 v13, v13
	v_exp_f32_e32 v12, v12
	v_exp_f32_e32 v19, v18
	v_mul_f32_e32 v18, 0xbfb8aa3b, v11
	v_pk_mul_f32 v[8:9], v[8:9], v[20:21]
	v_exp_f32_e32 v20, v18
	v_add_f32_e32 v13, 1.0, v13
	v_add_f32_e32 v12, 1.0, v12
	v_rcp_f32_e32 v18, v13
	v_add_f32_e32 v13, 1.0, v19
	v_rcp_f32_e32 v12, v12
	v_rcp_f32_e32 v13, v13
	v_add_f32_e32 v19, 1.0, v20
	v_rcp_f32_e32 v19, v19
	v_pk_mul_f32 v[8:9], v[8:9], v[0:1]
	v_pk_mul_f32 v[0:1], v[14:15], v[12:13]
	v_lshl_add_u64 v[12:13], v[16:17], 0, v[112:113]
	v_pk_mul_f32 v[6:7], v[0:1], v[6:7]
	v_pk_mul_f32 v[0:1], v[10:11], v[18:19]
	s_mov_b64 s[38:39], s[30:31]
	v_pk_mul_f32 v[10:11], v[0:1], v[2:3]
	v_cvt_pk_bf16_f32 v0, v4, v5
	v_cvt_pk_bf16_f32 v1, v6, v7
	v_cvt_pk_bf16_f32 v2, v8, v9
	v_cvt_pk_bf16_f32 v3, v10, v11
	global_store_dwordx4 v[12:13], v[0:3], off
	s_cbranch_vccz .LBB0_166
	s_waitcnt vmcnt(0)
	s_cmpk_gt_u32 s3, 0xff
	s_cbranch_scc1 .LBB0_173
	s_barrier

; #define PG8_STAGE(bufoff, gbase, voff) do { _Pragma("unroll") for (int _i = 0; _i < 2; ++_i) \
;         __builtin_amdgcn_global_load_lds((const unsigned*)((const char*)(gbase) + (voff)[_i]), (PG8_LAS unsigned*)(lds + (bufoff) + ldsw + _i * 8192), 16, 0, 0); } while (0)
; #define PG8_LDA(dst, b, h) do { _Pragma("unroll") for (int m = 0; m < 4; ++m) _Pragma("unroll") for (int k = 0; k < 2; ++k) dst[m][k] = *(const PG8_LAS bf16x8*)(lds + PG8_SA(b, h) + aoff + m * 2048 + k * 1024); } while (0)
; #define PG8_LDB(dst, b, h) do { _Pragma("unroll") for (int n = 0; n < 2; ++n) _Pragma("unroll") for (int k = 0; k < 2; ++k) dst[n][k] = *(const PG8_LAS bf16x8*)(lds + PG8_SB(b, h) + boff + n * 2048 + k * 1024); } while (0)
; #define PG8_MMA(ai, bj, At, Bt) do { __builtin_amdgcn_s_setprio(1); _Pragma("unroll") for (int m = 0; m < 4; ++m) _Pragma("unroll") for (int n = 0; n < 2; ++n) _Pragma("unroll") for (int k = 0; k < 2; ++k) \
;         acc[ai][bj][m][n] = __builtin_amdgcn_mfma_f32_16x16x32_bf16(Bt[n][k], At[m][k], acc[ai][bj][m][n], 0, 0, 0); __builtin_amdgcn_s_setprio(0); } while (0)
; #define PG8_WAIT_V(n) asm volatile("s_waitcnt vmcnt(" #n ")" ::: "memory")
; #define PG8_WAIT_L(n) asm volatile("s_waitcnt lgkmcnt(" #n ")" ::: "memory")
; #define PG8_BAR __builtin_amdgcn_s_barrier()
; #define PG8_SCHED __builtin_amdgcn_sched_barrier(0)
; template <class Epi, class Sched, bool ALIGN_EPI = false, bool SP2 = false>
; __device__ __forceinline__ void gemm_phase(PG8_LAS unsigned char* lds, const Gemm g, const Sched& S, const Epi& E) {
;     ...
;             PG8_LDB(B0, 0, 0); PG8_LDB(B1, 0, 1); PG8_SCHED; PG8_LDA(At, 0, 0); PG8_STAGE(PG8_SA(1, 1), a1 + hstep, voffA);
;             PG8_WAIT_V(8); PG8_WAIT_L(0); PG8_BAR; PG8_MMA(0, 0, At, B0); PG8_MMA(0, 1, At, B1); PG8_BAR; PG8_SCHED;
;             PG8_LDA(At, 0, 1); PG8_STAGE(PG8_SB(0, 0), b2, voffB); PG8_STAGE(PG8_SB(0, 1), b2 + hstep, voffB); PG8_STAGE(PG8_SA(0, 0), a2, voffA);
;             PG8_WAIT_V(8); PG8_WAIT_L(0); PG8_BAR; PG8_MMA(1, 0, At, B0); PG8_MMA(1, 1, At, B1); PG8_BAR; PG8_SCHED;
.LBB0_244:
	s_add_u32 s67, s46, 0x100
	v_mov_b32_e32 v220, v251
	s_addc_u32 s68, s47, 0
	s_mov_b32 s69, -2
	ds_read_b128 v[140:143], v169
	ds_read_b128 v[144:147], v169 offset:1024
	ds_read_b128 v[148:151], v169 offset:2048
	ds_read_b128 v[152:155], v169 offset:3072
	ds_read_b128 v[156:159], v170
	ds_read_b128 v[160:163], v170 offset:1024
	ds_read_b128 v[172:175], v170 offset:2048
	ds_read_b128 v[176:179], v170 offset:3072
	s_add_u32 s46, s44, 0x100
	s_addc_u32 s47, s45, 0
	s_cmpk_eq_i32 s69, 0x54
	s_cselect_b32 s51, s11, s47
	s_cselect_b32 s50, s10, s46
	s_cselect_b32 s49, s13, s68
	s_cselect_b32 s48, s12, s67
	s_add_i32 m0, s26, 0xc000
	ds_read_b128 v[180:183], v171
	ds_read_b128 v[184:187], v171 offset:1024
	ds_read_b128 v[188:191], v171 offset:2048
	ds_read_b128 v[192:195], v171 offset:3072
	ds_read_b128 v[196:199], v171 offset:4096
	ds_read_b128 v[200:203], v171 offset:5120
	ds_read_b128 v[204:207], v171 offset:6144
	ds_read_b128 v[208:211], v171 offset:7168
	global_load_lds_dwordx4 v136, s[44:45]
	s_add_i32 m0, s26, 0xe000
	s_nop 0
	global_load_lds_dwordx4 v138, s[44:45]
	s_waitcnt vmcnt(8)
	s_waitcnt lgkmcnt(0)
	s_barrier
	v_mfma_f32_16x16x32_bf16 v[124:127], v[140:143], v[180:183], 0
	v_mfma_f32_16x16x32_bf16 v[120:123], v[148:151], v[180:183], 0
	v_mfma_f32_16x16x32_bf16 v[116:119], v[140:143], v[188:191], 0
	v_mfma_f32_16x16x32_bf16 v[112:115], v[148:151], v[188:191], 0
	v_mfma_f32_16x16x32_bf16 v[108:111], v[140:143], v[196:199], 0
	v_mfma_f32_16x16x32_bf16 v[96:99], v[148:151], v[196:199], 0
	v_mfma_f32_16x16x32_bf16 v[84:87], v[140:143], v[204:207], 0
	v_mfma_f32_16x16x32_bf16 v[76:79], v[148:151], v[204:207], 0
	v_mfma_f32_16x16x32_bf16 v[124:127], v[144:147], v[184:187], v[124:127]
	v_mfma_f32_16x16x32_bf16 v[120:123], v[152:155], v[184:187], v[120:123]
	v_mfma_f32_16x16x32_bf16 v[116:119], v[144:147], v[192:195], v[116:119]
	v_mfma_f32_16x16x32_bf16 v[112:115], v[152:155], v[192:195], v[112:115]
	v_mfma_f32_16x16x32_bf16 v[108:111], v[144:147], v[200:203], v[108:111]
	v_mfma_f32_16x16x32_bf16 v[96:99], v[152:155], v[200:203], v[96:99]
	v_mfma_f32_16x16x32_bf16 v[84:87], v[144:147], v[208:211], v[84:87]
	v_mfma_f32_16x16x32_bf16 v[76:79], v[152:155], v[208:211], v[76:79]
	v_mfma_f32_16x16x32_bf16 v[104:107], v[156:159], v[180:183], 0
	v_mfma_f32_16x16x32_bf16 v[100:103], v[172:175], v[180:183], 0
	v_mfma_f32_16x16x32_bf16 v[92:95], v[156:159], v[188:191], 0
	v_mfma_f32_16x16x32_bf16 v[88:91], v[172:175], v[188:191], 0
	v_mfma_f32_16x16x32_bf16 v[80:83], v[156:159], v[196:199], 0
	v_mfma_f32_16x16x32_bf16 v[72:75], v[172:175], v[196:199], 0
	v_mfma_f32_16x16x32_bf16 v[68:71], v[156:159], v[204:207], 0
	v_mfma_f32_16x16x32_bf16 v[64:67], v[172:175], v[204:207], 0
	v_mfma_f32_16x16x32_bf16 v[104:107], v[160:163], v[184:187], v[104:107]
	v_mfma_f32_16x16x32_bf16 v[100:103], v[176:179], v[184:187], v[100:103]
	v_mfma_f32_16x16x32_bf16 v[92:95], v[160:163], v[192:195], v[92:95]
	v_mfma_f32_16x16x32_bf16 v[88:91], v[176:179], v[192:195], v[88:91]
	v_mfma_f32_16x16x32_bf16 v[80:83], v[160:163], v[200:203], v[80:83]
	v_mfma_f32_16x16x32_bf16 v[72:75], v[176:179], v[200:203], v[72:75]
	v_mfma_f32_16x16x32_bf16 v[68:71], v[160:163], v[208:211], v[68:71]
	v_mfma_f32_16x16x32_bf16 v[64:67], v[176:179], v[208:211], v[64:67]
	s_barrier
	s_add_i32 s44, s61, s25
	s_mov_b32 m0, s44
	ds_read_b128 v[180:183], v171 offset:16384
	ds_read_b128 v[184:187], v171 offset:17408
	ds_read_b128 v[188:191], v171 offset:18432
	ds_read_b128 v[192:195], v171 offset:19456
	ds_read_b128 v[196:199], v171 offset:20480
	ds_read_b128 v[200:203], v171 offset:21504
	ds_read_b128 v[204:207], v171 offset:22528
	ds_read_b128 v[208:211], v171 offset:23552
	global_load_lds_dwordx4 v130, s[48:49]
	s_add_i32 m0, s44, 0x2000
	s_add_u32 s44, s48, 0x160000
	s_addc_u32 s45, s49, 0
	s_add_i32 s70, s62, s25
	global_load_lds_dwordx4 v134, s[48:49]
	s_mov_b32 m0, s70
	s_nop 0
	global_load_lds_dwordx4 v130, s[44:45]
	s_add_i32 m0, s70, 0x2000
	s_nop 0
	global_load_lds_dwordx4 v134, s[44:45]
	s_mov_b32 m0, s26
	s_nop 0
	global_load_lds_dwordx4 v128, s[50:51]
	s_mov_b32 m0, s27
	s_nop 0
	global_load_lds_dwordx4 v132, s[50:51]
	s_waitcnt vmcnt(8)
	s_waitcnt lgkmcnt(0)
	s_barrier
	v_mfma_f32_16x16x32_bf16 v[60:63], v[140:143], v[180:183], 0
	v_mfma_f32_16x16x32_bf16 v[56:59], v[148:151], v[180:183], 0
	v_mfma_f32_16x16x32_bf16 v[52:55], v[140:143], v[188:191], 0
	v_mfma_f32_16x16x32_bf16 v[48:51], v[148:151], v[188:191], 0
	v_mfma_f32_16x16x32_bf16 v[44:47], v[140:143], v[196:199], 0
	v_mfma_f32_16x16x32_bf16 v[32:35], v[148:151], v[196:199], 0
	v_mfma_f32_16x16x32_bf16 v[20:23], v[140:143], v[204:207], 0
	v_mfma_f32_16x16x32_bf16 v[12:15], v[148:151], v[204:207], 0
	v_mfma_f32_16x16x32_bf16 v[60:63], v[144:147], v[184:187], v[60:63]
	v_mfma_f32_16x16x32_bf16 v[56:59], v[152:155], v[184:187], v[56:59]
	v_mfma_f32_16x16x32_bf16 v[52:55], v[144:147], v[192:195], v[52:55]
	v_mfma_f32_16x16x32_bf16 v[48:51], v[152:155], v[192:195], v[48:51]
	v_mfma_f32_16x16x32_bf16 v[44:47], v[144:147], v[200:203], v[44:47]
	v_mfma_f32_16x16x32_bf16 v[32:35], v[152:155], v[200:203], v[32:35]
	v_mfma_f32_16x16x32_bf16 v[20:23], v[144:147], v[208:211], v[20:23]
	v_mfma_f32_16x16x32_bf16 v[12:15], v[152:155], v[208:211], v[12:15]
	v_mfma_f32_16x16x32_bf16 v[40:43], v[156:159], v[180:183], 0
	v_mfma_f32_16x16x32_bf16 v[36:39], v[172:175], v[180:183], 0
	v_mfma_f32_16x16x32_bf16 v[28:31], v[156:159], v[188:191], 0
	v_mfma_f32_16x16x32_bf16 v[24:27], v[172:175], v[188:191], 0
	v_mfma_f32_16x16x32_bf16 v[16:19], v[156:159], v[196:199], 0
	v_mfma_f32_16x16x32_bf16 v[8:11], v[172:175], v[196:199], 0
	v_mfma_f32_16x16x32_bf16 v[4:7], v[156:159], v[204:207], 0
	v_mfma_f32_16x16x32_bf16 v[0:3], v[172:175], v[204:207], 0
	v_mfma_f32_16x16x32_bf16 v[40:43], v[160:163], v[184:187], v[40:43]
	v_mfma_f32_16x16x32_bf16 v[36:39], v[176:179], v[184:187], v[36:39]
	v_mfma_f32_16x16x32_bf16 v[28:31], v[160:163], v[192:195], v[28:31]
	v_mfma_f32_16x16x32_bf16 v[24:27], v[176:179], v[192:195], v[24:27]
	v_mfma_f32_16x16x32_bf16 v[16:19], v[160:163], v[200:203], v[16:19]
	v_mfma_f32_16x16x32_bf16 v[8:11], v[176:179], v[200:203], v[8:11]
	v_mfma_f32_16x16x32_bf16 v[4:7], v[160:163], v[208:211], v[4:7]
	v_mfma_f32_16x16x32_bf16 v[0:3], v[176:179], v[208:211], v[0:3]
	s_barrier
; #define PG8_STAGE(bufoff, gbase, voff) do { _Pragma("unroll") for (int _i = 0; _i < 2; ++_i) \
;         __builtin_amdgcn_global_load_lds((const unsigned*)((const char*)(gbase) + (voff)[_i]), (PG8_LAS unsigned*)(lds + (bufoff) + ldsw + _i * 8192), 16, 0, 0); } while (0)
; #define PG8_LDA(dst, b, h) do { _Pragma("unroll") for (int m = 0; m < 4; ++m) _Pragma("unroll") for (int k = 0; k < 2; ++k) dst[m][k] = *(const PG8_LAS bf16x8*)(lds + PG8_SA(b, h) + aoff + m * 2048 + k * 1024); } while (0)
; #define PG8_LDB(dst, b, h) do { _Pragma("unroll") for (int n = 0; n < 2; ++n) _Pragma("unroll") for (int k = 0; k < 2; ++k) dst[n][k] = *(const PG8_LAS bf16x8*)(lds + PG8_SB(b, h) + boff + n * 2048 + k * 1024); } while (0)
; #define PG8_MMA(ai, bj, At, Bt) do { __builtin_amdgcn_s_setprio(1); _Pragma("unroll") for (int m = 0; m < 4; ++m) _Pragma("unroll") for (int n = 0; n < 2; ++n) _Pragma("unroll") for (int k = 0; k < 2; ++k) \
;         acc[ai][bj][m][n] = __builtin_amdgcn_mfma_f32_16x16x32_bf16(Bt[n][k], At[m][k], acc[ai][bj][m][n], 0, 0, 0); __builtin_amdgcn_s_setprio(0); } while (0)
; #define PG8_WAIT_V(n) asm volatile("s_waitcnt vmcnt(" #n ")" ::: "memory")
; #define PG8_WAIT_L(n) asm volatile("s_waitcnt lgkmcnt(" #n ")" ::: "memory")
; #define PG8_BAR __builtin_amdgcn_s_barrier()
; #define PG8_SCHED __builtin_amdgcn_sched_barrier(0)
; template <class Epi, class Sched, bool ALIGN_EPI = false, bool SP2 = false>
; __device__ __forceinline__ void gemm_phase(PG8_LAS unsigned char* lds, const Gemm g, const Sched& S, const Epi& E) {
;     ...
;             PG8_LDB(B0, 1, 0); PG8_LDB(B1, 1, 1); PG8_SCHED; PG8_LDA(At, 1, 0); PG8_STAGE(PG8_SA(0, 1), a2 + hstep, voffA);
;             PG8_WAIT_V(8); PG8_WAIT_L(0); PG8_BAR; PG8_MMA(0, 0, At, B0); PG8_MMA(0, 1, At, B1); PG8_BAR; PG8_SCHED;
;             PG8_LDA(At, 1, 1); PG8_STAGE(PG8_SB(1, 0), b3, voffB); PG8_STAGE(PG8_SB(1, 1), b3 + hstep, voffB); PG8_STAGE(PG8_SA(1, 0), a3, voffA);
;             PG8_WAIT_V(8); PG8_WAIT_L(0); PG8_BAR; PG8_MMA(1, 0, At, B0); PG8_MMA(1, 1, At, B1); PG8_BAR; PG8_SCHED;
	s_add_i32 s70, 0, 0x18000
	s_add_i32 s71, 0, 0x1c000
	v_add_u32_e32 v152, s70, v167
	v_add_u32_e32 v176, s71, v167
	ds_read_b128 v[140:143], v152
	ds_read_b128 v[144:147], v152 offset:1024
	ds_read_b128 v[148:151], v152 offset:2048
	ds_read_b128 v[152:155], v152 offset:3072
	ds_read_b128 v[156:159], v176
	ds_read_b128 v[160:163], v176 offset:1024
	ds_read_b128 v[172:175], v176 offset:2048
	ds_read_b128 v[176:179], v176 offset:3072
	s_add_u32 s44, s50, 0x160000
	s_addc_u32 s45, s51, 0
	s_mov_b32 m0, s52
	ds_read_b128 v[180:183], v171 offset:32768
	ds_read_b128 v[184:187], v171 offset:33792
	ds_read_b128 v[188:191], v171 offset:34816
	ds_read_b128 v[192:195], v171 offset:35840
	ds_read_b128 v[196:199], v171 offset:36864
	ds_read_b128 v[200:203], v171 offset:37888
	ds_read_b128 v[204:207], v171 offset:38912
	ds_read_b128 v[208:211], v171 offset:39936
	global_load_lds_dwordx4 v128, s[44:45]
	s_mov_b32 m0, s53
	s_nop 0
	global_load_lds_dwordx4 v132, s[44:45]
	s_waitcnt vmcnt(8)
	s_waitcnt lgkmcnt(0)
	s_barrier
	v_mfma_f32_16x16x32_bf16 v[124:127], v[140:143], v[180:183], v[124:127]
	v_mfma_f32_16x16x32_bf16 v[120:123], v[148:151], v[180:183], v[120:123]
	v_mfma_f32_16x16x32_bf16 v[116:119], v[140:143], v[188:191], v[116:119]
	v_mfma_f32_16x16x32_bf16 v[112:115], v[148:151], v[188:191], v[112:115]
	v_mfma_f32_16x16x32_bf16 v[108:111], v[140:143], v[196:199], v[108:111]
	v_mfma_f32_16x16x32_bf16 v[96:99], v[148:151], v[196:199], v[96:99]
	v_mfma_f32_16x16x32_bf16 v[84:87], v[140:143], v[204:207], v[84:87]
	v_mfma_f32_16x16x32_bf16 v[76:79], v[148:151], v[204:207], v[76:79]
	v_mfma_f32_16x16x32_bf16 v[124:127], v[144:147], v[184:187], v[124:127]
	v_mfma_f32_16x16x32_bf16 v[120:123], v[152:155], v[184:187], v[120:123]
	v_mfma_f32_16x16x32_bf16 v[116:119], v[144:147], v[192:195], v[116:119]
	v_mfma_f32_16x16x32_bf16 v[112:115], v[152:155], v[192:195], v[112:115]
	v_mfma_f32_16x16x32_bf16 v[108:111], v[144:147], v[200:203], v[108:111]
	v_mfma_f32_16x16x32_bf16 v[96:99], v[152:155], v[200:203], v[96:99]
	v_mfma_f32_16x16x32_bf16 v[84:87], v[144:147], v[208:211], v[84:87]
	v_mfma_f32_16x16x32_bf16 v[76:79], v[152:155], v[208:211], v[76:79]
	v_mfma_f32_16x16x32_bf16 v[104:107], v[156:159], v[180:183], v[104:107]
	v_mfma_f32_16x16x32_bf16 v[100:103], v[172:175], v[180:183], v[100:103]
	v_mfma_f32_16x16x32_bf16 v[92:95], v[156:159], v[188:191], v[92:95]
	v_mfma_f32_16x16x32_bf16 v[88:91], v[172:175], v[188:191], v[88:91]
	v_mfma_f32_16x16x32_bf16 v[80:83], v[156:159], v[196:199], v[80:83]
	v_mfma_f32_16x16x32_bf16 v[72:75], v[172:175], v[196:199], v[72:75]
	v_mfma_f32_16x16x32_bf16 v[68:71], v[156:159], v[204:207], v[68:71]
	v_mfma_f32_16x16x32_bf16 v[64:67], v[172:175], v[204:207], v[64:67]
	v_mfma_f32_16x16x32_bf16 v[104:107], v[160:163], v[184:187], v[104:107]
	v_mfma_f32_16x16x32_bf16 v[100:103], v[176:179], v[184:187], v[100:103]
	v_mfma_f32_16x16x32_bf16 v[92:95], v[160:163], v[192:195], v[92:95]
	v_mfma_f32_16x16x32_bf16 v[88:91], v[176:179], v[192:195], v[88:91]
	v_mfma_f32_16x16x32_bf16 v[80:83], v[160:163], v[200:203], v[80:83]
	v_mfma_f32_16x16x32_bf16 v[72:75], v[176:179], v[200:203], v[72:75]
	v_mfma_f32_16x16x32_bf16 v[68:71], v[160:163], v[208:211], v[68:71]
	v_mfma_f32_16x16x32_bf16 v[64:67], v[176:179], v[208:211], v[64:67]
	s_barrier
	s_add_i32 s44, s70, s25
	s_add_u32 s86, s48, 0x80
	s_addc_u32 s87, s49, 0
	s_mov_b32 m0, s44
	ds_read_b128 v[180:183], v171 offset:49152
	ds_read_b128 v[184:187], v171 offset:50176
	ds_read_b128 v[188:191], v171 offset:51200
	ds_read_b128 v[192:195], v171 offset:52224
	ds_read_b128 v[196:199], v171 offset:53248
	ds_read_b128 v[200:203], v171 offset:54272
	ds_read_b128 v[204:207], v171 offset:55296
	ds_read_b128 v[208:211], v171 offset:56320
	global_load_lds_dwordx4 v130, s[86:87]
	s_add_i32 m0, s44, 0x2000
	s_add_u32 s44, s48, 0x160080
	s_addc_u32 s45, s49, 0
	s_add_i32 s48, s71, s25
	global_load_lds_dwordx4 v134, s[86:87]
	s_mov_b32 m0, s48
	s_nop 0
	global_load_lds_dwordx4 v130, s[44:45]
	s_add_i32 m0, s48, 0x2000
	s_nop 0
	global_load_lds_dwordx4 v134, s[44:45]
	s_add_u32 s84, s50, 0x80
	s_addc_u32 s85, s51, 0
	s_mov_b32 m0, s57
	s_nop 0
	global_load_lds_dwordx4 v128, s[84:85]
	s_mov_b32 m0, s58
	s_nop 0
	global_load_lds_dwordx4 v132, s[84:85]
	s_waitcnt vmcnt(8)
	s_waitcnt lgkmcnt(0)
	s_barrier
	v_mfma_f32_16x16x32_bf16 v[60:63], v[140:143], v[180:183], v[60:63]
	v_mfma_f32_16x16x32_bf16 v[56:59], v[148:151], v[180:183], v[56:59]
	v_mfma_f32_16x16x32_bf16 v[52:55], v[140:143], v[188:191], v[52:55]
	v_mfma_f32_16x16x32_bf16 v[48:51], v[148:151], v[188:191], v[48:51]
	v_mfma_f32_16x16x32_bf16 v[44:47], v[140:143], v[196:199], v[44:47]
	v_mfma_f32_16x16x32_bf16 v[32:35], v[148:151], v[196:199], v[32:35]
	v_mfma_f32_16x16x32_bf16 v[20:23], v[140:143], v[204:207], v[20:23]
	v_mfma_f32_16x16x32_bf16 v[12:15], v[148:151], v[204:207], v[12:15]
	v_mfma_f32_16x16x32_bf16 v[60:63], v[144:147], v[184:187], v[60:63]
	v_mfma_f32_16x16x32_bf16 v[56:59], v[152:155], v[184:187], v[56:59]
	v_mfma_f32_16x16x32_bf16 v[52:55], v[144:147], v[192:195], v[52:55]
	v_mfma_f32_16x16x32_bf16 v[48:51], v[152:155], v[192:195], v[48:51]
	v_mfma_f32_16x16x32_bf16 v[44:47], v[144:147], v[200:203], v[44:47]
	v_mfma_f32_16x16x32_bf16 v[32:35], v[152:155], v[200:203], v[32:35]
	v_mfma_f32_16x16x32_bf16 v[20:23], v[144:147], v[208:211], v[20:23]
	v_mfma_f32_16x16x32_bf16 v[12:15], v[152:155], v[208:211], v[12:15]
	v_mfma_f32_16x16x32_bf16 v[40:43], v[156:159], v[180:183], v[40:43]
	v_mfma_f32_16x16x32_bf16 v[36:39], v[172:175], v[180:183], v[36:39]
	v_mfma_f32_16x16x32_bf16 v[28:31], v[156:159], v[188:191], v[28:31]
	v_mfma_f32_16x16x32_bf16 v[24:27], v[172:175], v[188:191], v[24:27]
	v_mfma_f32_16x16x32_bf16 v[16:19], v[156:159], v[196:199], v[16:19]
	v_mfma_f32_16x16x32_bf16 v[8:11], v[172:175], v[196:199], v[8:11]
	v_mfma_f32_16x16x32_bf16 v[4:7], v[156:159], v[204:207], v[4:7]
	v_mfma_f32_16x16x32_bf16 v[0:3], v[172:175], v[204:207], v[0:3]
	v_mfma_f32_16x16x32_bf16 v[40:43], v[160:163], v[184:187], v[40:43]
	v_mfma_f32_16x16x32_bf16 v[36:39], v[176:179], v[184:187], v[36:39]
	v_mfma_f32_16x16x32_bf16 v[28:31], v[160:163], v[192:195], v[28:31]
	v_mfma_f32_16x16x32_bf16 v[24:27], v[176:179], v[192:195], v[24:27]
	v_mfma_f32_16x16x32_bf16 v[16:19], v[160:163], v[200:203], v[16:19]
	v_mfma_f32_16x16x32_bf16 v[8:11], v[176:179], v[200:203], v[8:11]
	v_mfma_f32_16x16x32_bf16 v[4:7], v[160:163], v[208:211], v[4:7]
	v_mfma_f32_16x16x32_bf16 v[0:3], v[176:179], v[208:211], v[0:3]
	s_barrier
	s_add_i32 s69, s69, 2
	s_add_u32 s67, s67, 0x100
	s_addc_u32 s68, s68, 0
	s_cmpk_gt_u32 s69, 0x55
	s_mov_b64 s[44:45], s[46:47]
; #define PG8_STAGE(bufoff, gbase, voff) do { _Pragma("unroll") for (int _i = 0; _i < 2; ++_i) \
;         __builtin_amdgcn_global_load_lds((const unsigned*)((const char*)(gbase) + (voff)[_i]), (PG8_LAS unsigned*)(lds + (bufoff) + ldsw + _i * 8192), 16, 0, 0); } while (0)
; #define PG8_LDA(dst, b, h) do { _Pragma("unroll") for (int m = 0; m < 4; ++m) _Pragma("unroll") for (int k = 0; k < 2; ++k) dst[m][k] = *(const PG8_LAS bf16x8*)(lds + PG8_SA(b, h) + aoff + m * 2048 + k * 1024); } while (0)
; #define PG8_LDB(dst, b, h) do { _Pragma("unroll") for (int n = 0; n < 2; ++n) _Pragma("unroll") for (int k = 0; k < 2; ++k) dst[n][k] = *(const PG8_LAS bf16x8*)(lds + PG8_SB(b, h) + boff + n * 2048 + k * 1024); } while (0)
; #define PG8_MMA(ai, bj, At, Bt) do { __builtin_amdgcn_s_setprio(1); _Pragma("unroll") for (int m = 0; m < 4; ++m) _Pragma("unroll") for (int n = 0; n < 2; ++n) _Pragma("unroll") for (int k = 0; k < 2; ++k) \
;         acc[ai][bj][m][n] = __builtin_amdgcn_mfma_f32_16x16x32_bf16(Bt[n][k], At[m][k], acc[ai][bj][m][n], 0, 0, 0); __builtin_amdgcn_s_setprio(0); } while (0)
; #define PG8_WAIT_V(n) asm volatile("s_waitcnt vmcnt(" #n ")" ::: "memory")
; #define PG8_WAIT_L(n) asm volatile("s_waitcnt lgkmcnt(" #n ")" ::: "memory")
; #define PG8_BAR __builtin_amdgcn_s_barrier()
; #define PG8_SCHED __builtin_amdgcn_sched_barrier(0)
; template <class Epi, class Sched, bool ALIGN_EPI = false, bool SP2 = false>
; __device__ __forceinline__ void gemm_phase(PG8_LAS unsigned char* lds, const Gemm g, const Sched& S, const Epi& E) {
;     ...
;             PG8_LDB(B0, 0, 0); PG8_LDB(B1, 0, 1); PG8_SCHED; PG8_LDA(At, 0, 0); PG8_STAGE(PG8_SA(1, 1), a1 + hstep, voffA);
;             PG8_WAIT_V(8); PG8_WAIT_L(0); PG8_BAR; PG8_MMA(0, 0, At, B0); PG8_MMA(0, 1, At, B1); PG8_BAR; PG8_SCHED;
;             PG8_LDA(At, 0, 1); PG8_STAGE(PG8_SB(0, 0), b2, voffB); PG8_STAGE(PG8_SB(0, 1), b2 + hstep, voffB); PG8_STAGE(PG8_SA(0, 0), a2, voffA);
;             PG8_WAIT_V(8); PG8_WAIT_L(0); PG8_BAR; PG8_MMA(1, 0, At, B0); PG8_MMA(1, 1, At, B1); PG8_BAR; PG8_SCHED;
.LBB0_245:
	ds_read_b128 v[140:143], v169
	ds_read_b128 v[144:147], v169 offset:1024
	ds_read_b128 v[148:151], v169 offset:2048
	ds_read_b128 v[152:155], v169 offset:3072
	ds_read_b128 v[156:159], v170
	ds_read_b128 v[160:163], v170 offset:1024
	ds_read_b128 v[172:175], v170 offset:2048
	ds_read_b128 v[176:179], v170 offset:3072
	s_add_u32 s46, s44, 0x100
	s_addc_u32 s47, s45, 0
	s_cmpk_eq_i32 s69, 0x54
	s_cselect_b32 s51, s11, s47
	s_cselect_b32 s50, s10, s46
	s_cselect_b32 s49, s13, s68
	s_cselect_b32 s48, s12, s67
	s_add_i32 m0, s26, 0xc000
	ds_read_b128 v[180:183], v171
	ds_read_b128 v[184:187], v171 offset:1024
	ds_read_b128 v[188:191], v171 offset:2048
	ds_read_b128 v[192:195], v171 offset:3072
	ds_read_b128 v[196:199], v171 offset:4096
	ds_read_b128 v[200:203], v171 offset:5120
	ds_read_b128 v[204:207], v171 offset:6144
	ds_read_b128 v[208:211], v171 offset:7168
	global_load_lds_dwordx4 v136, s[44:45]
	s_add_i32 m0, s26, 0xe000
	s_nop 0
	global_load_lds_dwordx4 v138, s[44:45]
	s_waitcnt vmcnt(8)
	s_waitcnt lgkmcnt(0)
	s_barrier
	v_mfma_f32_16x16x32_bf16 v[124:127], v[140:143], v[180:183], v[124:127]
	v_mfma_f32_16x16x32_bf16 v[120:123], v[148:151], v[180:183], v[120:123]
	v_mfma_f32_16x16x32_bf16 v[116:119], v[140:143], v[188:191], v[116:119]
	v_mfma_f32_16x16x32_bf16 v[112:115], v[148:151], v[188:191], v[112:115]
	v_mfma_f32_16x16x32_bf16 v[108:111], v[140:143], v[196:199], v[108:111]
	v_mfma_f32_16x16x32_bf16 v[96:99], v[148:151], v[196:199], v[96:99]
	v_mfma_f32_16x16x32_bf16 v[84:87], v[140:143], v[204:207], v[84:87]
	v_mfma_f32_16x16x32_bf16 v[76:79], v[148:151], v[204:207], v[76:79]
	v_mfma_f32_16x16x32_bf16 v[124:127], v[144:147], v[184:187], v[124:127]
	v_mfma_f32_16x16x32_bf16 v[120:123], v[152:155], v[184:187], v[120:123]
	v_mfma_f32_16x16x32_bf16 v[116:119], v[144:147], v[192:195], v[116:119]
	v_mfma_f32_16x16x32_bf16 v[112:115], v[152:155], v[192:195], v[112:115]
	v_mfma_f32_16x16x32_bf16 v[108:111], v[144:147], v[200:203], v[108:111]
	v_mfma_f32_16x16x32_bf16 v[96:99], v[152:155], v[200:203], v[96:99]
	v_mfma_f32_16x16x32_bf16 v[84:87], v[144:147], v[208:211], v[84:87]
	v_mfma_f32_16x16x32_bf16 v[76:79], v[152:155], v[208:211], v[76:79]
	v_mfma_f32_16x16x32_bf16 v[104:107], v[156:159], v[180:183], v[104:107]
	v_mfma_f32_16x16x32_bf16 v[100:103], v[172:175], v[180:183], v[100:103]
	v_mfma_f32_16x16x32_bf16 v[92:95], v[156:159], v[188:191], v[92:95]
	v_mfma_f32_16x16x32_bf16 v[88:91], v[172:175], v[188:191], v[88:91]
	v_mfma_f32_16x16x32_bf16 v[80:83], v[156:159], v[196:199], v[80:83]
	v_mfma_f32_16x16x32_bf16 v[72:75], v[172:175], v[196:199], v[72:75]
	v_mfma_f32_16x16x32_bf16 v[68:71], v[156:159], v[204:207], v[68:71]
	v_mfma_f32_16x16x32_bf16 v[64:67], v[172:175], v[204:207], v[64:67]
	v_mfma_f32_16x16x32_bf16 v[104:107], v[160:163], v[184:187], v[104:107]
	v_mfma_f32_16x16x32_bf16 v[100:103], v[176:179], v[184:187], v[100:103]
	v_mfma_f32_16x16x32_bf16 v[92:95], v[160:163], v[192:195], v[92:95]
	v_mfma_f32_16x16x32_bf16 v[88:91], v[176:179], v[192:195], v[88:91]
	v_mfma_f32_16x16x32_bf16 v[80:83], v[160:163], v[200:203], v[80:83]
	v_mfma_f32_16x16x32_bf16 v[72:75], v[176:179], v[200:203], v[72:75]
	v_mfma_f32_16x16x32_bf16 v[68:71], v[160:163], v[208:211], v[68:71]
	v_mfma_f32_16x16x32_bf16 v[64:67], v[176:179], v[208:211], v[64:67]
	s_barrier
	s_add_i32 s44, s61, s25
	s_mov_b32 m0, s44
	ds_read_b128 v[180:183], v171 offset:16384
	ds_read_b128 v[184:187], v171 offset:17408
	ds_read_b128 v[188:191], v171 offset:18432
	ds_read_b128 v[192:195], v171 offset:19456
	ds_read_b128 v[196:199], v171 offset:20480
	ds_read_b128 v[200:203], v171 offset:21504
	ds_read_b128 v[204:207], v171 offset:22528
	ds_read_b128 v[208:211], v171 offset:23552
	global_load_lds_dwordx4 v130, s[48:49]
	s_add_i32 m0, s44, 0x2000
	s_add_u32 s44, s48, 0x160000
	s_addc_u32 s45, s49, 0
	s_add_i32 s70, s62, s25
	global_load_lds_dwordx4 v134, s[48:49]
	s_mov_b32 m0, s70
	s_nop 0
	global_load_lds_dwordx4 v130, s[44:45]
	s_add_i32 m0, s70, 0x2000
	s_nop 0
	global_load_lds_dwordx4 v134, s[44:45]
	s_mov_b32 m0, s26
	s_nop 0
	global_load_lds_dwordx4 v128, s[50:51]
	s_mov_b32 m0, s27
	s_nop 0
	global_load_lds_dwordx4 v132, s[50:51]
	s_waitcnt vmcnt(8)
	s_waitcnt lgkmcnt(0)
	s_barrier
	v_mfma_f32_16x16x32_bf16 v[60:63], v[140:143], v[180:183], v[60:63]
	v_mfma_f32_16x16x32_bf16 v[56:59], v[148:151], v[180:183], v[56:59]
	v_mfma_f32_16x16x32_bf16 v[52:55], v[140:143], v[188:191], v[52:55]
	v_mfma_f32_16x16x32_bf16 v[48:51], v[148:151], v[188:191], v[48:51]
	v_mfma_f32_16x16x32_bf16 v[44:47], v[140:143], v[196:199], v[44:47]
	v_mfma_f32_16x16x32_bf16 v[32:35], v[148:151], v[196:199], v[32:35]
	v_mfma_f32_16x16x32_bf16 v[20:23], v[140:143], v[204:207], v[20:23]
	v_mfma_f32_16x16x32_bf16 v[12:15], v[148:151], v[204:207], v[12:15]
	v_mfma_f32_16x16x32_bf16 v[60:63], v[144:147], v[184:187], v[60:63]
	v_mfma_f32_16x16x32_bf16 v[56:59], v[152:155], v[184:187], v[56:59]
	v_mfma_f32_16x16x32_bf16 v[52:55], v[144:147], v[192:195], v[52:55]
	v_mfma_f32_16x16x32_bf16 v[48:51], v[152:155], v[192:195], v[48:51]
	v_mfma_f32_16x16x32_bf16 v[44:47], v[144:147], v[200:203], v[44:47]
	v_mfma_f32_16x16x32_bf16 v[32:35], v[152:155], v[200:203], v[32:35]
	v_mfma_f32_16x16x32_bf16 v[20:23], v[144:147], v[208:211], v[20:23]
	v_mfma_f32_16x16x32_bf16 v[12:15], v[152:155], v[208:211], v[12:15]
	v_mfma_f32_16x16x32_bf16 v[40:43], v[156:159], v[180:183], v[40:43]
	v_mfma_f32_16x16x32_bf16 v[36:39], v[172:175], v[180:183], v[36:39]
	v_mfma_f32_16x16x32_bf16 v[28:31], v[156:159], v[188:191], v[28:31]
	v_mfma_f32_16x16x32_bf16 v[24:27], v[172:175], v[188:191], v[24:27]
	v_mfma_f32_16x16x32_bf16 v[16:19], v[156:159], v[196:199], v[16:19]
	v_mfma_f32_16x16x32_bf16 v[8:11], v[172:175], v[196:199], v[8:11]
	v_mfma_f32_16x16x32_bf16 v[4:7], v[156:159], v[204:207], v[4:7]
	v_mfma_f32_16x16x32_bf16 v[0:3], v[172:175], v[204:207], v[0:3]
	v_mfma_f32_16x16x32_bf16 v[40:43], v[160:163], v[184:187], v[40:43]
	v_mfma_f32_16x16x32_bf16 v[36:39], v[176:179], v[184:187], v[36:39]
	v_mfma_f32_16x16x32_bf16 v[28:31], v[160:163], v[192:195], v[28:31]
	v_mfma_f32_16x16x32_bf16 v[24:27], v[176:179], v[192:195], v[24:27]
	v_mfma_f32_16x16x32_bf16 v[16:19], v[160:163], v[200:203], v[16:19]
	v_mfma_f32_16x16x32_bf16 v[8:11], v[176:179], v[200:203], v[8:11]
	v_mfma_f32_16x16x32_bf16 v[4:7], v[160:163], v[208:211], v[4:7]
	v_mfma_f32_16x16x32_bf16 v[0:3], v[176:179], v[208:211], v[0:3]
	s_barrier
; #define PG8_STAGE(bufoff, gbase, voff) do { _Pragma("unroll") for (int _i = 0; _i < 2; ++_i) \
;         __builtin_amdgcn_global_load_lds((const unsigned*)((const char*)(gbase) + (voff)[_i]), (PG8_LAS unsigned*)(lds + (bufoff) + ldsw + _i * 8192), 16, 0, 0); } while (0)
; #define PG8_LDA(dst, b, h) do { _Pragma("unroll") for (int m = 0; m < 4; ++m) _Pragma("unroll") for (int k = 0; k < 2; ++k) dst[m][k] = *(const PG8_LAS bf16x8*)(lds + PG8_SA(b, h) + aoff + m * 2048 + k * 1024); } while (0)
; #define PG8_LDB(dst, b, h) do { _Pragma("unroll") for (int n = 0; n < 2; ++n) _Pragma("unroll") for (int k = 0; k < 2; ++k) dst[n][k] = *(const PG8_LAS bf16x8*)(lds + PG8_SB(b, h) + boff + n * 2048 + k * 1024); } while (0)
; #define PG8_MMA(ai, bj, At, Bt) do { __builtin_amdgcn_s_setprio(1); _Pragma("unroll") for (int m = 0; m < 4; ++m) _Pragma("unroll") for (int n = 0; n < 2; ++n) _Pragma("unroll") for (int k = 0; k < 2; ++k) \
;         acc[ai][bj][m][n] = __builtin_amdgcn_mfma_f32_16x16x32_bf16(Bt[n][k], At[m][k], acc[ai][bj][m][n], 0, 0, 0); __builtin_amdgcn_s_setprio(0); } while (0)
; #define PG8_WAIT_V(n) asm volatile("s_waitcnt vmcnt(" #n ")" ::: "memory")
; #define PG8_WAIT_L(n) asm volatile("s_waitcnt lgkmcnt(" #n ")" ::: "memory")
; #define PG8_BAR __builtin_amdgcn_s_barrier()
; #define PG8_SCHED __builtin_amdgcn_sched_barrier(0)
; template <class Epi, class Sched, bool ALIGN_EPI = false, bool SP2 = false>
; __device__ __forceinline__ void gemm_phase(PG8_LAS unsigned char* lds, const Gemm g, const Sched& S, const Epi& E) {
;     ...
;             PG8_LDB(B0, 1, 0); PG8_LDB(B1, 1, 1); PG8_SCHED; PG8_LDA(At, 1, 0); PG8_STAGE(PG8_SA(0, 1), a2 + hstep, voffA);
;             PG8_WAIT_V(8); PG8_WAIT_L(0); PG8_BAR; PG8_MMA(0, 0, At, B0); PG8_MMA(0, 1, At, B1); PG8_BAR; PG8_SCHED;
;             PG8_LDA(At, 1, 1); PG8_STAGE(PG8_SB(1, 0), b3, voffB); PG8_STAGE(PG8_SB(1, 1), b3 + hstep, voffB); PG8_STAGE(PG8_SA(1, 0), a3, voffA);
;             PG8_WAIT_V(8); PG8_WAIT_L(0); PG8_BAR; PG8_MMA(1, 0, At, B0); PG8_MMA(1, 1, At, B1); PG8_BAR; PG8_SCHED;
	s_add_i32 s70, 0, 0x18000
	s_add_i32 s71, 0, 0x1c000
	v_add_u32_e32 v152, s70, v167
	v_add_u32_e32 v176, s71, v167
	ds_read_b128 v[140:143], v152
	ds_read_b128 v[144:147], v152 offset:1024
	ds_read_b128 v[148:151], v152 offset:2048
	ds_read_b128 v[152:155], v152 offset:3072
	ds_read_b128 v[156:159], v176
	ds_read_b128 v[160:163], v176 offset:1024
	ds_read_b128 v[172:175], v176 offset:2048
	ds_read_b128 v[176:179], v176 offset:3072
	s_add_u32 s44, s50, 0x160000
	s_addc_u32 s45, s51, 0
	s_mov_b32 m0, s52
	ds_read_b128 v[180:183], v171 offset:32768
	ds_read_b128 v[184:187], v171 offset:33792
	ds_read_b128 v[188:191], v171 offset:34816
	ds_read_b128 v[192:195], v171 offset:35840
	ds_read_b128 v[196:199], v171 offset:36864
	ds_read_b128 v[200:203], v171 offset:37888
	ds_read_b128 v[204:207], v171 offset:38912
	ds_read_b128 v[208:211], v171 offset:39936
	global_load_lds_dwordx4 v128, s[44:45]
	s_mov_b32 m0, s53
	s_nop 0
	global_load_lds_dwordx4 v132, s[44:45]
	s_waitcnt vmcnt(8)
	s_waitcnt lgkmcnt(0)
	s_barrier
	v_mfma_f32_16x16x32_bf16 v[124:127], v[140:143], v[180:183], v[124:127]
	v_mfma_f32_16x16x32_bf16 v[120:123], v[148:151], v[180:183], v[120:123]
	v_mfma_f32_16x16x32_bf16 v[116:119], v[140:143], v[188:191], v[116:119]
	v_mfma_f32_16x16x32_bf16 v[112:115], v[148:151], v[188:191], v[112:115]
	v_mfma_f32_16x16x32_bf16 v[108:111], v[140:143], v[196:199], v[108:111]
	v_mfma_f32_16x16x32_bf16 v[96:99], v[148:151], v[196:199], v[96:99]
	v_mfma_f32_16x16x32_bf16 v[84:87], v[140:143], v[204:207], v[84:87]
	v_mfma_f32_16x16x32_bf16 v[76:79], v[148:151], v[204:207], v[76:79]
	v_mfma_f32_16x16x32_bf16 v[124:127], v[144:147], v[184:187], v[124:127]
	v_mfma_f32_16x16x32_bf16 v[120:123], v[152:155], v[184:187], v[120:123]
	v_mfma_f32_16x16x32_bf16 v[116:119], v[144:147], v[192:195], v[116:119]
	v_mfma_f32_16x16x32_bf16 v[112:115], v[152:155], v[192:195], v[112:115]
	v_mfma_f32_16x16x32_bf16 v[108:111], v[144:147], v[200:203], v[108:111]
	v_mfma_f32_16x16x32_bf16 v[96:99], v[152:155], v[200:203], v[96:99]
	v_mfma_f32_16x16x32_bf16 v[84:87], v[144:147], v[208:211], v[84:87]
	v_mfma_f32_16x16x32_bf16 v[76:79], v[152:155], v[208:211], v[76:79]
	v_mfma_f32_16x16x32_bf16 v[104:107], v[156:159], v[180:183], v[104:107]
	v_mfma_f32_16x16x32_bf16 v[100:103], v[172:175], v[180:183], v[100:103]
	v_mfma_f32_16x16x32_bf16 v[92:95], v[156:159], v[188:191], v[92:95]
	v_mfma_f32_16x16x32_bf16 v[88:91], v[172:175], v[188:191], v[88:91]
	v_mfma_f32_16x16x32_bf16 v[80:83], v[156:159], v[196:199], v[80:83]
	v_mfma_f32_16x16x32_bf16 v[72:75], v[172:175], v[196:199], v[72:75]
	v_mfma_f32_16x16x32_bf16 v[68:71], v[156:159], v[204:207], v[68:71]
	v_mfma_f32_16x16x32_bf16 v[64:67], v[172:175], v[204:207], v[64:67]
	v_mfma_f32_16x16x32_bf16 v[104:107], v[160:163], v[184:187], v[104:107]
	v_mfma_f32_16x16x32_bf16 v[100:103], v[176:179], v[184:187], v[100:103]
	v_mfma_f32_16x16x32_bf16 v[92:95], v[160:163], v[192:195], v[92:95]
	v_mfma_f32_16x16x32_bf16 v[88:91], v[176:179], v[192:195], v[88:91]
	v_mfma_f32_16x16x32_bf16 v[80:83], v[160:163], v[200:203], v[80:83]
	v_mfma_f32_16x16x32_bf16 v[72:75], v[176:179], v[200:203], v[72:75]
	v_mfma_f32_16x16x32_bf16 v[68:71], v[160:163], v[208:211], v[68:71]
	v_mfma_f32_16x16x32_bf16 v[64:67], v[176:179], v[208:211], v[64:67]
	s_barrier
	s_add_i32 s44, s70, s25
	s_add_u32 s86, s48, 0x80
	s_addc_u32 s87, s49, 0
	s_mov_b32 m0, s44
	ds_read_b128 v[180:183], v171 offset:49152
	ds_read_b128 v[184:187], v171 offset:50176
	ds_read_b128 v[188:191], v171 offset:51200
	ds_read_b128 v[192:195], v171 offset:52224
	ds_read_b128 v[196:199], v171 offset:53248
	ds_read_b128 v[200:203], v171 offset:54272
	ds_read_b128 v[204:207], v171 offset:55296
	ds_read_b128 v[208:211], v171 offset:56320
	global_load_lds_dwordx4 v130, s[86:87]
	s_add_i32 m0, s44, 0x2000
	s_add_u32 s44, s48, 0x160080
	s_addc_u32 s45, s49, 0
	s_add_i32 s48, s71, s25
	global_load_lds_dwordx4 v134, s[86:87]
	s_mov_b32 m0, s48
	s_nop 0
	global_load_lds_dwordx4 v130, s[44:45]
	s_add_i32 m0, s48, 0x2000
	s_nop 0
	global_load_lds_dwordx4 v134, s[44:45]
	s_add_u32 s84, s50, 0x80
	s_addc_u32 s85, s51, 0
	s_mov_b32 m0, s57
	s_nop 0
	global_load_lds_dwordx4 v128, s[84:85]
	s_mov_b32 m0, s58
	s_nop 0
	global_load_lds_dwordx4 v132, s[84:85]
	s_waitcnt vmcnt(8)
	s_waitcnt lgkmcnt(0)
	s_barrier
	v_mfma_f32_16x16x32_bf16 v[60:63], v[140:143], v[180:183], v[60:63]
	v_mfma_f32_16x16x32_bf16 v[56:59], v[148:151], v[180:183], v[56:59]
	v_mfma_f32_16x16x32_bf16 v[52:55], v[140:143], v[188:191], v[52:55]
	v_mfma_f32_16x16x32_bf16 v[48:51], v[148:151], v[188:191], v[48:51]
	v_mfma_f32_16x16x32_bf16 v[44:47], v[140:143], v[196:199], v[44:47]
	v_mfma_f32_16x16x32_bf16 v[32:35], v[148:151], v[196:199], v[32:35]
	v_mfma_f32_16x16x32_bf16 v[20:23], v[140:143], v[204:207], v[20:23]
	v_mfma_f32_16x16x32_bf16 v[12:15], v[148:151], v[204:207], v[12:15]
	v_mfma_f32_16x16x32_bf16 v[60:63], v[144:147], v[184:187], v[60:63]
	v_mfma_f32_16x16x32_bf16 v[56:59], v[152:155], v[184:187], v[56:59]
	v_mfma_f32_16x16x32_bf16 v[52:55], v[144:147], v[192:195], v[52:55]
	v_mfma_f32_16x16x32_bf16 v[48:51], v[152:155], v[192:195], v[48:51]
	v_mfma_f32_16x16x32_bf16 v[44:47], v[144:147], v[200:203], v[44:47]
	v_mfma_f32_16x16x32_bf16 v[32:35], v[152:155], v[200:203], v[32:35]
	v_mfma_f32_16x16x32_bf16 v[20:23], v[144:147], v[208:211], v[20:23]
	v_mfma_f32_16x16x32_bf16 v[12:15], v[152:155], v[208:211], v[12:15]
	v_mfma_f32_16x16x32_bf16 v[40:43], v[156:159], v[180:183], v[40:43]
	v_mfma_f32_16x16x32_bf16 v[36:39], v[172:175], v[180:183], v[36:39]
	v_mfma_f32_16x16x32_bf16 v[28:31], v[156:159], v[188:191], v[28:31]
	v_mfma_f32_16x16x32_bf16 v[24:27], v[172:175], v[188:191], v[24:27]
	v_mfma_f32_16x16x32_bf16 v[16:19], v[156:159], v[196:199], v[16:19]
	v_mfma_f32_16x16x32_bf16 v[8:11], v[172:175], v[196:199], v[8:11]
	v_mfma_f32_16x16x32_bf16 v[4:7], v[156:159], v[204:207], v[4:7]
	v_mfma_f32_16x16x32_bf16 v[0:3], v[172:175], v[204:207], v[0:3]
	v_mfma_f32_16x16x32_bf16 v[40:43], v[160:163], v[184:187], v[40:43]
	v_mfma_f32_16x16x32_bf16 v[36:39], v[176:179], v[184:187], v[36:39]
	v_mfma_f32_16x16x32_bf16 v[28:31], v[160:163], v[192:195], v[28:31]
	v_mfma_f32_16x16x32_bf16 v[24:27], v[176:179], v[192:195], v[24:27]
	v_mfma_f32_16x16x32_bf16 v[16:19], v[160:163], v[200:203], v[16:19]
	v_mfma_f32_16x16x32_bf16 v[8:11], v[176:179], v[200:203], v[8:11]
	v_mfma_f32_16x16x32_bf16 v[4:7], v[160:163], v[208:211], v[4:7]
	v_mfma_f32_16x16x32_bf16 v[0:3], v[176:179], v[208:211], v[0:3]
	s_barrier
;     __device__ __forceinline__ void operator()(const f32x4 (&acc)[2][2][4][2], const Unit& u, int wr, int wc, int fr, int fq) const {
;         const int row0 = u.pm * BM + wr * 64 + fr, col0 = u.pn * BM + wc * 32 + 8 * fq;
;         const float* gp = gate + (u.pm >> 5) * 18432 + col0;
;         f32x4 gv[2][2];
; #pragma unroll
;         for (int bj = 0; bj < 2; ++bj)
; #pragma unroll
;             for (int n = 0; n < 2; ++n) gv[bj][n] = *(const f32x4*)(gp + bj * HALF + 4 * n) * scale;
; #pragma unroll
;         for (int ai = 0; ai < 2; ++ai) { f32x4 r[4][2][2];
; #pragma unroll
;             for (int m = 0; m < 4; ++m) { const size_t off = (size_t)(row0 + ai * HALF + m * 16) * 2048 + col0;
; #pragma unroll
;                 for (int bj = 0; bj < 2; ++bj)
; #pragma unroll
;                     for (int n = 0; n < 2; ++n) r[m][bj][n] = *(const f32x4*)(res + off + bj * HALF + 4 * n); }
; #pragma unroll
;             for (int m = 0; m < 4; ++m) { const size_t off = (size_t)(row0 + ai * HALF + m * 16) * 2048 + col0;
; #pragma unroll
;                 for (int bj = 0; bj < 2; ++bj)
; #pragma unroll
;                     for (int n = 0; n < 2; ++n) *(f32x4*)(out + off + bj * HALF + 4 * n) = r[m][bj][n] + gv[bj][n] * acc[ai][bj][m][n]; } }
	s_add_i32 s69, s69, 2
	s_add_u32 s67, s67, 0x100
	s_addc_u32 s68, s68, 0
	s_cmpk_gt_u32 s69, 0x55
	s_mov_b64 s[44:45], s[46:47]
	s_cbranch_scc0 .LBB0_245
	s_lshr_b32 s44, s65, 5
	s_mulk_i32 s44, 0x4800
	s_ashr_i32 s45, s44, 31
	v_lshl_or_b32 v140, s66, 8, v168
	s_lshl_b64 s[44:45], s[44:45], 2
	s_add_u32 s44, s55, s44
	v_ashrrev_i32_e32 v141, 31, v140
	s_addc_u32 s45, s56, s45
	v_lshlrev_b64 v[144:145], 2, v[140:141]
	v_lshl_add_u64 v[140:141], s[44:45], 0, v[144:145]
	global_load_dwordx4 v[146:149], v[140:141], off offset:16
	global_load_dwordx4 v[150:153], v[140:141], off
	global_load_dwordx4 v[172:175], v[140:141], off offset:528
	global_load_dwordx4 v[176:179], v[140:141], off offset:512
	v_lshl_add_u32 v140, s65, 8, v166
	v_ashrrev_i32_e32 v141, 31, v140
	v_lshl_add_u64 v[162:163], s[28:29], 0, v[144:145]
	v_lshlrev_b64 v[164:165], 13, v[140:141]
	v_lshl_add_u64 v[142:143], v[162:163], 0, v[164:165]
	global_load_dwordx4 v[180:183], v[142:143], off
	global_load_dwordx4 v[184:187], v[142:143], off offset:16
	global_load_dwordx4 v[188:191], v[142:143], off offset:528
	global_load_dwordx4 v[192:195], v[142:143], off offset:512
	v_or_b32_e32 v142, 16, v140
	v_ashrrev_i32_e32 v143, 31, v142
	v_lshlrev_b64 v[154:155], 13, v[142:143]
	v_lshl_add_u64 v[142:143], v[162:163], 0, v[154:155]
	global_load_dwordx4 v[196:199], v[142:143], off
	global_load_dwordx4 v[200:203], v[142:143], off offset:16
	global_load_dwordx4 v[204:207], v[142:143], off offset:528
	global_load_dwordx4 v[208:211], v[142:143], off offset:512
	v_or_b32_e32 v142, 32, v140
	v_ashrrev_i32_e32 v143, 31, v142
	v_lshlrev_b64 v[156:157], 13, v[142:143]
	v_or_b32_e32 v140, 48, v140
	v_lshl_add_u64 v[142:143], v[162:163], 0, v[156:157]
	v_ashrrev_i32_e32 v141, 31, v140
	global_load_dwordx4 v[214:217], v[142:143], off
	global_load_dwordx4 v[222:225], v[142:143], off offset:16
	global_load_dwordx4 v[232:235], v[142:143], off offset:512
	global_load_dwordx4 v[236:239], v[142:143], off offset:528
	v_lshlrev_b64 v[212:213], 13, v[140:141]
	v_lshl_add_u64 v[140:141], v[162:163], 0, v[212:213]
	global_load_dwordx4 v[240:243], v[140:141], off
	global_load_dwordx4 v[244:247], v[140:141], off offset:16
	global_load_dwordx4 v[248:251], v[140:141], off offset:512
	s_nop 0
	global_load_dwordx4 v[140:143], v[140:141], off offset:528
	v_lshl_add_u64 v[158:159], s[30:31], 0, v[164:165]
	v_lshl_add_u64 v[230:231], v[158:159], 0, v[144:145]
	v_lshl_add_u64 v[154:155], s[30:31], 0, v[154:155]
	v_lshl_add_u64 v[156:157], s[30:31], 0, v[156:157]
	v_lshl_add_u64 v[218:219], v[154:155], 0, v[144:145]
	v_lshl_add_u64 v[252:253], v[156:157], 0, v[144:145]
	s_and_b64 vcc, exec, s[8:9]
	s_mov_b32 s66, s63
	s_mov_b32 s65, s64
	s_mov_b64 s[46:47], s[12:13]
	s_mov_b64 s[44:45], s[10:11]
	s_waitcnt vmcnt(0)
	v_pk_mul_f32 v[154:155], v[148:149], 0.5 op_sel_hi:[1,0]
	v_pk_mul_f32 v[158:159], v[152:153], 0.5 op_sel_hi:[1,0]
	v_pk_mul_f32 v[160:161], v[150:151], 0.5 op_sel_hi:[1,0]
	v_pk_mul_f32 v[150:151], v[178:179], 0.5 op_sel_hi:[1,0]
	v_pk_mul_f32 v[152:153], v[176:177], 0.5 op_sel_hi:[1,0]
	v_pk_mul_f32 v[156:157], v[146:147], 0.5 op_sel_hi:[1,0]
	v_pk_mul_f32 v[146:147], v[174:175], 0.5 op_sel_hi:[1,0]
	v_pk_mul_f32 v[148:149], v[172:173], 0.5 op_sel_hi:[1,0]
	v_pk_fma_f32 v[126:127], v[126:127], v[158:159], v[182:183]
	v_pk_fma_f32 v[124:125], v[124:125], v[160:161], v[180:181]
	v_pk_fma_f32 v[122:123], v[122:123], v[154:155], v[186:187]
	v_pk_fma_f32 v[120:121], v[120:121], v[156:157], v[184:185]
	v_pk_fma_f32 v[106:107], v[106:107], v[150:151], v[194:195]
	v_pk_fma_f32 v[104:105], v[104:105], v[152:153], v[192:193]
	v_pk_fma_f32 v[102:103], v[102:103], v[146:147], v[190:191]
	v_pk_fma_f32 v[100:101], v[100:101], v[148:149], v[188:189]
	v_pk_fma_f32 v[118:119], v[118:119], v[158:159], v[198:199]
	v_pk_fma_f32 v[116:117], v[116:117], v[160:161], v[196:197]
	v_pk_fma_f32 v[114:115], v[114:115], v[154:155], v[202:203]
	v_pk_fma_f32 v[112:113], v[112:113], v[156:157], v[200:201]
	v_pk_fma_f32 v[82:83], v[82:83], v[150:151], v[234:235]
	v_pk_fma_f32 v[80:81], v[80:81], v[152:153], v[232:233]
	v_pk_fma_f32 v[94:95], v[94:95], v[150:151], v[210:211]
	v_pk_fma_f32 v[92:93], v[92:93], v[152:153], v[208:209]
	v_pk_fma_f32 v[90:91], v[90:91], v[146:147], v[206:207]
	v_pk_fma_f32 v[88:89], v[88:89], v[148:149], v[204:205]
	v_pk_fma_f32 v[110:111], v[110:111], v[158:159], v[216:217]
	v_pk_fma_f32 v[108:109], v[108:109], v[160:161], v[214:215]
	v_pk_fma_f32 v[98:99], v[98:99], v[154:155], v[224:225]
	v_pk_fma_f32 v[96:97], v[96:97], v[156:157], v[222:223]
	global_store_dwordx4 v[230:231], v[124:127], off
	global_store_dwordx4 v[230:231], v[120:123], off offset:16
	global_store_dwordx4 v[230:231], v[104:107], off offset:512
	global_store_dwordx4 v[230:231], v[100:103], off offset:528
	global_store_dwordx4 v[218:219], v[116:119], off
	global_store_dwordx4 v[218:219], v[112:115], off offset:16
	global_store_dwordx4 v[218:219], v[92:95], off offset:512
	global_store_dwordx4 v[218:219], v[88:91], off offset:528
	global_store_dwordx4 v[252:253], v[108:111], off
	global_store_dwordx4 v[252:253], v[96:99], off offset:16
	global_store_dwordx4 v[252:253], v[80:83], off offset:512
	v_pk_fma_f32 v[74:75], v[74:75], v[146:147], v[238:239]
	v_pk_fma_f32 v[72:73], v[72:73], v[148:149], v[236:237]
	v_lshl_add_u64 v[80:81], s[30:31], 0, v[212:213]
	global_store_dwordx4 v[252:253], v[72:75], off offset:528
; #define PG8_WAIT_V(n) asm volatile("s_waitcnt vmcnt(" #n ")" ::: "memory")
; #define PG8_BAR __builtin_amdgcn_s_barrier()
;     __device__ __forceinline__ void operator()(const f32x4 (&acc)[2][2][4][2], const Unit& u, int wr, int wc, int fr, int fq) const {
;     ...
;         for (int ai = 0; ai < 2; ++ai) { f32x4 r[4][2][2];
; #pragma unroll
;             for (int m = 0; m < 4; ++m) { const size_t off = (size_t)(row0 + ai * HALF + m * 16) * 2048 + col0;
; #pragma unroll
;                 for (int bj = 0; bj < 2; ++bj)
; #pragma unroll
;                     for (int n = 0; n < 2; ++n) r[m][bj][n] = *(const f32x4*)(res + off + bj * HALF + 4 * n); }
; #pragma unroll
;             for (int m = 0; m < 4; ++m) { const size_t off = (size_t)(row0 + ai * HALF + m * 16) * 2048 + col0;
; #pragma unroll
;                 for (int bj = 0; bj < 2; ++bj)
; #pragma unroll
;                     for (int n = 0; n < 2; ++n) *(f32x4*)(out + off + bj * HALF + 4 * n) = r[m][bj][n] + gv[bj][n] * acc[ai][bj][m][n]; } }
; template <class Epi, class Sched, bool ALIGN_EPI = false, bool SP2 = false>
; __device__ __forceinline__ void gemm_phase(PG8_LAS unsigned char* lds, const Gemm g, const Sched& S, const Epi& E) {
;     ...
;         if constexpr (!Epi::AFTER_DRAIN) { E(acc, cur, wr, wc, fr, fq); S.done(cur); }
;         if (!has_next) break;
; #pragma unroll
;         for (int a = 0; a < 2; ++a)
; #pragma unroll
;             for (int b = 0; b < 2; ++b)
; #pragma unroll
;                 for (int m = 0; m < 4; ++m)
; #pragma unroll
;                     for (int n = 0; n < 2; ++n) acc[a][b][m][n] = (f32x4){0.f, 0.f, 0.f, 0.f};
;         cur = nxt; cA = nA; cB = nB; ++ui;
;         if constexpr (ALIGN_EPI) { if (wr == 1) PG8_BAR; }
;     }
;     PG8_WAIT_V(0);
;     if constexpr (!ALIGN_EPI) { if (wr == 0) PG8_BAR; }
;     PG8_BAR;
	v_lshl_add_u64 v[80:81], v[80:81], 0, v[144:145]
	v_pk_fma_f32 v[70:71], v[70:71], v[150:151], v[250:251]
	v_pk_fma_f32 v[74:75], v[86:87], v[158:159], v[242:243]
	v_pk_fma_f32 v[72:73], v[84:85], v[160:161], v[240:241]
	global_store_dwordx4 v[80:81], v[72:75], off
	v_pk_fma_f32 v[68:69], v[68:69], v[152:153], v[248:249]
	v_pk_fma_f32 v[66:67], v[66:67], v[146:147], v[142:143]
	v_pk_fma_f32 v[74:75], v[78:79], v[154:155], v[246:247]
	v_pk_fma_f32 v[72:73], v[76:77], v[156:157], v[244:245]
	v_pk_fma_f32 v[64:65], v[64:65], v[148:149], v[140:141]
	v_lshl_add_u64 v[140:141], v[164:165], 0, s[38:39]
	v_lshl_add_u64 v[142:143], v[164:165], 0, s[40:41]
	v_lshl_add_u64 v[172:173], v[164:165], 0, s[42:43]
	global_store_dwordx4 v[80:81], v[72:75], off offset:16
	global_store_dwordx4 v[80:81], v[68:71], off offset:512
	global_store_dwordx4 v[80:81], v[64:67], off offset:528
	v_lshl_add_u64 v[76:77], v[162:163], 0, v[140:141]
	v_lshl_add_u64 v[92:93], v[162:163], 0, v[142:143]
	v_lshl_add_u64 v[108:109], v[162:163], 0, v[172:173]
	global_load_dwordx4 v[64:67], v[76:77], off
	global_load_dwordx4 v[68:71], v[76:77], off offset:16
	global_load_dwordx4 v[72:75], v[76:77], off offset:512
	s_nop 0
	global_load_dwordx4 v[76:79], v[76:77], off offset:528
	s_nop 0
	global_load_dwordx4 v[80:83], v[92:93], off
	global_load_dwordx4 v[84:87], v[92:93], off offset:16
	global_load_dwordx4 v[88:91], v[92:93], off offset:512
	s_nop 0
	global_load_dwordx4 v[92:95], v[92:93], off offset:528
	s_nop 0
	global_load_dwordx4 v[96:99], v[108:109], off
	global_load_dwordx4 v[100:103], v[108:109], off offset:16
	global_load_dwordx4 v[104:107], v[108:109], off offset:512
	s_nop 0
	global_load_dwordx4 v[108:111], v[108:109], off offset:528
	v_lshl_add_u64 v[164:165], v[164:165], 0, s[34:35]
	v_lshl_add_u64 v[124:125], v[162:163], 0, v[164:165]
	global_load_dwordx4 v[112:115], v[124:125], off
	global_load_dwordx4 v[116:119], v[124:125], off offset:16
	global_load_dwordx4 v[120:123], v[124:125], off offset:512
	s_nop 0
	global_load_dwordx4 v[124:127], v[124:125], off offset:528
	v_lshl_add_u64 v[140:141], s[30:31], 0, v[140:141]
	v_lshl_add_u64 v[162:163], s[30:31], 0, v[172:173]
	v_lshl_add_u64 v[142:143], s[30:31], 0, v[142:143]
	v_lshl_add_u64 v[140:141], v[140:141], 0, v[144:145]
	v_lshl_add_u64 v[162:163], v[162:163], 0, v[144:145]
	v_lshl_add_u64 v[142:143], v[142:143], 0, v[144:145]
	v_mov_b32_e32 v251, v220
	s_waitcnt vmcnt(15)
	v_pk_fma_f32 v[62:63], v[62:63], v[158:159], v[66:67]
	v_pk_fma_f32 v[60:61], v[60:61], v[160:161], v[64:65]
	s_waitcnt vmcnt(14)
	v_pk_fma_f32 v[58:59], v[58:59], v[154:155], v[70:71]
	v_pk_fma_f32 v[56:57], v[56:57], v[156:157], v[68:69]
	s_waitcnt vmcnt(5)
	v_pk_fma_f32 v[18:19], v[18:19], v[150:151], v[106:107]
	v_pk_fma_f32 v[16:17], v[16:17], v[152:153], v[104:105]
	v_pk_fma_f32 v[42:43], v[42:43], v[150:151], v[74:75]
	v_pk_fma_f32 v[40:41], v[40:41], v[152:153], v[72:73]
	v_pk_fma_f32 v[38:39], v[38:39], v[146:147], v[78:79]
	v_pk_fma_f32 v[36:37], v[36:37], v[148:149], v[76:77]
	v_pk_fma_f32 v[54:55], v[54:55], v[158:159], v[82:83]
	v_pk_fma_f32 v[52:53], v[52:53], v[160:161], v[80:81]
	v_pk_fma_f32 v[50:51], v[50:51], v[154:155], v[86:87]
	v_pk_fma_f32 v[48:49], v[48:49], v[156:157], v[84:85]
	v_pk_fma_f32 v[30:31], v[30:31], v[150:151], v[90:91]
	v_pk_fma_f32 v[28:29], v[28:29], v[152:153], v[88:89]
	v_pk_fma_f32 v[26:27], v[26:27], v[146:147], v[94:95]
	v_pk_fma_f32 v[24:25], v[24:25], v[148:149], v[92:93]
	v_pk_fma_f32 v[46:47], v[46:47], v[158:159], v[98:99]
	v_pk_fma_f32 v[44:45], v[44:45], v[160:161], v[96:97]
	v_pk_fma_f32 v[34:35], v[34:35], v[154:155], v[102:103]
	v_pk_fma_f32 v[32:33], v[32:33], v[156:157], v[100:101]
	global_store_dwordx4 v[140:141], v[60:63], off
	global_store_dwordx4 v[140:141], v[56:59], off offset:16
	global_store_dwordx4 v[140:141], v[40:43], off offset:512
	global_store_dwordx4 v[140:141], v[36:39], off offset:528
	global_store_dwordx4 v[142:143], v[52:55], off
	global_store_dwordx4 v[142:143], v[48:51], off offset:16
	global_store_dwordx4 v[142:143], v[28:31], off offset:512
	global_store_dwordx4 v[142:143], v[24:27], off offset:528
	global_store_dwordx4 v[162:163], v[44:47], off
	global_store_dwordx4 v[162:163], v[32:35], off offset:16
	global_store_dwordx4 v[162:163], v[16:19], off offset:512
	s_waitcnt vmcnt(15)
	v_pk_fma_f32 v[10:11], v[10:11], v[146:147], v[110:111]
	v_pk_fma_f32 v[8:9], v[8:9], v[148:149], v[108:109]
	v_lshl_add_u64 v[16:17], s[30:31], 0, v[164:165]
	global_store_dwordx4 v[162:163], v[8:11], off offset:528
	v_lshl_add_u64 v[16:17], v[16:17], 0, v[144:145]
	s_waitcnt vmcnt(13)
	v_pk_fma_f32 v[6:7], v[6:7], v[150:151], v[122:123]
	v_pk_fma_f32 v[10:11], v[22:23], v[158:159], v[114:115]
	v_pk_fma_f32 v[8:9], v[20:21], v[160:161], v[112:113]
	global_store_dwordx4 v[16:17], v[8:11], off
	v_pk_fma_f32 v[4:5], v[4:5], v[152:153], v[120:121]
	s_waitcnt vmcnt(13)
	v_pk_fma_f32 v[2:3], v[2:3], v[146:147], v[126:127]
	v_pk_fma_f32 v[10:11], v[14:15], v[154:155], v[118:119]
	v_pk_fma_f32 v[8:9], v[12:13], v[156:157], v[116:117]
	v_pk_fma_f32 v[0:1], v[0:1], v[148:149], v[124:125]
	global_store_dwordx4 v[16:17], v[8:11], off offset:16
	global_store_dwordx4 v[16:17], v[4:7], off offset:512
	global_store_dwordx4 v[16:17], v[0:3], off offset:528
	s_cbranch_vccz .LBB0_234
	s_waitcnt vmcnt(0)
	s_cmpk_gt_u32 s3, 0xff
	s_cbranch_scc1 .LBB0_249
	s_barrier

; #define PG8_STAGE(bufoff, gbase, voff) do { _Pragma("unroll") for (int _i = 0; _i < 2; ++_i) \
;         __builtin_amdgcn_global_load_lds((const unsigned*)((const char*)(gbase) + (voff)[_i]), (PG8_LAS unsigned*)(lds + (bufoff) + ldsw + _i * 8192), 16, 0, 0); } while (0)
; #define PG8_LDA(dst, b, h) do { _Pragma("unroll") for (int m = 0; m < 4; ++m) _Pragma("unroll") for (int k = 0; k < 2; ++k) dst[m][k] = *(const PG8_LAS bf16x8*)(lds + PG8_SA(b, h) + aoff + m * 2048 + k * 1024); } while (0)
; #define PG8_LDB(dst, b, h) do { _Pragma("unroll") for (int n = 0; n < 2; ++n) _Pragma("unroll") for (int k = 0; k < 2; ++k) dst[n][k] = *(const PG8_LAS bf16x8*)(lds + PG8_SB(b, h) + boff + n * 2048 + k * 1024); } while (0)
; #define PG8_WAIT_V(n) asm volatile("s_waitcnt vmcnt(" #n ")" ::: "memory")
; #define PG8_WAIT_L(n) asm volatile("s_waitcnt lgkmcnt(" #n ")" ::: "memory")
; #define PG8_BAR __builtin_amdgcn_s_barrier()
; #define PG8_SCHED __builtin_amdgcn_sched_barrier(0)
; template <class Epi, class Sched, bool ALIGN_EPI = false, bool SP2 = false>
; __device__ __forceinline__ void gemm_phase(PG8_LAS unsigned char* lds, const Gemm g, const Sched& S, const Epi& E) {
;     ...
;         const bool has_next = S.next(ui + 1, nxt);
;         const char* nA = has_next ? (const char*)g.A + (size_t)nxt.pm * tstep : cA; const char* nB = has_next ? (const char*)g.Bt + (size_t)nxt.pn * tstep : cB;
;         for (int t = 0; t < nt; t += 2) {
;             const bool last = (t == nt - 2);
;             const char* a1 = cA + (size_t)(t + 1) * kstep;
;             const char* a2 = last ? nA : cA + (size_t)(t + 2) * kstep; const char* b2 = last ? nB : cB + (size_t)(t + 2) * kstep;
;             const char* a3 = a2 + kstep; const char* b3 = b2 + kstep;
;             if (last && has_next) S.a_ready(nxt);
;             if constexpr (SP2) {
;             PG8_LDB(B0, 0, 0); PG8_LDB(B1, 0, 1); PG8_SCHED; PG8_LDA(At, 0, 0); PG8_STAGE(PG8_SA(1, 1), a1 + hstep, voffA);
;             PG8_WAIT_V(8); PG8_WAIT_L(0); PG8_BAR; PG8_MMA(0, 0, At, B0); PG8_MMA(0, 1, At, B1); PG8_BAR; PG8_SCHED;
;             PG8_LDA(At, 0, 1); PG8_STAGE(PG8_SB(0, 0), b2, voffB); PG8_STAGE(PG8_SB(0, 1), b2 + hstep, voffB); PG8_STAGE(PG8_SA(0, 0), a2, voffA);
;             PG8_WAIT_V(8); PG8_WAIT_L(0); PG8_BAR; PG8_MMA(1, 0, At, B0); PG8_MMA(1, 1, At, B1); PG8_BAR; PG8_SCHED;
.LBB0_363:
	s_ashr_i32 s77, s76, 31
	s_lshl_b64 s[38:39], s[76:77], 20
	v_cmp_lt_i64_e32 vcc, s[78:79], v[178:179]
	s_add_u32 s78, s73, s38
	s_addc_u32 s79, s96, s39
	s_and_b64 s[38:39], vcc, exec
	s_cselect_b32 s77, s79, s85
	s_cselect_b32 s83, s78, s84
	s_ashr_i32 s75, s74, 31
	s_lshl_b64 s[38:39], s[74:75], 20
	s_add_u32 s80, s97, s38
	s_addc_u32 s81, s90, s39
	s_and_b64 s[38:39], vcc, exec
	s_cselect_b32 s75, s81, s87
	s_cselect_b32 vcc_lo, s80, s86
	s_add_u32 s84, s84, 0x80080
	s_addc_u32 s85, s85, 0
	s_add_u32 vcc_hi, s86, 0x100
	s_addc_u32 s38, s87, 0
	s_mov_b32 s39, -2
	ds_read_b128 v[128:131], v214
	ds_read_b128 v[132:135], v214 offset:1024
	ds_read_b128 v[136:139], v214 offset:2048
	ds_read_b128 v[140:143], v214 offset:3072
	ds_read_b128 v[144:147], v215
	ds_read_b128 v[148:151], v215 offset:1024
	ds_read_b128 v[152:155], v215 offset:2048
	ds_read_b128 v[156:159], v215 offset:3072
	s_add_u32 s58, s84, 0xfff80080
	s_addc_u32 s59, s85, -1
	s_cmp_eq_u32 s39, 28
	s_cselect_b32 s89, s77, s59
	s_cselect_b32 s88, s83, s58
	s_cselect_b32 s87, s75, s38
	s_cselect_b32 s86, vcc_lo, vcc_hi
	s_add_i32 m0, s7, 0xc000
	ds_read_b128 v[160:163], v216
	ds_read_b128 v[182:185], v216 offset:1024
	ds_read_b128 v[186:189], v216 offset:2048
	ds_read_b128 v[190:193], v216 offset:3072
	ds_read_b128 v[222:225], v216 offset:4096
	ds_read_b128 v[232:235], v216 offset:5120
	ds_read_b128 v[236:239], v216 offset:6144
	ds_read_b128 v[240:243], v216 offset:7168
	global_load_lds_dwordx4 v174, s[84:85]
	s_add_i32 m0, s7, 0xe000
	s_nop 0
	global_load_lds_dwordx4 v176, s[84:85]
	s_waitcnt vmcnt(8)
	s_waitcnt lgkmcnt(0)
	s_barrier
	v_mfma_f32_16x16x32_bf16 v[124:127], v[128:131], v[160:163], 0
	v_mfma_f32_16x16x32_bf16 v[120:123], v[136:139], v[160:163], 0
	v_mfma_f32_16x16x32_bf16 v[116:119], v[128:131], v[186:189], 0
	v_mfma_f32_16x16x32_bf16 v[112:115], v[136:139], v[186:189], 0
	v_mfma_f32_16x16x32_bf16 v[100:103], v[128:131], v[222:225], 0
	v_mfma_f32_16x16x32_bf16 v[96:99], v[136:139], v[222:225], 0
	v_mfma_f32_16x16x32_bf16 v[84:87], v[128:131], v[236:239], 0
	v_mfma_f32_16x16x32_bf16 v[80:83], v[136:139], v[236:239], 0
	v_mfma_f32_16x16x32_bf16 v[124:127], v[132:135], v[182:185], v[124:127]
	v_mfma_f32_16x16x32_bf16 v[120:123], v[140:143], v[182:185], v[120:123]
	v_mfma_f32_16x16x32_bf16 v[116:119], v[132:135], v[190:193], v[116:119]
	v_mfma_f32_16x16x32_bf16 v[112:115], v[140:143], v[190:193], v[112:115]
	v_mfma_f32_16x16x32_bf16 v[100:103], v[132:135], v[232:235], v[100:103]
	v_mfma_f32_16x16x32_bf16 v[96:99], v[140:143], v[232:235], v[96:99]
	v_mfma_f32_16x16x32_bf16 v[84:87], v[132:135], v[240:243], v[84:87]
	v_mfma_f32_16x16x32_bf16 v[80:83], v[140:143], v[240:243], v[80:83]
	v_mfma_f32_16x16x32_bf16 v[108:111], v[144:147], v[160:163], 0
	v_mfma_f32_16x16x32_bf16 v[104:107], v[152:155], v[160:163], 0
	v_mfma_f32_16x16x32_bf16 v[92:95], v[144:147], v[186:189], 0
	v_mfma_f32_16x16x32_bf16 v[88:91], v[152:155], v[186:189], 0
	v_mfma_f32_16x16x32_bf16 v[76:79], v[144:147], v[222:225], 0
	v_mfma_f32_16x16x32_bf16 v[72:75], v[152:155], v[222:225], 0
	v_mfma_f32_16x16x32_bf16 v[68:71], v[144:147], v[236:239], 0
	v_mfma_f32_16x16x32_bf16 v[64:67], v[152:155], v[236:239], 0
	v_mfma_f32_16x16x32_bf16 v[108:111], v[148:151], v[182:185], v[108:111]
	v_mfma_f32_16x16x32_bf16 v[104:107], v[156:159], v[182:185], v[104:107]
	v_mfma_f32_16x16x32_bf16 v[92:95], v[148:151], v[190:193], v[92:95]
	v_mfma_f32_16x16x32_bf16 v[88:91], v[156:159], v[190:193], v[88:91]
	v_mfma_f32_16x16x32_bf16 v[76:79], v[148:151], v[232:235], v[76:79]
	v_mfma_f32_16x16x32_bf16 v[72:75], v[156:159], v[232:235], v[72:75]
	v_mfma_f32_16x16x32_bf16 v[68:71], v[148:151], v[240:243], v[68:71]
	v_mfma_f32_16x16x32_bf16 v[64:67], v[156:159], v[240:243], v[64:67]
	s_barrier
	s_add_i32 s58, s34, s24
	v_lshl_add_u64 v[194:195], s[86:87], 0, v[168:169]
	s_mov_b32 m0, s58
	ds_read_b128 v[160:163], v216 offset:16384
	ds_read_b128 v[182:185], v216 offset:17408
	ds_read_b128 v[186:189], v216 offset:18432
	ds_read_b128 v[190:193], v216 offset:19456
	ds_read_b128 v[222:225], v216 offset:20480
	ds_read_b128 v[232:235], v216 offset:21504
	ds_read_b128 v[236:239], v216 offset:22528
	ds_read_b128 v[240:243], v216 offset:23552
	global_load_lds_dwordx4 v168, s[86:87]
	s_add_i32 m0, s58, 0x2000
	s_add_u32 s58, s86, 0x80000
	v_lshl_add_u64 v[230:231], s[86:87], 0, v[164:165]
	s_addc_u32 s59, s87, 0
	s_add_i32 s48, s35, s24
	global_load_lds_dwordx4 v164, s[86:87]
	s_mov_b32 m0, s48
	v_lshl_add_u64 v[246:247], s[88:89], 0, v[166:167]
	global_load_lds_dwordx4 v168, s[58:59]
	s_add_i32 m0, s48, 0x2000
	s_nop 0
	global_load_lds_dwordx4 v164, s[58:59]
	v_lshl_add_u64 v[244:245], s[88:89], 0, v[170:171]
	s_mov_b32 m0, s7
	s_nop 0
	global_load_lds_dwordx4 v170, s[88:89]
	s_mov_b32 m0, s8
	s_nop 0
	global_load_lds_dwordx4 v166, s[88:89]
	s_waitcnt vmcnt(8)
	s_waitcnt lgkmcnt(0)
	s_barrier
; #define PG8_STAGE(bufoff, gbase, voff) do { _Pragma("unroll") for (int _i = 0; _i < 2; ++_i) \
;         __builtin_amdgcn_global_load_lds((const unsigned*)((const char*)(gbase) + (voff)[_i]), (PG8_LAS unsigned*)(lds + (bufoff) + ldsw + _i * 8192), 16, 0, 0); } while (0)
; #define PG8_LDA(dst, b, h) do { _Pragma("unroll") for (int m = 0; m < 4; ++m) _Pragma("unroll") for (int k = 0; k < 2; ++k) dst[m][k] = *(const PG8_LAS bf16x8*)(lds + PG8_SA(b, h) + aoff + m * 2048 + k * 1024); } while (0)
; #define PG8_LDB(dst, b, h) do { _Pragma("unroll") for (int n = 0; n < 2; ++n) _Pragma("unroll") for (int k = 0; k < 2; ++k) dst[n][k] = *(const PG8_LAS bf16x8*)(lds + PG8_SB(b, h) + boff + n * 2048 + k * 1024); } while (0)
; #define PG8_MMA(ai, bj, At, Bt) do { __builtin_amdgcn_s_setprio(1); _Pragma("unroll") for (int m = 0; m < 4; ++m) _Pragma("unroll") for (int n = 0; n < 2; ++n) _Pragma("unroll") for (int k = 0; k < 2; ++k) \
;         acc[ai][bj][m][n] = __builtin_amdgcn_mfma_f32_16x16x32_bf16(Bt[n][k], At[m][k], acc[ai][bj][m][n], 0, 0, 0); __builtin_amdgcn_s_setprio(0); } while (0)
; #define PG8_WAIT_V(n) asm volatile("s_waitcnt vmcnt(" #n ")" ::: "memory")
; #define PG8_WAIT_L(n) asm volatile("s_waitcnt lgkmcnt(" #n ")" ::: "memory")
; #define PG8_BAR __builtin_amdgcn_s_barrier()
; template <class Epi, class Sched, bool ALIGN_EPI = false, bool SP2 = false>
; __device__ __forceinline__ void gemm_phase(PG8_LAS unsigned char* lds, const Gemm g, const Sched& S, const Epi& E) {
;     ...
;             PG8_WAIT_V(8); PG8_WAIT_L(0); PG8_BAR; PG8_MMA(0, 0, At, B0); PG8_MMA(0, 1, At, B1); PG8_BAR; PG8_SCHED;
;             PG8_LDA(At, 0, 1); PG8_STAGE(PG8_SB(0, 0), b2, voffB); PG8_STAGE(PG8_SB(0, 1), b2 + hstep, voffB); PG8_STAGE(PG8_SA(0, 0), a2, voffA);
;             PG8_WAIT_V(8); PG8_WAIT_L(0); PG8_BAR; PG8_MMA(1, 0, At, B0); PG8_MMA(1, 1, At, B1); PG8_BAR; PG8_SCHED;
;             PG8_LDB(B0, 1, 0); PG8_LDB(B1, 1, 1); PG8_SCHED; PG8_LDA(At, 1, 0); PG8_STAGE(PG8_SA(0, 1), a2 + hstep, voffA);
;             PG8_WAIT_V(8); PG8_WAIT_L(0); PG8_BAR; PG8_MMA(0, 0, At, B0); PG8_MMA(0, 1, At, B1); PG8_BAR; PG8_SCHED;
;             PG8_LDA(At, 1, 1); PG8_STAGE(PG8_SB(1, 0), b3, voffB); PG8_STAGE(PG8_SB(1, 1), b3 + hstep, voffB); PG8_STAGE(PG8_SA(1, 0), a3, voffA);
;             PG8_WAIT_V(8); PG8_WAIT_L(0); PG8_BAR; PG8_MMA(1, 0, At, B0); PG8_MMA(1, 1, At, B1); PG8_BAR; PG8_SCHED;
	v_mfma_f32_16x16x32_bf16 v[60:63], v[128:131], v[160:163], 0
	v_mfma_f32_16x16x32_bf16 v[56:59], v[136:139], v[160:163], 0
	v_mfma_f32_16x16x32_bf16 v[52:55], v[128:131], v[186:189], 0
	v_mfma_f32_16x16x32_bf16 v[48:51], v[136:139], v[186:189], 0
	v_mfma_f32_16x16x32_bf16 v[36:39], v[128:131], v[222:225], 0
	v_mfma_f32_16x16x32_bf16 v[32:35], v[136:139], v[222:225], 0
	v_mfma_f32_16x16x32_bf16 v[20:23], v[128:131], v[236:239], 0
	v_mfma_f32_16x16x32_bf16 v[16:19], v[136:139], v[236:239], 0
	v_mfma_f32_16x16x32_bf16 v[60:63], v[132:135], v[182:185], v[60:63]
	v_mfma_f32_16x16x32_bf16 v[56:59], v[140:143], v[182:185], v[56:59]
	v_mfma_f32_16x16x32_bf16 v[52:55], v[132:135], v[190:193], v[52:55]
	v_mfma_f32_16x16x32_bf16 v[48:51], v[140:143], v[190:193], v[48:51]
	v_mfma_f32_16x16x32_bf16 v[36:39], v[132:135], v[232:235], v[36:39]
	v_mfma_f32_16x16x32_bf16 v[32:35], v[140:143], v[232:235], v[32:35]
	v_mfma_f32_16x16x32_bf16 v[20:23], v[132:135], v[240:243], v[20:23]
	v_mfma_f32_16x16x32_bf16 v[16:19], v[140:143], v[240:243], v[16:19]
	v_mfma_f32_16x16x32_bf16 v[44:47], v[144:147], v[160:163], 0
	v_mfma_f32_16x16x32_bf16 v[40:43], v[152:155], v[160:163], 0
	v_mfma_f32_16x16x32_bf16 v[28:31], v[144:147], v[186:189], 0
	v_mfma_f32_16x16x32_bf16 v[24:27], v[152:155], v[186:189], 0
	v_mfma_f32_16x16x32_bf16 v[12:15], v[144:147], v[222:225], 0
	v_mfma_f32_16x16x32_bf16 v[8:11], v[152:155], v[222:225], 0
	v_mfma_f32_16x16x32_bf16 v[4:7], v[144:147], v[236:239], 0
	v_mfma_f32_16x16x32_bf16 v[0:3], v[152:155], v[236:239], 0
	v_mfma_f32_16x16x32_bf16 v[44:47], v[148:151], v[182:185], v[44:47]
	v_mfma_f32_16x16x32_bf16 v[40:43], v[156:159], v[182:185], v[40:43]
	v_mfma_f32_16x16x32_bf16 v[28:31], v[148:151], v[190:193], v[28:31]
	v_mfma_f32_16x16x32_bf16 v[24:27], v[156:159], v[190:193], v[24:27]
	v_mfma_f32_16x16x32_bf16 v[12:15], v[148:151], v[232:235], v[12:15]
	v_mfma_f32_16x16x32_bf16 v[8:11], v[156:159], v[232:235], v[8:11]
	v_mfma_f32_16x16x32_bf16 v[4:7], v[148:151], v[240:243], v[4:7]
	v_mfma_f32_16x16x32_bf16 v[0:3], v[156:159], v[240:243], v[0:3]
	s_barrier
	s_add_i32 s48, 0, 0x18000
	s_add_i32 s60, 0, 0x1c000
	v_add_u32_e32 v140, s48, v197
	v_add_u32_e32 v156, s60, v197
	ds_read_b128 v[128:131], v140
	ds_read_b128 v[132:135], v140 offset:1024
	ds_read_b128 v[136:139], v140 offset:2048
	ds_read_b128 v[140:143], v140 offset:3072
	ds_read_b128 v[144:147], v156
	ds_read_b128 v[148:151], v156 offset:1024
	ds_read_b128 v[152:155], v156 offset:2048
	ds_read_b128 v[156:159], v156 offset:3072
	s_add_u32 s58, s88, 0x80000
	s_addc_u32 s59, s89, 0
	s_mov_b32 m0, s9
	ds_read_b128 v[160:163], v216 offset:32768
	ds_read_b128 v[182:185], v216 offset:33792
	ds_read_b128 v[186:189], v216 offset:34816
	ds_read_b128 v[190:193], v216 offset:35840
	ds_read_b128 v[222:225], v216 offset:36864
	ds_read_b128 v[232:235], v216 offset:37888
	ds_read_b128 v[236:239], v216 offset:38912
	ds_read_b128 v[240:243], v216 offset:39936
	global_load_lds_dwordx4 v170, s[58:59]
	s_mov_b32 m0, s26
	s_nop 0
	global_load_lds_dwordx4 v166, s[58:59]
	s_waitcnt vmcnt(8)
	s_waitcnt lgkmcnt(0)
	s_barrier
	v_mfma_f32_16x16x32_bf16 v[124:127], v[128:131], v[160:163], v[124:127]
	v_mfma_f32_16x16x32_bf16 v[120:123], v[136:139], v[160:163], v[120:123]
	v_mfma_f32_16x16x32_bf16 v[116:119], v[128:131], v[186:189], v[116:119]
	v_mfma_f32_16x16x32_bf16 v[112:115], v[136:139], v[186:189], v[112:115]
	v_mfma_f32_16x16x32_bf16 v[100:103], v[128:131], v[222:225], v[100:103]
	v_mfma_f32_16x16x32_bf16 v[96:99], v[136:139], v[222:225], v[96:99]
	v_mfma_f32_16x16x32_bf16 v[84:87], v[128:131], v[236:239], v[84:87]
	v_mfma_f32_16x16x32_bf16 v[80:83], v[136:139], v[236:239], v[80:83]
	v_mfma_f32_16x16x32_bf16 v[124:127], v[132:135], v[182:185], v[124:127]
	v_mfma_f32_16x16x32_bf16 v[120:123], v[140:143], v[182:185], v[120:123]
	v_mfma_f32_16x16x32_bf16 v[116:119], v[132:135], v[190:193], v[116:119]
	v_mfma_f32_16x16x32_bf16 v[112:115], v[140:143], v[190:193], v[112:115]
	v_mfma_f32_16x16x32_bf16 v[100:103], v[132:135], v[232:235], v[100:103]
	v_mfma_f32_16x16x32_bf16 v[96:99], v[140:143], v[232:235], v[96:99]
	v_mfma_f32_16x16x32_bf16 v[84:87], v[132:135], v[240:243], v[84:87]
	v_mfma_f32_16x16x32_bf16 v[80:83], v[140:143], v[240:243], v[80:83]
	v_mfma_f32_16x16x32_bf16 v[108:111], v[144:147], v[160:163], v[108:111]
	v_mfma_f32_16x16x32_bf16 v[104:107], v[152:155], v[160:163], v[104:107]
	v_mfma_f32_16x16x32_bf16 v[92:95], v[144:147], v[186:189], v[92:95]
	v_mfma_f32_16x16x32_bf16 v[88:91], v[152:155], v[186:189], v[88:91]
	v_mfma_f32_16x16x32_bf16 v[76:79], v[144:147], v[222:225], v[76:79]
	v_mfma_f32_16x16x32_bf16 v[72:75], v[152:155], v[222:225], v[72:75]
	v_mfma_f32_16x16x32_bf16 v[68:71], v[144:147], v[236:239], v[68:71]
	v_mfma_f32_16x16x32_bf16 v[64:67], v[152:155], v[236:239], v[64:67]
	v_mfma_f32_16x16x32_bf16 v[108:111], v[148:151], v[182:185], v[108:111]
	v_mfma_f32_16x16x32_bf16 v[104:107], v[156:159], v[182:185], v[104:107]
	v_mfma_f32_16x16x32_bf16 v[92:95], v[148:151], v[190:193], v[92:95]
	v_mfma_f32_16x16x32_bf16 v[88:91], v[156:159], v[190:193], v[88:91]
	v_mfma_f32_16x16x32_bf16 v[76:79], v[148:151], v[232:235], v[76:79]
	v_mfma_f32_16x16x32_bf16 v[72:75], v[156:159], v[232:235], v[72:75]
	v_mfma_f32_16x16x32_bf16 v[68:71], v[148:151], v[240:243], v[68:71]
	v_mfma_f32_16x16x32_bf16 v[64:67], v[156:159], v[240:243], v[64:67]
	s_barrier
; #define PG8_STAGE(bufoff, gbase, voff) do { _Pragma("unroll") for (int _i = 0; _i < 2; ++_i) \
;         __builtin_amdgcn_global_load_lds((const unsigned*)((const char*)(gbase) + (voff)[_i]), (PG8_LAS unsigned*)(lds + (bufoff) + ldsw + _i * 8192), 16, 0, 0); } while (0)
; #define PG8_LDA(dst, b, h) do { _Pragma("unroll") for (int m = 0; m < 4; ++m) _Pragma("unroll") for (int k = 0; k < 2; ++k) dst[m][k] = *(const PG8_LAS bf16x8*)(lds + PG8_SA(b, h) + aoff + m * 2048 + k * 1024); } while (0)
; #define PG8_LDB(dst, b, h) do { _Pragma("unroll") for (int n = 0; n < 2; ++n) _Pragma("unroll") for (int k = 0; k < 2; ++k) dst[n][k] = *(const PG8_LAS bf16x8*)(lds + PG8_SB(b, h) + boff + n * 2048 + k * 1024); } while (0)
; #define PG8_MMA(ai, bj, At, Bt) do { __builtin_amdgcn_s_setprio(1); _Pragma("unroll") for (int m = 0; m < 4; ++m) _Pragma("unroll") for (int n = 0; n < 2; ++n) _Pragma("unroll") for (int k = 0; k < 2; ++k) \
;         acc[ai][bj][m][n] = __builtin_amdgcn_mfma_f32_16x16x32_bf16(Bt[n][k], At[m][k], acc[ai][bj][m][n], 0, 0, 0); __builtin_amdgcn_s_setprio(0); } while (0)
; #define PG8_WAIT_V(n) asm volatile("s_waitcnt vmcnt(" #n ")" ::: "memory")
; #define PG8_WAIT_L(n) asm volatile("s_waitcnt lgkmcnt(" #n ")" ::: "memory")
; #define PG8_BAR __builtin_amdgcn_s_barrier()
; #define PG8_SCHED __builtin_amdgcn_sched_barrier(0)
; template <class Epi, class Sched, bool ALIGN_EPI = false, bool SP2 = false>
; __device__ __forceinline__ void gemm_phase(PG8_LAS unsigned char* lds, const Gemm g, const Sched& S, const Epi& E) {
;     ...
;             PG8_LDB(B0, 0, 0); PG8_LDB(B1, 0, 1); PG8_SCHED; PG8_LDA(At, 0, 0); PG8_STAGE(PG8_SA(1, 1), a1 + hstep, voffA);
;             PG8_WAIT_V(8); PG8_WAIT_L(0); PG8_BAR; PG8_MMA(0, 0, At, B0); PG8_MMA(0, 1, At, B1); PG8_BAR; PG8_SCHED;
;     ...
;             PG8_LDA(At, 1, 1); PG8_STAGE(PG8_SB(1, 0), b3, voffB); PG8_STAGE(PG8_SB(1, 1), b3 + hstep, voffB); PG8_STAGE(PG8_SA(1, 0), a3, voffA);
;             PG8_WAIT_V(8); PG8_WAIT_L(0); PG8_BAR; PG8_MMA(1, 0, At, B0); PG8_MMA(1, 1, At, B1); PG8_BAR; PG8_SCHED;
	s_add_i32 s48, s48, s24
	v_lshl_add_u64 v[194:195], v[194:195], 0, s[54:55]
	s_mov_b32 m0, s48
	ds_read_b128 v[160:163], v216 offset:49152
	ds_read_b128 v[182:185], v216 offset:50176
	ds_read_b128 v[186:189], v216 offset:51200
	ds_read_b128 v[190:193], v216 offset:52224
	ds_read_b128 v[222:225], v216 offset:53248
	ds_read_b128 v[232:235], v216 offset:54272
	ds_read_b128 v[236:239], v216 offset:55296
	ds_read_b128 v[240:243], v216 offset:56320
	global_load_lds_dwordx4 v[194:195], off
	s_add_i32 m0, s48, 0x2000
	s_add_u32 s58, s86, 0x80080
	v_lshl_add_u64 v[194:195], v[230:231], 0, s[54:55]
	s_addc_u32 s59, s87, 0
	s_add_i32 s48, s60, s24
	global_load_lds_dwordx4 v[194:195], off
	s_mov_b32 m0, s48
	s_nop 0
	global_load_lds_dwordx4 v168, s[58:59]
	s_add_i32 m0, s48, 0x2000
	s_nop 0
	global_load_lds_dwordx4 v164, s[58:59]
	v_lshl_add_u64 v[194:195], v[244:245], 0, s[54:55]
	s_mov_b32 m0, s36
	s_nop 0
	global_load_lds_dwordx4 v[194:195], off
	v_lshl_add_u64 v[194:195], v[246:247], 0, s[54:55]
	s_mov_b32 m0, s37
	s_nop 0
	global_load_lds_dwordx4 v[194:195], off
	s_waitcnt vmcnt(8)
	s_waitcnt lgkmcnt(0)
	s_barrier
	v_mfma_f32_16x16x32_bf16 v[60:63], v[128:131], v[160:163], v[60:63]
	v_mfma_f32_16x16x32_bf16 v[56:59], v[136:139], v[160:163], v[56:59]
	v_mfma_f32_16x16x32_bf16 v[52:55], v[128:131], v[186:189], v[52:55]
	v_mfma_f32_16x16x32_bf16 v[48:51], v[136:139], v[186:189], v[48:51]
	v_mfma_f32_16x16x32_bf16 v[36:39], v[128:131], v[222:225], v[36:39]
	v_mfma_f32_16x16x32_bf16 v[32:35], v[136:139], v[222:225], v[32:35]
	v_mfma_f32_16x16x32_bf16 v[20:23], v[128:131], v[236:239], v[20:23]
	v_mfma_f32_16x16x32_bf16 v[16:19], v[136:139], v[236:239], v[16:19]
	v_mfma_f32_16x16x32_bf16 v[60:63], v[132:135], v[182:185], v[60:63]
	v_mfma_f32_16x16x32_bf16 v[56:59], v[140:143], v[182:185], v[56:59]
	v_mfma_f32_16x16x32_bf16 v[52:55], v[132:135], v[190:193], v[52:55]
	v_mfma_f32_16x16x32_bf16 v[48:51], v[140:143], v[190:193], v[48:51]
	v_mfma_f32_16x16x32_bf16 v[36:39], v[132:135], v[232:235], v[36:39]
	v_mfma_f32_16x16x32_bf16 v[32:35], v[140:143], v[232:235], v[32:35]
	v_mfma_f32_16x16x32_bf16 v[20:23], v[132:135], v[240:243], v[20:23]
	v_mfma_f32_16x16x32_bf16 v[16:19], v[140:143], v[240:243], v[16:19]
	v_mfma_f32_16x16x32_bf16 v[44:47], v[144:147], v[160:163], v[44:47]
	v_mfma_f32_16x16x32_bf16 v[40:43], v[152:155], v[160:163], v[40:43]
	v_mfma_f32_16x16x32_bf16 v[28:31], v[144:147], v[186:189], v[28:31]
	v_mfma_f32_16x16x32_bf16 v[24:27], v[152:155], v[186:189], v[24:27]
	v_mfma_f32_16x16x32_bf16 v[12:15], v[144:147], v[222:225], v[12:15]
	v_mfma_f32_16x16x32_bf16 v[8:11], v[152:155], v[222:225], v[8:11]
	v_mfma_f32_16x16x32_bf16 v[4:7], v[144:147], v[236:239], v[4:7]
	v_mfma_f32_16x16x32_bf16 v[0:3], v[152:155], v[236:239], v[0:3]
	v_mfma_f32_16x16x32_bf16 v[44:47], v[148:151], v[182:185], v[44:47]
	v_mfma_f32_16x16x32_bf16 v[40:43], v[156:159], v[182:185], v[40:43]
	v_mfma_f32_16x16x32_bf16 v[28:31], v[148:151], v[190:193], v[28:31]
	v_mfma_f32_16x16x32_bf16 v[24:27], v[156:159], v[190:193], v[24:27]
	v_mfma_f32_16x16x32_bf16 v[12:15], v[148:151], v[232:235], v[12:15]
	v_mfma_f32_16x16x32_bf16 v[8:11], v[156:159], v[232:235], v[8:11]
	v_mfma_f32_16x16x32_bf16 v[4:7], v[148:151], v[240:243], v[4:7]
	v_mfma_f32_16x16x32_bf16 v[0:3], v[156:159], v[240:243], v[0:3]
	s_barrier
	s_add_i32 s39, s39, 2
	s_add_u32 s84, s84, 0x100
	s_addc_u32 s85, s85, 0
	s_add_u32 vcc_hi, vcc_hi, 0x100
	s_addc_u32 s38, s38, 0
	s_cmp_gt_u32 s39, 29
.LBB0_364:
	ds_read_b128 v[128:131], v214
	ds_read_b128 v[132:135], v214 offset:1024
	ds_read_b128 v[136:139], v214 offset:2048
	ds_read_b128 v[140:143], v214 offset:3072
	ds_read_b128 v[144:147], v215
	ds_read_b128 v[148:151], v215 offset:1024
	ds_read_b128 v[152:155], v215 offset:2048
	ds_read_b128 v[156:159], v215 offset:3072
	s_add_u32 s58, s84, 0xfff80080
	s_addc_u32 s59, s85, -1
	s_cmp_eq_u32 s39, 28
	s_cselect_b32 s89, s77, s59
	s_cselect_b32 s88, s83, s58
	s_cselect_b32 s87, s75, s38
	s_cselect_b32 s86, vcc_lo, vcc_hi
	s_add_i32 m0, s7, 0xc000
	ds_read_b128 v[160:163], v216
	ds_read_b128 v[182:185], v216 offset:1024
	ds_read_b128 v[186:189], v216 offset:2048
	ds_read_b128 v[190:193], v216 offset:3072
	ds_read_b128 v[222:225], v216 offset:4096
	ds_read_b128 v[232:235], v216 offset:5120
	ds_read_b128 v[236:239], v216 offset:6144
	ds_read_b128 v[240:243], v216 offset:7168
	global_load_lds_dwordx4 v174, s[84:85]
	s_add_i32 m0, s7, 0xe000
	s_nop 0
	global_load_lds_dwordx4 v176, s[84:85]
	s_waitcnt vmcnt(8)
	s_waitcnt lgkmcnt(0)
	s_barrier
; #define PG8_STAGE(bufoff, gbase, voff) do { _Pragma("unroll") for (int _i = 0; _i < 2; ++_i) \
;         __builtin_amdgcn_global_load_lds((const unsigned*)((const char*)(gbase) + (voff)[_i]), (PG8_LAS unsigned*)(lds + (bufoff) + ldsw + _i * 8192), 16, 0, 0); } while (0)
; #define PG8_LDA(dst, b, h) do { _Pragma("unroll") for (int m = 0; m < 4; ++m) _Pragma("unroll") for (int k = 0; k < 2; ++k) dst[m][k] = *(const PG8_LAS bf16x8*)(lds + PG8_SA(b, h) + aoff + m * 2048 + k * 1024); } while (0)
; #define PG8_MMA(ai, bj, At, Bt) do { __builtin_amdgcn_s_setprio(1); _Pragma("unroll") for (int m = 0; m < 4; ++m) _Pragma("unroll") for (int n = 0; n < 2; ++n) _Pragma("unroll") for (int k = 0; k < 2; ++k) \
;         acc[ai][bj][m][n] = __builtin_amdgcn_mfma_f32_16x16x32_bf16(Bt[n][k], At[m][k], acc[ai][bj][m][n], 0, 0, 0); __builtin_amdgcn_s_setprio(0); } while (0)
; #define PG8_WAIT_V(n) asm volatile("s_waitcnt vmcnt(" #n ")" ::: "memory")
; #define PG8_WAIT_L(n) asm volatile("s_waitcnt lgkmcnt(" #n ")" ::: "memory")
; #define PG8_BAR __builtin_amdgcn_s_barrier()
; #define PG8_SCHED __builtin_amdgcn_sched_barrier(0)
; template <class Epi, class Sched, bool ALIGN_EPI = false, bool SP2 = false>
; __device__ __forceinline__ void gemm_phase(PG8_LAS unsigned char* lds, const Gemm g, const Sched& S, const Epi& E) {
;     ...
;             PG8_WAIT_V(8); PG8_WAIT_L(0); PG8_BAR; PG8_MMA(0, 0, At, B0); PG8_MMA(0, 1, At, B1); PG8_BAR; PG8_SCHED;
;             PG8_LDA(At, 0, 1); PG8_STAGE(PG8_SB(0, 0), b2, voffB); PG8_STAGE(PG8_SB(0, 1), b2 + hstep, voffB); PG8_STAGE(PG8_SA(0, 0), a2, voffA);
;             PG8_WAIT_V(8); PG8_WAIT_L(0); PG8_BAR; PG8_MMA(1, 0, At, B0); PG8_MMA(1, 1, At, B1); PG8_BAR; PG8_SCHED;
	v_mfma_f32_16x16x32_bf16 v[124:127], v[128:131], v[160:163], v[124:127]
	v_mfma_f32_16x16x32_bf16 v[120:123], v[136:139], v[160:163], v[120:123]
	v_mfma_f32_16x16x32_bf16 v[116:119], v[128:131], v[186:189], v[116:119]
	v_mfma_f32_16x16x32_bf16 v[112:115], v[136:139], v[186:189], v[112:115]
	v_mfma_f32_16x16x32_bf16 v[100:103], v[128:131], v[222:225], v[100:103]
	v_mfma_f32_16x16x32_bf16 v[96:99], v[136:139], v[222:225], v[96:99]
	v_mfma_f32_16x16x32_bf16 v[84:87], v[128:131], v[236:239], v[84:87]
	v_mfma_f32_16x16x32_bf16 v[80:83], v[136:139], v[236:239], v[80:83]
	v_mfma_f32_16x16x32_bf16 v[124:127], v[132:135], v[182:185], v[124:127]
	v_mfma_f32_16x16x32_bf16 v[120:123], v[140:143], v[182:185], v[120:123]
	v_mfma_f32_16x16x32_bf16 v[116:119], v[132:135], v[190:193], v[116:119]
	v_mfma_f32_16x16x32_bf16 v[112:115], v[140:143], v[190:193], v[112:115]
	v_mfma_f32_16x16x32_bf16 v[100:103], v[132:135], v[232:235], v[100:103]
	v_mfma_f32_16x16x32_bf16 v[96:99], v[140:143], v[232:235], v[96:99]
	v_mfma_f32_16x16x32_bf16 v[84:87], v[132:135], v[240:243], v[84:87]
	v_mfma_f32_16x16x32_bf16 v[80:83], v[140:143], v[240:243], v[80:83]
	v_mfma_f32_16x16x32_bf16 v[108:111], v[144:147], v[160:163], v[108:111]
	v_mfma_f32_16x16x32_bf16 v[104:107], v[152:155], v[160:163], v[104:107]
	v_mfma_f32_16x16x32_bf16 v[92:95], v[144:147], v[186:189], v[92:95]
	v_mfma_f32_16x16x32_bf16 v[88:91], v[152:155], v[186:189], v[88:91]
	v_mfma_f32_16x16x32_bf16 v[76:79], v[144:147], v[222:225], v[76:79]
	v_mfma_f32_16x16x32_bf16 v[72:75], v[152:155], v[222:225], v[72:75]
	v_mfma_f32_16x16x32_bf16 v[68:71], v[144:147], v[236:239], v[68:71]
	v_mfma_f32_16x16x32_bf16 v[64:67], v[152:155], v[236:239], v[64:67]
	v_mfma_f32_16x16x32_bf16 v[108:111], v[148:151], v[182:185], v[108:111]
	v_mfma_f32_16x16x32_bf16 v[104:107], v[156:159], v[182:185], v[104:107]
	v_mfma_f32_16x16x32_bf16 v[92:95], v[148:151], v[190:193], v[92:95]
	v_mfma_f32_16x16x32_bf16 v[88:91], v[156:159], v[190:193], v[88:91]
	v_mfma_f32_16x16x32_bf16 v[76:79], v[148:151], v[232:235], v[76:79]
	v_mfma_f32_16x16x32_bf16 v[72:75], v[156:159], v[232:235], v[72:75]
	v_mfma_f32_16x16x32_bf16 v[68:71], v[148:151], v[240:243], v[68:71]
	v_mfma_f32_16x16x32_bf16 v[64:67], v[156:159], v[240:243], v[64:67]
	s_barrier
	s_add_i32 s58, s34, s24
	v_lshl_add_u64 v[194:195], s[86:87], 0, v[168:169]
	s_mov_b32 m0, s58
	ds_read_b128 v[160:163], v216 offset:16384
	ds_read_b128 v[182:185], v216 offset:17408
	ds_read_b128 v[186:189], v216 offset:18432
	ds_read_b128 v[190:193], v216 offset:19456
	ds_read_b128 v[222:225], v216 offset:20480
	ds_read_b128 v[232:235], v216 offset:21504
	ds_read_b128 v[236:239], v216 offset:22528
	ds_read_b128 v[240:243], v216 offset:23552
	global_load_lds_dwordx4 v168, s[86:87]
	s_add_i32 m0, s58, 0x2000
	s_add_u32 s58, s86, 0x80000
	v_lshl_add_u64 v[230:231], s[86:87], 0, v[164:165]
	s_addc_u32 s59, s87, 0
	s_add_i32 s48, s35, s24
	global_load_lds_dwordx4 v164, s[86:87]
	s_mov_b32 m0, s48
	v_lshl_add_u64 v[246:247], s[88:89], 0, v[166:167]
	global_load_lds_dwordx4 v168, s[58:59]
	s_add_i32 m0, s48, 0x2000
	s_nop 0
	global_load_lds_dwordx4 v164, s[58:59]
	v_lshl_add_u64 v[244:245], s[88:89], 0, v[170:171]
	s_mov_b32 m0, s7
	s_nop 0
	global_load_lds_dwordx4 v170, s[88:89]
	s_mov_b32 m0, s8
	s_nop 0
	global_load_lds_dwordx4 v166, s[88:89]
	s_waitcnt vmcnt(8)
	s_waitcnt lgkmcnt(0)
	s_barrier
	v_mfma_f32_16x16x32_bf16 v[60:63], v[128:131], v[160:163], v[60:63]
	v_mfma_f32_16x16x32_bf16 v[56:59], v[136:139], v[160:163], v[56:59]
	v_mfma_f32_16x16x32_bf16 v[52:55], v[128:131], v[186:189], v[52:55]
	v_mfma_f32_16x16x32_bf16 v[48:51], v[136:139], v[186:189], v[48:51]
	v_mfma_f32_16x16x32_bf16 v[36:39], v[128:131], v[222:225], v[36:39]
	v_mfma_f32_16x16x32_bf16 v[32:35], v[136:139], v[222:225], v[32:35]
	v_mfma_f32_16x16x32_bf16 v[20:23], v[128:131], v[236:239], v[20:23]
	v_mfma_f32_16x16x32_bf16 v[16:19], v[136:139], v[236:239], v[16:19]
	v_mfma_f32_16x16x32_bf16 v[60:63], v[132:135], v[182:185], v[60:63]
	v_mfma_f32_16x16x32_bf16 v[56:59], v[140:143], v[182:185], v[56:59]
	v_mfma_f32_16x16x32_bf16 v[52:55], v[132:135], v[190:193], v[52:55]
	v_mfma_f32_16x16x32_bf16 v[48:51], v[140:143], v[190:193], v[48:51]
	v_mfma_f32_16x16x32_bf16 v[36:39], v[132:135], v[232:235], v[36:39]
	v_mfma_f32_16x16x32_bf16 v[32:35], v[140:143], v[232:235], v[32:35]
	v_mfma_f32_16x16x32_bf16 v[20:23], v[132:135], v[240:243], v[20:23]
	v_mfma_f32_16x16x32_bf16 v[16:19], v[140:143], v[240:243], v[16:19]
	v_mfma_f32_16x16x32_bf16 v[44:47], v[144:147], v[160:163], v[44:47]
	v_mfma_f32_16x16x32_bf16 v[40:43], v[152:155], v[160:163], v[40:43]
	v_mfma_f32_16x16x32_bf16 v[28:31], v[144:147], v[186:189], v[28:31]
	v_mfma_f32_16x16x32_bf16 v[24:27], v[152:155], v[186:189], v[24:27]
	v_mfma_f32_16x16x32_bf16 v[12:15], v[144:147], v[222:225], v[12:15]
	v_mfma_f32_16x16x32_bf16 v[8:11], v[152:155], v[222:225], v[8:11]
	v_mfma_f32_16x16x32_bf16 v[4:7], v[144:147], v[236:239], v[4:7]
	v_mfma_f32_16x16x32_bf16 v[0:3], v[152:155], v[236:239], v[0:3]
	v_mfma_f32_16x16x32_bf16 v[44:47], v[148:151], v[182:185], v[44:47]
	v_mfma_f32_16x16x32_bf16 v[40:43], v[156:159], v[182:185], v[40:43]
	v_mfma_f32_16x16x32_bf16 v[28:31], v[148:151], v[190:193], v[28:31]
	v_mfma_f32_16x16x32_bf16 v[24:27], v[156:159], v[190:193], v[24:27]
	v_mfma_f32_16x16x32_bf16 v[12:15], v[148:151], v[232:235], v[12:15]
	v_mfma_f32_16x16x32_bf16 v[8:11], v[156:159], v[232:235], v[8:11]
	v_mfma_f32_16x16x32_bf16 v[4:7], v[148:151], v[240:243], v[4:7]
	v_mfma_f32_16x16x32_bf16 v[0:3], v[156:159], v[240:243], v[0:3]
	s_barrier
; #define PG8_STAGE(bufoff, gbase, voff) do { _Pragma("unroll") for (int _i = 0; _i < 2; ++_i) \
;         __builtin_amdgcn_global_load_lds((const unsigned*)((const char*)(gbase) + (voff)[_i]), (PG8_LAS unsigned*)(lds + (bufoff) + ldsw + _i * 8192), 16, 0, 0); } while (0)
; #define PG8_LDA(dst, b, h) do { _Pragma("unroll") for (int m = 0; m < 4; ++m) _Pragma("unroll") for (int k = 0; k < 2; ++k) dst[m][k] = *(const PG8_LAS bf16x8*)(lds + PG8_SA(b, h) + aoff + m * 2048 + k * 1024); } while (0)
; #define PG8_LDB(dst, b, h) do { _Pragma("unroll") for (int n = 0; n < 2; ++n) _Pragma("unroll") for (int k = 0; k < 2; ++k) dst[n][k] = *(const PG8_LAS bf16x8*)(lds + PG8_SB(b, h) + boff + n * 2048 + k * 1024); } while (0)
; #define PG8_MMA(ai, bj, At, Bt) do { __builtin_amdgcn_s_setprio(1); _Pragma("unroll") for (int m = 0; m < 4; ++m) _Pragma("unroll") for (int n = 0; n < 2; ++n) _Pragma("unroll") for (int k = 0; k < 2; ++k) \
;         acc[ai][bj][m][n] = __builtin_amdgcn_mfma_f32_16x16x32_bf16(Bt[n][k], At[m][k], acc[ai][bj][m][n], 0, 0, 0); __builtin_amdgcn_s_setprio(0); } while (0)
; #define PG8_WAIT_V(n) asm volatile("s_waitcnt vmcnt(" #n ")" ::: "memory")
; #define PG8_WAIT_L(n) asm volatile("s_waitcnt lgkmcnt(" #n ")" ::: "memory")
; #define PG8_BAR __builtin_amdgcn_s_barrier()
; #define PG8_SCHED __builtin_amdgcn_sched_barrier(0)
; template <class Epi, class Sched, bool ALIGN_EPI = false, bool SP2 = false>
; __device__ __forceinline__ void gemm_phase(PG8_LAS unsigned char* lds, const Gemm g, const Sched& S, const Epi& E) {
;     ...
;             PG8_LDB(B0, 1, 0); PG8_LDB(B1, 1, 1); PG8_SCHED; PG8_LDA(At, 1, 0); PG8_STAGE(PG8_SA(0, 1), a2 + hstep, voffA);
;             PG8_WAIT_V(8); PG8_WAIT_L(0); PG8_BAR; PG8_MMA(0, 0, At, B0); PG8_MMA(0, 1, At, B1); PG8_BAR; PG8_SCHED;
;             PG8_LDA(At, 1, 1); PG8_STAGE(PG8_SB(1, 0), b3, voffB); PG8_STAGE(PG8_SB(1, 1), b3 + hstep, voffB); PG8_STAGE(PG8_SA(1, 0), a3, voffA);
;             PG8_WAIT_V(8); PG8_WAIT_L(0); PG8_BAR; PG8_MMA(1, 0, At, B0); PG8_MMA(1, 1, At, B1); PG8_BAR; PG8_SCHED;
	s_add_i32 s48, 0, 0x18000
	s_add_i32 s60, 0, 0x1c000
	v_add_u32_e32 v140, s48, v197
	v_add_u32_e32 v156, s60, v197
	ds_read_b128 v[128:131], v140
	ds_read_b128 v[132:135], v140 offset:1024
	ds_read_b128 v[136:139], v140 offset:2048
	ds_read_b128 v[140:143], v140 offset:3072
	ds_read_b128 v[144:147], v156
	ds_read_b128 v[148:151], v156 offset:1024
	ds_read_b128 v[152:155], v156 offset:2048
	ds_read_b128 v[156:159], v156 offset:3072
	s_add_u32 s58, s88, 0x80000
	s_addc_u32 s59, s89, 0
	s_mov_b32 m0, s9
	ds_read_b128 v[160:163], v216 offset:32768
	ds_read_b128 v[182:185], v216 offset:33792
	ds_read_b128 v[186:189], v216 offset:34816
	ds_read_b128 v[190:193], v216 offset:35840
	ds_read_b128 v[222:225], v216 offset:36864
	ds_read_b128 v[232:235], v216 offset:37888
	ds_read_b128 v[236:239], v216 offset:38912
	ds_read_b128 v[240:243], v216 offset:39936
	global_load_lds_dwordx4 v170, s[58:59]
	s_mov_b32 m0, s26
	s_nop 0
	global_load_lds_dwordx4 v166, s[58:59]
	s_waitcnt vmcnt(8)
	s_waitcnt lgkmcnt(0)
	s_barrier
	v_mfma_f32_16x16x32_bf16 v[124:127], v[128:131], v[160:163], v[124:127]
	v_mfma_f32_16x16x32_bf16 v[120:123], v[136:139], v[160:163], v[120:123]
	v_mfma_f32_16x16x32_bf16 v[116:119], v[128:131], v[186:189], v[116:119]
	v_mfma_f32_16x16x32_bf16 v[112:115], v[136:139], v[186:189], v[112:115]
	v_mfma_f32_16x16x32_bf16 v[100:103], v[128:131], v[222:225], v[100:103]
	v_mfma_f32_16x16x32_bf16 v[96:99], v[136:139], v[222:225], v[96:99]
	v_mfma_f32_16x16x32_bf16 v[84:87], v[128:131], v[236:239], v[84:87]
	v_mfma_f32_16x16x32_bf16 v[80:83], v[136:139], v[236:239], v[80:83]
	v_mfma_f32_16x16x32_bf16 v[124:127], v[132:135], v[182:185], v[124:127]
	v_mfma_f32_16x16x32_bf16 v[120:123], v[140:143], v[182:185], v[120:123]
	v_mfma_f32_16x16x32_bf16 v[116:119], v[132:135], v[190:193], v[116:119]
	v_mfma_f32_16x16x32_bf16 v[112:115], v[140:143], v[190:193], v[112:115]
	v_mfma_f32_16x16x32_bf16 v[100:103], v[132:135], v[232:235], v[100:103]
	v_mfma_f32_16x16x32_bf16 v[96:99], v[140:143], v[232:235], v[96:99]
	v_mfma_f32_16x16x32_bf16 v[84:87], v[132:135], v[240:243], v[84:87]
	v_mfma_f32_16x16x32_bf16 v[80:83], v[140:143], v[240:243], v[80:83]
	v_mfma_f32_16x16x32_bf16 v[108:111], v[144:147], v[160:163], v[108:111]
	v_mfma_f32_16x16x32_bf16 v[104:107], v[152:155], v[160:163], v[104:107]
	v_mfma_f32_16x16x32_bf16 v[92:95], v[144:147], v[186:189], v[92:95]
	v_mfma_f32_16x16x32_bf16 v[88:91], v[152:155], v[186:189], v[88:91]
	v_mfma_f32_16x16x32_bf16 v[76:79], v[144:147], v[222:225], v[76:79]
	v_mfma_f32_16x16x32_bf16 v[72:75], v[152:155], v[222:225], v[72:75]
	v_mfma_f32_16x16x32_bf16 v[68:71], v[144:147], v[236:239], v[68:71]
	v_mfma_f32_16x16x32_bf16 v[64:67], v[152:155], v[236:239], v[64:67]
	v_mfma_f32_16x16x32_bf16 v[108:111], v[148:151], v[182:185], v[108:111]
	v_mfma_f32_16x16x32_bf16 v[104:107], v[156:159], v[182:185], v[104:107]
	v_mfma_f32_16x16x32_bf16 v[92:95], v[148:151], v[190:193], v[92:95]
	v_mfma_f32_16x16x32_bf16 v[88:91], v[156:159], v[190:193], v[88:91]
	v_mfma_f32_16x16x32_bf16 v[76:79], v[148:151], v[232:235], v[76:79]
	v_mfma_f32_16x16x32_bf16 v[72:75], v[156:159], v[232:235], v[72:75]
	v_mfma_f32_16x16x32_bf16 v[68:71], v[148:151], v[240:243], v[68:71]
	v_mfma_f32_16x16x32_bf16 v[64:67], v[156:159], v[240:243], v[64:67]
	s_barrier
	s_add_i32 s48, s48, s24
	v_lshl_add_u64 v[194:195], v[194:195], 0, s[54:55]
	s_mov_b32 m0, s48
	ds_read_b128 v[160:163], v216 offset:49152
	ds_read_b128 v[182:185], v216 offset:50176
	ds_read_b128 v[186:189], v216 offset:51200
	ds_read_b128 v[190:193], v216 offset:52224
	ds_read_b128 v[222:225], v216 offset:53248
	ds_read_b128 v[232:235], v216 offset:54272
	ds_read_b128 v[236:239], v216 offset:55296
	ds_read_b128 v[240:243], v216 offset:56320
	global_load_lds_dwordx4 v[194:195], off
	s_add_i32 m0, s48, 0x2000
	s_add_u32 s58, s86, 0x80080
	v_lshl_add_u64 v[194:195], v[230:231], 0, s[54:55]
	s_addc_u32 s59, s87, 0
	s_add_i32 s48, s60, s24
	global_load_lds_dwordx4 v[194:195], off
	s_mov_b32 m0, s48
	s_nop 0
	global_load_lds_dwordx4 v168, s[58:59]
	s_add_i32 m0, s48, 0x2000
	s_nop 0
	global_load_lds_dwordx4 v164, s[58:59]
	v_lshl_add_u64 v[194:195], v[244:245], 0, s[54:55]
	s_mov_b32 m0, s36
	s_nop 0
	global_load_lds_dwordx4 v[194:195], off
	v_lshl_add_u64 v[194:195], v[246:247], 0, s[54:55]
	s_mov_b32 m0, s37
	s_nop 0
	global_load_lds_dwordx4 v[194:195], off
	s_waitcnt vmcnt(8)
	s_waitcnt lgkmcnt(0)
	s_barrier
	v_mfma_f32_16x16x32_bf16 v[60:63], v[128:131], v[160:163], v[60:63]
	v_mfma_f32_16x16x32_bf16 v[56:59], v[136:139], v[160:163], v[56:59]
	v_mfma_f32_16x16x32_bf16 v[52:55], v[128:131], v[186:189], v[52:55]
	v_mfma_f32_16x16x32_bf16 v[48:51], v[136:139], v[186:189], v[48:51]
	v_mfma_f32_16x16x32_bf16 v[36:39], v[128:131], v[222:225], v[36:39]
	v_mfma_f32_16x16x32_bf16 v[32:35], v[136:139], v[222:225], v[32:35]
	v_mfma_f32_16x16x32_bf16 v[20:23], v[128:131], v[236:239], v[20:23]
	v_mfma_f32_16x16x32_bf16 v[16:19], v[136:139], v[236:239], v[16:19]
	v_mfma_f32_16x16x32_bf16 v[60:63], v[132:135], v[182:185], v[60:63]
	v_mfma_f32_16x16x32_bf16 v[56:59], v[140:143], v[182:185], v[56:59]
	v_mfma_f32_16x16x32_bf16 v[52:55], v[132:135], v[190:193], v[52:55]
	v_mfma_f32_16x16x32_bf16 v[48:51], v[140:143], v[190:193], v[48:51]
	v_mfma_f32_16x16x32_bf16 v[36:39], v[132:135], v[232:235], v[36:39]
	v_mfma_f32_16x16x32_bf16 v[32:35], v[140:143], v[232:235], v[32:35]
	v_mfma_f32_16x16x32_bf16 v[20:23], v[132:135], v[240:243], v[20:23]
	v_mfma_f32_16x16x32_bf16 v[16:19], v[140:143], v[240:243], v[16:19]
	v_mfma_f32_16x16x32_bf16 v[44:47], v[144:147], v[160:163], v[44:47]
	v_mfma_f32_16x16x32_bf16 v[40:43], v[152:155], v[160:163], v[40:43]
	v_mfma_f32_16x16x32_bf16 v[28:31], v[144:147], v[186:189], v[28:31]
	v_mfma_f32_16x16x32_bf16 v[24:27], v[152:155], v[186:189], v[24:27]
	v_mfma_f32_16x16x32_bf16 v[12:15], v[144:147], v[222:225], v[12:15]
	v_mfma_f32_16x16x32_bf16 v[8:11], v[152:155], v[222:225], v[8:11]
	v_mfma_f32_16x16x32_bf16 v[4:7], v[144:147], v[236:239], v[4:7]
	v_mfma_f32_16x16x32_bf16 v[0:3], v[152:155], v[236:239], v[0:3]
	v_mfma_f32_16x16x32_bf16 v[44:47], v[148:151], v[182:185], v[44:47]
	v_mfma_f32_16x16x32_bf16 v[40:43], v[156:159], v[182:185], v[40:43]
	v_mfma_f32_16x16x32_bf16 v[28:31], v[148:151], v[190:193], v[28:31]
	v_mfma_f32_16x16x32_bf16 v[24:27], v[156:159], v[190:193], v[24:27]
	v_mfma_f32_16x16x32_bf16 v[12:15], v[148:151], v[232:235], v[12:15]
	v_mfma_f32_16x16x32_bf16 v[8:11], v[156:159], v[232:235], v[8:11]
	v_mfma_f32_16x16x32_bf16 v[4:7], v[148:151], v[240:243], v[4:7]
	v_mfma_f32_16x16x32_bf16 v[0:3], v[156:159], v[240:243], v[0:3]
	s_barrier
; __device__ __forceinline__ float fsigmoid(float v) { return __builtin_amdgcn_rcpf(1.0f + __builtin_amdgcn_exp2f(-LOG2E * v)); }
; __device__ __forceinline__ float fsilu(float v) { return v * fsigmoid(v); }
; __device__ __forceinline__ u32x4 pack8(const f32x4 a, const f32x4 b) { u32x4 w; w.x = cvt_pk_bf16(a[0], a[1]); w.y = cvt_pk_bf16(a[2], a[3]); w.z = cvt_pk_bf16(b[0], b[1]); w.w = cvt_pk_bf16(b[2], b[3]); return w; }
;     template <int ACT> __device__ __forceinline__ void ew(const f32x4 (&acc)[2][2][4][2], bf16_t* D, int ld, int row0, int col0) const {
; #pragma unroll
;         for (int ai = 0; ai < 2; ++ai)
; #pragma unroll
;             for (int m = 0; m < 4; ++m) { bf16_t* rowp = D + (size_t)(row0 + ai * HALF + m * 16) * ld + col0;
; #pragma unroll
;                 for (int bj = 0; bj < 2; ++bj) { f32x4 v0 = acc[ai][bj][m][0], v1 = acc[ai][bj][m][1];
;                     if (ACT == 1) {
; #pragma unroll
;                         for (int j = 0; j < 4; ++j) { v0[j] = fsilu(v0[j]); v1[j] = fsilu(v1[j]); } }
;                     if (ACT == 2) {
; #pragma unroll
;                         for (int j = 0; j < 4; ++j) { v0[j] = fsigmoid(v0[j]); v1[j] = fsigmoid(v1[j]); } }
;                     *(u32x4*)(rowp + bj * HALF) = pack8(v0, v1); } }
;     }
;     __device__ __forceinline__ void operator()(const f32x4 (&acc)[2][2][4][2], const Unit& u, int wr, int wc, int fr, int fq) const {
;         const int pn = u.pn, row0 = u.pm * BM + wr * 64 + fr, cl = wc * 32 + 8 * fq;
;         if (pn < 4) ew<0>(acc, HQ, 1024, row0, pn * 256 + cl);
;     ...
;         else if (pn < 36) ew<2>(acc, SGA, 2048, row0, (pn - 28) * 256 + cl);
;         else ew<2>(acc, SGB, 2048, row0, (pn - 36) * 256 + cl);
	s_add_i32 s39, s39, 2
	s_add_u32 s84, s84, 0x100
	s_addc_u32 s85, s85, 0
	s_add_u32 vcc_hi, vcc_hi, 0x100
	s_addc_u32 s38, s38, 0
	s_cmp_gt_u32 s39, 29
	s_cbranch_scc0 .LBB0_364
	v_lshl_add_u32 v182, s82, 8, v196
	s_cmp_gt_i32 s23, 3
	s_mov_b64 s[82:83], -1
	s_cbranch_scc0 .LBB0_391
	s_cmp_gt_u32 s23, 7
	s_cbranch_scc0 .LBB0_388
	s_cmp_gt_u32 s23, 11
	s_cbranch_scc0 .LBB0_385
	s_cmp_gt_u32 s23, 15
	s_cbranch_scc0 .LBB0_382
	s_cmp_gt_u32 s23, 23
	s_cbranch_scc0 .LBB0_379
	s_lshl_b32 s75, s23, 8
	s_cmp_gt_u32 s23, 27
	s_cbranch_scc0 .LBB0_376
	v_mul_f32_e32 v129, 0xbfb8aa3b, v120
	v_exp_f32_e32 v129, v129
	v_mul_f32_e32 v130, 0xbfb8aa3b, v125
	v_mul_f32_e32 v131, 0xbfb8aa3b, v121
	v_exp_f32_e32 v130, v130
	v_exp_f32_e32 v131, v131
	v_add_f32_e32 v129, 1.0, v129
	v_mul_f32_e32 v128, 0xbfb8aa3b, v124
	v_rcp_f32_e32 v132, v129
	v_add_f32_e32 v129, 1.0, v130
	v_add_f32_e32 v130, 1.0, v131
	v_mul_f32_e32 v131, 0xbfb8aa3b, v126
	v_mul_f32_e32 v134, 0xbfb8aa3b, v127
	v_exp_f32_e32 v128, v128
	v_exp_f32_e32 v131, v131
	v_exp_f32_e32 v134, v134
	v_rcp_f32_e32 v129, v129
	v_add_f32_e32 v128, 1.0, v128
	v_add_f32_e32 v131, 1.0, v131
	v_add_f32_e32 v134, 1.0, v134
	v_rcp_f32_e32 v128, v128
	v_mul_f32_e32 v133, 0xbfb8aa3b, v122
	v_rcp_f32_e32 v131, v131
	v_mul_f32_e32 v135, 0xbfb8aa3b, v123
	v_rcp_f32_e32 v134, v134
	v_exp_f32_e32 v133, v133
	v_rcp_f32_e32 v130, v130
	v_exp_f32_e32 v135, v135
	v_cvt_pk_bf16_f32 v128, v128, v129
	v_cvt_pk_bf16_f32 v129, v131, v134
	v_mul_f32_e32 v131, 0xbfb8aa3b, v108
	v_add_f32_e32 v133, 1.0, v133
	v_add_f32_e32 v135, 1.0, v135
	v_cvt_pk_bf16_f32 v130, v132, v130
	v_exp_f32_e32 v132, v131
	v_mul_f32_e32 v131, 0xbfb8aa3b, v104
	v_rcp_f32_e32 v133, v133
	v_rcp_f32_e32 v135, v135
	v_exp_f32_e32 v134, v131
	v_mul_f32_e32 v137, 0xbfb8aa3b, v106
	v_mul_f32_e32 v138, 0xbfb8aa3b, v111
	v_cvt_pk_bf16_f32 v131, v133, v135
	v_add_f32_e32 v133, 1.0, v134
	v_mul_f32_e32 v134, 0xbfb8aa3b, v109
	v_mul_f32_e32 v135, 0xbfb8aa3b, v105
	v_exp_f32_e32 v134, v134
	v_exp_f32_e32 v135, v135
	v_rcp_f32_e32 v136, v133
	v_mul_f32_e32 v139, 0xbfb8aa3b, v107
	v_add_f32_e32 v133, 1.0, v134
	v_add_f32_e32 v134, 1.0, v135
	v_mul_f32_e32 v135, 0xbfb8aa3b, v110
	v_exp_f32_e32 v135, v135
	v_exp_f32_e32 v137, v137
	v_exp_f32_e32 v138, v138
	v_exp_f32_e32 v139, v139
	v_add_f32_e32 v132, 1.0, v132
	v_add_f32_e32 v135, 1.0, v135
	v_add_f32_e32 v137, 1.0, v137
	v_add_f32_e32 v138, 1.0, v138
	v_add_f32_e32 v139, 1.0, v139
	v_rcp_f32_e32 v132, v132
	v_rcp_f32_e32 v133, v133
	v_rcp_f32_e32 v135, v135
	v_rcp_f32_e32 v137, v137
	v_rcp_f32_e32 v138, v138
	v_rcp_f32_e32 v139, v139
	v_rcp_f32_e32 v134, v134
	v_cvt_pk_bf16_f32 v132, v132, v133
	v_cvt_pk_bf16_f32 v133, v135, v138
	v_cvt_pk_bf16_f32 v135, v137, v139
	v_mul_f32_e32 v138, 0xbfb8aa3b, v116
	v_mul_f32_e32 v139, 0xbfb8aa3b, v112
	v_exp_f32_e32 v138, v138
	v_exp_f32_e32 v139, v139
	v_cvt_pk_bf16_f32 v134, v136, v134
	v_or_b32_e32 v136, 16, v182
	v_ashrrev_i32_e32 v137, 31, v136
	v_lshlrev_b64 v[186:187], 12, v[136:137]
	v_add_f32_e32 v136, 1.0, v138
	v_add_f32_e32 v137, 1.0, v139
	v_mul_f32_e32 v138, 0xbfb8aa3b, v117
	v_mul_f32_e32 v139, 0xbfb8aa3b, v113
	v_exp_f32_e32 v138, v138
	v_exp_f32_e32 v139, v139
	v_rcp_f32_e32 v140, v137
	v_mul_f32_e32 v142, 0xbfb8aa3b, v119
	v_add_f32_e32 v137, 1.0, v138
	v_add_f32_e32 v138, 1.0, v139
	v_mul_f32_e32 v139, 0xbfb8aa3b, v118
	v_exp_f32_e32 v139, v139
	v_exp_f32_e32 v142, v142
	v_rcp_f32_e32 v136, v136
	v_rcp_f32_e32 v137, v137
	v_add_f32_e32 v139, 1.0, v139
	v_add_f32_e32 v142, 1.0, v142
	v_mul_f32_e32 v141, 0xbfb8aa3b, v114
	v_rcp_f32_e32 v139, v139
	v_mul_f32_e32 v143, 0xbfb8aa3b, v115
	v_rcp_f32_e32 v142, v142
	v_exp_f32_e32 v141, v141
	v_rcp_f32_e32 v138, v138
	v_exp_f32_e32 v143, v143
	v_cvt_pk_bf16_f32 v136, v136, v137
	v_cvt_pk_bf16_f32 v137, v139, v142
	v_mul_f32_e32 v139, 0xbfb8aa3b, v92
	v_add_f32_e32 v141, 1.0, v141
	v_add_f32_e32 v143, 1.0, v143
	v_cvt_pk_bf16_f32 v138, v140, v138
	v_exp_f32_e32 v140, v139
	v_mul_f32_e32 v139, 0xbfb8aa3b, v88
	v_rcp_f32_e32 v141, v141
	v_rcp_f32_e32 v143, v143
	v_exp_f32_e32 v142, v139
	v_mul_f32_e32 v145, 0xbfb8aa3b, v90
	v_mul_f32_e32 v146, 0xbfb8aa3b, v95
	v_cvt_pk_bf16_f32 v139, v141, v143
	v_add_f32_e32 v141, 1.0, v142
	v_mul_f32_e32 v142, 0xbfb8aa3b, v93
	v_mul_f32_e32 v143, 0xbfb8aa3b, v89
	v_exp_f32_e32 v142, v142
	v_exp_f32_e32 v143, v143
	v_rcp_f32_e32 v144, v141
	v_mul_f32_e32 v147, 0xbfb8aa3b, v91
	v_add_f32_e32 v141, 1.0, v142
	v_add_f32_e32 v142, 1.0, v143
	v_mul_f32_e32 v143, 0xbfb8aa3b, v94
	v_exp_f32_e32 v143, v143
	v_exp_f32_e32 v145, v145
	v_exp_f32_e32 v146, v146
	v_exp_f32_e32 v147, v147
	v_add_f32_e32 v140, 1.0, v140
	v_add_f32_e32 v143, 1.0, v143
	v_add_f32_e32 v145, 1.0, v145
	v_add_f32_e32 v146, 1.0, v146
	v_add_f32_e32 v147, 1.0, v147
	v_rcp_f32_e32 v140, v140
	v_rcp_f32_e32 v141, v141
	v_rcp_f32_e32 v143, v143
	v_rcp_f32_e32 v145, v145
	v_rcp_f32_e32 v146, v146
	v_rcp_f32_e32 v147, v147
	v_rcp_f32_e32 v142, v142
	v_cvt_pk_bf16_f32 v140, v140, v141
	v_cvt_pk_bf16_f32 v141, v143, v146
	v_cvt_pk_bf16_f32 v143, v145, v147
	v_mul_f32_e32 v146, 0xbfb8aa3b, v100
	v_mul_f32_e32 v147, 0xbfb8aa3b, v96
	v_exp_f32_e32 v146, v146
	v_exp_f32_e32 v147, v147
	v_cvt_pk_bf16_f32 v142, v144, v142
	v_or_b32_e32 v144, 32, v182
	v_ashrrev_i32_e32 v145, 31, v144
	v_lshlrev_b64 v[188:189], 12, v[144:145]
	v_add_f32_e32 v144, 1.0, v146
	v_add_f32_e32 v145, 1.0, v147
	v_mul_f32_e32 v146, 0xbfb8aa3b, v101
	v_mul_f32_e32 v147, 0xbfb8aa3b, v97
	v_exp_f32_e32 v146, v146
	v_exp_f32_e32 v147, v147
	v_rcp_f32_e32 v148, v145
	v_mul_f32_e32 v150, 0xbfb8aa3b, v103
	v_add_f32_e32 v145, 1.0, v146
	v_add_f32_e32 v146, 1.0, v147
; __device__ __forceinline__ float fsigmoid(float v) { return __builtin_amdgcn_rcpf(1.0f + __builtin_amdgcn_exp2f(-LOG2E * v)); }
; __device__ __forceinline__ float fsilu(float v) { return v * fsigmoid(v); }
; __device__ __forceinline__ u32x4 pack8(const f32x4 a, const f32x4 b) { u32x4 w; w.x = cvt_pk_bf16(a[0], a[1]); w.y = cvt_pk_bf16(a[2], a[3]); w.z = cvt_pk_bf16(b[0], b[1]); w.w = cvt_pk_bf16(b[2], b[3]); return w; }
;     template <int ACT> __device__ __forceinline__ void ew(const f32x4 (&acc)[2][2][4][2], bf16_t* D, int ld, int row0, int col0) const {
; #pragma unroll
;         for (int ai = 0; ai < 2; ++ai)
; #pragma unroll
;             for (int m = 0; m < 4; ++m) { bf16_t* rowp = D + (size_t)(row0 + ai * HALF + m * 16) * ld + col0;
; #pragma unroll
;                 for (int bj = 0; bj < 2; ++bj) { f32x4 v0 = acc[ai][bj][m][0], v1 = acc[ai][bj][m][1];
;                     if (ACT == 1) {
; #pragma unroll
;                         for (int j = 0; j < 4; ++j) { v0[j] = fsilu(v0[j]); v1[j] = fsilu(v1[j]); } }
;                     if (ACT == 2) {
; #pragma unroll
;                         for (int j = 0; j < 4; ++j) { v0[j] = fsigmoid(v0[j]); v1[j] = fsigmoid(v1[j]); } }
;                     *(u32x4*)(rowp + bj * HALF) = pack8(v0, v1); } }
;     __device__ __forceinline__ void operator()(const f32x4 (&acc)[2][2][4][2], const Unit& u, int wr, int wc, int fr, int fq) const {
;     ...
;         else if (pn < 36) ew<2>(acc, SGA, 2048, row0, (pn - 28) * 256 + cl);
;         else ew<2>(acc, SGB, 2048, row0, (pn - 36) * 256 + cl);
	v_mul_f32_e32 v147, 0xbfb8aa3b, v102
	v_exp_f32_e32 v147, v147
	v_exp_f32_e32 v150, v150
	v_rcp_f32_e32 v144, v144
	v_rcp_f32_e32 v145, v145
	v_add_f32_e32 v147, 1.0, v147
	v_add_f32_e32 v150, 1.0, v150
	v_mul_f32_e32 v149, 0xbfb8aa3b, v98
	v_rcp_f32_e32 v147, v147
	v_mul_f32_e32 v151, 0xbfb8aa3b, v99
	v_rcp_f32_e32 v150, v150
	v_exp_f32_e32 v149, v149
	v_rcp_f32_e32 v146, v146
	v_exp_f32_e32 v151, v151
	v_cvt_pk_bf16_f32 v144, v144, v145
	v_cvt_pk_bf16_f32 v145, v147, v150
	v_mul_f32_e32 v147, 0xbfb8aa3b, v76
	v_add_f32_e32 v149, 1.0, v149
	v_add_f32_e32 v151, 1.0, v151
	v_cvt_pk_bf16_f32 v146, v148, v146
	v_exp_f32_e32 v148, v147
	v_mul_f32_e32 v147, 0xbfb8aa3b, v72
	v_rcp_f32_e32 v149, v149
	v_rcp_f32_e32 v151, v151
	v_exp_f32_e32 v150, v147
	v_mul_f32_e32 v153, 0xbfb8aa3b, v74
	v_mul_f32_e32 v154, 0xbfb8aa3b, v79
	v_cvt_pk_bf16_f32 v147, v149, v151
	v_add_f32_e32 v149, 1.0, v150
	v_mul_f32_e32 v150, 0xbfb8aa3b, v77
	v_mul_f32_e32 v151, 0xbfb8aa3b, v73
	v_exp_f32_e32 v150, v150
	v_exp_f32_e32 v151, v151
	v_rcp_f32_e32 v152, v149
	v_mul_f32_e32 v155, 0xbfb8aa3b, v75
	v_add_f32_e32 v149, 1.0, v150
	v_add_f32_e32 v150, 1.0, v151
	v_mul_f32_e32 v151, 0xbfb8aa3b, v78
	v_exp_f32_e32 v151, v151
	v_exp_f32_e32 v153, v153
	v_exp_f32_e32 v154, v154
	v_exp_f32_e32 v155, v155
	v_add_f32_e32 v148, 1.0, v148
	v_add_f32_e32 v151, 1.0, v151
	v_add_f32_e32 v153, 1.0, v153
	v_add_f32_e32 v154, 1.0, v154
	v_add_f32_e32 v155, 1.0, v155
	v_rcp_f32_e32 v148, v148
	v_rcp_f32_e32 v149, v149
	v_rcp_f32_e32 v151, v151
	v_rcp_f32_e32 v153, v153
	v_rcp_f32_e32 v154, v154
	v_rcp_f32_e32 v155, v155
	v_rcp_f32_e32 v150, v150
	v_cvt_pk_bf16_f32 v148, v148, v149
	v_cvt_pk_bf16_f32 v149, v151, v154
	v_cvt_pk_bf16_f32 v151, v153, v155
	v_mul_f32_e32 v154, 0xbfb8aa3b, v84
	v_mul_f32_e32 v155, 0xbfb8aa3b, v80
	v_exp_f32_e32 v154, v154
	v_exp_f32_e32 v155, v155
	v_cvt_pk_bf16_f32 v150, v152, v150
	v_or_b32_e32 v152, 48, v182
	v_ashrrev_i32_e32 v153, 31, v152
	v_lshlrev_b64 v[190:191], 12, v[152:153]
	v_add_f32_e32 v152, 1.0, v154
	v_add_f32_e32 v153, 1.0, v155
	v_mul_f32_e32 v154, 0xbfb8aa3b, v85
	v_mul_f32_e32 v155, 0xbfb8aa3b, v81
	v_exp_f32_e32 v154, v154
	v_exp_f32_e32 v155, v155
	v_rcp_f32_e32 v156, v153
	v_mul_f32_e32 v158, 0xbfb8aa3b, v87
	v_add_f32_e32 v153, 1.0, v154
	v_add_f32_e32 v154, 1.0, v155
	v_mul_f32_e32 v155, 0xbfb8aa3b, v86
	v_exp_f32_e32 v155, v155
	v_exp_f32_e32 v158, v158
	v_rcp_f32_e32 v152, v152
	v_rcp_f32_e32 v153, v153
	v_add_f32_e32 v155, 1.0, v155
	v_add_f32_e32 v158, 1.0, v158
	v_mul_f32_e32 v157, 0xbfb8aa3b, v82
	v_rcp_f32_e32 v155, v155
	v_mul_f32_e32 v159, 0xbfb8aa3b, v83
	v_rcp_f32_e32 v158, v158
	v_exp_f32_e32 v157, v157
	v_rcp_f32_e32 v154, v154
	v_exp_f32_e32 v159, v159
	v_cvt_pk_bf16_f32 v152, v152, v153
	v_cvt_pk_bf16_f32 v153, v155, v158
	v_mul_f32_e32 v155, 0xbfb8aa3b, v68
	v_add_f32_e32 v157, 1.0, v157
	v_add_f32_e32 v159, 1.0, v159
	v_cvt_pk_bf16_f32 v154, v156, v154
	v_exp_f32_e32 v156, v155
	v_mul_f32_e32 v155, 0xbfb8aa3b, v64
	v_rcp_f32_e32 v157, v157
	v_rcp_f32_e32 v159, v159
	v_exp_f32_e32 v158, v155
	v_mul_f32_e32 v161, 0xbfb8aa3b, v66
	v_mul_f32_e32 v162, 0xbfb8aa3b, v71
	v_cvt_pk_bf16_f32 v155, v157, v159
	v_add_f32_e32 v157, 1.0, v158
	v_mul_f32_e32 v158, 0xbfb8aa3b, v69
	v_mul_f32_e32 v159, 0xbfb8aa3b, v65
	v_exp_f32_e32 v158, v158
	v_exp_f32_e32 v159, v159
	v_rcp_f32_e32 v160, v157
	v_mul_f32_e32 v163, 0xbfb8aa3b, v67
	v_add_f32_e32 v157, 1.0, v158
	v_add_f32_e32 v158, 1.0, v159
	v_mul_f32_e32 v159, 0xbfb8aa3b, v70
	v_exp_f32_e32 v159, v159
	v_exp_f32_e32 v161, v161
	v_exp_f32_e32 v162, v162
	v_exp_f32_e32 v163, v163
	v_add_f32_e32 v156, 1.0, v156
	v_add_f32_e32 v159, 1.0, v159
	v_add_f32_e32 v161, 1.0, v161
	v_add_f32_e32 v162, 1.0, v162
	v_add_f32_e32 v163, 1.0, v163
	v_rcp_f32_e32 v156, v156
	v_rcp_f32_e32 v157, v157
	v_rcp_f32_e32 v159, v159
	v_rcp_f32_e32 v161, v161
	v_rcp_f32_e32 v162, v162
	v_rcp_f32_e32 v163, v163
	v_cvt_pk_bf16_f32 v156, v156, v157
	v_rcp_f32_e32 v158, v158
	v_cvt_pk_bf16_f32 v157, v159, v162
	v_cvt_pk_bf16_f32 v159, v161, v163
	v_mul_f32_e32 v161, 0xbfb8aa3b, v56
	v_exp_f32_e32 v161, v161
	v_mul_f32_e32 v162, 0xbfb8aa3b, v61
	v_mul_f32_e32 v163, 0xbfb8aa3b, v57
	v_exp_f32_e32 v162, v162
	v_exp_f32_e32 v163, v163
	v_add_f32_e32 v161, 1.0, v161
	v_cvt_pk_bf16_f32 v158, v160, v158
	v_mul_f32_e32 v160, 0xbfb8aa3b, v60
	v_rcp_f32_e32 v172, v161
	v_add_f32_e32 v161, 1.0, v162
	v_add_f32_e32 v162, 1.0, v163
	v_mul_f32_e32 v163, 0xbfb8aa3b, v62
	v_mul_f32_e32 v194, 0xbfb8aa3b, v58
	v_mul_f32_e32 v195, 0xbfb8aa3b, v63
	v_mul_f32_e32 v212, 0xbfb8aa3b, v59
	v_exp_f32_e32 v160, v160
	v_exp_f32_e32 v163, v163
	v_exp_f32_e32 v194, v194
	v_exp_f32_e32 v195, v195
	v_exp_f32_e32 v212, v212
	v_add_f32_e32 v160, 1.0, v160
	v_add_f32_e32 v163, 1.0, v163
	v_add_f32_e32 v194, 1.0, v194
	v_add_f32_e32 v195, 1.0, v195
	v_add_f32_e32 v212, 1.0, v212
	v_rcp_f32_e32 v160, v160
	v_rcp_f32_e32 v161, v161
	v_rcp_f32_e32 v162, v162
	v_rcp_f32_e32 v163, v163
	v_rcp_f32_e32 v194, v194
	v_rcp_f32_e32 v195, v195
	v_rcp_f32_e32 v212, v212
	v_ashrrev_i32_e32 v183, 31, v182
	v_lshlrev_b64 v[184:185], 12, v[182:183]
	s_mov_b64 s[38:39], 0x80000
	s_cmp_gt_u32 s23, 35
	v_lshl_add_u64 v[192:193], v[184:185], 0, s[38:39]
	v_cvt_pk_bf16_f32 v160, v160, v161
	v_cvt_pk_bf16_f32 v161, v163, v195
	v_cvt_pk_bf16_f32 v162, v172, v162
	v_cvt_pk_bf16_f32 v163, v194, v212
	s_cbranch_scc0 .LBB0_373
; __device__ __forceinline__ float fsigmoid(float v) { return __builtin_amdgcn_rcpf(1.0f + __builtin_amdgcn_exp2f(-LOG2E * v)); }
; __device__ __forceinline__ float fsilu(float v) { return v * fsigmoid(v); }
; __device__ __forceinline__ u32x4 pack8(const f32x4 a, const f32x4 b) { u32x4 w; w.x = cvt_pk_bf16(a[0], a[1]); w.y = cvt_pk_bf16(a[2], a[3]); w.z = cvt_pk_bf16(b[0], b[1]); w.w = cvt_pk_bf16(b[2], b[3]); return w; }
;     template <int ACT> __device__ __forceinline__ void ew(const f32x4 (&acc)[2][2][4][2], bf16_t* D, int ld, int row0, int col0) const {
; #pragma unroll
;         for (int ai = 0; ai < 2; ++ai)
; #pragma unroll
;             for (int m = 0; m < 4; ++m) { bf16_t* rowp = D + (size_t)(row0 + ai * HALF + m * 16) * ld + col0;
; #pragma unroll
;                 for (int bj = 0; bj < 2; ++bj) { f32x4 v0 = acc[ai][bj][m][0], v1 = acc[ai][bj][m][1];
;                     if (ACT == 1) {
; #pragma unroll
;                         for (int j = 0; j < 4; ++j) { v0[j] = fsilu(v0[j]); v1[j] = fsilu(v1[j]); } }
;                     if (ACT == 2) {
; #pragma unroll
;                         for (int j = 0; j < 4; ++j) { v0[j] = fsigmoid(v0[j]); v1[j] = fsigmoid(v1[j]); } }
;                     *(u32x4*)(rowp + bj * HALF) = pack8(v0, v1); } }
;     __device__ __forceinline__ void operator()(const f32x4 (&acc)[2][2][4][2], const Unit& u, int wr, int wc, int fr, int fq) const {
;     ...
;         else if (pn < 36) ew<2>(acc, SGA, 2048, row0, (pn - 28) * 256 + cl);
;         else ew<2>(acc, SGB, 2048, row0, (pn - 36) * 256 + cl);
	v_readlane_b32 s38, v255, 23
	v_add_u32_e32 v172, s75, v199
	v_readlane_b32 s39, v255, 24
	v_mul_f32_e32 v212, 0xbfb8aa3b, v40
	v_mul_f32_e32 v220, 0xbfb8aa3b, v45
	v_lshl_add_u64 v[222:223], v[172:173], 1, s[38:39]
	v_lshl_add_u64 v[194:195], v[222:223], 0, v[184:185]
	v_lshl_add_u64 v[224:225], v[222:223], 0, v[186:187]
	global_store_dwordx4 v[194:195], v[128:131], off
	global_store_dwordx4 v[194:195], v[132:135], off offset:256
	global_store_dwordx4 v[224:225], v[136:139], off
	global_store_dwordx4 v[224:225], v[140:143], off offset:256
	v_lshl_add_u64 v[224:225], v[222:223], 0, v[188:189]
	global_store_dwordx4 v[224:225], v[144:147], off
	global_store_dwordx4 v[224:225], v[148:151], off offset:256
	v_lshl_add_u64 v[224:225], v[222:223], 0, v[190:191]
	v_lshl_add_u64 v[230:231], v[222:223], 0, v[192:193]
	v_mul_f32_e32 v222, 0xbfb8aa3b, v41
	v_exp_f32_e32 v222, v222
	v_mul_f32_e32 v223, 0xbfb8aa3b, v46
	global_store_dwordx4 v[224:225], v[152:155], off
	global_store_dwordx4 v[224:225], v[156:159], off offset:256
	v_exp_f32_e32 v223, v223
	v_mul_f32_e32 v224, 0xbfb8aa3b, v42
	v_exp_f32_e32 v224, v224
	v_add_f32_e32 v222, 1.0, v222
	v_rcp_f32_e32 v225, v222
	v_add_f32_e32 v222, 1.0, v223
	v_rcp_f32_e32 v223, v222
	v_add_f32_e32 v222, 1.0, v224
	v_mul_f32_e32 v224, 0xbfb8aa3b, v47
	v_mul_f32_e32 v172, 0xbfb8aa3b, v44
	v_exp_f32_e32 v224, v224
	v_mul_f32_e32 v232, 0xbfb8aa3b, v43
	v_exp_f32_e32 v172, v172
	v_exp_f32_e32 v212, v212
	v_exp_f32_e32 v220, v220
	v_exp_f32_e32 v232, v232
	v_rcp_f32_e32 v233, v222
	v_add_f32_e32 v222, 1.0, v224
	v_add_f32_e32 v172, 1.0, v172
	v_add_f32_e32 v212, 1.0, v212
	v_add_f32_e32 v220, 1.0, v220
	v_rcp_f32_e32 v224, v222
	v_add_f32_e32 v222, 1.0, v232
	v_rcp_f32_e32 v172, v172
	v_rcp_f32_e32 v212, v212
	v_rcp_f32_e32 v220, v220
	v_rcp_f32_e32 v232, v222
	v_cvt_pk_bf16_f32 v223, v223, v224
	v_cvt_pk_bf16_f32 v224, v212, v225
	v_cvt_pk_bf16_f32 v222, v172, v220
	v_cvt_pk_bf16_f32 v225, v233, v232
	global_store_dwordx4 v[230:231], v[222:225], off offset:256
	v_mul_f32_e32 v212, 0xbfb8aa3b, v48
	v_mul_f32_e32 v232, 0xbfb8aa3b, v51
	v_mul_f32_e32 v222, 0xbfb8aa3b, v49
	v_exp_f32_e32 v222, v222
	v_mul_f32_e32 v223, 0xbfb8aa3b, v54
	v_exp_f32_e32 v223, v223
	v_mul_f32_e32 v224, 0xbfb8aa3b, v50
	v_exp_f32_e32 v224, v224
	v_add_f32_e32 v222, 1.0, v222
	v_rcp_f32_e32 v225, v222
	v_add_f32_e32 v222, 1.0, v223
	v_rcp_f32_e32 v223, v222
	v_add_f32_e32 v222, 1.0, v224
	v_mul_f32_e32 v224, 0xbfb8aa3b, v55
	v_exp_f32_e32 v224, v224
	v_mul_f32_e32 v172, 0xbfb8aa3b, v52
	v_exp_f32_e32 v212, v212
	v_mul_f32_e32 v220, 0xbfb8aa3b, v53
	v_exp_f32_e32 v232, v232
	v_exp_f32_e32 v172, v172
	v_exp_f32_e32 v220, v220
	v_rcp_f32_e32 v233, v222
	v_add_f32_e32 v222, 1.0, v224
	v_add_f32_e32 v212, 1.0, v212
	v_rcp_f32_e32 v224, v222
	v_add_f32_e32 v222, 1.0, v232
	v_add_f32_e32 v172, 1.0, v172
	v_rcp_f32_e32 v212, v212
	v_add_f32_e32 v220, 1.0, v220
	v_rcp_f32_e32 v232, v222
	v_rcp_f32_e32 v172, v172
	v_rcp_f32_e32 v220, v220
	s_mov_b64 s[38:39], 0x90000
	global_store_dwordx4 v[230:231], v[160:163], off
	v_lshl_add_u64 v[230:231], v[194:195], 0, s[38:39]
	s_mov_b32 s38, 0x90000
	v_cvt_pk_bf16_f32 v223, v223, v224
	v_cvt_pk_bf16_f32 v224, v212, v225
	v_cvt_pk_bf16_f32 v225, v233, v232
	v_add_co_u32_e32 v232, vcc, s38, v194
	v_cvt_pk_bf16_f32 v222, v172, v220
	s_nop 0
	v_addc_co_u32_e32 v233, vcc, 0, v195, vcc
	global_store_dwordx4 v[232:233], v[222:225], off
	v_mul_f32_e32 v172, 0xbfb8aa3b, v28
	v_mul_f32_e32 v212, 0xbfb8aa3b, v24
	v_mul_f32_e32 v222, 0xbfb8aa3b, v25
	v_exp_f32_e32 v222, v222
	v_mul_f32_e32 v223, 0xbfb8aa3b, v30
	v_exp_f32_e32 v223, v223
	v_mul_f32_e32 v224, 0xbfb8aa3b, v26
	v_exp_f32_e32 v224, v224
	v_add_f32_e32 v222, 1.0, v222
	v_rcp_f32_e32 v225, v222
	v_add_f32_e32 v222, 1.0, v223
	v_rcp_f32_e32 v223, v222
	v_add_f32_e32 v222, 1.0, v224
	v_mul_f32_e32 v224, 0xbfb8aa3b, v31
	v_mul_f32_e32 v220, 0xbfb8aa3b, v29
	v_exp_f32_e32 v224, v224
	v_mul_f32_e32 v232, 0xbfb8aa3b, v27
	v_exp_f32_e32 v172, v172
	v_exp_f32_e32 v212, v212
	v_exp_f32_e32 v220, v220
	v_exp_f32_e32 v232, v232
	v_rcp_f32_e32 v233, v222
	v_add_f32_e32 v222, 1.0, v224
	v_add_f32_e32 v172, 1.0, v172
	v_add_f32_e32 v212, 1.0, v212
	v_add_f32_e32 v220, 1.0, v220
	v_rcp_f32_e32 v224, v222
	v_add_f32_e32 v222, 1.0, v232
	v_rcp_f32_e32 v172, v172
	v_rcp_f32_e32 v212, v212
	v_rcp_f32_e32 v220, v220
	v_rcp_f32_e32 v232, v222
	v_cvt_pk_bf16_f32 v223, v223, v224
	v_cvt_pk_bf16_f32 v224, v212, v225
	v_cvt_pk_bf16_f32 v222, v172, v220
	v_cvt_pk_bf16_f32 v225, v233, v232
	global_store_dwordx4 v[230:231], v[222:225], off offset:256
	v_mul_f32_e32 v212, 0xbfb8aa3b, v32
	v_mul_f32_e32 v232, 0xbfb8aa3b, v35
	v_mul_f32_e32 v222, 0xbfb8aa3b, v33
	v_exp_f32_e32 v222, v222
	v_mul_f32_e32 v223, 0xbfb8aa3b, v38
; __device__ __forceinline__ float fsigmoid(float v) { return __builtin_amdgcn_rcpf(1.0f + __builtin_amdgcn_exp2f(-LOG2E * v)); }
; __device__ __forceinline__ float fsilu(float v) { return v * fsigmoid(v); }
; __device__ __forceinline__ u32x4 pack8(const f32x4 a, const f32x4 b) { u32x4 w; w.x = cvt_pk_bf16(a[0], a[1]); w.y = cvt_pk_bf16(a[2], a[3]); w.z = cvt_pk_bf16(b[0], b[1]); w.w = cvt_pk_bf16(b[2], b[3]); return w; }
;     template <int ACT> __device__ __forceinline__ void ew(const f32x4 (&acc)[2][2][4][2], bf16_t* D, int ld, int row0, int col0) const {
; #pragma unroll
;         for (int ai = 0; ai < 2; ++ai)
; #pragma unroll
;             for (int m = 0; m < 4; ++m) { bf16_t* rowp = D + (size_t)(row0 + ai * HALF + m * 16) * ld + col0;
; #pragma unroll
;                 for (int bj = 0; bj < 2; ++bj) { f32x4 v0 = acc[ai][bj][m][0], v1 = acc[ai][bj][m][1];
;                     if (ACT == 1) {
; #pragma unroll
;                         for (int j = 0; j < 4; ++j) { v0[j] = fsilu(v0[j]); v1[j] = fsilu(v1[j]); } }
;                     if (ACT == 2) {
; #pragma unroll
;                         for (int j = 0; j < 4; ++j) { v0[j] = fsigmoid(v0[j]); v1[j] = fsigmoid(v1[j]); } }
;                     *(u32x4*)(rowp + bj * HALF) = pack8(v0, v1); } }
;     __device__ __forceinline__ void operator()(const f32x4 (&acc)[2][2][4][2], const Unit& u, int wr, int wc, int fr, int fq) const {
;     ...
;         else if (pn < 36) ew<2>(acc, SGA, 2048, row0, (pn - 28) * 256 + cl);
;         else ew<2>(acc, SGB, 2048, row0, (pn - 36) * 256 + cl);
	v_exp_f32_e32 v223, v223
	v_mul_f32_e32 v224, 0xbfb8aa3b, v34
	v_exp_f32_e32 v224, v224
	v_add_f32_e32 v222, 1.0, v222
	v_rcp_f32_e32 v225, v222
	v_add_f32_e32 v222, 1.0, v223
	v_rcp_f32_e32 v223, v222
	v_add_f32_e32 v222, 1.0, v224
	v_mul_f32_e32 v224, 0xbfb8aa3b, v39
	v_exp_f32_e32 v224, v224
	v_mul_f32_e32 v172, 0xbfb8aa3b, v36
	v_exp_f32_e32 v212, v212
	v_mul_f32_e32 v220, 0xbfb8aa3b, v37
	v_exp_f32_e32 v232, v232
	v_exp_f32_e32 v172, v172
	v_exp_f32_e32 v220, v220
	v_rcp_f32_e32 v233, v222
	v_add_f32_e32 v222, 1.0, v224
	v_add_f32_e32 v212, 1.0, v212
	v_rcp_f32_e32 v224, v222
	v_add_f32_e32 v222, 1.0, v232
	v_add_f32_e32 v172, 1.0, v172
	v_rcp_f32_e32 v212, v212
	v_add_f32_e32 v220, 1.0, v220
	v_rcp_f32_e32 v232, v222
	v_rcp_f32_e32 v172, v172
	v_rcp_f32_e32 v220, v220
	v_cvt_pk_bf16_f32 v223, v223, v224
	v_cvt_pk_bf16_f32 v224, v212, v225
	v_cvt_pk_bf16_f32 v225, v233, v232
	v_add_co_u32_e32 v232, vcc, s49, v194
	v_cvt_pk_bf16_f32 v222, v172, v220
	s_nop 0
	v_addc_co_u32_e32 v233, vcc, 0, v195, vcc
	global_store_dwordx4 v[232:233], v[222:225], off
	v_mul_f32_e32 v172, 0xbfb8aa3b, v12
	v_mul_f32_e32 v212, 0xbfb8aa3b, v8
	v_mul_f32_e32 v222, 0xbfb8aa3b, v9
	v_exp_f32_e32 v222, v222
	v_mul_f32_e32 v223, 0xbfb8aa3b, v14
	v_exp_f32_e32 v223, v223
	v_mul_f32_e32 v224, 0xbfb8aa3b, v10
	v_exp_f32_e32 v224, v224
	v_add_f32_e32 v222, 1.0, v222
	v_rcp_f32_e32 v225, v222
	v_add_f32_e32 v222, 1.0, v223
	v_rcp_f32_e32 v223, v222
	v_add_f32_e32 v222, 1.0, v224
	v_mul_f32_e32 v224, 0xbfb8aa3b, v15
	v_mul_f32_e32 v220, 0xbfb8aa3b, v13
	v_exp_f32_e32 v224, v224
	v_mul_f32_e32 v232, 0xbfb8aa3b, v11
	v_exp_f32_e32 v172, v172
	v_exp_f32_e32 v212, v212
	v_exp_f32_e32 v220, v220
	v_exp_f32_e32 v232, v232
	v_rcp_f32_e32 v233, v222
	v_add_f32_e32 v222, 1.0, v224
	v_add_f32_e32 v172, 1.0, v172
	v_add_f32_e32 v212, 1.0, v212
	v_add_f32_e32 v220, 1.0, v220
	v_rcp_f32_e32 v224, v222
	v_add_f32_e32 v222, 1.0, v232
	v_rcp_f32_e32 v172, v172
	v_rcp_f32_e32 v212, v212
	v_rcp_f32_e32 v220, v220
	v_rcp_f32_e32 v232, v222
	s_mov_b64 s[38:39], 0xa0000
	v_lshl_add_u64 v[230:231], v[194:195], 0, s[38:39]
	v_cvt_pk_bf16_f32 v222, v172, v220
	v_cvt_pk_bf16_f32 v223, v223, v224
	v_cvt_pk_bf16_f32 v224, v212, v225
	v_cvt_pk_bf16_f32 v225, v233, v232
	global_store_dwordx4 v[230:231], v[222:225], off offset:256
	v_mul_f32_e32 v212, 0xbfb8aa3b, v16
	v_exp_f32_e32 v212, v212
	v_mul_f32_e32 v222, 0xbfb8aa3b, v17
	v_exp_f32_e32 v222, v222
	v_mul_f32_e32 v223, 0xbfb8aa3b, v22
	v_exp_f32_e32 v223, v223
	v_mul_f32_e32 v224, 0xbfb8aa3b, v18
	v_exp_f32_e32 v224, v224
	v_add_f32_e32 v222, 1.0, v222
	v_rcp_f32_e32 v225, v222
	v_add_f32_e32 v222, 1.0, v223
	v_rcp_f32_e32 v223, v222
	v_add_f32_e32 v222, 1.0, v224
	v_mul_f32_e32 v224, 0xbfb8aa3b, v23
	v_exp_f32_e32 v224, v224
	v_mul_f32_e32 v172, 0xbfb8aa3b, v20
	v_mul_f32_e32 v220, 0xbfb8aa3b, v21
	v_mul_f32_e32 v232, 0xbfb8aa3b, v19
	v_exp_f32_e32 v172, v172
	v_exp_f32_e32 v220, v220
	v_exp_f32_e32 v232, v232
	v_add_f32_e32 v212, 1.0, v212
	v_rcp_f32_e32 v233, v222
	v_add_f32_e32 v222, 1.0, v224
	v_rcp_f32_e32 v212, v212
	v_rcp_f32_e32 v224, v222
	v_add_f32_e32 v172, 1.0, v172
	v_add_f32_e32 v220, 1.0, v220
	v_add_f32_e32 v222, 1.0, v232
	v_rcp_f32_e32 v172, v172
	v_rcp_f32_e32 v220, v220
	v_rcp_f32_e32 v232, v222
	v_cvt_pk_bf16_f32 v223, v223, v224
	v_cvt_pk_bf16_f32 v224, v212, v225
	v_mul_f32_e32 v212, 0xbfb8aa3b, v0
	v_lshl_add_u64 v[230:231], v[194:195], 0, s[62:63]
	v_add_co_u32_e32 v194, vcc, s50, v194
	v_exp_f32_e32 v212, v212
	v_cvt_pk_bf16_f32 v222, v172, v220
	v_cvt_pk_bf16_f32 v225, v233, v232
	v_addc_co_u32_e32 v195, vcc, 0, v195, vcc
	global_store_dwordx4 v[194:195], v[222:225], off
	v_mul_f32_e32 v172, 0xbfb8aa3b, v4
	v_add_f32_e32 v194, 1.0, v212
	v_mul_f32_e32 v222, 0xbfb8aa3b, v2
	v_exp_f32_e32 v222, v222
	v_mul_f32_e32 v223, 0xbfb8aa3b, v7
	v_mul_f32_e32 v195, 0xbfb8aa3b, v5
	v_mul_f32_e32 v212, 0xbfb8aa3b, v1
	v_mul_f32_e32 v220, 0xbfb8aa3b, v6
	v_exp_f32_e32 v223, v223
	v_mul_f32_e32 v224, 0xbfb8aa3b, v3
	v_exp_f32_e32 v172, v172
	v_exp_f32_e32 v195, v195
	v_exp_f32_e32 v212, v212
	v_exp_f32_e32 v220, v220
	v_exp_f32_e32 v224, v224
	v_add_f32_e32 v222, 1.0, v222
	v_rcp_f32_e32 v225, v222
	v_add_f32_e32 v222, 1.0, v223
	v_add_f32_e32 v172, 1.0, v172
	v_add_f32_e32 v195, 1.0, v195
	v_add_f32_e32 v212, 1.0, v212
	v_add_f32_e32 v220, 1.0, v220
	v_rcp_f32_e32 v223, v222
	v_add_f32_e32 v222, 1.0, v224
	v_rcp_f32_e32 v172, v172
	v_rcp_f32_e32 v194, v194
	v_rcp_f32_e32 v195, v195
	v_rcp_f32_e32 v212, v212
	v_rcp_f32_e32 v220, v220
	v_rcp_f32_e32 v232, v222
	v_cvt_pk_bf16_f32 v222, v172, v195
	v_cvt_pk_bf16_f32 v224, v194, v212
	v_cvt_pk_bf16_f32 v223, v220, v223
	v_cvt_pk_bf16_f32 v225, v225, v232
	global_store_dwordx4 v[230:231], v[222:225], off offset:256
	s_mov_b64 s[82:83], 0

; #define PG8_STAGE(bufoff, gbase, voff) do { _Pragma("unroll") for (int _i = 0; _i < 2; ++_i) \
;         __builtin_amdgcn_global_load_lds((const unsigned*)((const char*)(gbase) + (voff)[_i]), (PG8_LAS unsigned*)(lds + (bufoff) + ldsw + _i * 8192), 16, 0, 0); } while (0)
; #define PG8_LDA(dst, b, h) do { _Pragma("unroll") for (int m = 0; m < 4; ++m) _Pragma("unroll") for (int k = 0; k < 2; ++k) dst[m][k] = *(const PG8_LAS bf16x8*)(lds + PG8_SA(b, h) + aoff + m * 2048 + k * 1024); } while (0)
; #define PG8_LDB(dst, b, h) do { _Pragma("unroll") for (int n = 0; n < 2; ++n) _Pragma("unroll") for (int k = 0; k < 2; ++k) dst[n][k] = *(const PG8_LAS bf16x8*)(lds + PG8_SB(b, h) + boff + n * 2048 + k * 1024); } while (0)
; #define PG8_WAIT_V(n) asm volatile("s_waitcnt vmcnt(" #n ")" ::: "memory")
; #define PG8_WAIT_L(n) asm volatile("s_waitcnt lgkmcnt(" #n ")" ::: "memory")
; #define PG8_BAR __builtin_amdgcn_s_barrier()
; #define PG8_SCHED __builtin_amdgcn_sched_barrier(0)
; template <class Epi, class Sched, bool ALIGN_EPI = false, bool SP2 = false>
; __device__ __forceinline__ void gemm_phase(PG8_LAS unsigned char* lds, const Gemm g, const Sched& S, const Epi& E) {
;     ...
;         const bool has_next = S.next(ui + 1, nxt);
;         const char* nA = has_next ? (const char*)g.A + (size_t)nxt.pm * tstep : cA; const char* nB = has_next ? (const char*)g.Bt + (size_t)nxt.pn * tstep : cB;
;         for (int t = 0; t < nt; t += 2) {
;             const bool last = (t == nt - 2);
;             const char* a1 = cA + (size_t)(t + 1) * kstep;
;             const char* a2 = last ? nA : cA + (size_t)(t + 2) * kstep; const char* b2 = last ? nB : cB + (size_t)(t + 2) * kstep;
;             const char* a3 = a2 + kstep; const char* b3 = b2 + kstep;
;             if (last && has_next) S.a_ready(nxt);
;             if constexpr (SP2) {
;             PG8_LDB(B0, 0, 0); PG8_LDB(B1, 0, 1); PG8_SCHED; PG8_LDA(At, 0, 0); PG8_STAGE(PG8_SA(1, 1), a1 + hstep, voffA);
;             PG8_WAIT_V(8); PG8_WAIT_L(0); PG8_BAR; PG8_MMA(0, 0, At, B0); PG8_MMA(0, 1, At, B1); PG8_BAR; PG8_SCHED;
;             PG8_LDA(At, 0, 1); PG8_STAGE(PG8_SB(0, 0), b2, voffB); PG8_STAGE(PG8_SB(0, 1), b2 + hstep, voffB); PG8_STAGE(PG8_SA(0, 0), a2, voffA);
;             PG8_WAIT_V(8); PG8_WAIT_L(0); PG8_BAR; PG8_MMA(1, 0, At, B0); PG8_MMA(1, 1, At, B1); PG8_BAR; PG8_SCHED;
.LBB0_734:
	s_ashr_i32 s39, s38, 31
	v_cmp_lt_i64_e32 vcc, s[40:41], v[140:141]
	s_lshl_b64 s[40:41], s[38:39], 19
	s_add_u32 s40, s9, s40
	s_addc_u32 s41, s22, s41
	s_and_b64 s[42:43], vcc, exec
	s_cselect_b32 s39, s41, s47
	s_cselect_b32 s65, s40, s46
	s_ashr_i32 s37, s36, 31
	s_lshl_b64 s[42:43], s[36:37], 19
	s_add_u32 s42, s23, s42
	s_addc_u32 s43, s52, s43
	s_and_b64 s[50:51], vcc, exec
	s_cselect_b32 s37, s43, s49
	s_cselect_b32 s66, s42, s48
	s_add_u32 s46, s46, 0x40080
	s_addc_u32 s47, s47, 0
	s_add_u32 s67, s48, 0x100
	s_addc_u32 s68, s49, 0
	s_mov_b32 s69, -2
	ds_read_b128 v[144:147], v155
	ds_read_b128 v[148:151], v155 offset:1024
	ds_read_b128 v[158:161], v155 offset:2048
	ds_read_b128 v[162:165], v155 offset:3072
	ds_read_b128 v[166:169], v156
	ds_read_b128 v[170:173], v156 offset:1024
	ds_read_b128 v[174:177], v156 offset:2048
	ds_read_b128 v[178:181], v156 offset:3072
	s_add_u32 s48, s46, 0xfffc0080
	s_addc_u32 s49, s47, -1
	s_cmp_eq_u32 s69, 12
	s_cselect_b32 s51, s39, s49
	s_cselect_b32 s50, s65, s48
	s_cselect_b32 s49, s37, s68
	s_cselect_b32 s48, s66, s67
	s_add_i32 m0, s45, 0xc000
	ds_read_b128 v[182:185], v157
	ds_read_b128 v[186:189], v157 offset:1024
	ds_read_b128 v[190:193], v157 offset:2048
	ds_read_b128 v[194:197], v157 offset:3072
	ds_read_b128 v[198:201], v157 offset:4096
	ds_read_b128 v[202:205], v157 offset:5120
	ds_read_b128 v[206:209], v157 offset:6144
	ds_read_b128 v[214:217], v157 offset:7168
	global_load_lds_dwordx4 v136, s[46:47]
	s_add_i32 m0, s45, 0xe000
	s_nop 0
	global_load_lds_dwordx4 v138, s[46:47]
	s_waitcnt vmcnt(8)
	s_waitcnt lgkmcnt(0)
	s_barrier
	v_mfma_f32_16x16x32_bf16 v[124:127], v[144:147], v[182:185], 0
	v_mfma_f32_16x16x32_bf16 v[120:123], v[158:161], v[182:185], 0
	v_mfma_f32_16x16x32_bf16 v[116:119], v[144:147], v[190:193], 0
	v_mfma_f32_16x16x32_bf16 v[112:115], v[158:161], v[190:193], 0
	v_mfma_f32_16x16x32_bf16 v[96:99], v[144:147], v[198:201], 0
	v_mfma_f32_16x16x32_bf16 v[88:91], v[158:161], v[198:201], 0
	v_mfma_f32_16x16x32_bf16 v[80:83], v[144:147], v[206:209], 0
	v_mfma_f32_16x16x32_bf16 v[72:75], v[158:161], v[206:209], 0
	v_mfma_f32_16x16x32_bf16 v[124:127], v[148:151], v[186:189], v[124:127]
	v_mfma_f32_16x16x32_bf16 v[120:123], v[162:165], v[186:189], v[120:123]
	v_mfma_f32_16x16x32_bf16 v[116:119], v[148:151], v[194:197], v[116:119]
	v_mfma_f32_16x16x32_bf16 v[112:115], v[162:165], v[194:197], v[112:115]
	v_mfma_f32_16x16x32_bf16 v[96:99], v[148:151], v[202:205], v[96:99]
	v_mfma_f32_16x16x32_bf16 v[88:91], v[162:165], v[202:205], v[88:91]
	v_mfma_f32_16x16x32_bf16 v[80:83], v[148:151], v[214:217], v[80:83]
	v_mfma_f32_16x16x32_bf16 v[72:75], v[162:165], v[214:217], v[72:75]
	v_mfma_f32_16x16x32_bf16 v[108:111], v[166:169], v[182:185], 0
	v_mfma_f32_16x16x32_bf16 v[104:107], v[174:177], v[182:185], 0
	v_mfma_f32_16x16x32_bf16 v[100:103], v[166:169], v[190:193], 0
	v_mfma_f32_16x16x32_bf16 v[92:95], v[174:177], v[190:193], 0
	v_mfma_f32_16x16x32_bf16 v[84:87], v[166:169], v[198:201], 0
	v_mfma_f32_16x16x32_bf16 v[76:79], v[174:177], v[198:201], 0
	v_mfma_f32_16x16x32_bf16 v[68:71], v[166:169], v[206:209], 0
	v_mfma_f32_16x16x32_bf16 v[64:67], v[174:177], v[206:209], 0
	v_mfma_f32_16x16x32_bf16 v[108:111], v[170:173], v[186:189], v[108:111]
	v_mfma_f32_16x16x32_bf16 v[104:107], v[178:181], v[186:189], v[104:107]
	v_mfma_f32_16x16x32_bf16 v[100:103], v[170:173], v[194:197], v[100:103]
	v_mfma_f32_16x16x32_bf16 v[92:95], v[178:181], v[194:197], v[92:95]
	v_mfma_f32_16x16x32_bf16 v[84:87], v[170:173], v[202:205], v[84:87]
	v_mfma_f32_16x16x32_bf16 v[76:79], v[178:181], v[202:205], v[76:79]
	v_mfma_f32_16x16x32_bf16 v[68:71], v[170:173], v[214:217], v[68:71]
	v_mfma_f32_16x16x32_bf16 v[64:67], v[178:181], v[214:217], v[64:67]
	s_barrier
	s_add_i32 s70, s62, s53
	s_mov_b32 m0, s70
	ds_read_b128 v[182:185], v157 offset:16384
	ds_read_b128 v[186:189], v157 offset:17408
	ds_read_b128 v[190:193], v157 offset:18432
	ds_read_b128 v[194:197], v157 offset:19456
	ds_read_b128 v[198:201], v157 offset:20480
	ds_read_b128 v[202:205], v157 offset:21504
	ds_read_b128 v[206:209], v157 offset:22528
	ds_read_b128 v[214:217], v157 offset:23552
	global_load_lds_dwordx4 v130, s[48:49]
	s_add_i32 m0, s70, 0x2000
	s_add_u32 s70, s48, 0x40000
	s_addc_u32 s71, s49, 0
	s_add_i32 s72, s63, s53
	global_load_lds_dwordx4 v134, s[48:49]
	s_mov_b32 m0, s72
	s_nop 0
	global_load_lds_dwordx4 v130, s[70:71]
	s_add_i32 m0, s72, 0x2000
	s_nop 0
	global_load_lds_dwordx4 v134, s[70:71]
	s_mov_b32 m0, s45
	s_nop 0
	global_load_lds_dwordx4 v128, s[50:51]
	s_mov_b32 m0, s54
	s_nop 0
	global_load_lds_dwordx4 v132, s[50:51]
	s_waitcnt vmcnt(8)
	s_waitcnt lgkmcnt(0)
	s_barrier
; #define PG8_STAGE(bufoff, gbase, voff) do { _Pragma("unroll") for (int _i = 0; _i < 2; ++_i) \
;         __builtin_amdgcn_global_load_lds((const unsigned*)((const char*)(gbase) + (voff)[_i]), (PG8_LAS unsigned*)(lds + (bufoff) + ldsw + _i * 8192), 16, 0, 0); } while (0)
; #define PG8_LDA(dst, b, h) do { _Pragma("unroll") for (int m = 0; m < 4; ++m) _Pragma("unroll") for (int k = 0; k < 2; ++k) dst[m][k] = *(const PG8_LAS bf16x8*)(lds + PG8_SA(b, h) + aoff + m * 2048 + k * 1024); } while (0)
; #define PG8_LDB(dst, b, h) do { _Pragma("unroll") for (int n = 0; n < 2; ++n) _Pragma("unroll") for (int k = 0; k < 2; ++k) dst[n][k] = *(const PG8_LAS bf16x8*)(lds + PG8_SB(b, h) + boff + n * 2048 + k * 1024); } while (0)
; #define PG8_MMA(ai, bj, At, Bt) do { __builtin_amdgcn_s_setprio(1); _Pragma("unroll") for (int m = 0; m < 4; ++m) _Pragma("unroll") for (int n = 0; n < 2; ++n) _Pragma("unroll") for (int k = 0; k < 2; ++k) \
;         acc[ai][bj][m][n] = __builtin_amdgcn_mfma_f32_16x16x32_bf16(Bt[n][k], At[m][k], acc[ai][bj][m][n], 0, 0, 0); __builtin_amdgcn_s_setprio(0); } while (0)
; #define PG8_WAIT_V(n) asm volatile("s_waitcnt vmcnt(" #n ")" ::: "memory")
; #define PG8_WAIT_L(n) asm volatile("s_waitcnt lgkmcnt(" #n ")" ::: "memory")
; #define PG8_BAR __builtin_amdgcn_s_barrier()
; #define PG8_SCHED __builtin_amdgcn_sched_barrier(0)
; template <class Epi, class Sched, bool ALIGN_EPI = false, bool SP2 = false>
; __device__ __forceinline__ void gemm_phase(PG8_LAS unsigned char* lds, const Gemm g, const Sched& S, const Epi& E) {
;     ...
;             PG8_WAIT_V(8); PG8_WAIT_L(0); PG8_BAR; PG8_MMA(0, 0, At, B0); PG8_MMA(0, 1, At, B1); PG8_BAR; PG8_SCHED;
;             PG8_LDA(At, 0, 1); PG8_STAGE(PG8_SB(0, 0), b2, voffB); PG8_STAGE(PG8_SB(0, 1), b2 + hstep, voffB); PG8_STAGE(PG8_SA(0, 0), a2, voffA);
;             PG8_WAIT_V(8); PG8_WAIT_L(0); PG8_BAR; PG8_MMA(1, 0, At, B0); PG8_MMA(1, 1, At, B1); PG8_BAR; PG8_SCHED;
;             PG8_LDB(B0, 1, 0); PG8_LDB(B1, 1, 1); PG8_SCHED; PG8_LDA(At, 1, 0); PG8_STAGE(PG8_SA(0, 1), a2 + hstep, voffA);
;             PG8_WAIT_V(8); PG8_WAIT_L(0); PG8_BAR; PG8_MMA(0, 0, At, B0); PG8_MMA(0, 1, At, B1); PG8_BAR; PG8_SCHED;
	v_mfma_f32_16x16x32_bf16 v[60:63], v[144:147], v[182:185], 0
	v_mfma_f32_16x16x32_bf16 v[56:59], v[158:161], v[182:185], 0
	v_mfma_f32_16x16x32_bf16 v[48:51], v[144:147], v[190:193], 0
	v_mfma_f32_16x16x32_bf16 v[40:43], v[158:161], v[190:193], 0
	v_mfma_f32_16x16x32_bf16 v[32:35], v[144:147], v[198:201], 0
	v_mfma_f32_16x16x32_bf16 v[24:27], v[158:161], v[198:201], 0
	v_mfma_f32_16x16x32_bf16 v[16:19], v[144:147], v[206:209], 0
	v_mfma_f32_16x16x32_bf16 v[8:11], v[158:161], v[206:209], 0
	v_mfma_f32_16x16x32_bf16 v[60:63], v[148:151], v[186:189], v[60:63]
	v_mfma_f32_16x16x32_bf16 v[56:59], v[162:165], v[186:189], v[56:59]
	v_mfma_f32_16x16x32_bf16 v[48:51], v[148:151], v[194:197], v[48:51]
	v_mfma_f32_16x16x32_bf16 v[40:43], v[162:165], v[194:197], v[40:43]
	v_mfma_f32_16x16x32_bf16 v[32:35], v[148:151], v[202:205], v[32:35]
	v_mfma_f32_16x16x32_bf16 v[24:27], v[162:165], v[202:205], v[24:27]
	v_mfma_f32_16x16x32_bf16 v[16:19], v[148:151], v[214:217], v[16:19]
	v_mfma_f32_16x16x32_bf16 v[8:11], v[162:165], v[214:217], v[8:11]
	v_mfma_f32_16x16x32_bf16 v[52:55], v[166:169], v[182:185], 0
	v_mfma_f32_16x16x32_bf16 v[44:47], v[174:177], v[182:185], 0
	v_mfma_f32_16x16x32_bf16 v[36:39], v[166:169], v[190:193], 0
	v_mfma_f32_16x16x32_bf16 v[28:31], v[174:177], v[190:193], 0
	v_mfma_f32_16x16x32_bf16 v[20:23], v[166:169], v[198:201], 0
	v_mfma_f32_16x16x32_bf16 v[12:15], v[174:177], v[198:201], 0
	v_mfma_f32_16x16x32_bf16 v[4:7], v[166:169], v[206:209], 0
	v_mfma_f32_16x16x32_bf16 v[0:3], v[174:177], v[206:209], 0
	v_mfma_f32_16x16x32_bf16 v[52:55], v[170:173], v[186:189], v[52:55]
	v_mfma_f32_16x16x32_bf16 v[44:47], v[178:181], v[186:189], v[44:47]
	v_mfma_f32_16x16x32_bf16 v[36:39], v[170:173], v[194:197], v[36:39]
	v_mfma_f32_16x16x32_bf16 v[28:31], v[178:181], v[194:197], v[28:31]
	v_mfma_f32_16x16x32_bf16 v[20:23], v[170:173], v[202:205], v[20:23]
	v_mfma_f32_16x16x32_bf16 v[12:15], v[178:181], v[202:205], v[12:15]
	v_mfma_f32_16x16x32_bf16 v[4:7], v[170:173], v[214:217], v[4:7]
	v_mfma_f32_16x16x32_bf16 v[0:3], v[178:181], v[214:217], v[0:3]
	s_barrier
	s_add_i32 s70, 0, 0x18000
	s_add_i32 s71, 0, 0x1c000
	v_add_u32_e32 v162, s70, v153
	v_add_u32_e32 v178, s71, v153
	ds_read_b128 v[144:147], v162
	ds_read_b128 v[148:151], v162 offset:1024
	ds_read_b128 v[158:161], v162 offset:2048
	ds_read_b128 v[162:165], v162 offset:3072
	ds_read_b128 v[166:169], v178
	ds_read_b128 v[170:173], v178 offset:1024
	ds_read_b128 v[174:177], v178 offset:2048
	ds_read_b128 v[178:181], v178 offset:3072
	s_add_u32 s80, s50, 0x80
	s_addc_u32 s81, s51, 0
	s_add_u32 s50, s50, 0x40000
	s_addc_u32 s51, s51, 0
	s_mov_b32 m0, s55
	ds_read_b128 v[182:185], v157 offset:32768
	ds_read_b128 v[186:189], v157 offset:33792
	ds_read_b128 v[190:193], v157 offset:34816
	ds_read_b128 v[194:197], v157 offset:35840
	ds_read_b128 v[198:201], v157 offset:36864
	ds_read_b128 v[202:205], v157 offset:37888
	ds_read_b128 v[206:209], v157 offset:38912
	ds_read_b128 v[214:217], v157 offset:39936
	global_load_lds_dwordx4 v128, s[50:51]
	s_mov_b32 m0, s56
	s_nop 0
	global_load_lds_dwordx4 v132, s[50:51]
	s_waitcnt vmcnt(8)
	s_waitcnt lgkmcnt(0)
	s_barrier
	v_mfma_f32_16x16x32_bf16 v[124:127], v[144:147], v[182:185], v[124:127]
	v_mfma_f32_16x16x32_bf16 v[120:123], v[158:161], v[182:185], v[120:123]
	v_mfma_f32_16x16x32_bf16 v[116:119], v[144:147], v[190:193], v[116:119]
	v_mfma_f32_16x16x32_bf16 v[112:115], v[158:161], v[190:193], v[112:115]
	v_mfma_f32_16x16x32_bf16 v[96:99], v[144:147], v[198:201], v[96:99]
	v_mfma_f32_16x16x32_bf16 v[88:91], v[158:161], v[198:201], v[88:91]
	v_mfma_f32_16x16x32_bf16 v[80:83], v[144:147], v[206:209], v[80:83]
	v_mfma_f32_16x16x32_bf16 v[72:75], v[158:161], v[206:209], v[72:75]
	v_mfma_f32_16x16x32_bf16 v[124:127], v[148:151], v[186:189], v[124:127]
	v_mfma_f32_16x16x32_bf16 v[120:123], v[162:165], v[186:189], v[120:123]
	v_mfma_f32_16x16x32_bf16 v[116:119], v[148:151], v[194:197], v[116:119]
	v_mfma_f32_16x16x32_bf16 v[112:115], v[162:165], v[194:197], v[112:115]
	v_mfma_f32_16x16x32_bf16 v[96:99], v[148:151], v[202:205], v[96:99]
	v_mfma_f32_16x16x32_bf16 v[88:91], v[162:165], v[202:205], v[88:91]
	v_mfma_f32_16x16x32_bf16 v[80:83], v[148:151], v[214:217], v[80:83]
	v_mfma_f32_16x16x32_bf16 v[72:75], v[162:165], v[214:217], v[72:75]
	v_mfma_f32_16x16x32_bf16 v[108:111], v[166:169], v[182:185], v[108:111]
	v_mfma_f32_16x16x32_bf16 v[104:107], v[174:177], v[182:185], v[104:107]
	v_mfma_f32_16x16x32_bf16 v[100:103], v[166:169], v[190:193], v[100:103]
	v_mfma_f32_16x16x32_bf16 v[92:95], v[174:177], v[190:193], v[92:95]
	v_mfma_f32_16x16x32_bf16 v[84:87], v[166:169], v[198:201], v[84:87]
	v_mfma_f32_16x16x32_bf16 v[76:79], v[174:177], v[198:201], v[76:79]
	v_mfma_f32_16x16x32_bf16 v[68:71], v[166:169], v[206:209], v[68:71]
	v_mfma_f32_16x16x32_bf16 v[64:67], v[174:177], v[206:209], v[64:67]
	v_mfma_f32_16x16x32_bf16 v[108:111], v[170:173], v[186:189], v[108:111]
	v_mfma_f32_16x16x32_bf16 v[104:107], v[178:181], v[186:189], v[104:107]
	v_mfma_f32_16x16x32_bf16 v[100:103], v[170:173], v[194:197], v[100:103]
	v_mfma_f32_16x16x32_bf16 v[92:95], v[178:181], v[194:197], v[92:95]
	v_mfma_f32_16x16x32_bf16 v[84:87], v[170:173], v[202:205], v[84:87]
	v_mfma_f32_16x16x32_bf16 v[76:79], v[178:181], v[202:205], v[76:79]
	v_mfma_f32_16x16x32_bf16 v[68:71], v[170:173], v[214:217], v[68:71]
	v_mfma_f32_16x16x32_bf16 v[64:67], v[178:181], v[214:217], v[64:67]
	s_barrier
; #define PG8_STAGE(bufoff, gbase, voff) do { _Pragma("unroll") for (int _i = 0; _i < 2; ++_i) \
;         __builtin_amdgcn_global_load_lds((const unsigned*)((const char*)(gbase) + (voff)[_i]), (PG8_LAS unsigned*)(lds + (bufoff) + ldsw + _i * 8192), 16, 0, 0); } while (0)
; #define PG8_LDA(dst, b, h) do { _Pragma("unroll") for (int m = 0; m < 4; ++m) _Pragma("unroll") for (int k = 0; k < 2; ++k) dst[m][k] = *(const PG8_LAS bf16x8*)(lds + PG8_SA(b, h) + aoff + m * 2048 + k * 1024); } while (0)
; #define PG8_LDB(dst, b, h) do { _Pragma("unroll") for (int n = 0; n < 2; ++n) _Pragma("unroll") for (int k = 0; k < 2; ++k) dst[n][k] = *(const PG8_LAS bf16x8*)(lds + PG8_SB(b, h) + boff + n * 2048 + k * 1024); } while (0)
; #define PG8_MMA(ai, bj, At, Bt) do { __builtin_amdgcn_s_setprio(1); _Pragma("unroll") for (int m = 0; m < 4; ++m) _Pragma("unroll") for (int n = 0; n < 2; ++n) _Pragma("unroll") for (int k = 0; k < 2; ++k) \
;         acc[ai][bj][m][n] = __builtin_amdgcn_mfma_f32_16x16x32_bf16(Bt[n][k], At[m][k], acc[ai][bj][m][n], 0, 0, 0); __builtin_amdgcn_s_setprio(0); } while (0)
; #define PG8_WAIT_V(n) asm volatile("s_waitcnt vmcnt(" #n ")" ::: "memory")
; #define PG8_WAIT_L(n) asm volatile("s_waitcnt lgkmcnt(" #n ")" ::: "memory")
; #define PG8_BAR __builtin_amdgcn_s_barrier()
; #define PG8_SCHED __builtin_amdgcn_sched_barrier(0)
; template <class Epi, class Sched, bool ALIGN_EPI = false, bool SP2 = false>
; __device__ __forceinline__ void gemm_phase(PG8_LAS unsigned char* lds, const Gemm g, const Sched& S, const Epi& E) {
;     ...
;             PG8_LDB(B0, 0, 0); PG8_LDB(B1, 0, 1); PG8_SCHED; PG8_LDA(At, 0, 0); PG8_STAGE(PG8_SA(1, 1), a1 + hstep, voffA);
;             PG8_WAIT_V(8); PG8_WAIT_L(0); PG8_BAR; PG8_MMA(0, 0, At, B0); PG8_MMA(0, 1, At, B1); PG8_BAR; PG8_SCHED;
;     ...
;             PG8_LDA(At, 1, 1); PG8_STAGE(PG8_SB(1, 0), b3, voffB); PG8_STAGE(PG8_SB(1, 1), b3 + hstep, voffB); PG8_STAGE(PG8_SA(1, 0), a3, voffA);
;             PG8_WAIT_V(8); PG8_WAIT_L(0); PG8_BAR; PG8_MMA(1, 0, At, B0); PG8_MMA(1, 1, At, B1); PG8_BAR; PG8_SCHED;
	s_add_i32 s50, s70, s53
	s_add_u32 s82, s48, 0x80
	s_addc_u32 s83, s49, 0
	s_mov_b32 m0, s50
	ds_read_b128 v[182:185], v157 offset:49152
	ds_read_b128 v[186:189], v157 offset:50176
	ds_read_b128 v[190:193], v157 offset:51200
	ds_read_b128 v[194:197], v157 offset:52224
	ds_read_b128 v[198:201], v157 offset:53248
	ds_read_b128 v[202:205], v157 offset:54272
	ds_read_b128 v[206:209], v157 offset:55296
	ds_read_b128 v[214:217], v157 offset:56320
	global_load_lds_dwordx4 v130, s[82:83]
	s_add_i32 m0, s50, 0x2000
	s_add_u32 s48, s48, 0x40080
	s_addc_u32 s49, s49, 0
	s_add_i32 s50, s71, s53
	global_load_lds_dwordx4 v134, s[82:83]
	s_mov_b32 m0, s50
	s_nop 0
	global_load_lds_dwordx4 v130, s[48:49]
	s_add_i32 m0, s50, 0x2000
	s_nop 0
	global_load_lds_dwordx4 v134, s[48:49]
	s_mov_b32 m0, s58
	s_nop 0
	global_load_lds_dwordx4 v128, s[80:81]
	s_mov_b32 m0, s59
	s_nop 0
	global_load_lds_dwordx4 v132, s[80:81]
	s_waitcnt vmcnt(8)
	s_waitcnt lgkmcnt(0)
	s_barrier
	v_mfma_f32_16x16x32_bf16 v[60:63], v[144:147], v[182:185], v[60:63]
	v_mfma_f32_16x16x32_bf16 v[56:59], v[158:161], v[182:185], v[56:59]
	v_mfma_f32_16x16x32_bf16 v[48:51], v[144:147], v[190:193], v[48:51]
	v_mfma_f32_16x16x32_bf16 v[40:43], v[158:161], v[190:193], v[40:43]
	v_mfma_f32_16x16x32_bf16 v[32:35], v[144:147], v[198:201], v[32:35]
	v_mfma_f32_16x16x32_bf16 v[24:27], v[158:161], v[198:201], v[24:27]
	v_mfma_f32_16x16x32_bf16 v[16:19], v[144:147], v[206:209], v[16:19]
	v_mfma_f32_16x16x32_bf16 v[8:11], v[158:161], v[206:209], v[8:11]
	v_mfma_f32_16x16x32_bf16 v[60:63], v[148:151], v[186:189], v[60:63]
	v_mfma_f32_16x16x32_bf16 v[56:59], v[162:165], v[186:189], v[56:59]
	v_mfma_f32_16x16x32_bf16 v[48:51], v[148:151], v[194:197], v[48:51]
	v_mfma_f32_16x16x32_bf16 v[40:43], v[162:165], v[194:197], v[40:43]
	v_mfma_f32_16x16x32_bf16 v[32:35], v[148:151], v[202:205], v[32:35]
	v_mfma_f32_16x16x32_bf16 v[24:27], v[162:165], v[202:205], v[24:27]
	v_mfma_f32_16x16x32_bf16 v[16:19], v[148:151], v[214:217], v[16:19]
	v_mfma_f32_16x16x32_bf16 v[8:11], v[162:165], v[214:217], v[8:11]
	v_mfma_f32_16x16x32_bf16 v[52:55], v[166:169], v[182:185], v[52:55]
	v_mfma_f32_16x16x32_bf16 v[44:47], v[174:177], v[182:185], v[44:47]
	v_mfma_f32_16x16x32_bf16 v[36:39], v[166:169], v[190:193], v[36:39]
	v_mfma_f32_16x16x32_bf16 v[28:31], v[174:177], v[190:193], v[28:31]
	v_mfma_f32_16x16x32_bf16 v[20:23], v[166:169], v[198:201], v[20:23]
	v_mfma_f32_16x16x32_bf16 v[12:15], v[174:177], v[198:201], v[12:15]
	v_mfma_f32_16x16x32_bf16 v[4:7], v[166:169], v[206:209], v[4:7]
	v_mfma_f32_16x16x32_bf16 v[0:3], v[174:177], v[206:209], v[0:3]
	v_mfma_f32_16x16x32_bf16 v[52:55], v[170:173], v[186:189], v[52:55]
	v_mfma_f32_16x16x32_bf16 v[44:47], v[178:181], v[186:189], v[44:47]
	v_mfma_f32_16x16x32_bf16 v[36:39], v[170:173], v[194:197], v[36:39]
	v_mfma_f32_16x16x32_bf16 v[28:31], v[178:181], v[194:197], v[28:31]
	v_mfma_f32_16x16x32_bf16 v[20:23], v[170:173], v[202:205], v[20:23]
	v_mfma_f32_16x16x32_bf16 v[12:15], v[178:181], v[202:205], v[12:15]
	v_mfma_f32_16x16x32_bf16 v[4:7], v[170:173], v[214:217], v[4:7]
	v_mfma_f32_16x16x32_bf16 v[0:3], v[178:181], v[214:217], v[0:3]
	s_barrier
	s_add_i32 s69, s69, 2
	s_add_u32 s46, s46, 0x100
	s_addc_u32 s47, s47, 0
	s_add_u32 s67, s67, 0x100
	s_addc_u32 s68, s68, 0
	s_cmp_gt_u32 s69, 13
.LBB0_735:
	ds_read_b128 v[144:147], v155
	ds_read_b128 v[148:151], v155 offset:1024
	ds_read_b128 v[158:161], v155 offset:2048
	ds_read_b128 v[162:165], v155 offset:3072
	ds_read_b128 v[166:169], v156
	ds_read_b128 v[170:173], v156 offset:1024
	ds_read_b128 v[174:177], v156 offset:2048
	ds_read_b128 v[178:181], v156 offset:3072
	s_add_u32 s48, s46, 0xfffc0080
	s_addc_u32 s49, s47, -1
	s_cmp_eq_u32 s69, 12
	s_cselect_b32 s51, s39, s49
	s_cselect_b32 s50, s65, s48
	s_cselect_b32 s49, s37, s68
	s_cselect_b32 s48, s66, s67
	s_add_i32 m0, s45, 0xc000
	ds_read_b128 v[182:185], v157
	ds_read_b128 v[186:189], v157 offset:1024
	ds_read_b128 v[190:193], v157 offset:2048
	ds_read_b128 v[194:197], v157 offset:3072
	ds_read_b128 v[198:201], v157 offset:4096
	ds_read_b128 v[202:205], v157 offset:5120
	ds_read_b128 v[206:209], v157 offset:6144
	ds_read_b128 v[214:217], v157 offset:7168
	global_load_lds_dwordx4 v136, s[46:47]
	s_add_i32 m0, s45, 0xe000
	s_nop 0
	global_load_lds_dwordx4 v138, s[46:47]
	s_waitcnt vmcnt(8)
	s_waitcnt lgkmcnt(0)
	s_barrier
	v_mfma_f32_16x16x32_bf16 v[124:127], v[144:147], v[182:185], v[124:127]
	v_mfma_f32_16x16x32_bf16 v[120:123], v[158:161], v[182:185], v[120:123]
	v_mfma_f32_16x16x32_bf16 v[116:119], v[144:147], v[190:193], v[116:119]
	v_mfma_f32_16x16x32_bf16 v[112:115], v[158:161], v[190:193], v[112:115]
	v_mfma_f32_16x16x32_bf16 v[96:99], v[144:147], v[198:201], v[96:99]
	v_mfma_f32_16x16x32_bf16 v[88:91], v[158:161], v[198:201], v[88:91]
	v_mfma_f32_16x16x32_bf16 v[80:83], v[144:147], v[206:209], v[80:83]
	v_mfma_f32_16x16x32_bf16 v[72:75], v[158:161], v[206:209], v[72:75]
	v_mfma_f32_16x16x32_bf16 v[124:127], v[148:151], v[186:189], v[124:127]
	v_mfma_f32_16x16x32_bf16 v[120:123], v[162:165], v[186:189], v[120:123]
	v_mfma_f32_16x16x32_bf16 v[116:119], v[148:151], v[194:197], v[116:119]
	v_mfma_f32_16x16x32_bf16 v[112:115], v[162:165], v[194:197], v[112:115]
	v_mfma_f32_16x16x32_bf16 v[96:99], v[148:151], v[202:205], v[96:99]
	v_mfma_f32_16x16x32_bf16 v[88:91], v[162:165], v[202:205], v[88:91]
	v_mfma_f32_16x16x32_bf16 v[80:83], v[148:151], v[214:217], v[80:83]
	v_mfma_f32_16x16x32_bf16 v[72:75], v[162:165], v[214:217], v[72:75]
	v_mfma_f32_16x16x32_bf16 v[108:111], v[166:169], v[182:185], v[108:111]
	v_mfma_f32_16x16x32_bf16 v[104:107], v[174:177], v[182:185], v[104:107]
	v_mfma_f32_16x16x32_bf16 v[100:103], v[166:169], v[190:193], v[100:103]
	v_mfma_f32_16x16x32_bf16 v[92:95], v[174:177], v[190:193], v[92:95]
	v_mfma_f32_16x16x32_bf16 v[84:87], v[166:169], v[198:201], v[84:87]
	v_mfma_f32_16x16x32_bf16 v[76:79], v[174:177], v[198:201], v[76:79]
	v_mfma_f32_16x16x32_bf16 v[68:71], v[166:169], v[206:209], v[68:71]
	v_mfma_f32_16x16x32_bf16 v[64:67], v[174:177], v[206:209], v[64:67]
	v_mfma_f32_16x16x32_bf16 v[108:111], v[170:173], v[186:189], v[108:111]
	v_mfma_f32_16x16x32_bf16 v[104:107], v[178:181], v[186:189], v[104:107]
	v_mfma_f32_16x16x32_bf16 v[100:103], v[170:173], v[194:197], v[100:103]
	v_mfma_f32_16x16x32_bf16 v[92:95], v[178:181], v[194:197], v[92:95]
	v_mfma_f32_16x16x32_bf16 v[84:87], v[170:173], v[202:205], v[84:87]
	v_mfma_f32_16x16x32_bf16 v[76:79], v[178:181], v[202:205], v[76:79]
	v_mfma_f32_16x16x32_bf16 v[68:71], v[170:173], v[214:217], v[68:71]
	v_mfma_f32_16x16x32_bf16 v[64:67], v[178:181], v[214:217], v[64:67]
	s_barrier
; #define PG8_STAGE(bufoff, gbase, voff) do { _Pragma("unroll") for (int _i = 0; _i < 2; ++_i) \
;         __builtin_amdgcn_global_load_lds((const unsigned*)((const char*)(gbase) + (voff)[_i]), (PG8_LAS unsigned*)(lds + (bufoff) + ldsw + _i * 8192), 16, 0, 0); } while (0)
; #define PG8_LDA(dst, b, h) do { _Pragma("unroll") for (int m = 0; m < 4; ++m) _Pragma("unroll") for (int k = 0; k < 2; ++k) dst[m][k] = *(const PG8_LAS bf16x8*)(lds + PG8_SA(b, h) + aoff + m * 2048 + k * 1024); } while (0)
; #define PG8_LDB(dst, b, h) do { _Pragma("unroll") for (int n = 0; n < 2; ++n) _Pragma("unroll") for (int k = 0; k < 2; ++k) dst[n][k] = *(const PG8_LAS bf16x8*)(lds + PG8_SB(b, h) + boff + n * 2048 + k * 1024); } while (0)
; #define PG8_MMA(ai, bj, At, Bt) do { __builtin_amdgcn_s_setprio(1); _Pragma("unroll") for (int m = 0; m < 4; ++m) _Pragma("unroll") for (int n = 0; n < 2; ++n) _Pragma("unroll") for (int k = 0; k < 2; ++k) \
;         acc[ai][bj][m][n] = __builtin_amdgcn_mfma_f32_16x16x32_bf16(Bt[n][k], At[m][k], acc[ai][bj][m][n], 0, 0, 0); __builtin_amdgcn_s_setprio(0); } while (0)
; #define PG8_WAIT_V(n) asm volatile("s_waitcnt vmcnt(" #n ")" ::: "memory")
; #define PG8_WAIT_L(n) asm volatile("s_waitcnt lgkmcnt(" #n ")" ::: "memory")
; #define PG8_BAR __builtin_amdgcn_s_barrier()
; #define PG8_SCHED __builtin_amdgcn_sched_barrier(0)
; template <class Epi, class Sched, bool ALIGN_EPI = false, bool SP2 = false>
; __device__ __forceinline__ void gemm_phase(PG8_LAS unsigned char* lds, const Gemm g, const Sched& S, const Epi& E) {
;     ...
;             PG8_LDA(At, 0, 1); PG8_STAGE(PG8_SB(0, 0), b2, voffB); PG8_STAGE(PG8_SB(0, 1), b2 + hstep, voffB); PG8_STAGE(PG8_SA(0, 0), a2, voffA);
;             PG8_WAIT_V(8); PG8_WAIT_L(0); PG8_BAR; PG8_MMA(1, 0, At, B0); PG8_MMA(1, 1, At, B1); PG8_BAR; PG8_SCHED;
;             PG8_LDB(B0, 1, 0); PG8_LDB(B1, 1, 1); PG8_SCHED; PG8_LDA(At, 1, 0); PG8_STAGE(PG8_SA(0, 1), a2 + hstep, voffA);
;             PG8_WAIT_V(8); PG8_WAIT_L(0); PG8_BAR; PG8_MMA(0, 0, At, B0); PG8_MMA(0, 1, At, B1); PG8_BAR; PG8_SCHED;
	s_add_i32 s70, s62, s53
	s_mov_b32 m0, s70
	ds_read_b128 v[182:185], v157 offset:16384
	ds_read_b128 v[186:189], v157 offset:17408
	ds_read_b128 v[190:193], v157 offset:18432
	ds_read_b128 v[194:197], v157 offset:19456
	ds_read_b128 v[198:201], v157 offset:20480
	ds_read_b128 v[202:205], v157 offset:21504
	ds_read_b128 v[206:209], v157 offset:22528
	ds_read_b128 v[214:217], v157 offset:23552
	global_load_lds_dwordx4 v130, s[48:49]
	s_add_i32 m0, s70, 0x2000
	s_add_u32 s70, s48, 0x40000
	s_addc_u32 s71, s49, 0
	s_add_i32 s72, s63, s53
	global_load_lds_dwordx4 v134, s[48:49]
	s_mov_b32 m0, s72
	s_nop 0
	global_load_lds_dwordx4 v130, s[70:71]
	s_add_i32 m0, s72, 0x2000
	s_nop 0
	global_load_lds_dwordx4 v134, s[70:71]
	s_mov_b32 m0, s45
	s_nop 0
	global_load_lds_dwordx4 v128, s[50:51]
	s_mov_b32 m0, s54
	s_nop 0
	global_load_lds_dwordx4 v132, s[50:51]
	s_waitcnt vmcnt(8)
	s_waitcnt lgkmcnt(0)
	s_barrier
	v_mfma_f32_16x16x32_bf16 v[60:63], v[144:147], v[182:185], v[60:63]
	v_mfma_f32_16x16x32_bf16 v[56:59], v[158:161], v[182:185], v[56:59]
	v_mfma_f32_16x16x32_bf16 v[48:51], v[144:147], v[190:193], v[48:51]
	v_mfma_f32_16x16x32_bf16 v[40:43], v[158:161], v[190:193], v[40:43]
	v_mfma_f32_16x16x32_bf16 v[32:35], v[144:147], v[198:201], v[32:35]
	v_mfma_f32_16x16x32_bf16 v[24:27], v[158:161], v[198:201], v[24:27]
	v_mfma_f32_16x16x32_bf16 v[16:19], v[144:147], v[206:209], v[16:19]
	v_mfma_f32_16x16x32_bf16 v[8:11], v[158:161], v[206:209], v[8:11]
	v_mfma_f32_16x16x32_bf16 v[60:63], v[148:151], v[186:189], v[60:63]
	v_mfma_f32_16x16x32_bf16 v[56:59], v[162:165], v[186:189], v[56:59]
	v_mfma_f32_16x16x32_bf16 v[48:51], v[148:151], v[194:197], v[48:51]
	v_mfma_f32_16x16x32_bf16 v[40:43], v[162:165], v[194:197], v[40:43]
	v_mfma_f32_16x16x32_bf16 v[32:35], v[148:151], v[202:205], v[32:35]
	v_mfma_f32_16x16x32_bf16 v[24:27], v[162:165], v[202:205], v[24:27]
	v_mfma_f32_16x16x32_bf16 v[16:19], v[148:151], v[214:217], v[16:19]
	v_mfma_f32_16x16x32_bf16 v[8:11], v[162:165], v[214:217], v[8:11]
	v_mfma_f32_16x16x32_bf16 v[52:55], v[166:169], v[182:185], v[52:55]
	v_mfma_f32_16x16x32_bf16 v[44:47], v[174:177], v[182:185], v[44:47]
	v_mfma_f32_16x16x32_bf16 v[36:39], v[166:169], v[190:193], v[36:39]
	v_mfma_f32_16x16x32_bf16 v[28:31], v[174:177], v[190:193], v[28:31]
	v_mfma_f32_16x16x32_bf16 v[20:23], v[166:169], v[198:201], v[20:23]
	v_mfma_f32_16x16x32_bf16 v[12:15], v[174:177], v[198:201], v[12:15]
	v_mfma_f32_16x16x32_bf16 v[4:7], v[166:169], v[206:209], v[4:7]
	v_mfma_f32_16x16x32_bf16 v[0:3], v[174:177], v[206:209], v[0:3]
	v_mfma_f32_16x16x32_bf16 v[52:55], v[170:173], v[186:189], v[52:55]
	v_mfma_f32_16x16x32_bf16 v[44:47], v[178:181], v[186:189], v[44:47]
	v_mfma_f32_16x16x32_bf16 v[36:39], v[170:173], v[194:197], v[36:39]
	v_mfma_f32_16x16x32_bf16 v[28:31], v[178:181], v[194:197], v[28:31]
	v_mfma_f32_16x16x32_bf16 v[20:23], v[170:173], v[202:205], v[20:23]
	v_mfma_f32_16x16x32_bf16 v[12:15], v[178:181], v[202:205], v[12:15]
	v_mfma_f32_16x16x32_bf16 v[4:7], v[170:173], v[214:217], v[4:7]
	v_mfma_f32_16x16x32_bf16 v[0:3], v[178:181], v[214:217], v[0:3]
	s_barrier
	s_add_i32 s70, 0, 0x18000
	s_add_i32 s71, 0, 0x1c000
	v_add_u32_e32 v162, s70, v153
	v_add_u32_e32 v178, s71, v153
	ds_read_b128 v[144:147], v162
	ds_read_b128 v[148:151], v162 offset:1024
	ds_read_b128 v[158:161], v162 offset:2048
	ds_read_b128 v[162:165], v162 offset:3072
	ds_read_b128 v[166:169], v178
	ds_read_b128 v[170:173], v178 offset:1024
	ds_read_b128 v[174:177], v178 offset:2048
	ds_read_b128 v[178:181], v178 offset:3072
	s_add_u32 s80, s50, 0x80
	s_addc_u32 s81, s51, 0
	s_add_u32 s50, s50, 0x40000
	s_addc_u32 s51, s51, 0
	s_mov_b32 m0, s55
	ds_read_b128 v[182:185], v157 offset:32768
	ds_read_b128 v[186:189], v157 offset:33792
	ds_read_b128 v[190:193], v157 offset:34816
	ds_read_b128 v[194:197], v157 offset:35840
	ds_read_b128 v[198:201], v157 offset:36864
	ds_read_b128 v[202:205], v157 offset:37888
	ds_read_b128 v[206:209], v157 offset:38912
	ds_read_b128 v[214:217], v157 offset:39936
	global_load_lds_dwordx4 v128, s[50:51]
	s_mov_b32 m0, s56
	s_nop 0
	global_load_lds_dwordx4 v132, s[50:51]
	s_waitcnt vmcnt(8)
	s_waitcnt lgkmcnt(0)
	s_barrier
	v_mfma_f32_16x16x32_bf16 v[124:127], v[144:147], v[182:185], v[124:127]
	v_mfma_f32_16x16x32_bf16 v[120:123], v[158:161], v[182:185], v[120:123]
	v_mfma_f32_16x16x32_bf16 v[116:119], v[144:147], v[190:193], v[116:119]
	v_mfma_f32_16x16x32_bf16 v[112:115], v[158:161], v[190:193], v[112:115]
	v_mfma_f32_16x16x32_bf16 v[96:99], v[144:147], v[198:201], v[96:99]
	v_mfma_f32_16x16x32_bf16 v[88:91], v[158:161], v[198:201], v[88:91]
	v_mfma_f32_16x16x32_bf16 v[80:83], v[144:147], v[206:209], v[80:83]
	v_mfma_f32_16x16x32_bf16 v[72:75], v[158:161], v[206:209], v[72:75]
	v_mfma_f32_16x16x32_bf16 v[124:127], v[148:151], v[186:189], v[124:127]
	v_mfma_f32_16x16x32_bf16 v[120:123], v[162:165], v[186:189], v[120:123]
	v_mfma_f32_16x16x32_bf16 v[116:119], v[148:151], v[194:197], v[116:119]
	v_mfma_f32_16x16x32_bf16 v[112:115], v[162:165], v[194:197], v[112:115]
	v_mfma_f32_16x16x32_bf16 v[96:99], v[148:151], v[202:205], v[96:99]
	v_mfma_f32_16x16x32_bf16 v[88:91], v[162:165], v[202:205], v[88:91]
	v_mfma_f32_16x16x32_bf16 v[80:83], v[148:151], v[214:217], v[80:83]
	v_mfma_f32_16x16x32_bf16 v[72:75], v[162:165], v[214:217], v[72:75]
	v_mfma_f32_16x16x32_bf16 v[108:111], v[166:169], v[182:185], v[108:111]
	v_mfma_f32_16x16x32_bf16 v[104:107], v[174:177], v[182:185], v[104:107]
	v_mfma_f32_16x16x32_bf16 v[100:103], v[166:169], v[190:193], v[100:103]
	v_mfma_f32_16x16x32_bf16 v[92:95], v[174:177], v[190:193], v[92:95]
	v_mfma_f32_16x16x32_bf16 v[84:87], v[166:169], v[198:201], v[84:87]
	v_mfma_f32_16x16x32_bf16 v[76:79], v[174:177], v[198:201], v[76:79]
	v_mfma_f32_16x16x32_bf16 v[68:71], v[166:169], v[206:209], v[68:71]
	v_mfma_f32_16x16x32_bf16 v[64:67], v[174:177], v[206:209], v[64:67]
	v_mfma_f32_16x16x32_bf16 v[108:111], v[170:173], v[186:189], v[108:111]
	v_mfma_f32_16x16x32_bf16 v[104:107], v[178:181], v[186:189], v[104:107]
	v_mfma_f32_16x16x32_bf16 v[100:103], v[170:173], v[194:197], v[100:103]
	v_mfma_f32_16x16x32_bf16 v[92:95], v[178:181], v[194:197], v[92:95]
	v_mfma_f32_16x16x32_bf16 v[84:87], v[170:173], v[202:205], v[84:87]
	v_mfma_f32_16x16x32_bf16 v[76:79], v[178:181], v[202:205], v[76:79]
	v_mfma_f32_16x16x32_bf16 v[68:71], v[170:173], v[214:217], v[68:71]
	v_mfma_f32_16x16x32_bf16 v[64:67], v[178:181], v[214:217], v[64:67]
	s_barrier
; #define PG8_STAGE(bufoff, gbase, voff) do { _Pragma("unroll") for (int _i = 0; _i < 2; ++_i) \
;         __builtin_amdgcn_global_load_lds((const unsigned*)((const char*)(gbase) + (voff)[_i]), (PG8_LAS unsigned*)(lds + (bufoff) + ldsw + _i * 8192), 16, 0, 0); } while (0)
; #define PG8_LDA(dst, b, h) do { _Pragma("unroll") for (int m = 0; m < 4; ++m) _Pragma("unroll") for (int k = 0; k < 2; ++k) dst[m][k] = *(const PG8_LAS bf16x8*)(lds + PG8_SA(b, h) + aoff + m * 2048 + k * 1024); } while (0)
; #define PG8_MMA(ai, bj, At, Bt) do { __builtin_amdgcn_s_setprio(1); _Pragma("unroll") for (int m = 0; m < 4; ++m) _Pragma("unroll") for (int n = 0; n < 2; ++n) _Pragma("unroll") for (int k = 0; k < 2; ++k) \
;         acc[ai][bj][m][n] = __builtin_amdgcn_mfma_f32_16x16x32_bf16(Bt[n][k], At[m][k], acc[ai][bj][m][n], 0, 0, 0); __builtin_amdgcn_s_setprio(0); } while (0)
; #define PG8_WAIT_V(n) asm volatile("s_waitcnt vmcnt(" #n ")" ::: "memory")
; #define PG8_WAIT_L(n) asm volatile("s_waitcnt lgkmcnt(" #n ")" ::: "memory")
; #define PG8_BAR __builtin_amdgcn_s_barrier()
; #define PG8_SCHED __builtin_amdgcn_sched_barrier(0)
;     __device__ __forceinline__ void operator()(const f32x4 (&acc)[2][2][4][2], const Unit& u, int wr, int wc, int fr, int fq) const {
;         const int row0 = u.pm * BM + wr * 64 + fr, col0 = u.pn * BM + wc * 32 + 8 * fq;
; #pragma unroll
;         for (int ai = 0; ai < 2; ++ai) { u32x4 gw[4][2], pw[4][2];
; #pragma unroll
;             for (int m = 0; m < 4; ++m) { const size_t off = (size_t)(row0 + ai * HALF + m * 16) * 2048 + col0;
; #pragma unroll
;                 for (int bj = 0; bj < 2; ++bj) { gw[m][bj] = *(const u32x4*)(G + off + bj * HALF); if (PASS == 1) pw[m][bj] = *(const u32x4*)(MIX + off + bj * HALF); } }
; template <class Epi, class Sched, bool ALIGN_EPI = false, bool SP2 = false>
; __device__ __forceinline__ void gemm_phase(PG8_LAS unsigned char* lds, const Gemm g, const Sched& S, const Epi& E) {
;     ...
;             PG8_LDA(At, 1, 1); PG8_STAGE(PG8_SB(1, 0), b3, voffB); PG8_STAGE(PG8_SB(1, 1), b3 + hstep, voffB); PG8_STAGE(PG8_SA(1, 0), a3, voffA);
;             PG8_WAIT_V(8); PG8_WAIT_L(0); PG8_BAR; PG8_MMA(1, 0, At, B0); PG8_MMA(1, 1, At, B1); PG8_BAR; PG8_SCHED;
	s_add_i32 s50, s70, s53
	s_add_u32 s82, s48, 0x80
	s_addc_u32 s83, s49, 0
	s_mov_b32 m0, s50
	ds_read_b128 v[182:185], v157 offset:49152
	ds_read_b128 v[186:189], v157 offset:50176
	ds_read_b128 v[190:193], v157 offset:51200
	ds_read_b128 v[194:197], v157 offset:52224
	ds_read_b128 v[198:201], v157 offset:53248
	ds_read_b128 v[202:205], v157 offset:54272
	ds_read_b128 v[206:209], v157 offset:55296
	ds_read_b128 v[214:217], v157 offset:56320
	global_load_lds_dwordx4 v130, s[82:83]
	s_add_i32 m0, s50, 0x2000
	s_add_u32 s48, s48, 0x40080
	s_addc_u32 s49, s49, 0
	s_add_i32 s50, s71, s53
	global_load_lds_dwordx4 v134, s[82:83]
	s_mov_b32 m0, s50
	s_nop 0
	global_load_lds_dwordx4 v130, s[48:49]
	s_add_i32 m0, s50, 0x2000
	s_nop 0
	global_load_lds_dwordx4 v134, s[48:49]
	s_mov_b32 m0, s58
	s_nop 0
	global_load_lds_dwordx4 v128, s[80:81]
	s_mov_b32 m0, s59
	s_nop 0
	global_load_lds_dwordx4 v132, s[80:81]
	s_waitcnt vmcnt(8)
	s_waitcnt lgkmcnt(0)
	s_barrier
	v_mfma_f32_16x16x32_bf16 v[60:63], v[144:147], v[182:185], v[60:63]
	v_mfma_f32_16x16x32_bf16 v[56:59], v[158:161], v[182:185], v[56:59]
	v_mfma_f32_16x16x32_bf16 v[48:51], v[144:147], v[190:193], v[48:51]
	v_mfma_f32_16x16x32_bf16 v[40:43], v[158:161], v[190:193], v[40:43]
	v_mfma_f32_16x16x32_bf16 v[32:35], v[144:147], v[198:201], v[32:35]
	v_mfma_f32_16x16x32_bf16 v[24:27], v[158:161], v[198:201], v[24:27]
	v_mfma_f32_16x16x32_bf16 v[16:19], v[144:147], v[206:209], v[16:19]
	v_mfma_f32_16x16x32_bf16 v[8:11], v[158:161], v[206:209], v[8:11]
	v_mfma_f32_16x16x32_bf16 v[60:63], v[148:151], v[186:189], v[60:63]
	v_mfma_f32_16x16x32_bf16 v[56:59], v[162:165], v[186:189], v[56:59]
	v_mfma_f32_16x16x32_bf16 v[48:51], v[148:151], v[194:197], v[48:51]
	v_mfma_f32_16x16x32_bf16 v[40:43], v[162:165], v[194:197], v[40:43]
	v_mfma_f32_16x16x32_bf16 v[32:35], v[148:151], v[202:205], v[32:35]
	v_mfma_f32_16x16x32_bf16 v[24:27], v[162:165], v[202:205], v[24:27]
	v_mfma_f32_16x16x32_bf16 v[16:19], v[148:151], v[214:217], v[16:19]
	v_mfma_f32_16x16x32_bf16 v[8:11], v[162:165], v[214:217], v[8:11]
	v_mfma_f32_16x16x32_bf16 v[52:55], v[166:169], v[182:185], v[52:55]
	v_mfma_f32_16x16x32_bf16 v[44:47], v[174:177], v[182:185], v[44:47]
	v_mfma_f32_16x16x32_bf16 v[36:39], v[166:169], v[190:193], v[36:39]
	v_mfma_f32_16x16x32_bf16 v[28:31], v[174:177], v[190:193], v[28:31]
	v_mfma_f32_16x16x32_bf16 v[20:23], v[166:169], v[198:201], v[20:23]
	v_mfma_f32_16x16x32_bf16 v[12:15], v[174:177], v[198:201], v[12:15]
	v_mfma_f32_16x16x32_bf16 v[4:7], v[166:169], v[206:209], v[4:7]
	v_mfma_f32_16x16x32_bf16 v[0:3], v[174:177], v[206:209], v[0:3]
	v_mfma_f32_16x16x32_bf16 v[52:55], v[170:173], v[186:189], v[52:55]
	v_mfma_f32_16x16x32_bf16 v[44:47], v[178:181], v[186:189], v[44:47]
	v_mfma_f32_16x16x32_bf16 v[36:39], v[170:173], v[194:197], v[36:39]
	v_mfma_f32_16x16x32_bf16 v[28:31], v[178:181], v[194:197], v[28:31]
	v_mfma_f32_16x16x32_bf16 v[20:23], v[170:173], v[202:205], v[20:23]
	v_mfma_f32_16x16x32_bf16 v[12:15], v[178:181], v[202:205], v[12:15]
	v_mfma_f32_16x16x32_bf16 v[4:7], v[170:173], v[214:217], v[4:7]
	v_mfma_f32_16x16x32_bf16 v[0:3], v[178:181], v[214:217], v[0:3]
	s_barrier
	s_add_i32 s69, s69, 2
	s_add_u32 s46, s46, 0x100
	s_addc_u32 s47, s47, 0
	s_add_u32 s67, s67, 0x100
	s_addc_u32 s68, s68, 0
	s_cmp_gt_u32 s69, 13
	s_cbranch_scc0 .LBB0_735
	v_lshl_add_u32 v150, s44, 8, v152
	v_lshl_or_b32 v144, s64, 8, v154
	v_ashrrev_i32_e32 v145, 31, v144
	v_or_b32_e32 v166, 16, v150
	v_lshlrev_b64 v[144:145], 1, v[144:145]
	v_ashrrev_i32_e32 v151, 31, v150
	v_ashrrev_i32_e32 v167, 31, v166
	v_lshl_add_u64 v[146:147], s[12:13], 0, v[144:145]
	v_lshlrev_b64 v[148:149], 12, v[150:151]
	v_lshlrev_b64 v[178:179], 12, v[166:167]
	v_lshl_add_u64 v[162:163], v[146:147], 0, v[148:149]
	v_lshl_add_u64 v[170:171], v[146:147], 0, v[178:179]
	global_load_dwordx4 v[158:161], v[162:163], off
	s_nop 0
	global_load_dwordx4 v[162:165], v[162:163], off offset:256
	s_nop 0
	global_load_dwordx4 v[166:169], v[170:171], off
	s_nop 0
	global_load_dwordx4 v[170:173], v[170:171], off offset:256
	v_or_b32_e32 v174, 32, v150
	v_ashrrev_i32_e32 v175, 31, v174
	v_lshlrev_b64 v[190:191], 12, v[174:175]
	v_lshl_add_u64 v[180:181], v[146:147], 0, v[190:191]
	global_load_dwordx4 v[174:177], v[180:181], off
	v_or_b32_e32 v150, 48, v150
	v_ashrrev_i32_e32 v151, 31, v150
	v_lshlrev_b64 v[150:151], 12, v[150:151]
	v_lshl_add_u64 v[182:183], s[14:15], 0, v[148:149]
	v_lshl_add_u64 v[186:187], v[146:147], 0, v[150:151]
	v_lshl_add_u64 v[192:193], v[182:183], 0, v[144:145]
	v_lshl_add_u64 v[194:195], s[14:15], 0, v[178:179]
	global_load_dwordx4 v[178:181], v[180:181], off offset:256
	s_nop 0
	global_load_dwordx4 v[182:185], v[186:187], off
	s_nop 0
	global_load_dwordx4 v[186:189], v[186:187], off offset:256
	v_lshl_add_u64 v[194:195], v[194:195], 0, v[144:145]
	s_and_b64 vcc, exec, s[10:11]
	s_mov_b32 s64, s36
	s_mov_b32 s44, s38
	s_mov_b64 s[48:49], s[42:43]
	s_mov_b64 s[46:47], s[40:41]
	s_waitcnt vmcnt(0)
; __device__ __forceinline__ float bf_lo(unsigned w) { return __uint_as_float(w << 16); }
; __device__ __forceinline__ float bf_hi(unsigned w) { return __uint_as_float(w & 0xffff0000u); }
; __device__ __forceinline__ u32x4 pack8(const f32x4 a, const f32x4 b) { u32x4 w; w.x = cvt_pk_bf16(a[0], a[1]); w.y = cvt_pk_bf16(a[2], a[3]); w.z = cvt_pk_bf16(b[0], b[1]); w.w = cvt_pk_bf16(b[2], b[3]); return w; }
;     __device__ __forceinline__ void operator()(const f32x4 (&acc)[2][2][4][2], const Unit& u, int wr, int wc, int fr, int fq) const {
;         const int row0 = u.pm * BM + wr * 64 + fr, col0 = u.pn * BM + wc * 32 + 8 * fq;
; #pragma unroll
;         for (int ai = 0; ai < 2; ++ai) { u32x4 gw[4][2], pw[4][2];
; #pragma unroll
;             for (int m = 0; m < 4; ++m) { const size_t off = (size_t)(row0 + ai * HALF + m * 16) * 2048 + col0;
; #pragma unroll
;                 for (int bj = 0; bj < 2; ++bj) { gw[m][bj] = *(const u32x4*)(G + off + bj * HALF); if (PASS == 1) pw[m][bj] = *(const u32x4*)(MIX + off + bj * HALF); } }
; #pragma unroll
;             for (int m = 0; m < 4; ++m) { const size_t off = (size_t)(row0 + ai * HALF + m * 16) * 2048 + col0;
; #pragma unroll
;                 for (int bj = 0; bj < 2; ++bj) { const u32x4 g4 = gw[m][bj];
;                     f32x4 v0 = (f32x4){bf_lo(g4.x), bf_hi(g4.x), bf_lo(g4.y), bf_hi(g4.y)} * acc[ai][bj][m][0], v1 = (f32x4){bf_lo(g4.z), bf_hi(g4.z), bf_lo(g4.w), bf_hi(g4.w)} * acc[ai][bj][m][1];
;                     if (PASS == 1) { const u32x4 p4 = pw[m][bj]; v0 += (f32x4){bf_lo(p4.x), bf_hi(p4.x), bf_lo(p4.y), bf_hi(p4.y)}; v1 += (f32x4){bf_lo(p4.z), bf_hi(p4.z), bf_lo(p4.w), bf_hi(p4.w)}; }
;                     *(u32x4*)(MIX + off + bj * HALF) = pack8(v0, v1); } } }
	v_lshlrev_b32_e32 v196, 16, v158
	v_and_b32_e32 v197, 0xffff0000, v158
	v_lshlrev_b32_e32 v158, 16, v159
	v_and_b32_e32 v159, 0xffff0000, v159
	v_lshlrev_b32_e32 v198, 16, v160
	v_and_b32_e32 v199, 0xffff0000, v160
	v_lshlrev_b32_e32 v160, 16, v161
	v_and_b32_e32 v161, 0xffff0000, v161
	v_lshlrev_b32_e32 v200, 16, v162
	v_and_b32_e32 v201, 0xffff0000, v162
	v_lshlrev_b32_e32 v162, 16, v163
	v_and_b32_e32 v163, 0xffff0000, v163
	v_lshlrev_b32_e32 v202, 16, v164
	v_and_b32_e32 v203, 0xffff0000, v164
	v_lshlrev_b32_e32 v164, 16, v165
	v_and_b32_e32 v165, 0xffff0000, v165
	v_lshlrev_b32_e32 v204, 16, v166
	v_and_b32_e32 v205, 0xffff0000, v166
	v_lshlrev_b32_e32 v166, 16, v167
	v_and_b32_e32 v167, 0xffff0000, v167
	v_lshlrev_b32_e32 v206, 16, v168
	v_and_b32_e32 v207, 0xffff0000, v168
	v_lshlrev_b32_e32 v168, 16, v169
	v_and_b32_e32 v169, 0xffff0000, v169
	v_lshlrev_b32_e32 v208, 16, v170
	v_and_b32_e32 v209, 0xffff0000, v170
	v_lshlrev_b32_e32 v170, 16, v171
	v_and_b32_e32 v171, 0xffff0000, v171
	v_pk_mul_f32 v[126:127], v[126:127], v[158:159]
	v_pk_mul_f32 v[124:125], v[124:125], v[196:197]
	v_pk_mul_f32 v[122:123], v[122:123], v[160:161]
	v_pk_mul_f32 v[120:121], v[120:121], v[198:199]
	v_pk_mul_f32 v[110:111], v[110:111], v[162:163]
	v_pk_mul_f32 v[108:109], v[108:109], v[200:201]
	v_pk_mul_f32 v[158:159], v[106:107], v[164:165]
	v_pk_mul_f32 v[106:107], v[104:105], v[202:203]
	v_pk_mul_f32 v[118:119], v[118:119], v[166:167]
	v_pk_mul_f32 v[116:117], v[116:117], v[204:205]
	v_pk_mul_f32 v[114:115], v[114:115], v[168:169]
	v_pk_mul_f32 v[112:113], v[112:113], v[206:207]
	v_pk_mul_f32 v[160:161], v[102:103], v[170:171]
	v_pk_mul_f32 v[162:163], v[100:101], v[208:209]
	v_cvt_pk_bf16_f32 v100, v124, v125
	v_cvt_pk_bf16_f32 v101, v126, v127
	v_cvt_pk_bf16_f32 v102, v120, v121
	v_cvt_pk_bf16_f32 v103, v122, v123
	v_cvt_pk_bf16_f32 v104, v108, v109
	v_cvt_pk_bf16_f32 v105, v110, v111
	v_cvt_pk_bf16_f32 v106, v106, v107
	v_cvt_pk_bf16_f32 v107, v158, v159
	v_cvt_pk_bf16_f32 v108, v116, v117
	v_cvt_pk_bf16_f32 v109, v118, v119
	v_cvt_pk_bf16_f32 v110, v112, v113
	v_cvt_pk_bf16_f32 v111, v114, v115
	global_store_dwordx4 v[192:193], v[100:103], off
	global_store_dwordx4 v[192:193], v[104:107], off offset:256
	global_store_dwordx4 v[194:195], v[108:111], off
	v_lshlrev_b32_e32 v100, 16, v172
	v_and_b32_e32 v101, 0xffff0000, v172
	v_lshlrev_b32_e32 v102, 16, v173
	v_and_b32_e32 v103, 0xffff0000, v173
	v_pk_mul_f32 v[102:103], v[94:95], v[102:103]
	v_pk_mul_f32 v[94:95], v[92:93], v[100:101]
	v_cvt_pk_bf16_f32 v92, v162, v163
	v_cvt_pk_bf16_f32 v93, v160, v161
	v_cvt_pk_bf16_f32 v94, v94, v95
	v_cvt_pk_bf16_f32 v95, v102, v103
	global_store_dwordx4 v[194:195], v[92:95], off offset:256
	v_lshl_add_u64 v[100:101], v[148:149], 0, s[30:31]
	v_lshl_add_u64 v[102:103], v[148:149], 0, s[34:35]
	v_lshlrev_b32_e32 v92, 16, v174
	v_and_b32_e32 v93, 0xffff0000, v174
	v_lshlrev_b32_e32 v94, 16, v175
	v_and_b32_e32 v95, 0xffff0000, v175
	v_pk_mul_f32 v[94:95], v[98:99], v[94:95]
	v_pk_mul_f32 v[92:93], v[96:97], v[92:93]
	v_lshlrev_b32_e32 v96, 16, v176
	v_and_b32_e32 v97, 0xffff0000, v176
	v_lshlrev_b32_e32 v98, 16, v177
	v_and_b32_e32 v99, 0xffff0000, v177
	v_pk_mul_f32 v[98:99], v[90:91], v[98:99]
	v_pk_mul_f32 v[90:91], v[88:89], v[96:97]
	v_cvt_pk_bf16_f32 v88, v92, v93
	v_lshl_add_u64 v[92:93], s[14:15], 0, v[190:191]
	v_cvt_pk_bf16_f32 v89, v94, v95
	v_cvt_pk_bf16_f32 v90, v90, v91
	v_cvt_pk_bf16_f32 v91, v98, v99
	v_lshl_add_u64 v[92:93], v[92:93], 0, v[144:145]
	global_store_dwordx4 v[92:93], v[88:91], off
	v_lshl_add_u64 v[96:97], v[148:149], 0, s[26:27]
	v_lshl_add_u64 v[98:99], v[148:149], 0, s[28:29]
	v_lshlrev_b32_e32 v88, 16, v178
	v_and_b32_e32 v89, 0xffff0000, v178
	v_lshlrev_b32_e32 v90, 16, v179
	v_and_b32_e32 v91, 0xffff0000, v179
	v_pk_mul_f32 v[86:87], v[86:87], v[90:91]
	v_pk_mul_f32 v[84:85], v[84:85], v[88:89]
	v_lshlrev_b32_e32 v88, 16, v180
	v_and_b32_e32 v89, 0xffff0000, v180
	v_lshlrev_b32_e32 v90, 16, v181
	v_and_b32_e32 v91, 0xffff0000, v181
	v_pk_mul_f32 v[90:91], v[78:79], v[90:91]
	v_pk_mul_f32 v[78:79], v[76:77], v[88:89]
	v_cvt_pk_bf16_f32 v76, v84, v85
	v_cvt_pk_bf16_f32 v77, v86, v87
	v_cvt_pk_bf16_f32 v78, v78, v79
	v_cvt_pk_bf16_f32 v79, v90, v91
	global_store_dwordx4 v[92:93], v[76:79], off offset:256
	s_nop 1
	v_lshlrev_b32_e32 v76, 16, v182
	v_and_b32_e32 v77, 0xffff0000, v182
	v_lshlrev_b32_e32 v78, 16, v183
	v_and_b32_e32 v79, 0xffff0000, v183
	v_pk_mul_f32 v[78:79], v[82:83], v[78:79]
	v_pk_mul_f32 v[76:77], v[80:81], v[76:77]
	v_lshlrev_b32_e32 v80, 16, v184
	v_and_b32_e32 v81, 0xffff0000, v184
	v_lshlrev_b32_e32 v82, 16, v185
	v_and_b32_e32 v83, 0xffff0000, v185
	v_pk_mul_f32 v[82:83], v[74:75], v[82:83]
	v_pk_mul_f32 v[74:75], v[72:73], v[80:81]
	v_cvt_pk_bf16_f32 v72, v76, v77
	v_lshl_add_u64 v[76:77], s[14:15], 0, v[150:151]
	v_cvt_pk_bf16_f32 v73, v78, v79
	v_cvt_pk_bf16_f32 v74, v74, v75
	v_cvt_pk_bf16_f32 v75, v82, v83
	v_lshl_add_u64 v[76:77], v[76:77], 0, v[144:145]
	global_store_dwordx4 v[76:77], v[72:75], off
	s_nop 1
	v_lshlrev_b32_e32 v72, 16, v186
	v_and_b32_e32 v73, 0xffff0000, v186
	v_lshlrev_b32_e32 v74, 16, v187
	v_and_b32_e32 v75, 0xffff0000, v187
	v_pk_mul_f32 v[70:71], v[70:71], v[74:75]
	v_pk_mul_f32 v[68:69], v[68:69], v[72:73]
	v_lshlrev_b32_e32 v72, 16, v188
	v_and_b32_e32 v73, 0xffff0000, v188
	v_lshlrev_b32_e32 v74, 16, v189
	v_and_b32_e32 v75, 0xffff0000, v189
	v_pk_mul_f32 v[74:75], v[66:67], v[74:75]
	v_pk_mul_f32 v[66:67], v[64:65], v[72:73]
	v_cvt_pk_bf16_f32 v64, v68, v69
	v_cvt_pk_bf16_f32 v65, v70, v71
	v_cvt_pk_bf16_f32 v66, v66, v67
	v_cvt_pk_bf16_f32 v67, v74, v75
	global_store_dwordx4 v[76:77], v[64:67], off offset:256
	s_nop 1
	v_lshl_add_u64 v[64:65], v[146:147], 0, v[96:97]
	global_load_dwordx4 v[68:71], v[64:65], off
	global_load_dwordx4 v[72:75], v[64:65], off offset:256
	v_lshl_add_u64 v[64:65], v[146:147], 0, v[98:99]
	global_load_dwordx4 v[76:79], v[64:65], off
	global_load_dwordx4 v[80:83], v[64:65], off offset:256
	v_lshl_add_u64 v[64:65], v[146:147], 0, v[100:101]
	global_load_dwordx4 v[84:87], v[64:65], off
	global_load_dwordx4 v[88:91], v[64:65], off offset:256
	v_lshl_add_u64 v[64:65], v[146:147], 0, v[102:103]
	global_load_dwordx4 v[92:95], v[64:65], off
	s_nop 0
	global_load_dwordx4 v[64:67], v[64:65], off offset:256
	s_waitcnt vmcnt(7)
; __device__ __forceinline__ float bf_lo(unsigned w) { return __uint_as_float(w << 16); }
; __device__ __forceinline__ float bf_hi(unsigned w) { return __uint_as_float(w & 0xffff0000u); }
; __device__ __forceinline__ u32x4 pack8(const f32x4 a, const f32x4 b) { u32x4 w; w.x = cvt_pk_bf16(a[0], a[1]); w.y = cvt_pk_bf16(a[2], a[3]); w.z = cvt_pk_bf16(b[0], b[1]); w.w = cvt_pk_bf16(b[2], b[3]); return w; }
; #define PG8_WAIT_V(n) asm volatile("s_waitcnt vmcnt(" #n ")" ::: "memory")
; #define PG8_BAR __builtin_amdgcn_s_barrier()
;     __device__ __forceinline__ void operator()(const f32x4 (&acc)[2][2][4][2], const Unit& u, int wr, int wc, int fr, int fq) const {
;     ...
;             for (int m = 0; m < 4; ++m) { const size_t off = (size_t)(row0 + ai * HALF + m * 16) * 2048 + col0;
; #pragma unroll
;                 for (int bj = 0; bj < 2; ++bj) { const u32x4 g4 = gw[m][bj];
;                     f32x4 v0 = (f32x4){bf_lo(g4.x), bf_hi(g4.x), bf_lo(g4.y), bf_hi(g4.y)} * acc[ai][bj][m][0], v1 = (f32x4){bf_lo(g4.z), bf_hi(g4.z), bf_lo(g4.w), bf_hi(g4.w)} * acc[ai][bj][m][1];
;                     if (PASS == 1) { const u32x4 p4 = pw[m][bj]; v0 += (f32x4){bf_lo(p4.x), bf_hi(p4.x), bf_lo(p4.y), bf_hi(p4.y)}; v1 += (f32x4){bf_lo(p4.z), bf_hi(p4.z), bf_lo(p4.w), bf_hi(p4.w)}; }
;                     *(u32x4*)(MIX + off + bj * HALF) = pack8(v0, v1); } } }
; template <class Epi, class Sched, bool ALIGN_EPI = false, bool SP2 = false>
; __device__ __forceinline__ void gemm_phase(PG8_LAS unsigned char* lds, const Gemm g, const Sched& S, const Epi& E) {
;     ...
;         if constexpr (!Epi::AFTER_DRAIN) { E(acc, cur, wr, wc, fr, fq); S.done(cur); }
;         if (!has_next) break;
; #pragma unroll
;         for (int a = 0; a < 2; ++a)
; #pragma unroll
;             for (int b = 0; b < 2; ++b)
; #pragma unroll
;                 for (int m = 0; m < 4; ++m)
; #pragma unroll
;                     for (int n = 0; n < 2; ++n) acc[a][b][m][n] = (f32x4){0.f, 0.f, 0.f, 0.f};
;         cur = nxt; cA = nA; cB = nB; ++ui;
;         if constexpr (ALIGN_EPI) { if (wr == 1) PG8_BAR; }
;     }
;     PG8_WAIT_V(0);
;     if constexpr (!ALIGN_EPI) { if (wr == 0) PG8_BAR; }
;     PG8_BAR;
	v_lshlrev_b32_e32 v104, 16, v68
	v_and_b32_e32 v105, 0xffff0000, v68
	v_lshlrev_b32_e32 v68, 16, v69
	v_and_b32_e32 v69, 0xffff0000, v69
	v_pk_mul_f32 v[62:63], v[62:63], v[68:69]
	v_pk_mul_f32 v[60:61], v[60:61], v[104:105]
	v_lshlrev_b32_e32 v68, 16, v70
	v_and_b32_e32 v69, 0xffff0000, v70
	v_lshlrev_b32_e32 v70, 16, v71
	v_and_b32_e32 v71, 0xffff0000, v71
	v_pk_mul_f32 v[70:71], v[58:59], v[70:71]
	v_pk_mul_f32 v[58:59], v[56:57], v[68:69]
	v_cvt_pk_bf16_f32 v56, v60, v61
	v_lshl_add_u64 v[60:61], s[14:15], 0, v[96:97]
	v_cvt_pk_bf16_f32 v57, v62, v63
	v_cvt_pk_bf16_f32 v58, v58, v59
	v_cvt_pk_bf16_f32 v59, v70, v71
	v_lshl_add_u64 v[60:61], v[60:61], 0, v[144:145]
	global_store_dwordx4 v[60:61], v[56:59], off
	s_waitcnt vmcnt(7)
	s_nop 0
	v_lshlrev_b32_e32 v56, 16, v72
	v_and_b32_e32 v57, 0xffff0000, v72
	v_lshlrev_b32_e32 v58, 16, v73
	v_and_b32_e32 v59, 0xffff0000, v73
	v_pk_mul_f32 v[54:55], v[54:55], v[58:59]
	v_pk_mul_f32 v[52:53], v[52:53], v[56:57]
	v_lshlrev_b32_e32 v56, 16, v74
	v_and_b32_e32 v57, 0xffff0000, v74
	v_lshlrev_b32_e32 v58, 16, v75
	v_and_b32_e32 v59, 0xffff0000, v75
	v_pk_mul_f32 v[58:59], v[46:47], v[58:59]
	v_pk_mul_f32 v[46:47], v[44:45], v[56:57]
	v_cvt_pk_bf16_f32 v44, v52, v53
	v_cvt_pk_bf16_f32 v45, v54, v55
	v_cvt_pk_bf16_f32 v46, v46, v47
	v_cvt_pk_bf16_f32 v47, v58, v59
	global_store_dwordx4 v[60:61], v[44:47], off offset:256
	s_waitcnt vmcnt(7)
	s_nop 0
	v_lshlrev_b32_e32 v44, 16, v76
	v_and_b32_e32 v45, 0xffff0000, v76
	v_lshlrev_b32_e32 v46, 16, v77
	v_and_b32_e32 v47, 0xffff0000, v77
	v_pk_mul_f32 v[46:47], v[50:51], v[46:47]
	v_pk_mul_f32 v[44:45], v[48:49], v[44:45]
	v_lshlrev_b32_e32 v48, 16, v78
	v_and_b32_e32 v49, 0xffff0000, v78
	v_lshlrev_b32_e32 v50, 16, v79
	v_and_b32_e32 v51, 0xffff0000, v79
	v_pk_mul_f32 v[50:51], v[42:43], v[50:51]
	v_pk_mul_f32 v[42:43], v[40:41], v[48:49]
	v_cvt_pk_bf16_f32 v40, v44, v45
	v_lshl_add_u64 v[44:45], s[14:15], 0, v[98:99]
	v_cvt_pk_bf16_f32 v41, v46, v47
	v_cvt_pk_bf16_f32 v42, v42, v43
	v_cvt_pk_bf16_f32 v43, v50, v51
	v_lshl_add_u64 v[44:45], v[44:45], 0, v[144:145]
	global_store_dwordx4 v[44:45], v[40:43], off
	s_waitcnt vmcnt(7)
	s_nop 0
	v_lshlrev_b32_e32 v40, 16, v80
	v_and_b32_e32 v41, 0xffff0000, v80
	v_lshlrev_b32_e32 v42, 16, v81
	v_and_b32_e32 v43, 0xffff0000, v81
	v_pk_mul_f32 v[38:39], v[38:39], v[42:43]
	v_pk_mul_f32 v[36:37], v[36:37], v[40:41]
	v_lshlrev_b32_e32 v40, 16, v82
	v_and_b32_e32 v41, 0xffff0000, v82
	v_lshlrev_b32_e32 v42, 16, v83
	v_and_b32_e32 v43, 0xffff0000, v83
	v_pk_mul_f32 v[42:43], v[30:31], v[42:43]
	v_pk_mul_f32 v[30:31], v[28:29], v[40:41]
	v_cvt_pk_bf16_f32 v28, v36, v37
	v_cvt_pk_bf16_f32 v29, v38, v39
	v_cvt_pk_bf16_f32 v30, v30, v31
	v_cvt_pk_bf16_f32 v31, v42, v43
	global_store_dwordx4 v[44:45], v[28:31], off offset:256
	s_waitcnt vmcnt(7)
	s_nop 0
	v_lshlrev_b32_e32 v28, 16, v84
	v_and_b32_e32 v29, 0xffff0000, v84
	v_lshlrev_b32_e32 v30, 16, v85
	v_and_b32_e32 v31, 0xffff0000, v85
	v_pk_mul_f32 v[30:31], v[34:35], v[30:31]
	v_pk_mul_f32 v[28:29], v[32:33], v[28:29]
	v_lshlrev_b32_e32 v32, 16, v86
	v_and_b32_e32 v33, 0xffff0000, v86
	v_lshlrev_b32_e32 v34, 16, v87
	v_and_b32_e32 v35, 0xffff0000, v87
	v_pk_mul_f32 v[34:35], v[26:27], v[34:35]
	v_pk_mul_f32 v[26:27], v[24:25], v[32:33]
	v_cvt_pk_bf16_f32 v24, v28, v29
	v_lshl_add_u64 v[28:29], s[14:15], 0, v[100:101]
	v_cvt_pk_bf16_f32 v25, v30, v31
	v_cvt_pk_bf16_f32 v26, v26, v27
	v_cvt_pk_bf16_f32 v27, v34, v35
	v_lshl_add_u64 v[28:29], v[28:29], 0, v[144:145]
	global_store_dwordx4 v[28:29], v[24:27], off
	s_waitcnt vmcnt(7)
	s_nop 0
	v_lshlrev_b32_e32 v24, 16, v88
	v_and_b32_e32 v25, 0xffff0000, v88
	v_lshlrev_b32_e32 v26, 16, v89
	v_and_b32_e32 v27, 0xffff0000, v89
	v_pk_mul_f32 v[22:23], v[22:23], v[26:27]
	v_pk_mul_f32 v[20:21], v[20:21], v[24:25]
	v_lshlrev_b32_e32 v24, 16, v90
	v_and_b32_e32 v25, 0xffff0000, v90
	v_lshlrev_b32_e32 v26, 16, v91
	v_and_b32_e32 v27, 0xffff0000, v91
	v_pk_mul_f32 v[26:27], v[14:15], v[26:27]
	v_pk_mul_f32 v[14:15], v[12:13], v[24:25]
	v_cvt_pk_bf16_f32 v12, v20, v21
	v_cvt_pk_bf16_f32 v13, v22, v23
	v_cvt_pk_bf16_f32 v14, v14, v15
	v_cvt_pk_bf16_f32 v15, v26, v27
	global_store_dwordx4 v[28:29], v[12:15], off offset:256
	s_waitcnt vmcnt(7)
	s_nop 0
	v_lshlrev_b32_e32 v12, 16, v92
	v_and_b32_e32 v13, 0xffff0000, v92
	v_lshlrev_b32_e32 v14, 16, v93
	v_and_b32_e32 v15, 0xffff0000, v93
	v_pk_mul_f32 v[14:15], v[18:19], v[14:15]
	v_pk_mul_f32 v[12:13], v[16:17], v[12:13]
	v_lshlrev_b32_e32 v16, 16, v94
	v_and_b32_e32 v17, 0xffff0000, v94
	v_lshlrev_b32_e32 v18, 16, v95
	v_and_b32_e32 v19, 0xffff0000, v95
	v_pk_mul_f32 v[18:19], v[10:11], v[18:19]
	v_pk_mul_f32 v[10:11], v[8:9], v[16:17]
	v_cvt_pk_bf16_f32 v8, v12, v13
	v_lshl_add_u64 v[12:13], s[14:15], 0, v[102:103]
	v_cvt_pk_bf16_f32 v9, v14, v15
	v_cvt_pk_bf16_f32 v10, v10, v11
	v_cvt_pk_bf16_f32 v11, v18, v19
	v_lshl_add_u64 v[12:13], v[12:13], 0, v[144:145]
	global_store_dwordx4 v[12:13], v[8:11], off
	s_waitcnt vmcnt(7)
	s_nop 0
	v_lshlrev_b32_e32 v8, 16, v64
	v_and_b32_e32 v9, 0xffff0000, v64
	v_lshlrev_b32_e32 v10, 16, v65
	v_and_b32_e32 v11, 0xffff0000, v65
	v_pk_mul_f32 v[6:7], v[6:7], v[10:11]
	v_pk_mul_f32 v[4:5], v[4:5], v[8:9]
	v_lshlrev_b32_e32 v8, 16, v66
	v_and_b32_e32 v9, 0xffff0000, v66
	v_lshlrev_b32_e32 v10, 16, v67
	v_and_b32_e32 v11, 0xffff0000, v67
	v_pk_mul_f32 v[10:11], v[2:3], v[10:11]
	v_pk_mul_f32 v[2:3], v[0:1], v[8:9]
	v_cvt_pk_bf16_f32 v0, v4, v5
	v_cvt_pk_bf16_f32 v1, v6, v7
	v_cvt_pk_bf16_f32 v2, v2, v3
	v_cvt_pk_bf16_f32 v3, v10, v11
	global_store_dwordx4 v[12:13], v[0:3], off offset:256
	s_cbranch_vccz .LBB0_728
	s_waitcnt vmcnt(0)
	s_cmpk_gt_u32 s3, 0xff
	s_cbranch_scc1 .LBB0_739
	s_barrier

; #define PG8_STAGE(bufoff, gbase, voff) do { _Pragma("unroll") for (int _i = 0; _i < 2; ++_i) \
;         __builtin_amdgcn_global_load_lds((const unsigned*)((const char*)(gbase) + (voff)[_i]), (PG8_LAS unsigned*)(lds + (bufoff) + ldsw + _i * 8192), 16, 0, 0); } while (0)
; #define PG8_LDA(dst, b, h) do { _Pragma("unroll") for (int m = 0; m < 4; ++m) _Pragma("unroll") for (int k = 0; k < 2; ++k) dst[m][k] = *(const PG8_LAS bf16x8*)(lds + PG8_SA(b, h) + aoff + m * 2048 + k * 1024); } while (0)
; #define PG8_LDB(dst, b, h) do { _Pragma("unroll") for (int n = 0; n < 2; ++n) _Pragma("unroll") for (int k = 0; k < 2; ++k) dst[n][k] = *(const PG8_LAS bf16x8*)(lds + PG8_SB(b, h) + boff + n * 2048 + k * 1024); } while (0)
; #define PG8_MMA(ai, bj, At, Bt) do { __builtin_amdgcn_s_setprio(1); _Pragma("unroll") for (int m = 0; m < 4; ++m) _Pragma("unroll") for (int n = 0; n < 2; ++n) _Pragma("unroll") for (int k = 0; k < 2; ++k) \
;         acc[ai][bj][m][n] = __builtin_amdgcn_mfma_f32_16x16x32_bf16(Bt[n][k], At[m][k], acc[ai][bj][m][n], 0, 0, 0); __builtin_amdgcn_s_setprio(0); } while (0)
; #define PG8_WAIT_V(n) asm volatile("s_waitcnt vmcnt(" #n ")" ::: "memory")
; #define PG8_WAIT_L(n) asm volatile("s_waitcnt lgkmcnt(" #n ")" ::: "memory")
; #define PG8_BAR __builtin_amdgcn_s_barrier()
; template <class Epi, class Sched, bool ALIGN_EPI = false, bool SP2 = false>
; __device__ __forceinline__ void gemm_phase(PG8_LAS unsigned char* lds, const Gemm g, const Sched& S, const Epi& E) {
;     ...
;         const bool has_next = S.next(ui + 1, nxt);
;         const char* nA = has_next ? (const char*)g.A + (size_t)nxt.pm * tstep : cA; const char* nB = has_next ? (const char*)g.Bt + (size_t)nxt.pn * tstep : cB;
;         for (int t = 0; t < nt; t += 2) {
;             const bool last = (t == nt - 2);
;             const char* a1 = cA + (size_t)(t + 1) * kstep;
;             const char* a2 = last ? nA : cA + (size_t)(t + 2) * kstep; const char* b2 = last ? nB : cB + (size_t)(t + 2) * kstep;
;             const char* a3 = a2 + kstep; const char* b3 = b2 + kstep;
;             if (last && has_next) S.a_ready(nxt);
;             if constexpr (SP2) {
;             PG8_LDB(B0, 0, 0); PG8_LDB(B1, 0, 1); PG8_SCHED; PG8_LDA(At, 0, 0); PG8_STAGE(PG8_SA(1, 1), a1 + hstep, voffA);
;             PG8_WAIT_V(8); PG8_WAIT_L(0); PG8_BAR; PG8_MMA(0, 0, At, B0); PG8_MMA(0, 1, At, B1); PG8_BAR; PG8_SCHED;
.LBB0_754:
	s_ashr_i32 s29, s28, 31
	v_cmp_lt_i64_e32 vcc, s[30:31], v[160:161]
	s_lshl_b64 s[30:31], s[28:29], 19
	s_add_u32 s30, s9, s30
	s_addc_u32 s31, s22, s31
	s_and_b64 s[34:35], vcc, exec
	s_cselect_b32 s29, s31, s39
	s_cselect_b32 s57, s30, s38
	s_ashr_i32 s27, s26, 31
	s_lshl_b64 s[34:35], s[26:27], 19
	s_add_u32 s34, s23, s34
	s_addc_u32 s35, s44, s35
	s_and_b64 s[42:43], vcc, exec
	s_cselect_b32 s27, s35, s41
	s_cselect_b32 s58, s34, s40
	s_add_u32 s38, s38, 0x40080
	s_addc_u32 s39, s39, 0
	s_add_u32 s59, s40, 0x100
	s_addc_u32 s60, s41, 0
	s_mov_b32 s61, -2
	ds_read_b128 v[128:131], v177
	ds_read_b128 v[132:135], v177 offset:1024
	ds_read_b128 v[136:139], v177 offset:2048
	ds_read_b128 v[140:143], v177 offset:3072
	ds_read_b128 v[144:147], v178
	ds_read_b128 v[164:167], v178 offset:1024
	ds_read_b128 v[168:171], v178 offset:2048
	ds_read_b128 v[180:183], v178 offset:3072
	s_add_u32 s40, s38, 0xfffc0080
	s_addc_u32 s41, s39, -1
	s_cmp_eq_u32 s61, 12
	s_cselect_b32 s43, s29, s41
	s_cselect_b32 s42, s57, s40
	s_cselect_b32 s41, s27, s60
	s_cselect_b32 s40, s58, s59
	s_add_i32 m0, s37, 0xc000
	ds_read_b128 v[184:187], v179
	ds_read_b128 v[188:191], v179 offset:1024
	ds_read_b128 v[192:195], v179 offset:2048
	ds_read_b128 v[196:199], v179 offset:3072
	ds_read_b128 v[200:203], v179 offset:4096
	ds_read_b128 v[204:207], v179 offset:5120
	ds_read_b128 v[208:211], v179 offset:6144
	ds_read_b128 v[214:217], v179 offset:7168
	global_load_lds_dwordx4 v156, s[38:39]
	s_add_i32 m0, s37, 0xe000
	s_nop 0
	global_load_lds_dwordx4 v158, s[38:39]
	s_waitcnt vmcnt(8)
	s_waitcnt lgkmcnt(0)
	s_barrier
	v_mfma_f32_16x16x32_bf16 v[124:127], v[128:131], v[184:187], 0
	v_mfma_f32_16x16x32_bf16 v[120:123], v[136:139], v[184:187], 0
	v_mfma_f32_16x16x32_bf16 v[108:111], v[128:131], v[192:195], 0
	v_mfma_f32_16x16x32_bf16 v[104:107], v[136:139], v[192:195], 0
	v_mfma_f32_16x16x32_bf16 v[92:95], v[128:131], v[200:203], 0
	v_mfma_f32_16x16x32_bf16 v[88:91], v[136:139], v[200:203], 0
	v_mfma_f32_16x16x32_bf16 v[76:79], v[128:131], v[208:211], 0
	v_mfma_f32_16x16x32_bf16 v[72:75], v[136:139], v[208:211], 0
	v_mfma_f32_16x16x32_bf16 v[124:127], v[132:135], v[188:191], v[124:127]
	v_mfma_f32_16x16x32_bf16 v[120:123], v[140:143], v[188:191], v[120:123]
	v_mfma_f32_16x16x32_bf16 v[108:111], v[132:135], v[196:199], v[108:111]
	v_mfma_f32_16x16x32_bf16 v[104:107], v[140:143], v[196:199], v[104:107]
	v_mfma_f32_16x16x32_bf16 v[92:95], v[132:135], v[204:207], v[92:95]
	v_mfma_f32_16x16x32_bf16 v[88:91], v[140:143], v[204:207], v[88:91]
	v_mfma_f32_16x16x32_bf16 v[76:79], v[132:135], v[214:217], v[76:79]
	v_mfma_f32_16x16x32_bf16 v[72:75], v[140:143], v[214:217], v[72:75]
	v_mfma_f32_16x16x32_bf16 v[116:119], v[144:147], v[184:187], 0
	v_mfma_f32_16x16x32_bf16 v[112:115], v[168:171], v[184:187], 0
	v_mfma_f32_16x16x32_bf16 v[100:103], v[144:147], v[192:195], 0
	v_mfma_f32_16x16x32_bf16 v[96:99], v[168:171], v[192:195], 0
	v_mfma_f32_16x16x32_bf16 v[84:87], v[144:147], v[200:203], 0
	v_mfma_f32_16x16x32_bf16 v[80:83], v[168:171], v[200:203], 0
	v_mfma_f32_16x16x32_bf16 v[68:71], v[144:147], v[208:211], 0
	v_mfma_f32_16x16x32_bf16 v[64:67], v[168:171], v[208:211], 0
	v_mfma_f32_16x16x32_bf16 v[116:119], v[164:167], v[188:191], v[116:119]
	v_mfma_f32_16x16x32_bf16 v[112:115], v[180:183], v[188:191], v[112:115]
	v_mfma_f32_16x16x32_bf16 v[100:103], v[164:167], v[196:199], v[100:103]
	v_mfma_f32_16x16x32_bf16 v[96:99], v[180:183], v[196:199], v[96:99]
	v_mfma_f32_16x16x32_bf16 v[84:87], v[164:167], v[204:207], v[84:87]
	v_mfma_f32_16x16x32_bf16 v[80:83], v[180:183], v[204:207], v[80:83]
	v_mfma_f32_16x16x32_bf16 v[68:71], v[164:167], v[214:217], v[68:71]
	v_mfma_f32_16x16x32_bf16 v[64:67], v[180:183], v[214:217], v[64:67]
	s_barrier
	s_add_i32 s62, s54, s45
	s_mov_b32 m0, s62
	ds_read_b128 v[184:187], v179 offset:16384
	ds_read_b128 v[188:191], v179 offset:17408
	ds_read_b128 v[192:195], v179 offset:18432
	ds_read_b128 v[196:199], v179 offset:19456
	ds_read_b128 v[200:203], v179 offset:20480
	ds_read_b128 v[204:207], v179 offset:21504
	ds_read_b128 v[208:211], v179 offset:22528
	ds_read_b128 v[214:217], v179 offset:23552
	global_load_lds_dwordx4 v150, s[40:41]
	s_add_i32 m0, s62, 0x2000
	s_add_u32 s62, s40, 0x40000
	s_addc_u32 s63, s41, 0
	s_add_i32 s64, s55, s45
	global_load_lds_dwordx4 v154, s[40:41]
	s_mov_b32 m0, s64
	s_nop 0
	global_load_lds_dwordx4 v150, s[62:63]
	s_add_i32 m0, s64, 0x2000
	s_nop 0
	global_load_lds_dwordx4 v154, s[62:63]
	s_mov_b32 m0, s37
	s_nop 0
	global_load_lds_dwordx4 v148, s[42:43]
	s_mov_b32 m0, s46
	s_nop 0
	global_load_lds_dwordx4 v152, s[42:43]
	s_waitcnt vmcnt(8)
	s_waitcnt lgkmcnt(0)
	s_barrier
; #define PG8_STAGE(bufoff, gbase, voff) do { _Pragma("unroll") for (int _i = 0; _i < 2; ++_i) \
;         __builtin_amdgcn_global_load_lds((const unsigned*)((const char*)(gbase) + (voff)[_i]), (PG8_LAS unsigned*)(lds + (bufoff) + ldsw + _i * 8192), 16, 0, 0); } while (0)
; #define PG8_LDA(dst, b, h) do { _Pragma("unroll") for (int m = 0; m < 4; ++m) _Pragma("unroll") for (int k = 0; k < 2; ++k) dst[m][k] = *(const PG8_LAS bf16x8*)(lds + PG8_SA(b, h) + aoff + m * 2048 + k * 1024); } while (0)
; #define PG8_LDB(dst, b, h) do { _Pragma("unroll") for (int n = 0; n < 2; ++n) _Pragma("unroll") for (int k = 0; k < 2; ++k) dst[n][k] = *(const PG8_LAS bf16x8*)(lds + PG8_SB(b, h) + boff + n * 2048 + k * 1024); } while (0)
; #define PG8_MMA(ai, bj, At, Bt) do { __builtin_amdgcn_s_setprio(1); _Pragma("unroll") for (int m = 0; m < 4; ++m) _Pragma("unroll") for (int n = 0; n < 2; ++n) _Pragma("unroll") for (int k = 0; k < 2; ++k) \
;         acc[ai][bj][m][n] = __builtin_amdgcn_mfma_f32_16x16x32_bf16(Bt[n][k], At[m][k], acc[ai][bj][m][n], 0, 0, 0); __builtin_amdgcn_s_setprio(0); } while (0)
; #define PG8_WAIT_V(n) asm volatile("s_waitcnt vmcnt(" #n ")" ::: "memory")
; template <class Epi, class Sched, bool ALIGN_EPI = false, bool SP2 = false>
; __device__ __forceinline__ void gemm_phase(PG8_LAS unsigned char* lds, const Gemm g, const Sched& S, const Epi& E) {
;     ...
;             PG8_LDB(B0, 0, 0); PG8_LDB(B1, 0, 1); PG8_SCHED; PG8_LDA(At, 0, 0); PG8_STAGE(PG8_SA(1, 1), a1 + hstep, voffA);
;             PG8_WAIT_V(8); PG8_WAIT_L(0); PG8_BAR; PG8_MMA(0, 0, At, B0); PG8_MMA(0, 1, At, B1); PG8_BAR; PG8_SCHED;
;             PG8_LDA(At, 0, 1); PG8_STAGE(PG8_SB(0, 0), b2, voffB); PG8_STAGE(PG8_SB(0, 1), b2 + hstep, voffB); PG8_STAGE(PG8_SA(0, 0), a2, voffA);
;             PG8_WAIT_V(8); PG8_WAIT_L(0); PG8_BAR; PG8_MMA(1, 0, At, B0); PG8_MMA(1, 1, At, B1); PG8_BAR; PG8_SCHED;
;             PG8_LDB(B0, 1, 0); PG8_LDB(B1, 1, 1); PG8_SCHED; PG8_LDA(At, 1, 0); PG8_STAGE(PG8_SA(0, 1), a2 + hstep, voffA);
;             PG8_WAIT_V(8); PG8_WAIT_L(0); PG8_BAR; PG8_MMA(0, 0, At, B0); PG8_MMA(0, 1, At, B1); PG8_BAR; PG8_SCHED;
;             PG8_LDA(At, 1, 1); PG8_STAGE(PG8_SB(1, 0), b3, voffB); PG8_STAGE(PG8_SB(1, 1), b3 + hstep, voffB); PG8_STAGE(PG8_SA(1, 0), a3, voffA);
;             PG8_WAIT_V(8); PG8_WAIT_L(0); PG8_BAR; PG8_MMA(1, 0, At, B0); PG8_MMA(1, 1, At, B1); PG8_BAR; PG8_SCHED;
	v_mfma_f32_16x16x32_bf16 v[60:63], v[128:131], v[184:187], 0
	v_mfma_f32_16x16x32_bf16 v[56:59], v[136:139], v[184:187], 0
	v_mfma_f32_16x16x32_bf16 v[44:47], v[128:131], v[192:195], 0
	v_mfma_f32_16x16x32_bf16 v[40:43], v[136:139], v[192:195], 0
	v_mfma_f32_16x16x32_bf16 v[28:31], v[128:131], v[200:203], 0
	v_mfma_f32_16x16x32_bf16 v[24:27], v[136:139], v[200:203], 0
	v_mfma_f32_16x16x32_bf16 v[12:15], v[128:131], v[208:211], 0
	v_mfma_f32_16x16x32_bf16 v[8:11], v[136:139], v[208:211], 0
	v_mfma_f32_16x16x32_bf16 v[60:63], v[132:135], v[188:191], v[60:63]
	v_mfma_f32_16x16x32_bf16 v[56:59], v[140:143], v[188:191], v[56:59]
	v_mfma_f32_16x16x32_bf16 v[44:47], v[132:135], v[196:199], v[44:47]
	v_mfma_f32_16x16x32_bf16 v[40:43], v[140:143], v[196:199], v[40:43]
	v_mfma_f32_16x16x32_bf16 v[28:31], v[132:135], v[204:207], v[28:31]
	v_mfma_f32_16x16x32_bf16 v[24:27], v[140:143], v[204:207], v[24:27]
	v_mfma_f32_16x16x32_bf16 v[12:15], v[132:135], v[214:217], v[12:15]
	v_mfma_f32_16x16x32_bf16 v[8:11], v[140:143], v[214:217], v[8:11]
	v_mfma_f32_16x16x32_bf16 v[52:55], v[144:147], v[184:187], 0
	v_mfma_f32_16x16x32_bf16 v[48:51], v[168:171], v[184:187], 0
	v_mfma_f32_16x16x32_bf16 v[36:39], v[144:147], v[192:195], 0
	v_mfma_f32_16x16x32_bf16 v[32:35], v[168:171], v[192:195], 0
	v_mfma_f32_16x16x32_bf16 v[20:23], v[144:147], v[200:203], 0
	v_mfma_f32_16x16x32_bf16 v[16:19], v[168:171], v[200:203], 0
	v_mfma_f32_16x16x32_bf16 v[4:7], v[144:147], v[208:211], 0
	v_mfma_f32_16x16x32_bf16 v[0:3], v[168:171], v[208:211], 0
	v_mfma_f32_16x16x32_bf16 v[52:55], v[164:167], v[188:191], v[52:55]
	v_mfma_f32_16x16x32_bf16 v[48:51], v[180:183], v[188:191], v[48:51]
	v_mfma_f32_16x16x32_bf16 v[36:39], v[164:167], v[196:199], v[36:39]
	v_mfma_f32_16x16x32_bf16 v[32:35], v[180:183], v[196:199], v[32:35]
	v_mfma_f32_16x16x32_bf16 v[20:23], v[164:167], v[204:207], v[20:23]
	v_mfma_f32_16x16x32_bf16 v[16:19], v[180:183], v[204:207], v[16:19]
	v_mfma_f32_16x16x32_bf16 v[4:7], v[164:167], v[214:217], v[4:7]
	v_mfma_f32_16x16x32_bf16 v[0:3], v[180:183], v[214:217], v[0:3]
	s_barrier
	s_add_i32 s62, 0, 0x18000
	s_add_i32 s63, 0, 0x1c000
	v_add_u32_e32 v140, s62, v175
	v_add_u32_e32 v180, s63, v175
	ds_read_b128 v[128:131], v140
	ds_read_b128 v[132:135], v140 offset:1024
	ds_read_b128 v[136:139], v140 offset:2048
	ds_read_b128 v[140:143], v140 offset:3072
	ds_read_b128 v[144:147], v180
	ds_read_b128 v[164:167], v180 offset:1024
	ds_read_b128 v[168:171], v180 offset:2048
	ds_read_b128 v[180:183], v180 offset:3072
	s_add_u32 s84, s42, 0x80
	s_addc_u32 s85, s43, 0
	s_add_u32 s42, s42, 0x40000
	s_addc_u32 s43, s43, 0
	s_mov_b32 m0, s47
	ds_read_b128 v[184:187], v179 offset:32768
	ds_read_b128 v[188:191], v179 offset:33792
	ds_read_b128 v[192:195], v179 offset:34816
	ds_read_b128 v[196:199], v179 offset:35840
	ds_read_b128 v[200:203], v179 offset:36864
	ds_read_b128 v[204:207], v179 offset:37888
	ds_read_b128 v[208:211], v179 offset:38912
	ds_read_b128 v[214:217], v179 offset:39936
	global_load_lds_dwordx4 v148, s[42:43]
	s_mov_b32 m0, s48
	s_nop 0
	global_load_lds_dwordx4 v152, s[42:43]
	s_waitcnt vmcnt(8)
	s_waitcnt lgkmcnt(0)
	s_barrier
	v_mfma_f32_16x16x32_bf16 v[124:127], v[128:131], v[184:187], v[124:127]
	v_mfma_f32_16x16x32_bf16 v[120:123], v[136:139], v[184:187], v[120:123]
	v_mfma_f32_16x16x32_bf16 v[108:111], v[128:131], v[192:195], v[108:111]
	v_mfma_f32_16x16x32_bf16 v[104:107], v[136:139], v[192:195], v[104:107]
	v_mfma_f32_16x16x32_bf16 v[92:95], v[128:131], v[200:203], v[92:95]
	v_mfma_f32_16x16x32_bf16 v[88:91], v[136:139], v[200:203], v[88:91]
	v_mfma_f32_16x16x32_bf16 v[76:79], v[128:131], v[208:211], v[76:79]
	v_mfma_f32_16x16x32_bf16 v[72:75], v[136:139], v[208:211], v[72:75]
	v_mfma_f32_16x16x32_bf16 v[124:127], v[132:135], v[188:191], v[124:127]
	v_mfma_f32_16x16x32_bf16 v[120:123], v[140:143], v[188:191], v[120:123]
	v_mfma_f32_16x16x32_bf16 v[108:111], v[132:135], v[196:199], v[108:111]
	v_mfma_f32_16x16x32_bf16 v[104:107], v[140:143], v[196:199], v[104:107]
	v_mfma_f32_16x16x32_bf16 v[92:95], v[132:135], v[204:207], v[92:95]
	v_mfma_f32_16x16x32_bf16 v[88:91], v[140:143], v[204:207], v[88:91]
	v_mfma_f32_16x16x32_bf16 v[76:79], v[132:135], v[214:217], v[76:79]
	v_mfma_f32_16x16x32_bf16 v[72:75], v[140:143], v[214:217], v[72:75]
	v_mfma_f32_16x16x32_bf16 v[116:119], v[144:147], v[184:187], v[116:119]
	v_mfma_f32_16x16x32_bf16 v[112:115], v[168:171], v[184:187], v[112:115]
	v_mfma_f32_16x16x32_bf16 v[100:103], v[144:147], v[192:195], v[100:103]
	v_mfma_f32_16x16x32_bf16 v[96:99], v[168:171], v[192:195], v[96:99]
	v_mfma_f32_16x16x32_bf16 v[84:87], v[144:147], v[200:203], v[84:87]
	v_mfma_f32_16x16x32_bf16 v[80:83], v[168:171], v[200:203], v[80:83]
	v_mfma_f32_16x16x32_bf16 v[68:71], v[144:147], v[208:211], v[68:71]
	v_mfma_f32_16x16x32_bf16 v[64:67], v[168:171], v[208:211], v[64:67]
	v_mfma_f32_16x16x32_bf16 v[116:119], v[164:167], v[188:191], v[116:119]
	v_mfma_f32_16x16x32_bf16 v[112:115], v[180:183], v[188:191], v[112:115]
	v_mfma_f32_16x16x32_bf16 v[100:103], v[164:167], v[196:199], v[100:103]
	v_mfma_f32_16x16x32_bf16 v[96:99], v[180:183], v[196:199], v[96:99]
	v_mfma_f32_16x16x32_bf16 v[84:87], v[164:167], v[204:207], v[84:87]
	v_mfma_f32_16x16x32_bf16 v[80:83], v[180:183], v[204:207], v[80:83]
	v_mfma_f32_16x16x32_bf16 v[68:71], v[164:167], v[214:217], v[68:71]
	v_mfma_f32_16x16x32_bf16 v[64:67], v[180:183], v[214:217], v[64:67]
	s_barrier
; #define PG8_STAGE(bufoff, gbase, voff) do { _Pragma("unroll") for (int _i = 0; _i < 2; ++_i) \
;         __builtin_amdgcn_global_load_lds((const unsigned*)((const char*)(gbase) + (voff)[_i]), (PG8_LAS unsigned*)(lds + (bufoff) + ldsw + _i * 8192), 16, 0, 0); } while (0)
; #define PG8_LDA(dst, b, h) do { _Pragma("unroll") for (int m = 0; m < 4; ++m) _Pragma("unroll") for (int k = 0; k < 2; ++k) dst[m][k] = *(const PG8_LAS bf16x8*)(lds + PG8_SA(b, h) + aoff + m * 2048 + k * 1024); } while (0)
; #define PG8_LDB(dst, b, h) do { _Pragma("unroll") for (int n = 0; n < 2; ++n) _Pragma("unroll") for (int k = 0; k < 2; ++k) dst[n][k] = *(const PG8_LAS bf16x8*)(lds + PG8_SB(b, h) + boff + n * 2048 + k * 1024); } while (0)
; #define PG8_MMA(ai, bj, At, Bt) do { __builtin_amdgcn_s_setprio(1); _Pragma("unroll") for (int m = 0; m < 4; ++m) _Pragma("unroll") for (int n = 0; n < 2; ++n) _Pragma("unroll") for (int k = 0; k < 2; ++k) \
;         acc[ai][bj][m][n] = __builtin_amdgcn_mfma_f32_16x16x32_bf16(Bt[n][k], At[m][k], acc[ai][bj][m][n], 0, 0, 0); __builtin_amdgcn_s_setprio(0); } while (0)
; #define PG8_WAIT_V(n) asm volatile("s_waitcnt vmcnt(" #n ")" ::: "memory")
; template <class Epi, class Sched, bool ALIGN_EPI = false, bool SP2 = false>
; __device__ __forceinline__ void gemm_phase(PG8_LAS unsigned char* lds, const Gemm g, const Sched& S, const Epi& E) {
;     ...
;             PG8_LDB(B0, 0, 0); PG8_LDB(B1, 0, 1); PG8_SCHED; PG8_LDA(At, 0, 0); PG8_STAGE(PG8_SA(1, 1), a1 + hstep, voffA);
;             PG8_WAIT_V(8); PG8_WAIT_L(0); PG8_BAR; PG8_MMA(0, 0, At, B0); PG8_MMA(0, 1, At, B1); PG8_BAR; PG8_SCHED;
;             PG8_LDA(At, 0, 1); PG8_STAGE(PG8_SB(0, 0), b2, voffB); PG8_STAGE(PG8_SB(0, 1), b2 + hstep, voffB); PG8_STAGE(PG8_SA(0, 0), a2, voffA);
;             PG8_WAIT_V(8); PG8_WAIT_L(0); PG8_BAR; PG8_MMA(1, 0, At, B0); PG8_MMA(1, 1, At, B1); PG8_BAR; PG8_SCHED;
;             PG8_LDB(B0, 1, 0); PG8_LDB(B1, 1, 1); PG8_SCHED; PG8_LDA(At, 1, 0); PG8_STAGE(PG8_SA(0, 1), a2 + hstep, voffA);
;             PG8_WAIT_V(8); PG8_WAIT_L(0); PG8_BAR; PG8_MMA(0, 0, At, B0); PG8_MMA(0, 1, At, B1); PG8_BAR; PG8_SCHED;
;             PG8_LDA(At, 1, 1); PG8_STAGE(PG8_SB(1, 0), b3, voffB); PG8_STAGE(PG8_SB(1, 1), b3 + hstep, voffB); PG8_STAGE(PG8_SA(1, 0), a3, voffA);
;             PG8_WAIT_V(8); PG8_WAIT_L(0); PG8_BAR; PG8_MMA(1, 0, At, B0); PG8_MMA(1, 1, At, B1); PG8_BAR; PG8_SCHED;
	s_add_i32 s42, s62, s45
	s_add_u32 s86, s40, 0x80
	s_addc_u32 s87, s41, 0
	s_mov_b32 m0, s42
	ds_read_b128 v[184:187], v179 offset:49152
	ds_read_b128 v[188:191], v179 offset:50176
	ds_read_b128 v[192:195], v179 offset:51200
	ds_read_b128 v[196:199], v179 offset:52224
	ds_read_b128 v[200:203], v179 offset:53248
	ds_read_b128 v[204:207], v179 offset:54272
	ds_read_b128 v[208:211], v179 offset:55296
	ds_read_b128 v[214:217], v179 offset:56320
	global_load_lds_dwordx4 v150, s[86:87]
	s_add_i32 m0, s42, 0x2000
	s_add_u32 s40, s40, 0x40080
	s_addc_u32 s41, s41, 0
	s_add_i32 s42, s63, s45
	global_load_lds_dwordx4 v154, s[86:87]
	s_mov_b32 m0, s42
	s_nop 0
	global_load_lds_dwordx4 v150, s[40:41]
	s_add_i32 m0, s42, 0x2000
	s_nop 0
	global_load_lds_dwordx4 v154, s[40:41]
	s_mov_b32 m0, s50
	s_nop 0
	global_load_lds_dwordx4 v148, s[84:85]
	s_mov_b32 m0, s51
	s_nop 0
	global_load_lds_dwordx4 v152, s[84:85]
	s_waitcnt vmcnt(8)
	s_waitcnt lgkmcnt(0)
	s_barrier
	v_mfma_f32_16x16x32_bf16 v[60:63], v[128:131], v[184:187], v[60:63]
	v_mfma_f32_16x16x32_bf16 v[56:59], v[136:139], v[184:187], v[56:59]
	v_mfma_f32_16x16x32_bf16 v[44:47], v[128:131], v[192:195], v[44:47]
	v_mfma_f32_16x16x32_bf16 v[40:43], v[136:139], v[192:195], v[40:43]
	v_mfma_f32_16x16x32_bf16 v[28:31], v[128:131], v[200:203], v[28:31]
	v_mfma_f32_16x16x32_bf16 v[24:27], v[136:139], v[200:203], v[24:27]
	v_mfma_f32_16x16x32_bf16 v[12:15], v[128:131], v[208:211], v[12:15]
	v_mfma_f32_16x16x32_bf16 v[8:11], v[136:139], v[208:211], v[8:11]
	v_mfma_f32_16x16x32_bf16 v[60:63], v[132:135], v[188:191], v[60:63]
	v_mfma_f32_16x16x32_bf16 v[56:59], v[140:143], v[188:191], v[56:59]
	v_mfma_f32_16x16x32_bf16 v[44:47], v[132:135], v[196:199], v[44:47]
	v_mfma_f32_16x16x32_bf16 v[40:43], v[140:143], v[196:199], v[40:43]
	v_mfma_f32_16x16x32_bf16 v[28:31], v[132:135], v[204:207], v[28:31]
	v_mfma_f32_16x16x32_bf16 v[24:27], v[140:143], v[204:207], v[24:27]
	v_mfma_f32_16x16x32_bf16 v[12:15], v[132:135], v[214:217], v[12:15]
	v_mfma_f32_16x16x32_bf16 v[8:11], v[140:143], v[214:217], v[8:11]
	v_mfma_f32_16x16x32_bf16 v[52:55], v[144:147], v[184:187], v[52:55]
	v_mfma_f32_16x16x32_bf16 v[48:51], v[168:171], v[184:187], v[48:51]
	v_mfma_f32_16x16x32_bf16 v[36:39], v[144:147], v[192:195], v[36:39]
	v_mfma_f32_16x16x32_bf16 v[32:35], v[168:171], v[192:195], v[32:35]
	v_mfma_f32_16x16x32_bf16 v[20:23], v[144:147], v[200:203], v[20:23]
	v_mfma_f32_16x16x32_bf16 v[16:19], v[168:171], v[200:203], v[16:19]
	v_mfma_f32_16x16x32_bf16 v[4:7], v[144:147], v[208:211], v[4:7]
	v_mfma_f32_16x16x32_bf16 v[0:3], v[168:171], v[208:211], v[0:3]
	v_mfma_f32_16x16x32_bf16 v[52:55], v[164:167], v[188:191], v[52:55]
	v_mfma_f32_16x16x32_bf16 v[48:51], v[180:183], v[188:191], v[48:51]
	v_mfma_f32_16x16x32_bf16 v[36:39], v[164:167], v[196:199], v[36:39]
	v_mfma_f32_16x16x32_bf16 v[32:35], v[180:183], v[196:199], v[32:35]
	v_mfma_f32_16x16x32_bf16 v[20:23], v[164:167], v[204:207], v[20:23]
	v_mfma_f32_16x16x32_bf16 v[16:19], v[180:183], v[204:207], v[16:19]
	v_mfma_f32_16x16x32_bf16 v[4:7], v[164:167], v[214:217], v[4:7]
	v_mfma_f32_16x16x32_bf16 v[0:3], v[180:183], v[214:217], v[0:3]
	s_barrier
	s_add_i32 s61, s61, 2
	s_add_u32 s38, s38, 0x100
	s_addc_u32 s39, s39, 0
	s_add_u32 s59, s59, 0x100
	s_addc_u32 s60, s60, 0
	s_cmp_gt_u32 s61, 13
.LBB0_755:
	ds_read_b128 v[128:131], v177
	ds_read_b128 v[132:135], v177 offset:1024
	ds_read_b128 v[136:139], v177 offset:2048
	ds_read_b128 v[140:143], v177 offset:3072
	ds_read_b128 v[144:147], v178
	ds_read_b128 v[164:167], v178 offset:1024
	ds_read_b128 v[168:171], v178 offset:2048
	ds_read_b128 v[180:183], v178 offset:3072
	s_add_u32 s40, s38, 0xfffc0080
	s_addc_u32 s41, s39, -1
	s_cmp_eq_u32 s61, 12
	s_cselect_b32 s43, s29, s41
	s_cselect_b32 s42, s57, s40
	s_cselect_b32 s41, s27, s60
	s_cselect_b32 s40, s58, s59
	s_add_i32 m0, s37, 0xc000
	ds_read_b128 v[184:187], v179
	ds_read_b128 v[188:191], v179 offset:1024
	ds_read_b128 v[192:195], v179 offset:2048
	ds_read_b128 v[196:199], v179 offset:3072
	ds_read_b128 v[200:203], v179 offset:4096
	ds_read_b128 v[204:207], v179 offset:5120
	ds_read_b128 v[208:211], v179 offset:6144
	ds_read_b128 v[214:217], v179 offset:7168
	global_load_lds_dwordx4 v156, s[38:39]
	s_add_i32 m0, s37, 0xe000
	s_nop 0
	global_load_lds_dwordx4 v158, s[38:39]
	s_waitcnt vmcnt(8)
	s_waitcnt lgkmcnt(0)
	s_barrier
	v_mfma_f32_16x16x32_bf16 v[124:127], v[128:131], v[184:187], v[124:127]
	v_mfma_f32_16x16x32_bf16 v[120:123], v[136:139], v[184:187], v[120:123]
	v_mfma_f32_16x16x32_bf16 v[108:111], v[128:131], v[192:195], v[108:111]
	v_mfma_f32_16x16x32_bf16 v[104:107], v[136:139], v[192:195], v[104:107]
	v_mfma_f32_16x16x32_bf16 v[92:95], v[128:131], v[200:203], v[92:95]
	v_mfma_f32_16x16x32_bf16 v[88:91], v[136:139], v[200:203], v[88:91]
	v_mfma_f32_16x16x32_bf16 v[76:79], v[128:131], v[208:211], v[76:79]
	v_mfma_f32_16x16x32_bf16 v[72:75], v[136:139], v[208:211], v[72:75]
	v_mfma_f32_16x16x32_bf16 v[124:127], v[132:135], v[188:191], v[124:127]
	v_mfma_f32_16x16x32_bf16 v[120:123], v[140:143], v[188:191], v[120:123]
	v_mfma_f32_16x16x32_bf16 v[108:111], v[132:135], v[196:199], v[108:111]
	v_mfma_f32_16x16x32_bf16 v[104:107], v[140:143], v[196:199], v[104:107]
	v_mfma_f32_16x16x32_bf16 v[92:95], v[132:135], v[204:207], v[92:95]
	v_mfma_f32_16x16x32_bf16 v[88:91], v[140:143], v[204:207], v[88:91]
	v_mfma_f32_16x16x32_bf16 v[76:79], v[132:135], v[214:217], v[76:79]
	v_mfma_f32_16x16x32_bf16 v[72:75], v[140:143], v[214:217], v[72:75]
	v_mfma_f32_16x16x32_bf16 v[116:119], v[144:147], v[184:187], v[116:119]
	v_mfma_f32_16x16x32_bf16 v[112:115], v[168:171], v[184:187], v[112:115]
	v_mfma_f32_16x16x32_bf16 v[100:103], v[144:147], v[192:195], v[100:103]
	v_mfma_f32_16x16x32_bf16 v[96:99], v[168:171], v[192:195], v[96:99]
	v_mfma_f32_16x16x32_bf16 v[84:87], v[144:147], v[200:203], v[84:87]
	v_mfma_f32_16x16x32_bf16 v[80:83], v[168:171], v[200:203], v[80:83]
	v_mfma_f32_16x16x32_bf16 v[68:71], v[144:147], v[208:211], v[68:71]
	v_mfma_f32_16x16x32_bf16 v[64:67], v[168:171], v[208:211], v[64:67]
	v_mfma_f32_16x16x32_bf16 v[116:119], v[164:167], v[188:191], v[116:119]
	v_mfma_f32_16x16x32_bf16 v[112:115], v[180:183], v[188:191], v[112:115]
	v_mfma_f32_16x16x32_bf16 v[100:103], v[164:167], v[196:199], v[100:103]
	v_mfma_f32_16x16x32_bf16 v[96:99], v[180:183], v[196:199], v[96:99]
	v_mfma_f32_16x16x32_bf16 v[84:87], v[164:167], v[204:207], v[84:87]
	v_mfma_f32_16x16x32_bf16 v[80:83], v[180:183], v[204:207], v[80:83]
	v_mfma_f32_16x16x32_bf16 v[68:71], v[164:167], v[214:217], v[68:71]
	v_mfma_f32_16x16x32_bf16 v[64:67], v[180:183], v[214:217], v[64:67]
	s_barrier
; #define PG8_STAGE(bufoff, gbase, voff) do { _Pragma("unroll") for (int _i = 0; _i < 2; ++_i) \
;         __builtin_amdgcn_global_load_lds((const unsigned*)((const char*)(gbase) + (voff)[_i]), (PG8_LAS unsigned*)(lds + (bufoff) + ldsw + _i * 8192), 16, 0, 0); } while (0)
; #define PG8_LDA(dst, b, h) do { _Pragma("unroll") for (int m = 0; m < 4; ++m) _Pragma("unroll") for (int k = 0; k < 2; ++k) dst[m][k] = *(const PG8_LAS bf16x8*)(lds + PG8_SA(b, h) + aoff + m * 2048 + k * 1024); } while (0)
; #define PG8_LDB(dst, b, h) do { _Pragma("unroll") for (int n = 0; n < 2; ++n) _Pragma("unroll") for (int k = 0; k < 2; ++k) dst[n][k] = *(const PG8_LAS bf16x8*)(lds + PG8_SB(b, h) + boff + n * 2048 + k * 1024); } while (0)
; #define PG8_MMA(ai, bj, At, Bt) do { __builtin_amdgcn_s_setprio(1); _Pragma("unroll") for (int m = 0; m < 4; ++m) _Pragma("unroll") for (int n = 0; n < 2; ++n) _Pragma("unroll") for (int k = 0; k < 2; ++k) \
;         acc[ai][bj][m][n] = __builtin_amdgcn_mfma_f32_16x16x32_bf16(Bt[n][k], At[m][k], acc[ai][bj][m][n], 0, 0, 0); __builtin_amdgcn_s_setprio(0); } while (0)
; #define PG8_WAIT_V(n) asm volatile("s_waitcnt vmcnt(" #n ")" ::: "memory")
; template <class Epi, class Sched, bool ALIGN_EPI = false, bool SP2 = false>
; __device__ __forceinline__ void gemm_phase(PG8_LAS unsigned char* lds, const Gemm g, const Sched& S, const Epi& E) {
;     ...
;             PG8_LDB(B0, 0, 0); PG8_LDB(B1, 0, 1); PG8_SCHED; PG8_LDA(At, 0, 0); PG8_STAGE(PG8_SA(1, 1), a1 + hstep, voffA);
;             PG8_WAIT_V(8); PG8_WAIT_L(0); PG8_BAR; PG8_MMA(0, 0, At, B0); PG8_MMA(0, 1, At, B1); PG8_BAR; PG8_SCHED;
;             PG8_LDA(At, 0, 1); PG8_STAGE(PG8_SB(0, 0), b2, voffB); PG8_STAGE(PG8_SB(0, 1), b2 + hstep, voffB); PG8_STAGE(PG8_SA(0, 0), a2, voffA);
;             PG8_WAIT_V(8); PG8_WAIT_L(0); PG8_BAR; PG8_MMA(1, 0, At, B0); PG8_MMA(1, 1, At, B1); PG8_BAR; PG8_SCHED;
;             PG8_LDB(B0, 1, 0); PG8_LDB(B1, 1, 1); PG8_SCHED; PG8_LDA(At, 1, 0); PG8_STAGE(PG8_SA(0, 1), a2 + hstep, voffA);
;             PG8_WAIT_V(8); PG8_WAIT_L(0); PG8_BAR; PG8_MMA(0, 0, At, B0); PG8_MMA(0, 1, At, B1); PG8_BAR; PG8_SCHED;
;             PG8_LDA(At, 1, 1); PG8_STAGE(PG8_SB(1, 0), b3, voffB); PG8_STAGE(PG8_SB(1, 1), b3 + hstep, voffB); PG8_STAGE(PG8_SA(1, 0), a3, voffA);
;             PG8_WAIT_V(8); PG8_WAIT_L(0); PG8_BAR; PG8_MMA(1, 0, At, B0); PG8_MMA(1, 1, At, B1); PG8_BAR; PG8_SCHED;
	s_add_i32 s62, s54, s45
	s_mov_b32 m0, s62
	ds_read_b128 v[184:187], v179 offset:16384
	ds_read_b128 v[188:191], v179 offset:17408
	ds_read_b128 v[192:195], v179 offset:18432
	ds_read_b128 v[196:199], v179 offset:19456
	ds_read_b128 v[200:203], v179 offset:20480
	ds_read_b128 v[204:207], v179 offset:21504
	ds_read_b128 v[208:211], v179 offset:22528
	ds_read_b128 v[214:217], v179 offset:23552
	global_load_lds_dwordx4 v150, s[40:41]
	s_add_i32 m0, s62, 0x2000
	s_add_u32 s62, s40, 0x40000
	s_addc_u32 s63, s41, 0
	s_add_i32 s64, s55, s45
	global_load_lds_dwordx4 v154, s[40:41]
	s_mov_b32 m0, s64
	s_nop 0
	global_load_lds_dwordx4 v150, s[62:63]
	s_add_i32 m0, s64, 0x2000
	s_nop 0
	global_load_lds_dwordx4 v154, s[62:63]
	s_mov_b32 m0, s37
	s_nop 0
	global_load_lds_dwordx4 v148, s[42:43]
	s_mov_b32 m0, s46
	s_nop 0
	global_load_lds_dwordx4 v152, s[42:43]
	s_waitcnt vmcnt(8)
	s_waitcnt lgkmcnt(0)
	s_barrier
	v_mfma_f32_16x16x32_bf16 v[60:63], v[128:131], v[184:187], v[60:63]
	v_mfma_f32_16x16x32_bf16 v[56:59], v[136:139], v[184:187], v[56:59]
	v_mfma_f32_16x16x32_bf16 v[44:47], v[128:131], v[192:195], v[44:47]
	v_mfma_f32_16x16x32_bf16 v[40:43], v[136:139], v[192:195], v[40:43]
	v_mfma_f32_16x16x32_bf16 v[28:31], v[128:131], v[200:203], v[28:31]
	v_mfma_f32_16x16x32_bf16 v[24:27], v[136:139], v[200:203], v[24:27]
	v_mfma_f32_16x16x32_bf16 v[12:15], v[128:131], v[208:211], v[12:15]
	v_mfma_f32_16x16x32_bf16 v[8:11], v[136:139], v[208:211], v[8:11]
	v_mfma_f32_16x16x32_bf16 v[60:63], v[132:135], v[188:191], v[60:63]
	v_mfma_f32_16x16x32_bf16 v[56:59], v[140:143], v[188:191], v[56:59]
	v_mfma_f32_16x16x32_bf16 v[44:47], v[132:135], v[196:199], v[44:47]
	v_mfma_f32_16x16x32_bf16 v[40:43], v[140:143], v[196:199], v[40:43]
	v_mfma_f32_16x16x32_bf16 v[28:31], v[132:135], v[204:207], v[28:31]
	v_mfma_f32_16x16x32_bf16 v[24:27], v[140:143], v[204:207], v[24:27]
	v_mfma_f32_16x16x32_bf16 v[12:15], v[132:135], v[214:217], v[12:15]
	v_mfma_f32_16x16x32_bf16 v[8:11], v[140:143], v[214:217], v[8:11]
	v_mfma_f32_16x16x32_bf16 v[52:55], v[144:147], v[184:187], v[52:55]
	v_mfma_f32_16x16x32_bf16 v[48:51], v[168:171], v[184:187], v[48:51]
	v_mfma_f32_16x16x32_bf16 v[36:39], v[144:147], v[192:195], v[36:39]
	v_mfma_f32_16x16x32_bf16 v[32:35], v[168:171], v[192:195], v[32:35]
	v_mfma_f32_16x16x32_bf16 v[20:23], v[144:147], v[200:203], v[20:23]
	v_mfma_f32_16x16x32_bf16 v[16:19], v[168:171], v[200:203], v[16:19]
	v_mfma_f32_16x16x32_bf16 v[4:7], v[144:147], v[208:211], v[4:7]
	v_mfma_f32_16x16x32_bf16 v[0:3], v[168:171], v[208:211], v[0:3]
	v_mfma_f32_16x16x32_bf16 v[52:55], v[164:167], v[188:191], v[52:55]
	v_mfma_f32_16x16x32_bf16 v[48:51], v[180:183], v[188:191], v[48:51]
	v_mfma_f32_16x16x32_bf16 v[36:39], v[164:167], v[196:199], v[36:39]
	v_mfma_f32_16x16x32_bf16 v[32:35], v[180:183], v[196:199], v[32:35]
	v_mfma_f32_16x16x32_bf16 v[20:23], v[164:167], v[204:207], v[20:23]
	v_mfma_f32_16x16x32_bf16 v[16:19], v[180:183], v[204:207], v[16:19]
	v_mfma_f32_16x16x32_bf16 v[4:7], v[164:167], v[214:217], v[4:7]
	v_mfma_f32_16x16x32_bf16 v[0:3], v[180:183], v[214:217], v[0:3]
	s_barrier
	s_add_i32 s62, 0, 0x18000
	s_add_i32 s63, 0, 0x1c000
	v_add_u32_e32 v140, s62, v175
	v_add_u32_e32 v180, s63, v175
	ds_read_b128 v[128:131], v140
	ds_read_b128 v[132:135], v140 offset:1024
	ds_read_b128 v[136:139], v140 offset:2048
	ds_read_b128 v[140:143], v140 offset:3072
	ds_read_b128 v[144:147], v180
	ds_read_b128 v[164:167], v180 offset:1024
	ds_read_b128 v[168:171], v180 offset:2048
	ds_read_b128 v[180:183], v180 offset:3072
	s_add_u32 s84, s42, 0x80
	s_addc_u32 s85, s43, 0
	s_add_u32 s42, s42, 0x40000
	s_addc_u32 s43, s43, 0
	s_mov_b32 m0, s47
	ds_read_b128 v[184:187], v179 offset:32768
	ds_read_b128 v[188:191], v179 offset:33792
	ds_read_b128 v[192:195], v179 offset:34816
	ds_read_b128 v[196:199], v179 offset:35840
	ds_read_b128 v[200:203], v179 offset:36864
	ds_read_b128 v[204:207], v179 offset:37888
	ds_read_b128 v[208:211], v179 offset:38912
	ds_read_b128 v[214:217], v179 offset:39936
	global_load_lds_dwordx4 v148, s[42:43]
	s_mov_b32 m0, s48
	s_nop 0
	global_load_lds_dwordx4 v152, s[42:43]
	s_waitcnt vmcnt(8)
	s_waitcnt lgkmcnt(0)
	s_barrier
	v_mfma_f32_16x16x32_bf16 v[124:127], v[128:131], v[184:187], v[124:127]
	v_mfma_f32_16x16x32_bf16 v[120:123], v[136:139], v[184:187], v[120:123]
	v_mfma_f32_16x16x32_bf16 v[108:111], v[128:131], v[192:195], v[108:111]
	v_mfma_f32_16x16x32_bf16 v[104:107], v[136:139], v[192:195], v[104:107]
	v_mfma_f32_16x16x32_bf16 v[92:95], v[128:131], v[200:203], v[92:95]
	v_mfma_f32_16x16x32_bf16 v[88:91], v[136:139], v[200:203], v[88:91]
	v_mfma_f32_16x16x32_bf16 v[76:79], v[128:131], v[208:211], v[76:79]
	v_mfma_f32_16x16x32_bf16 v[72:75], v[136:139], v[208:211], v[72:75]
	v_mfma_f32_16x16x32_bf16 v[124:127], v[132:135], v[188:191], v[124:127]
	v_mfma_f32_16x16x32_bf16 v[120:123], v[140:143], v[188:191], v[120:123]
	v_mfma_f32_16x16x32_bf16 v[108:111], v[132:135], v[196:199], v[108:111]
	v_mfma_f32_16x16x32_bf16 v[104:107], v[140:143], v[196:199], v[104:107]
	v_mfma_f32_16x16x32_bf16 v[92:95], v[132:135], v[204:207], v[92:95]
	v_mfma_f32_16x16x32_bf16 v[88:91], v[140:143], v[204:207], v[88:91]
	v_mfma_f32_16x16x32_bf16 v[76:79], v[132:135], v[214:217], v[76:79]
	v_mfma_f32_16x16x32_bf16 v[72:75], v[140:143], v[214:217], v[72:75]
	v_mfma_f32_16x16x32_bf16 v[116:119], v[144:147], v[184:187], v[116:119]
	v_mfma_f32_16x16x32_bf16 v[112:115], v[168:171], v[184:187], v[112:115]
	v_mfma_f32_16x16x32_bf16 v[100:103], v[144:147], v[192:195], v[100:103]
	v_mfma_f32_16x16x32_bf16 v[96:99], v[168:171], v[192:195], v[96:99]
	v_mfma_f32_16x16x32_bf16 v[84:87], v[144:147], v[200:203], v[84:87]
	v_mfma_f32_16x16x32_bf16 v[80:83], v[168:171], v[200:203], v[80:83]
	v_mfma_f32_16x16x32_bf16 v[68:71], v[144:147], v[208:211], v[68:71]
	v_mfma_f32_16x16x32_bf16 v[64:67], v[168:171], v[208:211], v[64:67]
	v_mfma_f32_16x16x32_bf16 v[116:119], v[164:167], v[188:191], v[116:119]
	v_mfma_f32_16x16x32_bf16 v[112:115], v[180:183], v[188:191], v[112:115]
	v_mfma_f32_16x16x32_bf16 v[100:103], v[164:167], v[196:199], v[100:103]
	v_mfma_f32_16x16x32_bf16 v[96:99], v[180:183], v[196:199], v[96:99]
	v_mfma_f32_16x16x32_bf16 v[84:87], v[164:167], v[204:207], v[84:87]
	v_mfma_f32_16x16x32_bf16 v[80:83], v[180:183], v[204:207], v[80:83]
	v_mfma_f32_16x16x32_bf16 v[68:71], v[164:167], v[214:217], v[68:71]
	v_mfma_f32_16x16x32_bf16 v[64:67], v[180:183], v[214:217], v[64:67]
	s_barrier
;     __device__ __forceinline__ void operator()(const f32x4 (&acc)[2][2][4][2], const Unit& u, int wr, int wc, int fr, int fq) const {
;     ...
;         for (int ai = 0; ai < 2; ++ai) { u32x4 gw[4][2], pw[4][2];
; #pragma unroll
;             for (int m = 0; m < 4; ++m) { const size_t off = (size_t)(row0 + ai * HALF + m * 16) * 2048 + col0;
; #pragma unroll
;                 for (int bj = 0; bj < 2; ++bj) { gw[m][bj] = *(const u32x4*)(G + off + bj * HALF); if (PASS == 1) pw[m][bj] = *(const u32x4*)(MIX + off + bj * HALF); } }
; #pragma unroll
;             for (int m = 0; m < 4; ++m) { const size_t off = (size_t)(row0 + ai * HALF + m * 16) * 2048 + col0;
; #pragma unroll
;                 for (int bj = 0; bj < 2; ++bj) { const u32x4 g4 = gw[m][bj];
;                     f32x4 v0 = (f32x4){bf_lo(g4.x), bf_hi(g4.x), bf_lo(g4.y), bf_hi(g4.y)} * acc[ai][bj][m][0], v1 = (f32x4){bf_lo(g4.z), bf_hi(g4.z), bf_lo(g4.w), bf_hi(g4.w)} * acc[ai][bj][m][1];
;                     if (PASS == 1) { const u32x4 p4 = pw[m][bj]; v0 += (f32x4){bf_lo(p4.x), bf_hi(p4.x), bf_lo(p4.y), bf_hi(p4.y)}; v1 += (f32x4){bf_lo(p4.z), bf_hi(p4.z), bf_lo(p4.w), bf_hi(p4.w)}; }
; template <class Epi, class Sched, bool ALIGN_EPI = false, bool SP2 = false>
; __device__ __forceinline__ void gemm_phase(PG8_LAS unsigned char* lds, const Gemm g, const Sched& S, const Epi& E) {
;     ...
;             PG8_LDB(B0, 0, 0); PG8_LDB(B1, 0, 1); PG8_SCHED; PG8_LDA(At, 0, 0); PG8_STAGE(PG8_SA(1, 1), a1 + hstep, voffA);
;             PG8_WAIT_V(8); PG8_WAIT_L(0); PG8_BAR; PG8_MMA(0, 0, At, B0); PG8_MMA(0, 1, At, B1); PG8_BAR; PG8_SCHED;
;             PG8_LDA(At, 0, 1); PG8_STAGE(PG8_SB(0, 0), b2, voffB); PG8_STAGE(PG8_SB(0, 1), b2 + hstep, voffB); PG8_STAGE(PG8_SA(0, 0), a2, voffA);
;             PG8_WAIT_V(8); PG8_WAIT_L(0); PG8_BAR; PG8_MMA(1, 0, At, B0); PG8_MMA(1, 1, At, B1); PG8_BAR; PG8_SCHED;
;             PG8_LDB(B0, 1, 0); PG8_LDB(B1, 1, 1); PG8_SCHED; PG8_LDA(At, 1, 0); PG8_STAGE(PG8_SA(0, 1), a2 + hstep, voffA);
;             PG8_WAIT_V(8); PG8_WAIT_L(0); PG8_BAR; PG8_MMA(0, 0, At, B0); PG8_MMA(0, 1, At, B1); PG8_BAR; PG8_SCHED;
;             PG8_LDA(At, 1, 1); PG8_STAGE(PG8_SB(1, 0), b3, voffB); PG8_STAGE(PG8_SB(1, 1), b3 + hstep, voffB); PG8_STAGE(PG8_SA(1, 0), a3, voffA);
;             PG8_WAIT_V(8); PG8_WAIT_L(0); PG8_BAR; PG8_MMA(1, 0, At, B0); PG8_MMA(1, 1, At, B1); PG8_BAR; PG8_SCHED;
	s_add_i32 s42, s62, s45
	s_add_u32 s86, s40, 0x80
	s_addc_u32 s87, s41, 0
	s_mov_b32 m0, s42
	ds_read_b128 v[184:187], v179 offset:49152
	ds_read_b128 v[188:191], v179 offset:50176
	ds_read_b128 v[192:195], v179 offset:51200
	ds_read_b128 v[196:199], v179 offset:52224
	ds_read_b128 v[200:203], v179 offset:53248
	ds_read_b128 v[204:207], v179 offset:54272
	ds_read_b128 v[208:211], v179 offset:55296
	ds_read_b128 v[214:217], v179 offset:56320
	global_load_lds_dwordx4 v150, s[86:87]
	s_add_i32 m0, s42, 0x2000
	s_add_u32 s40, s40, 0x40080
	s_addc_u32 s41, s41, 0
	s_add_i32 s42, s63, s45
	global_load_lds_dwordx4 v154, s[86:87]
	s_mov_b32 m0, s42
	s_nop 0
	global_load_lds_dwordx4 v150, s[40:41]
	s_add_i32 m0, s42, 0x2000
	s_nop 0
	global_load_lds_dwordx4 v154, s[40:41]
	s_mov_b32 m0, s50
	s_nop 0
	global_load_lds_dwordx4 v148, s[84:85]
	s_mov_b32 m0, s51
	s_nop 0
	global_load_lds_dwordx4 v152, s[84:85]
	s_waitcnt vmcnt(8)
	s_waitcnt lgkmcnt(0)
	s_barrier
	v_mfma_f32_16x16x32_bf16 v[60:63], v[128:131], v[184:187], v[60:63]
	v_mfma_f32_16x16x32_bf16 v[56:59], v[136:139], v[184:187], v[56:59]
	v_mfma_f32_16x16x32_bf16 v[44:47], v[128:131], v[192:195], v[44:47]
	v_mfma_f32_16x16x32_bf16 v[40:43], v[136:139], v[192:195], v[40:43]
	v_mfma_f32_16x16x32_bf16 v[28:31], v[128:131], v[200:203], v[28:31]
	v_mfma_f32_16x16x32_bf16 v[24:27], v[136:139], v[200:203], v[24:27]
	v_mfma_f32_16x16x32_bf16 v[12:15], v[128:131], v[208:211], v[12:15]
	v_mfma_f32_16x16x32_bf16 v[8:11], v[136:139], v[208:211], v[8:11]
	v_mfma_f32_16x16x32_bf16 v[60:63], v[132:135], v[188:191], v[60:63]
	v_mfma_f32_16x16x32_bf16 v[56:59], v[140:143], v[188:191], v[56:59]
	v_mfma_f32_16x16x32_bf16 v[44:47], v[132:135], v[196:199], v[44:47]
	v_mfma_f32_16x16x32_bf16 v[40:43], v[140:143], v[196:199], v[40:43]
	v_mfma_f32_16x16x32_bf16 v[28:31], v[132:135], v[204:207], v[28:31]
	v_mfma_f32_16x16x32_bf16 v[24:27], v[140:143], v[204:207], v[24:27]
	v_mfma_f32_16x16x32_bf16 v[12:15], v[132:135], v[214:217], v[12:15]
	v_mfma_f32_16x16x32_bf16 v[8:11], v[140:143], v[214:217], v[8:11]
	v_mfma_f32_16x16x32_bf16 v[52:55], v[144:147], v[184:187], v[52:55]
	v_mfma_f32_16x16x32_bf16 v[48:51], v[168:171], v[184:187], v[48:51]
	v_mfma_f32_16x16x32_bf16 v[36:39], v[144:147], v[192:195], v[36:39]
	v_mfma_f32_16x16x32_bf16 v[32:35], v[168:171], v[192:195], v[32:35]
	v_mfma_f32_16x16x32_bf16 v[20:23], v[144:147], v[200:203], v[20:23]
	v_mfma_f32_16x16x32_bf16 v[16:19], v[168:171], v[200:203], v[16:19]
	v_mfma_f32_16x16x32_bf16 v[4:7], v[144:147], v[208:211], v[4:7]
	v_mfma_f32_16x16x32_bf16 v[0:3], v[168:171], v[208:211], v[0:3]
	v_mfma_f32_16x16x32_bf16 v[52:55], v[164:167], v[188:191], v[52:55]
	v_mfma_f32_16x16x32_bf16 v[48:51], v[180:183], v[188:191], v[48:51]
	v_mfma_f32_16x16x32_bf16 v[36:39], v[164:167], v[196:199], v[36:39]
	v_mfma_f32_16x16x32_bf16 v[32:35], v[180:183], v[196:199], v[32:35]
	v_mfma_f32_16x16x32_bf16 v[20:23], v[164:167], v[204:207], v[20:23]
	v_mfma_f32_16x16x32_bf16 v[16:19], v[180:183], v[204:207], v[16:19]
	v_mfma_f32_16x16x32_bf16 v[4:7], v[164:167], v[214:217], v[4:7]
	v_mfma_f32_16x16x32_bf16 v[0:3], v[180:183], v[214:217], v[0:3]
	s_barrier
	s_add_i32 s61, s61, 2
	s_add_u32 s38, s38, 0x100
	s_addc_u32 s39, s39, 0
	s_add_u32 s59, s59, 0x100
	s_addc_u32 s60, s60, 0
	s_cmp_gt_u32 s61, 13
	s_cbranch_scc0 .LBB0_755
	v_lshl_add_u32 v168, s36, 8, v174
	v_lshl_or_b32 v166, s56, 8, v176
	v_ashrrev_i32_e32 v169, 31, v168
	v_ashrrev_i32_e32 v167, 31, v166
	v_lshlrev_b64 v[128:129], 11, v[168:169]
	v_lshl_add_u64 v[128:129], v[128:129], 0, v[166:167]
	v_lshlrev_b64 v[128:129], 1, v[128:129]
	v_lshl_add_u64 v[130:131], s[12:13], 0, v[128:129]
	global_load_dwordx4 v[180:183], v[130:131], off
	v_lshl_add_u64 v[128:129], s[14:15], 0, v[128:129]
	v_or_b32_e32 v212, 16, v168
	global_load_dwordx4 v[184:187], v[128:129], off
	global_load_dwordx4 v[188:191], v[130:131], off offset:256
	global_load_dwordx4 v[192:195], v[128:129], off offset:256
	v_ashrrev_i32_e32 v213, 31, v212
	v_lshlrev_b64 v[128:129], 11, v[212:213]
	v_lshl_add_u64 v[128:129], v[128:129], 0, v[166:167]
	v_lshlrev_b64 v[128:129], 1, v[128:129]
	v_lshl_add_u64 v[130:131], s[12:13], 0, v[128:129]
	v_lshl_add_u64 v[128:129], s[14:15], 0, v[128:129]
	global_load_dwordx4 v[196:199], v[130:131], off
	global_load_dwordx4 v[200:203], v[128:129], off
	v_or_b32_e32 v172, 32, v168
	v_or_b32_e32 v170, 48, v168
	v_ashrrev_i32_e32 v173, 31, v172
	v_ashrrev_i32_e32 v171, 31, v170
	v_lshlrev_b64 v[132:133], 12, v[168:169]
	v_lshlrev_b64 v[134:135], 11, v[172:173]
	v_lshlrev_b64 v[136:137], 11, v[170:171]
	v_lshlrev_b64 v[164:165], 1, v[166:167]
	v_lshl_add_u64 v[132:133], s[14:15], 0, v[132:133]
	v_lshl_add_u64 v[134:135], v[134:135], 0, v[166:167]
	v_lshl_add_u64 v[136:137], v[136:137], 0, v[166:167]
	v_lshl_add_u64 v[218:219], v[132:133], 0, v[164:165]
	v_lshlrev_b64 v[132:133], 1, v[134:135]
	v_lshlrev_b64 v[134:135], 1, v[136:137]
	v_lshl_add_u64 v[136:137], s[12:13], 0, v[132:133]
	v_lshl_add_u64 v[132:133], s[14:15], 0, v[132:133]
	v_lshl_add_u64 v[138:139], s[12:13], 0, v[134:135]
	v_lshl_add_u64 v[230:231], s[14:15], 0, v[134:135]
	global_load_dwordx4 v[204:207], v[130:131], off offset:256
	global_load_dwordx4 v[208:211], v[128:129], off offset:256
	global_load_dwordx4 v[214:217], v[136:137], off
	global_load_dwordx4 v[222:225], v[136:137], off offset:256
	global_load_dwordx4 v[232:235], v[132:133], off
	global_load_dwordx4 v[144:147], v[132:133], off offset:256
	global_load_dwordx4 v[140:143], v[138:139], off
	s_nop 0
	global_load_dwordx4 v[132:135], v[138:139], off offset:256
	s_nop 0
	global_load_dwordx4 v[136:139], v[230:231], off
	global_load_dwordx4 v[128:131], v[230:231], off offset:256
	s_and_b64 vcc, exec, s[10:11]
	s_mov_b32 s56, s26
	s_mov_b32 s36, s28
	s_mov_b64 s[40:41], s[34:35]
	s_mov_b64 s[38:39], s[30:31]
	s_waitcnt vmcnt(0)
; __device__ __forceinline__ float bf_lo(unsigned w) { return __uint_as_float(w << 16); }
; __device__ __forceinline__ float bf_hi(unsigned w) { return __uint_as_float(w & 0xffff0000u); }
; __device__ __forceinline__ u32x4 pack8(const f32x4 a, const f32x4 b) { u32x4 w; w.x = cvt_pk_bf16(a[0], a[1]); w.y = cvt_pk_bf16(a[2], a[3]); w.z = cvt_pk_bf16(b[0], b[1]); w.w = cvt_pk_bf16(b[2], b[3]); return w; }
;     __device__ __forceinline__ void operator()(const f32x4 (&acc)[2][2][4][2], const Unit& u, int wr, int wc, int fr, int fq) const {
;     ...
;         for (int ai = 0; ai < 2; ++ai) { u32x4 gw[4][2], pw[4][2];
; #pragma unroll
;             for (int m = 0; m < 4; ++m) { const size_t off = (size_t)(row0 + ai * HALF + m * 16) * 2048 + col0;
; #pragma unroll
;                 for (int bj = 0; bj < 2; ++bj) { gw[m][bj] = *(const u32x4*)(G + off + bj * HALF); if (PASS == 1) pw[m][bj] = *(const u32x4*)(MIX + off + bj * HALF); } }
; #pragma unroll
;             for (int m = 0; m < 4; ++m) { const size_t off = (size_t)(row0 + ai * HALF + m * 16) * 2048 + col0;
; #pragma unroll
;                 for (int bj = 0; bj < 2; ++bj) { const u32x4 g4 = gw[m][bj];
;                     f32x4 v0 = (f32x4){bf_lo(g4.x), bf_hi(g4.x), bf_lo(g4.y), bf_hi(g4.y)} * acc[ai][bj][m][0], v1 = (f32x4){bf_lo(g4.z), bf_hi(g4.z), bf_lo(g4.w), bf_hi(g4.w)} * acc[ai][bj][m][1];
;                     if (PASS == 1) { const u32x4 p4 = pw[m][bj]; v0 += (f32x4){bf_lo(p4.x), bf_hi(p4.x), bf_lo(p4.y), bf_hi(p4.y)}; v1 += (f32x4){bf_lo(p4.z), bf_hi(p4.z), bf_lo(p4.w), bf_hi(p4.w)}; }
;                     *(u32x4*)(MIX + off + bj * HALF) = pack8(v0, v1); } } }
	v_lshlrev_b32_e32 v230, 16, v180
	v_and_b32_e32 v231, 0xffff0000, v180
	v_lshlrev_b32_e32 v180, 16, v181
	v_and_b32_e32 v181, 0xffff0000, v181
	v_lshlrev_b32_e32 v236, 16, v182
	v_and_b32_e32 v237, 0xffff0000, v182
	v_lshlrev_b32_e32 v182, 16, v183
	v_and_b32_e32 v183, 0xffff0000, v183
	v_lshlrev_b32_e32 v238, 16, v184
	v_and_b32_e32 v239, 0xffff0000, v184
	v_lshlrev_b32_e32 v184, 16, v185
	v_and_b32_e32 v185, 0xffff0000, v185
	v_lshlrev_b32_e32 v240, 16, v186
	v_and_b32_e32 v241, 0xffff0000, v186
	v_lshlrev_b32_e32 v186, 16, v187
	v_and_b32_e32 v187, 0xffff0000, v187
	v_lshlrev_b32_e32 v242, 16, v188
	v_and_b32_e32 v243, 0xffff0000, v188
	v_lshlrev_b32_e32 v188, 16, v189
	v_and_b32_e32 v189, 0xffff0000, v189
	v_lshlrev_b32_e32 v246, 16, v192
	v_and_b32_e32 v247, 0xffff0000, v192
	v_lshlrev_b32_e32 v192, 16, v193
	v_and_b32_e32 v193, 0xffff0000, v193
	v_pk_fma_f32 v[126:127], v[126:127], v[180:181], v[184:185]
	v_pk_fma_f32 v[124:125], v[124:125], v[230:231], v[238:239]
	v_pk_fma_f32 v[122:123], v[122:123], v[182:183], v[186:187]
	v_pk_fma_f32 v[120:121], v[120:121], v[236:237], v[240:241]
	v_pk_fma_f32 v[180:181], v[118:119], v[188:189], v[192:193]
	v_pk_fma_f32 v[182:183], v[116:117], v[242:243], v[246:247]
	v_cvt_pk_bf16_f32 v116, v124, v125
	v_cvt_pk_bf16_f32 v117, v126, v127
	v_cvt_pk_bf16_f32 v118, v120, v121
	v_cvt_pk_bf16_f32 v119, v122, v123
	v_lshlrev_b32_e32 v244, 16, v190
	v_and_b32_e32 v245, 0xffff0000, v190
	v_lshlrev_b32_e32 v190, 16, v191
	v_and_b32_e32 v191, 0xffff0000, v191
	v_lshlrev_b32_e32 v248, 16, v194
	global_store_dwordx4 v[218:219], v[116:119], off
	v_and_b32_e32 v249, 0xffff0000, v194
	v_lshlrev_b32_e32 v122, 16, v200
	v_lshlrev_b32_e32 v116, 16, v195
	v_and_b32_e32 v117, 0xffff0000, v195
	v_pk_fma_f32 v[116:117], v[114:115], v[190:191], v[116:117]
	v_pk_fma_f32 v[114:115], v[112:113], v[244:245], v[248:249]
	v_cvt_pk_bf16_f32 v112, v182, v183
	v_cvt_pk_bf16_f32 v113, v180, v181
	v_cvt_pk_bf16_f32 v114, v114, v115
	v_cvt_pk_bf16_f32 v115, v116, v117
	global_store_dwordx4 v[218:219], v[112:115], off offset:256
	v_lshlrev_b32_e32 v116, 16, v197
	v_and_b32_e32 v117, 0xffff0000, v197
	v_lshlrev_b32_e32 v114, 16, v196
	v_and_b32_e32 v115, 0xffff0000, v196
	v_and_b32_e32 v123, 0xffff0000, v200
	v_lshlrev_b32_e32 v124, 16, v201
	v_and_b32_e32 v125, 0xffff0000, v201
	v_lshlrev_b64 v[112:113], 12, v[212:213]
	v_lshlrev_b32_e32 v118, 16, v198
	v_and_b32_e32 v119, 0xffff0000, v198
	v_lshlrev_b32_e32 v120, 16, v199
	v_and_b32_e32 v121, 0xffff0000, v199
	v_pk_fma_f32 v[110:111], v[110:111], v[116:117], v[124:125]
	v_pk_fma_f32 v[108:109], v[108:109], v[114:115], v[122:123]
	v_lshlrev_b32_e32 v114, 16, v202
	v_and_b32_e32 v115, 0xffff0000, v202
	v_lshlrev_b32_e32 v116, 16, v203
	v_and_b32_e32 v117, 0xffff0000, v203
	v_pk_fma_f32 v[116:117], v[106:107], v[120:121], v[116:117]
	v_pk_fma_f32 v[106:107], v[104:105], v[118:119], v[114:115]
	v_cvt_pk_bf16_f32 v104, v108, v109
	v_lshl_add_u64 v[108:109], s[14:15], 0, v[112:113]
	v_cvt_pk_bf16_f32 v105, v110, v111
	v_cvt_pk_bf16_f32 v106, v106, v107
	v_cvt_pk_bf16_f32 v107, v116, v117
	v_lshl_add_u64 v[108:109], v[108:109], 0, v[164:165]
	global_store_dwordx4 v[108:109], v[104:107], off
	v_lshlrev_b32_e32 v114, 16, v208
	v_and_b32_e32 v115, 0xffff0000, v208
	v_lshlrev_b32_e32 v104, 16, v204
	v_and_b32_e32 v105, 0xffff0000, v204
	v_lshlrev_b32_e32 v106, 16, v205
	v_and_b32_e32 v107, 0xffff0000, v205
	v_lshlrev_b32_e32 v116, 16, v209
	v_and_b32_e32 v117, 0xffff0000, v209
	v_lshlrev_b32_e32 v110, 16, v206
	v_and_b32_e32 v111, 0xffff0000, v206
	v_lshlrev_b32_e32 v112, 16, v207
	v_and_b32_e32 v113, 0xffff0000, v207
	v_pk_fma_f32 v[102:103], v[102:103], v[106:107], v[116:117]
	v_pk_fma_f32 v[100:101], v[100:101], v[104:105], v[114:115]
	v_lshlrev_b32_e32 v104, 16, v210
	v_and_b32_e32 v105, 0xffff0000, v210
	v_lshlrev_b32_e32 v106, 16, v211
	v_and_b32_e32 v107, 0xffff0000, v211
	v_pk_fma_f32 v[106:107], v[98:99], v[112:113], v[106:107]
	v_pk_fma_f32 v[98:99], v[96:97], v[110:111], v[104:105]
	v_cvt_pk_bf16_f32 v96, v100, v101
	v_cvt_pk_bf16_f32 v97, v102, v103
	v_cvt_pk_bf16_f32 v98, v98, v99
	v_cvt_pk_bf16_f32 v99, v106, v107
	global_store_dwordx4 v[108:109], v[96:99], off offset:256
	v_lshlrev_b32_e32 v100, 16, v215
	v_and_b32_e32 v101, 0xffff0000, v215
	v_lshlrev_b32_e32 v98, 16, v214
	v_and_b32_e32 v99, 0xffff0000, v214
	v_lshlrev_b32_e32 v106, 16, v232
	v_and_b32_e32 v107, 0xffff0000, v232
	v_lshlrev_b32_e32 v108, 16, v233
	v_and_b32_e32 v109, 0xffff0000, v233
	v_lshlrev_b64 v[96:97], 12, v[172:173]
	v_lshlrev_b32_e32 v102, 16, v216
	v_and_b32_e32 v103, 0xffff0000, v216
	v_lshlrev_b32_e32 v104, 16, v217
	v_and_b32_e32 v105, 0xffff0000, v217
	v_pk_fma_f32 v[94:95], v[94:95], v[100:101], v[108:109]
	v_pk_fma_f32 v[92:93], v[92:93], v[98:99], v[106:107]
	v_lshlrev_b32_e32 v98, 16, v234
	v_and_b32_e32 v99, 0xffff0000, v234
	v_lshlrev_b32_e32 v100, 16, v235
	v_and_b32_e32 v101, 0xffff0000, v235
	v_pk_fma_f32 v[100:101], v[90:91], v[104:105], v[100:101]
	v_pk_fma_f32 v[90:91], v[88:89], v[102:103], v[98:99]
	v_cvt_pk_bf16_f32 v88, v92, v93
	v_lshl_add_u64 v[92:93], s[14:15], 0, v[96:97]
	v_cvt_pk_bf16_f32 v89, v94, v95
	v_cvt_pk_bf16_f32 v90, v90, v91
	v_cvt_pk_bf16_f32 v91, v100, v101
	v_lshl_add_u64 v[92:93], v[92:93], 0, v[164:165]
	global_store_dwordx4 v[92:93], v[88:91], off
	v_lshlrev_b32_e32 v98, 16, v144
	v_and_b32_e32 v99, 0xffff0000, v144
	v_lshlrev_b32_e32 v88, 16, v222
	v_and_b32_e32 v89, 0xffff0000, v222
	v_lshlrev_b32_e32 v90, 16, v223
	v_and_b32_e32 v91, 0xffff0000, v223
	v_lshlrev_b32_e32 v100, 16, v145
	v_and_b32_e32 v101, 0xffff0000, v145
	v_lshlrev_b32_e32 v94, 16, v224
; __device__ __forceinline__ float bf_lo(unsigned w) { return __uint_as_float(w << 16); }
; __device__ __forceinline__ float bf_hi(unsigned w) { return __uint_as_float(w & 0xffff0000u); }
; __device__ __forceinline__ u32x4 pack8(const f32x4 a, const f32x4 b) { u32x4 w; w.x = cvt_pk_bf16(a[0], a[1]); w.y = cvt_pk_bf16(a[2], a[3]); w.z = cvt_pk_bf16(b[0], b[1]); w.w = cvt_pk_bf16(b[2], b[3]); return w; }
;     __device__ __forceinline__ void operator()(const f32x4 (&acc)[2][2][4][2], const Unit& u, int wr, int wc, int fr, int fq) const {
;     ...
;         for (int ai = 0; ai < 2; ++ai) { u32x4 gw[4][2], pw[4][2];
; #pragma unroll
;             for (int m = 0; m < 4; ++m) { const size_t off = (size_t)(row0 + ai * HALF + m * 16) * 2048 + col0;
; #pragma unroll
;                 for (int bj = 0; bj < 2; ++bj) { gw[m][bj] = *(const u32x4*)(G + off + bj * HALF); if (PASS == 1) pw[m][bj] = *(const u32x4*)(MIX + off + bj * HALF); } }
; #pragma unroll
;             for (int m = 0; m < 4; ++m) { const size_t off = (size_t)(row0 + ai * HALF + m * 16) * 2048 + col0;
; #pragma unroll
;                 for (int bj = 0; bj < 2; ++bj) { const u32x4 g4 = gw[m][bj];
;                     f32x4 v0 = (f32x4){bf_lo(g4.x), bf_hi(g4.x), bf_lo(g4.y), bf_hi(g4.y)} * acc[ai][bj][m][0], v1 = (f32x4){bf_lo(g4.z), bf_hi(g4.z), bf_lo(g4.w), bf_hi(g4.w)} * acc[ai][bj][m][1];
;                     if (PASS == 1) { const u32x4 p4 = pw[m][bj]; v0 += (f32x4){bf_lo(p4.x), bf_hi(p4.x), bf_lo(p4.y), bf_hi(p4.y)}; v1 += (f32x4){bf_lo(p4.z), bf_hi(p4.z), bf_lo(p4.w), bf_hi(p4.w)}; }
;                     *(u32x4*)(MIX + off + bj * HALF) = pack8(v0, v1); } } }
	v_and_b32_e32 v95, 0xffff0000, v224
	v_lshlrev_b32_e32 v96, 16, v225
	v_and_b32_e32 v97, 0xffff0000, v225
	v_pk_fma_f32 v[86:87], v[86:87], v[90:91], v[100:101]
	v_pk_fma_f32 v[84:85], v[84:85], v[88:89], v[98:99]
	v_lshlrev_b32_e32 v88, 16, v146
	v_and_b32_e32 v89, 0xffff0000, v146
	v_lshlrev_b32_e32 v90, 16, v147
	v_and_b32_e32 v91, 0xffff0000, v147
	v_pk_fma_f32 v[90:91], v[82:83], v[96:97], v[90:91]
	v_pk_fma_f32 v[82:83], v[80:81], v[94:95], v[88:89]
	v_cvt_pk_bf16_f32 v80, v84, v85
	v_cvt_pk_bf16_f32 v81, v86, v87
	v_cvt_pk_bf16_f32 v82, v82, v83
	v_cvt_pk_bf16_f32 v83, v90, v91
	global_store_dwordx4 v[92:93], v[80:83], off offset:256
	v_lshlrev_b32_e32 v84, 16, v141
	v_and_b32_e32 v85, 0xffff0000, v141
	v_lshlrev_b32_e32 v82, 16, v140
	v_and_b32_e32 v83, 0xffff0000, v140
	v_lshlrev_b32_e32 v90, 16, v136
	v_and_b32_e32 v91, 0xffff0000, v136
	v_lshlrev_b32_e32 v92, 16, v137
	v_and_b32_e32 v93, 0xffff0000, v137
	v_lshlrev_b64 v[80:81], 12, v[170:171]
	v_lshlrev_b32_e32 v86, 16, v142
	v_and_b32_e32 v87, 0xffff0000, v142
	v_lshlrev_b32_e32 v88, 16, v143
	v_and_b32_e32 v89, 0xffff0000, v143
	v_pk_fma_f32 v[78:79], v[78:79], v[84:85], v[92:93]
	v_pk_fma_f32 v[76:77], v[76:77], v[82:83], v[90:91]
	v_lshlrev_b32_e32 v82, 16, v138
	v_and_b32_e32 v83, 0xffff0000, v138
	v_lshlrev_b32_e32 v84, 16, v139
	v_and_b32_e32 v85, 0xffff0000, v139
	v_pk_fma_f32 v[84:85], v[74:75], v[88:89], v[84:85]
	v_pk_fma_f32 v[74:75], v[72:73], v[86:87], v[82:83]
	v_cvt_pk_bf16_f32 v72, v76, v77
	v_lshl_add_u64 v[76:77], s[14:15], 0, v[80:81]
	v_cvt_pk_bf16_f32 v73, v78, v79
	v_cvt_pk_bf16_f32 v74, v74, v75
	v_cvt_pk_bf16_f32 v75, v84, v85
	v_lshl_add_u64 v[76:77], v[76:77], 0, v[164:165]
	global_store_dwordx4 v[76:77], v[72:75], off
	v_lshlrev_b32_e32 v82, 16, v128
	v_and_b32_e32 v83, 0xffff0000, v128
	v_lshlrev_b32_e32 v72, 16, v132
	v_and_b32_e32 v73, 0xffff0000, v132
	v_lshlrev_b32_e32 v74, 16, v133
	v_and_b32_e32 v75, 0xffff0000, v133
	v_lshlrev_b32_e32 v84, 16, v129
	v_and_b32_e32 v85, 0xffff0000, v129
	v_lshlrev_b32_e32 v78, 16, v134
	v_and_b32_e32 v79, 0xffff0000, v134
	v_lshlrev_b32_e32 v80, 16, v135
	v_and_b32_e32 v81, 0xffff0000, v135
	v_pk_fma_f32 v[70:71], v[70:71], v[74:75], v[84:85]
	v_pk_fma_f32 v[68:69], v[68:69], v[72:73], v[82:83]
	v_lshlrev_b32_e32 v72, 16, v130
	v_and_b32_e32 v73, 0xffff0000, v130
	v_lshlrev_b32_e32 v74, 16, v131
	v_and_b32_e32 v75, 0xffff0000, v131
	v_pk_fma_f32 v[74:75], v[66:67], v[80:81], v[74:75]
	v_pk_fma_f32 v[66:67], v[64:65], v[78:79], v[72:73]
	v_add_u32_e32 v130, 0x80, v168
	v_cvt_pk_bf16_f32 v64, v68, v69
	v_cvt_pk_bf16_f32 v65, v70, v71
	v_cvt_pk_bf16_f32 v66, v66, v67
	v_cvt_pk_bf16_f32 v67, v74, v75
	v_ashrrev_i32_e32 v131, 31, v130
	global_store_dwordx4 v[76:77], v[64:67], off offset:256
	v_add_u32_e32 v132, 0x90, v168
	v_ashrrev_i32_e32 v133, 31, v132
	v_lshlrev_b64 v[64:65], 11, v[130:131]
	v_lshl_add_u64 v[64:65], v[64:65], 0, v[166:167]
	v_lshlrev_b64 v[64:65], 1, v[64:65]
	v_lshl_add_u64 v[66:67], s[12:13], 0, v[64:65]
	global_load_dwordx4 v[90:93], v[66:67], off
	v_lshl_add_u64 v[64:65], s[14:15], 0, v[64:65]
	global_load_dwordx4 v[94:97], v[64:65], off
	global_load_dwordx4 v[98:101], v[66:67], off offset:256
	global_load_dwordx4 v[102:105], v[64:65], off offset:256
	v_lshlrev_b64 v[64:65], 11, v[132:133]
	v_lshl_add_u64 v[64:65], v[64:65], 0, v[166:167]
	v_lshlrev_b64 v[64:65], 1, v[64:65]
	v_lshl_add_u64 v[66:67], s[12:13], 0, v[64:65]
	v_lshl_add_u64 v[64:65], s[14:15], 0, v[64:65]
	global_load_dwordx4 v[106:109], v[66:67], off
	global_load_dwordx4 v[110:113], v[66:67], off offset:256
	global_load_dwordx4 v[114:117], v[64:65], off
	global_load_dwordx4 v[118:121], v[64:65], off offset:256
	v_add_u32_e32 v134, 0xa0, v168
	v_ashrrev_i32_e32 v135, 31, v134
	v_lshlrev_b64 v[64:65], 11, v[134:135]
	v_lshl_add_u64 v[64:65], v[64:65], 0, v[166:167]
	v_lshlrev_b64 v[64:65], 1, v[64:65]
	v_lshl_add_u64 v[66:67], s[12:13], 0, v[64:65]
	v_lshl_add_u64 v[64:65], s[14:15], 0, v[64:65]
	global_load_dwordx4 v[122:125], v[66:67], off
	global_load_dwordx4 v[84:87], v[66:67], off offset:256
	global_load_dwordx4 v[126:129], v[64:65], off
	global_load_dwordx4 v[80:83], v[64:65], off offset:256
	v_add_u32_e32 v88, 0xb0, v168
	v_ashrrev_i32_e32 v89, 31, v88
	v_lshlrev_b64 v[64:65], 11, v[88:89]
	v_lshl_add_u64 v[64:65], v[64:65], 0, v[166:167]
	v_lshlrev_b64 v[64:65], 1, v[64:65]
	v_lshl_add_u64 v[66:67], s[12:13], 0, v[64:65]
	v_lshl_add_u64 v[64:65], s[14:15], 0, v[64:65]
	global_load_dwordx4 v[76:79], v[66:67], off
	global_load_dwordx4 v[68:71], v[66:67], off offset:256
	global_load_dwordx4 v[72:75], v[64:65], off
	s_nop 0
	global_load_dwordx4 v[64:67], v[64:65], off offset:256
	v_lshlrev_b64 v[130:131], 12, v[130:131]
	s_waitcnt vmcnt(15)
	v_lshlrev_b32_e32 v136, 16, v90
	v_and_b32_e32 v137, 0xffff0000, v90
	v_lshlrev_b32_e32 v90, 16, v91
	v_and_b32_e32 v91, 0xffff0000, v91
	s_waitcnt vmcnt(14)
	v_lshlrev_b32_e32 v140, 16, v94
	v_and_b32_e32 v141, 0xffff0000, v94
	v_lshlrev_b32_e32 v94, 16, v95
	v_and_b32_e32 v95, 0xffff0000, v95
	v_lshlrev_b32_e32 v138, 16, v92
	v_and_b32_e32 v139, 0xffff0000, v92
	v_lshlrev_b32_e32 v92, 16, v93
	v_and_b32_e32 v93, 0xffff0000, v93
	v_pk_fma_f32 v[62:63], v[62:63], v[90:91], v[94:95]
	v_pk_fma_f32 v[60:61], v[60:61], v[136:137], v[140:141]
	v_lshlrev_b32_e32 v90, 16, v96
	v_and_b32_e32 v91, 0xffff0000, v96
	v_lshlrev_b32_e32 v94, 16, v97
	v_and_b32_e32 v95, 0xffff0000, v97
	v_pk_fma_f32 v[92:93], v[58:59], v[92:93], v[94:95]
	v_pk_fma_f32 v[58:59], v[56:57], v[138:139], v[90:91]
	v_cvt_pk_bf16_f32 v56, v60, v61
	v_lshl_add_u64 v[60:61], s[14:15], 0, v[130:131]
	v_cvt_pk_bf16_f32 v57, v62, v63
	v_cvt_pk_bf16_f32 v58, v58, v59
	v_cvt_pk_bf16_f32 v59, v92, v93
	v_lshl_add_u64 v[60:61], v[60:61], 0, v[164:165]
	global_store_dwordx4 v[60:61], v[56:59], off
	s_waitcnt vmcnt(13)
; __device__ __forceinline__ float bf_lo(unsigned w) { return __uint_as_float(w << 16); }
; __device__ __forceinline__ float bf_hi(unsigned w) { return __uint_as_float(w & 0xffff0000u); }
; __device__ __forceinline__ u32x4 pack8(const f32x4 a, const f32x4 b) { u32x4 w; w.x = cvt_pk_bf16(a[0], a[1]); w.y = cvt_pk_bf16(a[2], a[3]); w.z = cvt_pk_bf16(b[0], b[1]); w.w = cvt_pk_bf16(b[2], b[3]); return w; }
;     __device__ __forceinline__ void operator()(const f32x4 (&acc)[2][2][4][2], const Unit& u, int wr, int wc, int fr, int fq) const {
;     ...
;         for (int ai = 0; ai < 2; ++ai) { u32x4 gw[4][2], pw[4][2];
; #pragma unroll
;             for (int m = 0; m < 4; ++m) { const size_t off = (size_t)(row0 + ai * HALF + m * 16) * 2048 + col0;
; #pragma unroll
;                 for (int bj = 0; bj < 2; ++bj) { gw[m][bj] = *(const u32x4*)(G + off + bj * HALF); if (PASS == 1) pw[m][bj] = *(const u32x4*)(MIX + off + bj * HALF); } }
; #pragma unroll
;             for (int m = 0; m < 4; ++m) { const size_t off = (size_t)(row0 + ai * HALF + m * 16) * 2048 + col0;
; #pragma unroll
;                 for (int bj = 0; bj < 2; ++bj) { const u32x4 g4 = gw[m][bj];
;                     f32x4 v0 = (f32x4){bf_lo(g4.x), bf_hi(g4.x), bf_lo(g4.y), bf_hi(g4.y)} * acc[ai][bj][m][0], v1 = (f32x4){bf_lo(g4.z), bf_hi(g4.z), bf_lo(g4.w), bf_hi(g4.w)} * acc[ai][bj][m][1];
;                     if (PASS == 1) { const u32x4 p4 = pw[m][bj]; v0 += (f32x4){bf_lo(p4.x), bf_hi(p4.x), bf_lo(p4.y), bf_hi(p4.y)}; v1 += (f32x4){bf_lo(p4.z), bf_hi(p4.z), bf_lo(p4.w), bf_hi(p4.w)}; }
;                     *(u32x4*)(MIX + off + bj * HALF) = pack8(v0, v1); } } }
	v_lshlrev_b32_e32 v92, 16, v102
	v_and_b32_e32 v93, 0xffff0000, v102
	v_lshlrev_b32_e32 v56, 16, v98
	v_and_b32_e32 v57, 0xffff0000, v98
	v_lshlrev_b32_e32 v58, 16, v99
	v_and_b32_e32 v59, 0xffff0000, v99
	v_lshlrev_b32_e32 v94, 16, v103
	v_and_b32_e32 v95, 0xffff0000, v103
	v_lshlrev_b32_e32 v62, 16, v100
	v_and_b32_e32 v63, 0xffff0000, v100
	v_lshlrev_b32_e32 v90, 16, v101
	v_and_b32_e32 v91, 0xffff0000, v101
	v_pk_fma_f32 v[54:55], v[54:55], v[58:59], v[94:95]
	v_pk_fma_f32 v[52:53], v[52:53], v[56:57], v[92:93]
	v_lshlrev_b32_e32 v56, 16, v104
	v_and_b32_e32 v57, 0xffff0000, v104
	v_lshlrev_b32_e32 v58, 16, v105
	v_and_b32_e32 v59, 0xffff0000, v105
	v_pk_fma_f32 v[58:59], v[50:51], v[90:91], v[58:59]
	v_pk_fma_f32 v[50:51], v[48:49], v[62:63], v[56:57]
	v_cvt_pk_bf16_f32 v48, v52, v53
	v_cvt_pk_bf16_f32 v49, v54, v55
	v_cvt_pk_bf16_f32 v50, v50, v51
	v_cvt_pk_bf16_f32 v51, v58, v59
	global_store_dwordx4 v[60:61], v[48:51], off offset:256
	s_waitcnt vmcnt(13)
	v_lshlrev_b32_e32 v52, 16, v107
	v_and_b32_e32 v53, 0xffff0000, v107
	v_lshlrev_b32_e32 v50, 16, v106
	v_and_b32_e32 v51, 0xffff0000, v106
	s_waitcnt vmcnt(11)
	v_lshlrev_b32_e32 v58, 16, v114
	v_and_b32_e32 v59, 0xffff0000, v114
	v_lshlrev_b32_e32 v60, 16, v115
	v_and_b32_e32 v61, 0xffff0000, v115
	v_lshlrev_b64 v[48:49], 12, v[132:133]
	v_lshlrev_b32_e32 v54, 16, v108
	v_and_b32_e32 v55, 0xffff0000, v108
	v_lshlrev_b32_e32 v56, 16, v109
	v_and_b32_e32 v57, 0xffff0000, v109
	v_pk_fma_f32 v[46:47], v[46:47], v[52:53], v[60:61]
	v_pk_fma_f32 v[44:45], v[44:45], v[50:51], v[58:59]
	v_lshlrev_b32_e32 v50, 16, v116
	v_and_b32_e32 v51, 0xffff0000, v116
	v_lshlrev_b32_e32 v52, 16, v117
	v_and_b32_e32 v53, 0xffff0000, v117
	v_pk_fma_f32 v[52:53], v[42:43], v[56:57], v[52:53]
	v_pk_fma_f32 v[42:43], v[40:41], v[54:55], v[50:51]
	v_cvt_pk_bf16_f32 v40, v44, v45
	v_lshl_add_u64 v[44:45], s[14:15], 0, v[48:49]
	v_cvt_pk_bf16_f32 v41, v46, v47
	v_cvt_pk_bf16_f32 v42, v42, v43
	v_cvt_pk_bf16_f32 v43, v52, v53
	v_lshl_add_u64 v[44:45], v[44:45], 0, v[164:165]
	global_store_dwordx4 v[44:45], v[40:43], off
	s_waitcnt vmcnt(11)
	v_lshlrev_b32_e32 v50, 16, v118
	v_and_b32_e32 v51, 0xffff0000, v118
	v_lshlrev_b32_e32 v40, 16, v110
	v_and_b32_e32 v41, 0xffff0000, v110
	v_lshlrev_b32_e32 v42, 16, v111
	v_and_b32_e32 v43, 0xffff0000, v111
	v_lshlrev_b32_e32 v52, 16, v119
	v_and_b32_e32 v53, 0xffff0000, v119
	v_lshlrev_b32_e32 v46, 16, v112
	v_and_b32_e32 v47, 0xffff0000, v112
	v_lshlrev_b32_e32 v48, 16, v113
	v_and_b32_e32 v49, 0xffff0000, v113
	v_pk_fma_f32 v[38:39], v[38:39], v[42:43], v[52:53]
	v_pk_fma_f32 v[36:37], v[36:37], v[40:41], v[50:51]
	v_lshlrev_b32_e32 v40, 16, v120
	v_and_b32_e32 v41, 0xffff0000, v120
	v_lshlrev_b32_e32 v42, 16, v121
	v_and_b32_e32 v43, 0xffff0000, v121
	v_pk_fma_f32 v[42:43], v[34:35], v[48:49], v[42:43]
	v_pk_fma_f32 v[34:35], v[32:33], v[46:47], v[40:41]
	v_cvt_pk_bf16_f32 v32, v36, v37
	v_cvt_pk_bf16_f32 v33, v38, v39
	v_cvt_pk_bf16_f32 v34, v34, v35
	v_cvt_pk_bf16_f32 v35, v42, v43
	global_store_dwordx4 v[44:45], v[32:35], off offset:256
	s_waitcnt vmcnt(11)
	v_lshlrev_b32_e32 v36, 16, v123
	v_and_b32_e32 v37, 0xffff0000, v123
	v_lshlrev_b32_e32 v34, 16, v122
	v_and_b32_e32 v35, 0xffff0000, v122
	s_waitcnt vmcnt(9)
; __device__ __forceinline__ float bf_lo(unsigned w) { return __uint_as_float(w << 16); }
; __device__ __forceinline__ float bf_hi(unsigned w) { return __uint_as_float(w & 0xffff0000u); }
; #define PG8_WAIT_V(n) asm volatile("s_waitcnt vmcnt(" #n ")" ::: "memory")
; #define PG8_BAR __builtin_amdgcn_s_barrier()
;     __device__ __forceinline__ void operator()(const f32x4 (&acc)[2][2][4][2], const Unit& u, int wr, int wc, int fr, int fq) const {
;     ...
;         for (int ai = 0; ai < 2; ++ai) { u32x4 gw[4][2], pw[4][2];
; #pragma unroll
;             for (int m = 0; m < 4; ++m) { const size_t off = (size_t)(row0 + ai * HALF + m * 16) * 2048 + col0;
; #pragma unroll
;                 for (int bj = 0; bj < 2; ++bj) { gw[m][bj] = *(const u32x4*)(G + off + bj * HALF); if (PASS == 1) pw[m][bj] = *(const u32x4*)(MIX + off + bj * HALF); } }
; #pragma unroll
;             for (int m = 0; m < 4; ++m) { const size_t off = (size_t)(row0 + ai * HALF + m * 16) * 2048 + col0;
; #pragma unroll
;                 for (int bj = 0; bj < 2; ++bj) { const u32x4 g4 = gw[m][bj];
;                     f32x4 v0 = (f32x4){bf_lo(g4.x), bf_hi(g4.x), bf_lo(g4.y), bf_hi(g4.y)} * acc[ai][bj][m][0], v1 = (f32x4){bf_lo(g4.z), bf_hi(g4.z), bf_lo(g4.w), bf_hi(g4.w)} * acc[ai][bj][m][1];
;                     if (PASS == 1) { const u32x4 p4 = pw[m][bj]; v0 += (f32x4){bf_lo(p4.x), bf_hi(p4.x), bf_lo(p4.y), bf_hi(p4.y)}; v1 += (f32x4){bf_lo(p4.z), bf_hi(p4.z), bf_lo(p4.w), bf_hi(p4.w)}; }
;                     *(u32x4*)(MIX + off + bj * HALF) = pack8(v0, v1); } } }
; template <class Epi, class Sched, bool ALIGN_EPI = false, bool SP2 = false>
; __device__ __forceinline__ void gemm_phase(PG8_LAS unsigned char* lds, const Gemm g, const Sched& S, const Epi& E) {
;     ...
;         if constexpr (!Epi::AFTER_DRAIN) { E(acc, cur, wr, wc, fr, fq); S.done(cur); }
;         if (!has_next) break;
; #pragma unroll
;         for (int a = 0; a < 2; ++a)
; #pragma unroll
;             for (int b = 0; b < 2; ++b)
; #pragma unroll
;                 for (int m = 0; m < 4; ++m)
; #pragma unroll
;                     for (int n = 0; n < 2; ++n) acc[a][b][m][n] = (f32x4){0.f, 0.f, 0.f, 0.f};
;         cur = nxt; cA = nA; cB = nB; ++ui;
;         if constexpr (ALIGN_EPI) { if (wr == 1) PG8_BAR; }
;     }
;     PG8_WAIT_V(0);
;     if constexpr (!ALIGN_EPI) { if (wr == 0) PG8_BAR; }
	v_lshlrev_b32_e32 v42, 16, v126
	v_and_b32_e32 v43, 0xffff0000, v126
	v_lshlrev_b32_e32 v44, 16, v127
	v_and_b32_e32 v45, 0xffff0000, v127
	v_lshlrev_b64 v[32:33], 12, v[134:135]
	v_lshlrev_b32_e32 v38, 16, v124
	v_and_b32_e32 v39, 0xffff0000, v124
	v_lshlrev_b32_e32 v40, 16, v125
	v_and_b32_e32 v41, 0xffff0000, v125
	v_pk_fma_f32 v[30:31], v[30:31], v[36:37], v[44:45]
	v_pk_fma_f32 v[28:29], v[28:29], v[34:35], v[42:43]
	v_lshlrev_b32_e32 v34, 16, v128
	v_and_b32_e32 v35, 0xffff0000, v128
	v_lshlrev_b32_e32 v36, 16, v129
	v_and_b32_e32 v37, 0xffff0000, v129
	v_pk_fma_f32 v[36:37], v[26:27], v[40:41], v[36:37]
	v_pk_fma_f32 v[26:27], v[24:25], v[38:39], v[34:35]
	v_cvt_pk_bf16_f32 v24, v28, v29
	v_lshl_add_u64 v[28:29], s[14:15], 0, v[32:33]
	v_cvt_pk_bf16_f32 v25, v30, v31
	v_cvt_pk_bf16_f32 v26, v26, v27
	v_cvt_pk_bf16_f32 v27, v36, v37
	v_lshl_add_u64 v[28:29], v[28:29], 0, v[164:165]
	global_store_dwordx4 v[28:29], v[24:27], off
	s_waitcnt vmcnt(9)
	v_lshlrev_b32_e32 v34, 16, v80
	v_and_b32_e32 v35, 0xffff0000, v80
	v_lshlrev_b32_e32 v24, 16, v84
	v_and_b32_e32 v25, 0xffff0000, v84
	v_lshlrev_b32_e32 v26, 16, v85
	v_and_b32_e32 v27, 0xffff0000, v85
	v_lshlrev_b32_e32 v36, 16, v81
	v_and_b32_e32 v37, 0xffff0000, v81
	v_lshlrev_b32_e32 v30, 16, v86
	v_and_b32_e32 v31, 0xffff0000, v86
	v_lshlrev_b32_e32 v32, 16, v87
	v_and_b32_e32 v33, 0xffff0000, v87
	v_pk_fma_f32 v[22:23], v[22:23], v[26:27], v[36:37]
	v_pk_fma_f32 v[20:21], v[20:21], v[24:25], v[34:35]
	v_lshlrev_b32_e32 v24, 16, v82
	v_and_b32_e32 v25, 0xffff0000, v82
	v_lshlrev_b32_e32 v26, 16, v83
	v_and_b32_e32 v27, 0xffff0000, v83
	v_pk_fma_f32 v[26:27], v[18:19], v[32:33], v[26:27]
	v_pk_fma_f32 v[18:19], v[16:17], v[30:31], v[24:25]
	v_cvt_pk_bf16_f32 v16, v20, v21
	v_cvt_pk_bf16_f32 v17, v22, v23
	v_cvt_pk_bf16_f32 v18, v18, v19
	v_cvt_pk_bf16_f32 v19, v26, v27
	global_store_dwordx4 v[28:29], v[16:19], off offset:256
	s_waitcnt vmcnt(9)
	v_lshlrev_b32_e32 v20, 16, v77
	v_and_b32_e32 v21, 0xffff0000, v77
	v_lshlrev_b32_e32 v18, 16, v76
	v_and_b32_e32 v19, 0xffff0000, v76
	s_waitcnt vmcnt(7)
	v_lshlrev_b32_e32 v26, 16, v72
	v_and_b32_e32 v27, 0xffff0000, v72
	v_lshlrev_b32_e32 v28, 16, v73
	v_and_b32_e32 v29, 0xffff0000, v73
	v_lshlrev_b64 v[16:17], 12, v[88:89]
	v_lshlrev_b32_e32 v22, 16, v78
	v_and_b32_e32 v23, 0xffff0000, v78
	v_lshlrev_b32_e32 v24, 16, v79
	v_and_b32_e32 v25, 0xffff0000, v79
	v_pk_fma_f32 v[14:15], v[14:15], v[20:21], v[28:29]
	v_pk_fma_f32 v[12:13], v[12:13], v[18:19], v[26:27]
	v_lshlrev_b32_e32 v18, 16, v74
	v_and_b32_e32 v19, 0xffff0000, v74
	v_lshlrev_b32_e32 v20, 16, v75
	v_and_b32_e32 v21, 0xffff0000, v75
	v_pk_fma_f32 v[20:21], v[10:11], v[24:25], v[20:21]
	v_pk_fma_f32 v[10:11], v[8:9], v[22:23], v[18:19]
	v_cvt_pk_bf16_f32 v8, v12, v13
	v_lshl_add_u64 v[12:13], s[14:15], 0, v[16:17]
	v_cvt_pk_bf16_f32 v9, v14, v15
	v_cvt_pk_bf16_f32 v10, v10, v11
	v_cvt_pk_bf16_f32 v11, v20, v21
	v_lshl_add_u64 v[12:13], v[12:13], 0, v[164:165]
	global_store_dwordx4 v[12:13], v[8:11], off
	s_waitcnt vmcnt(7)
	v_lshlrev_b32_e32 v18, 16, v64
	v_and_b32_e32 v19, 0xffff0000, v64
	v_lshlrev_b32_e32 v8, 16, v68
	v_and_b32_e32 v9, 0xffff0000, v68
	v_lshlrev_b32_e32 v10, 16, v69
	v_and_b32_e32 v11, 0xffff0000, v69
	v_lshlrev_b32_e32 v20, 16, v65
	v_and_b32_e32 v21, 0xffff0000, v65
	v_lshlrev_b32_e32 v14, 16, v70
	v_and_b32_e32 v15, 0xffff0000, v70
	v_lshlrev_b32_e32 v16, 16, v71
	v_and_b32_e32 v17, 0xffff0000, v71
	v_pk_fma_f32 v[6:7], v[6:7], v[10:11], v[20:21]
	v_pk_fma_f32 v[4:5], v[4:5], v[8:9], v[18:19]
	v_lshlrev_b32_e32 v8, 16, v66
	v_and_b32_e32 v9, 0xffff0000, v66
	v_lshlrev_b32_e32 v10, 16, v67
	v_and_b32_e32 v11, 0xffff0000, v67
	v_pk_fma_f32 v[10:11], v[2:3], v[16:17], v[10:11]
	v_pk_fma_f32 v[2:3], v[0:1], v[14:15], v[8:9]
	v_cvt_pk_bf16_f32 v0, v4, v5
	v_cvt_pk_bf16_f32 v1, v6, v7
	v_cvt_pk_bf16_f32 v2, v2, v3
	v_cvt_pk_bf16_f32 v3, v10, v11
	global_store_dwordx4 v[12:13], v[0:3], off offset:256
	s_cbranch_vccz .LBB0_748
	s_waitcnt vmcnt(0)
	s_cmpk_gt_u32 s3, 0xff
	s_cbranch_scc1 .LBB0_759
	s_barrier

; #define PG8_STAGE(bufoff, gbase, voff) do { _Pragma("unroll") for (int _i = 0; _i < 2; ++_i) \
;         __builtin_amdgcn_global_load_lds((const unsigned*)((const char*)(gbase) + (voff)[_i]), (PG8_LAS unsigned*)(lds + (bufoff) + ldsw + _i * 8192), 16, 0, 0); } while (0)
; #define PG8_LDA(dst, b, h) do { _Pragma("unroll") for (int m = 0; m < 4; ++m) _Pragma("unroll") for (int k = 0; k < 2; ++k) dst[m][k] = *(const PG8_LAS bf16x8*)(lds + PG8_SA(b, h) + aoff + m * 2048 + k * 1024); } while (0)
; #define PG8_LDB(dst, b, h) do { _Pragma("unroll") for (int n = 0; n < 2; ++n) _Pragma("unroll") for (int k = 0; k < 2; ++k) dst[n][k] = *(const PG8_LAS bf16x8*)(lds + PG8_SB(b, h) + boff + n * 2048 + k * 1024); } while (0)
; #define PG8_WAIT_V(n) asm volatile("s_waitcnt vmcnt(" #n ")" ::: "memory")
; #define PG8_WAIT_L(n) asm volatile("s_waitcnt lgkmcnt(" #n ")" ::: "memory")
; #define PG8_BAR __builtin_amdgcn_s_barrier()
; #define PG8_SCHED __builtin_amdgcn_sched_barrier(0)
; template <class Epi, class Sched, bool ALIGN_EPI = false, bool SP2 = false>
; __device__ __forceinline__ void gemm_phase(PG8_LAS unsigned char* lds, const Gemm g, const Sched& S, const Epi& E) {
;     ...
;         const bool has_next = S.next(ui + 1, nxt);
;         const char* nA = has_next ? (const char*)g.A + (size_t)nxt.pm * tstep : cA; const char* nB = has_next ? (const char*)g.Bt + (size_t)nxt.pn * tstep : cB;
;         for (int t = 0; t < nt; t += 2) {
;             const bool last = (t == nt - 2);
;             const char* a1 = cA + (size_t)(t + 1) * kstep;
;             const char* a2 = last ? nA : cA + (size_t)(t + 2) * kstep; const char* b2 = last ? nB : cB + (size_t)(t + 2) * kstep;
;             const char* a3 = a2 + kstep; const char* b3 = b2 + kstep;
;             if (last && has_next) S.a_ready(nxt);
;             if constexpr (SP2) {
;             PG8_LDB(B0, 0, 0); PG8_LDB(B1, 0, 1); PG8_SCHED; PG8_LDA(At, 0, 0); PG8_STAGE(PG8_SA(1, 1), a1 + hstep, voffA);
;             PG8_WAIT_V(8); PG8_WAIT_L(0); PG8_BAR; PG8_MMA(0, 0, At, B0); PG8_MMA(0, 1, At, B1); PG8_BAR; PG8_SCHED;
;             PG8_LDA(At, 0, 1); PG8_STAGE(PG8_SB(0, 0), b2, voffB); PG8_STAGE(PG8_SB(0, 1), b2 + hstep, voffB); PG8_STAGE(PG8_SA(0, 0), a2, voffA);
;             PG8_WAIT_V(8); PG8_WAIT_L(0); PG8_BAR; PG8_MMA(1, 0, At, B0); PG8_MMA(1, 1, At, B1); PG8_BAR; PG8_SCHED;
.LBB0_826:
	s_ashr_i32 s39, s38, 31
	v_cmp_lt_i64_e32 vcc, s[40:41], v[156:157]
	s_lshl_b64 s[40:41], s[38:39], 20
	s_add_u32 s40, s9, s40
	s_addc_u32 s41, s22, s41
	s_and_b64 s[42:43], vcc, exec
	s_cselect_b32 s39, s41, s47
	s_cselect_b32 s67, s40, s46
	s_ashr_i32 s37, s36, 31
	s_lshl_b64 s[42:43], s[36:37], 20
	s_add_u32 s42, s23, s42
	s_addc_u32 s43, s52, s43
	s_and_b64 s[50:51], vcc, exec
	s_cselect_b32 s37, s43, s49
	s_cselect_b32 s68, s42, s48
	s_add_u32 s46, s46, 0x80080
	s_addc_u32 s47, s47, 0
	s_add_u32 s69, s48, 0x100
	s_addc_u32 s70, s49, 0
	s_mov_b32 s71, -2
	ds_read_b128 v[128:131], v169
	ds_read_b128 v[132:135], v169 offset:1024
	ds_read_b128 v[136:139], v169 offset:2048
	ds_read_b128 v[140:143], v169 offset:3072
	ds_read_b128 v[160:163], v170
	ds_read_b128 v[172:175], v170 offset:1024
	ds_read_b128 v[176:179], v170 offset:2048
	ds_read_b128 v[180:183], v170 offset:3072
	s_add_u32 s48, s46, 0xfff80080
	s_addc_u32 s49, s47, -1
	s_cmp_eq_u32 s71, 28
	s_cselect_b32 s51, s39, s49
	s_cselect_b32 s50, s67, s48
	s_cselect_b32 s49, s37, s70
	s_cselect_b32 s48, s68, s69
	s_add_i32 m0, s45, 0xc000
	ds_read_b128 v[184:187], v171
	ds_read_b128 v[188:191], v171 offset:1024
	ds_read_b128 v[192:195], v171 offset:2048
	ds_read_b128 v[196:199], v171 offset:3072
	ds_read_b128 v[200:203], v171 offset:4096
	ds_read_b128 v[204:207], v171 offset:5120
	ds_read_b128 v[208:211], v171 offset:6144
	ds_read_b128 v[214:217], v171 offset:7168
	global_load_lds_dwordx4 v152, s[46:47]
	s_add_i32 m0, s45, 0xe000
	s_nop 0
	global_load_lds_dwordx4 v154, s[46:47]
	s_waitcnt vmcnt(8)
	s_waitcnt lgkmcnt(0)
	s_barrier
	v_mfma_f32_16x16x32_bf16 v[124:127], v[128:131], v[184:187], 0
	v_mfma_f32_16x16x32_bf16 v[120:123], v[136:139], v[184:187], 0
	v_mfma_f32_16x16x32_bf16 v[116:119], v[128:131], v[192:195], 0
	v_mfma_f32_16x16x32_bf16 v[112:115], v[136:139], v[192:195], 0
	v_mfma_f32_16x16x32_bf16 v[108:111], v[128:131], v[200:203], 0
	v_mfma_f32_16x16x32_bf16 v[96:99], v[136:139], v[200:203], 0
	v_mfma_f32_16x16x32_bf16 v[80:83], v[128:131], v[208:211], 0
	v_mfma_f32_16x16x32_bf16 v[72:75], v[136:139], v[208:211], 0
	v_mfma_f32_16x16x32_bf16 v[124:127], v[132:135], v[188:191], v[124:127]
	v_mfma_f32_16x16x32_bf16 v[120:123], v[140:143], v[188:191], v[120:123]
	v_mfma_f32_16x16x32_bf16 v[116:119], v[132:135], v[196:199], v[116:119]
	v_mfma_f32_16x16x32_bf16 v[112:115], v[140:143], v[196:199], v[112:115]
	v_mfma_f32_16x16x32_bf16 v[108:111], v[132:135], v[204:207], v[108:111]
	v_mfma_f32_16x16x32_bf16 v[96:99], v[140:143], v[204:207], v[96:99]
	v_mfma_f32_16x16x32_bf16 v[80:83], v[132:135], v[214:217], v[80:83]
	v_mfma_f32_16x16x32_bf16 v[72:75], v[140:143], v[214:217], v[72:75]
	v_mfma_f32_16x16x32_bf16 v[104:107], v[160:163], v[184:187], 0
	v_mfma_f32_16x16x32_bf16 v[100:103], v[176:179], v[184:187], 0
	v_mfma_f32_16x16x32_bf16 v[92:95], v[160:163], v[192:195], 0
	v_mfma_f32_16x16x32_bf16 v[88:91], v[176:179], v[192:195], 0
	v_mfma_f32_16x16x32_bf16 v[84:87], v[160:163], v[200:203], 0
	v_mfma_f32_16x16x32_bf16 v[76:79], v[176:179], v[200:203], 0
	v_mfma_f32_16x16x32_bf16 v[68:71], v[160:163], v[208:211], 0
	v_mfma_f32_16x16x32_bf16 v[64:67], v[176:179], v[208:211], 0
	v_mfma_f32_16x16x32_bf16 v[104:107], v[172:175], v[188:191], v[104:107]
	v_mfma_f32_16x16x32_bf16 v[100:103], v[180:183], v[188:191], v[100:103]
	v_mfma_f32_16x16x32_bf16 v[92:95], v[172:175], v[196:199], v[92:95]
	v_mfma_f32_16x16x32_bf16 v[88:91], v[180:183], v[196:199], v[88:91]
	v_mfma_f32_16x16x32_bf16 v[84:87], v[172:175], v[204:207], v[84:87]
	v_mfma_f32_16x16x32_bf16 v[76:79], v[180:183], v[204:207], v[76:79]
	v_mfma_f32_16x16x32_bf16 v[68:71], v[172:175], v[214:217], v[68:71]
	v_mfma_f32_16x16x32_bf16 v[64:67], v[180:183], v[214:217], v[64:67]
	s_barrier
	s_add_i32 s72, s64, s53
	s_mov_b32 m0, s72
	ds_read_b128 v[184:187], v171 offset:16384
	ds_read_b128 v[188:191], v171 offset:17408
	ds_read_b128 v[192:195], v171 offset:18432
	ds_read_b128 v[196:199], v171 offset:19456
	ds_read_b128 v[200:203], v171 offset:20480
	ds_read_b128 v[204:207], v171 offset:21504
	ds_read_b128 v[208:211], v171 offset:22528
	ds_read_b128 v[214:217], v171 offset:23552
	global_load_lds_dwordx4 v146, s[48:49]
	s_add_i32 m0, s72, 0x2000
	s_add_u32 s72, s48, 0x80000
	s_addc_u32 s73, s49, 0
	s_add_i32 s74, s65, s53
	global_load_lds_dwordx4 v150, s[48:49]
	s_mov_b32 m0, s74
	s_nop 0
	global_load_lds_dwordx4 v146, s[72:73]
	s_add_i32 m0, s74, 0x2000
	s_nop 0
	global_load_lds_dwordx4 v150, s[72:73]
	s_mov_b32 m0, s45
	s_nop 0
	global_load_lds_dwordx4 v144, s[50:51]
	s_mov_b32 m0, s54
	s_nop 0
	global_load_lds_dwordx4 v148, s[50:51]
	s_waitcnt vmcnt(8)
	s_waitcnt lgkmcnt(0)
	s_barrier
; #define PG8_STAGE(bufoff, gbase, voff) do { _Pragma("unroll") for (int _i = 0; _i < 2; ++_i) \
;         __builtin_amdgcn_global_load_lds((const unsigned*)((const char*)(gbase) + (voff)[_i]), (PG8_LAS unsigned*)(lds + (bufoff) + ldsw + _i * 8192), 16, 0, 0); } while (0)
; #define PG8_LDA(dst, b, h) do { _Pragma("unroll") for (int m = 0; m < 4; ++m) _Pragma("unroll") for (int k = 0; k < 2; ++k) dst[m][k] = *(const PG8_LAS bf16x8*)(lds + PG8_SA(b, h) + aoff + m * 2048 + k * 1024); } while (0)
; #define PG8_LDB(dst, b, h) do { _Pragma("unroll") for (int n = 0; n < 2; ++n) _Pragma("unroll") for (int k = 0; k < 2; ++k) dst[n][k] = *(const PG8_LAS bf16x8*)(lds + PG8_SB(b, h) + boff + n * 2048 + k * 1024); } while (0)
; #define PG8_MMA(ai, bj, At, Bt) do { __builtin_amdgcn_s_setprio(1); _Pragma("unroll") for (int m = 0; m < 4; ++m) _Pragma("unroll") for (int n = 0; n < 2; ++n) _Pragma("unroll") for (int k = 0; k < 2; ++k) \
;         acc[ai][bj][m][n] = __builtin_amdgcn_mfma_f32_16x16x32_bf16(Bt[n][k], At[m][k], acc[ai][bj][m][n], 0, 0, 0); __builtin_amdgcn_s_setprio(0); } while (0)
; #define PG8_WAIT_V(n) asm volatile("s_waitcnt vmcnt(" #n ")" ::: "memory")
; template <class Epi, class Sched, bool ALIGN_EPI = false, bool SP2 = false>
; __device__ __forceinline__ void gemm_phase(PG8_LAS unsigned char* lds, const Gemm g, const Sched& S, const Epi& E) {
;     ...
;             PG8_LDB(B0, 0, 0); PG8_LDB(B1, 0, 1); PG8_SCHED; PG8_LDA(At, 0, 0); PG8_STAGE(PG8_SA(1, 1), a1 + hstep, voffA);
;             PG8_WAIT_V(8); PG8_WAIT_L(0); PG8_BAR; PG8_MMA(0, 0, At, B0); PG8_MMA(0, 1, At, B1); PG8_BAR; PG8_SCHED;
;             PG8_LDA(At, 0, 1); PG8_STAGE(PG8_SB(0, 0), b2, voffB); PG8_STAGE(PG8_SB(0, 1), b2 + hstep, voffB); PG8_STAGE(PG8_SA(0, 0), a2, voffA);
;             PG8_WAIT_V(8); PG8_WAIT_L(0); PG8_BAR; PG8_MMA(1, 0, At, B0); PG8_MMA(1, 1, At, B1); PG8_BAR; PG8_SCHED;
;             PG8_LDB(B0, 1, 0); PG8_LDB(B1, 1, 1); PG8_SCHED; PG8_LDA(At, 1, 0); PG8_STAGE(PG8_SA(0, 1), a2 + hstep, voffA);
;             PG8_WAIT_V(8); PG8_WAIT_L(0); PG8_BAR; PG8_MMA(0, 0, At, B0); PG8_MMA(0, 1, At, B1); PG8_BAR; PG8_SCHED;
;             PG8_LDA(At, 1, 1); PG8_STAGE(PG8_SB(1, 0), b3, voffB); PG8_STAGE(PG8_SB(1, 1), b3 + hstep, voffB); PG8_STAGE(PG8_SA(1, 0), a3, voffA);
;             PG8_WAIT_V(8); PG8_WAIT_L(0); PG8_BAR; PG8_MMA(1, 0, At, B0); PG8_MMA(1, 1, At, B1); PG8_BAR; PG8_SCHED;
	v_mfma_f32_16x16x32_bf16 v[60:63], v[128:131], v[184:187], 0
	v_mfma_f32_16x16x32_bf16 v[56:59], v[136:139], v[184:187], 0
	v_mfma_f32_16x16x32_bf16 v[52:55], v[128:131], v[192:195], 0
	v_mfma_f32_16x16x32_bf16 v[48:51], v[136:139], v[192:195], 0
	v_mfma_f32_16x16x32_bf16 v[44:47], v[128:131], v[200:203], 0
	v_mfma_f32_16x16x32_bf16 v[32:35], v[136:139], v[200:203], 0
	v_mfma_f32_16x16x32_bf16 v[20:23], v[128:131], v[208:211], 0
	v_mfma_f32_16x16x32_bf16 v[8:11], v[136:139], v[208:211], 0
	v_mfma_f32_16x16x32_bf16 v[60:63], v[132:135], v[188:191], v[60:63]
	v_mfma_f32_16x16x32_bf16 v[56:59], v[140:143], v[188:191], v[56:59]
	v_mfma_f32_16x16x32_bf16 v[52:55], v[132:135], v[196:199], v[52:55]
	v_mfma_f32_16x16x32_bf16 v[48:51], v[140:143], v[196:199], v[48:51]
	v_mfma_f32_16x16x32_bf16 v[44:47], v[132:135], v[204:207], v[44:47]
	v_mfma_f32_16x16x32_bf16 v[32:35], v[140:143], v[204:207], v[32:35]
	v_mfma_f32_16x16x32_bf16 v[20:23], v[132:135], v[214:217], v[20:23]
	v_mfma_f32_16x16x32_bf16 v[8:11], v[140:143], v[214:217], v[8:11]
	v_mfma_f32_16x16x32_bf16 v[40:43], v[160:163], v[184:187], 0
	v_mfma_f32_16x16x32_bf16 v[36:39], v[176:179], v[184:187], 0
	v_mfma_f32_16x16x32_bf16 v[28:31], v[160:163], v[192:195], 0
	v_mfma_f32_16x16x32_bf16 v[24:27], v[176:179], v[192:195], 0
	v_mfma_f32_16x16x32_bf16 v[16:19], v[160:163], v[200:203], 0
	v_mfma_f32_16x16x32_bf16 v[12:15], v[176:179], v[200:203], 0
	v_mfma_f32_16x16x32_bf16 v[4:7], v[160:163], v[208:211], 0
	v_mfma_f32_16x16x32_bf16 v[0:3], v[176:179], v[208:211], 0
	v_mfma_f32_16x16x32_bf16 v[40:43], v[172:175], v[188:191], v[40:43]
	v_mfma_f32_16x16x32_bf16 v[36:39], v[180:183], v[188:191], v[36:39]
	v_mfma_f32_16x16x32_bf16 v[28:31], v[172:175], v[196:199], v[28:31]
	v_mfma_f32_16x16x32_bf16 v[24:27], v[180:183], v[196:199], v[24:27]
	v_mfma_f32_16x16x32_bf16 v[16:19], v[172:175], v[204:207], v[16:19]
	v_mfma_f32_16x16x32_bf16 v[12:15], v[180:183], v[204:207], v[12:15]
	v_mfma_f32_16x16x32_bf16 v[4:7], v[172:175], v[214:217], v[4:7]
	v_mfma_f32_16x16x32_bf16 v[0:3], v[180:183], v[214:217], v[0:3]
	s_barrier
	s_add_i32 s72, 0, 0x18000
	s_add_i32 s73, 0, 0x1c000
	v_add_u32_e32 v140, s72, v167
	v_add_u32_e32 v180, s73, v167
	ds_read_b128 v[128:131], v140
	ds_read_b128 v[132:135], v140 offset:1024
	ds_read_b128 v[136:139], v140 offset:2048
	ds_read_b128 v[140:143], v140 offset:3072
	ds_read_b128 v[160:163], v180
	ds_read_b128 v[172:175], v180 offset:1024
	ds_read_b128 v[176:179], v180 offset:2048
	ds_read_b128 v[180:183], v180 offset:3072
	s_add_u32 s84, s50, 0x80
	s_addc_u32 s85, s51, 0
	s_add_u32 s50, s50, 0x80000
	s_addc_u32 s51, s51, 0
	s_mov_b32 m0, s55
	ds_read_b128 v[184:187], v171 offset:32768
	ds_read_b128 v[188:191], v171 offset:33792
	ds_read_b128 v[192:195], v171 offset:34816
	ds_read_b128 v[196:199], v171 offset:35840
	ds_read_b128 v[200:203], v171 offset:36864
	ds_read_b128 v[204:207], v171 offset:37888
	ds_read_b128 v[208:211], v171 offset:38912
	ds_read_b128 v[214:217], v171 offset:39936
	global_load_lds_dwordx4 v144, s[50:51]
	s_mov_b32 m0, s56
	s_nop 0
	global_load_lds_dwordx4 v148, s[50:51]
	s_waitcnt vmcnt(8)
	s_waitcnt lgkmcnt(0)
	s_barrier
	v_mfma_f32_16x16x32_bf16 v[124:127], v[128:131], v[184:187], v[124:127]
	v_mfma_f32_16x16x32_bf16 v[120:123], v[136:139], v[184:187], v[120:123]
	v_mfma_f32_16x16x32_bf16 v[116:119], v[128:131], v[192:195], v[116:119]
	v_mfma_f32_16x16x32_bf16 v[112:115], v[136:139], v[192:195], v[112:115]
	v_mfma_f32_16x16x32_bf16 v[108:111], v[128:131], v[200:203], v[108:111]
	v_mfma_f32_16x16x32_bf16 v[96:99], v[136:139], v[200:203], v[96:99]
	v_mfma_f32_16x16x32_bf16 v[80:83], v[128:131], v[208:211], v[80:83]
	v_mfma_f32_16x16x32_bf16 v[72:75], v[136:139], v[208:211], v[72:75]
	v_mfma_f32_16x16x32_bf16 v[124:127], v[132:135], v[188:191], v[124:127]
	v_mfma_f32_16x16x32_bf16 v[120:123], v[140:143], v[188:191], v[120:123]
	v_mfma_f32_16x16x32_bf16 v[116:119], v[132:135], v[196:199], v[116:119]
	v_mfma_f32_16x16x32_bf16 v[112:115], v[140:143], v[196:199], v[112:115]
	v_mfma_f32_16x16x32_bf16 v[108:111], v[132:135], v[204:207], v[108:111]
	v_mfma_f32_16x16x32_bf16 v[96:99], v[140:143], v[204:207], v[96:99]
	v_mfma_f32_16x16x32_bf16 v[80:83], v[132:135], v[214:217], v[80:83]
	v_mfma_f32_16x16x32_bf16 v[72:75], v[140:143], v[214:217], v[72:75]
	v_mfma_f32_16x16x32_bf16 v[104:107], v[160:163], v[184:187], v[104:107]
	v_mfma_f32_16x16x32_bf16 v[100:103], v[176:179], v[184:187], v[100:103]
	v_mfma_f32_16x16x32_bf16 v[92:95], v[160:163], v[192:195], v[92:95]
	v_mfma_f32_16x16x32_bf16 v[88:91], v[176:179], v[192:195], v[88:91]
	v_mfma_f32_16x16x32_bf16 v[84:87], v[160:163], v[200:203], v[84:87]
	v_mfma_f32_16x16x32_bf16 v[76:79], v[176:179], v[200:203], v[76:79]
	v_mfma_f32_16x16x32_bf16 v[68:71], v[160:163], v[208:211], v[68:71]
	v_mfma_f32_16x16x32_bf16 v[64:67], v[176:179], v[208:211], v[64:67]
	v_mfma_f32_16x16x32_bf16 v[104:107], v[172:175], v[188:191], v[104:107]
	v_mfma_f32_16x16x32_bf16 v[100:103], v[180:183], v[188:191], v[100:103]
	v_mfma_f32_16x16x32_bf16 v[92:95], v[172:175], v[196:199], v[92:95]
	v_mfma_f32_16x16x32_bf16 v[88:91], v[180:183], v[196:199], v[88:91]
	v_mfma_f32_16x16x32_bf16 v[84:87], v[172:175], v[204:207], v[84:87]
	v_mfma_f32_16x16x32_bf16 v[76:79], v[180:183], v[204:207], v[76:79]
	v_mfma_f32_16x16x32_bf16 v[68:71], v[172:175], v[214:217], v[68:71]
	v_mfma_f32_16x16x32_bf16 v[64:67], v[180:183], v[214:217], v[64:67]
	s_barrier
; #define PG8_STAGE(bufoff, gbase, voff) do { _Pragma("unroll") for (int _i = 0; _i < 2; ++_i) \
;         __builtin_amdgcn_global_load_lds((const unsigned*)((const char*)(gbase) + (voff)[_i]), (PG8_LAS unsigned*)(lds + (bufoff) + ldsw + _i * 8192), 16, 0, 0); } while (0)
; #define PG8_LDA(dst, b, h) do { _Pragma("unroll") for (int m = 0; m < 4; ++m) _Pragma("unroll") for (int k = 0; k < 2; ++k) dst[m][k] = *(const PG8_LAS bf16x8*)(lds + PG8_SA(b, h) + aoff + m * 2048 + k * 1024); } while (0)
; #define PG8_LDB(dst, b, h) do { _Pragma("unroll") for (int n = 0; n < 2; ++n) _Pragma("unroll") for (int k = 0; k < 2; ++k) dst[n][k] = *(const PG8_LAS bf16x8*)(lds + PG8_SB(b, h) + boff + n * 2048 + k * 1024); } while (0)
; #define PG8_MMA(ai, bj, At, Bt) do { __builtin_amdgcn_s_setprio(1); _Pragma("unroll") for (int m = 0; m < 4; ++m) _Pragma("unroll") for (int n = 0; n < 2; ++n) _Pragma("unroll") for (int k = 0; k < 2; ++k) \
;         acc[ai][bj][m][n] = __builtin_amdgcn_mfma_f32_16x16x32_bf16(Bt[n][k], At[m][k], acc[ai][bj][m][n], 0, 0, 0); __builtin_amdgcn_s_setprio(0); } while (0)
; #define PG8_WAIT_V(n) asm volatile("s_waitcnt vmcnt(" #n ")" ::: "memory")
; template <class Epi, class Sched, bool ALIGN_EPI = false, bool SP2 = false>
; __device__ __forceinline__ void gemm_phase(PG8_LAS unsigned char* lds, const Gemm g, const Sched& S, const Epi& E) {
;     ...
;             PG8_LDB(B0, 0, 0); PG8_LDB(B1, 0, 1); PG8_SCHED; PG8_LDA(At, 0, 0); PG8_STAGE(PG8_SA(1, 1), a1 + hstep, voffA);
;             PG8_WAIT_V(8); PG8_WAIT_L(0); PG8_BAR; PG8_MMA(0, 0, At, B0); PG8_MMA(0, 1, At, B1); PG8_BAR; PG8_SCHED;
;             PG8_LDA(At, 0, 1); PG8_STAGE(PG8_SB(0, 0), b2, voffB); PG8_STAGE(PG8_SB(0, 1), b2 + hstep, voffB); PG8_STAGE(PG8_SA(0, 0), a2, voffA);
;             PG8_WAIT_V(8); PG8_WAIT_L(0); PG8_BAR; PG8_MMA(1, 0, At, B0); PG8_MMA(1, 1, At, B1); PG8_BAR; PG8_SCHED;
;             PG8_LDB(B0, 1, 0); PG8_LDB(B1, 1, 1); PG8_SCHED; PG8_LDA(At, 1, 0); PG8_STAGE(PG8_SA(0, 1), a2 + hstep, voffA);
;             PG8_WAIT_V(8); PG8_WAIT_L(0); PG8_BAR; PG8_MMA(0, 0, At, B0); PG8_MMA(0, 1, At, B1); PG8_BAR; PG8_SCHED;
;             PG8_LDA(At, 1, 1); PG8_STAGE(PG8_SB(1, 0), b3, voffB); PG8_STAGE(PG8_SB(1, 1), b3 + hstep, voffB); PG8_STAGE(PG8_SA(1, 0), a3, voffA);
;             PG8_WAIT_V(8); PG8_WAIT_L(0); PG8_BAR; PG8_MMA(1, 0, At, B0); PG8_MMA(1, 1, At, B1); PG8_BAR; PG8_SCHED;
	s_add_i32 s50, s72, s53
	s_add_u32 s86, s48, 0x80
	s_addc_u32 s87, s49, 0
	s_mov_b32 m0, s50
	ds_read_b128 v[184:187], v171 offset:49152
	ds_read_b128 v[188:191], v171 offset:50176
	ds_read_b128 v[192:195], v171 offset:51200
	ds_read_b128 v[196:199], v171 offset:52224
	ds_read_b128 v[200:203], v171 offset:53248
	ds_read_b128 v[204:207], v171 offset:54272
	ds_read_b128 v[208:211], v171 offset:55296
	ds_read_b128 v[214:217], v171 offset:56320
	global_load_lds_dwordx4 v146, s[86:87]
	s_add_i32 m0, s50, 0x2000
	s_add_u32 s48, s48, 0x80080
	s_addc_u32 s49, s49, 0
	s_add_i32 s50, s73, s53
	global_load_lds_dwordx4 v150, s[86:87]
	s_mov_b32 m0, s50
	s_nop 0
	global_load_lds_dwordx4 v146, s[48:49]
	s_add_i32 m0, s50, 0x2000
	s_nop 0
	global_load_lds_dwordx4 v150, s[48:49]
	s_mov_b32 m0, s60
	s_nop 0
	global_load_lds_dwordx4 v144, s[84:85]
	s_mov_b32 m0, s61
	s_nop 0
	global_load_lds_dwordx4 v148, s[84:85]
	s_waitcnt vmcnt(8)
	s_waitcnt lgkmcnt(0)
	s_barrier
	v_mfma_f32_16x16x32_bf16 v[60:63], v[128:131], v[184:187], v[60:63]
	v_mfma_f32_16x16x32_bf16 v[56:59], v[136:139], v[184:187], v[56:59]
	v_mfma_f32_16x16x32_bf16 v[52:55], v[128:131], v[192:195], v[52:55]
	v_mfma_f32_16x16x32_bf16 v[48:51], v[136:139], v[192:195], v[48:51]
	v_mfma_f32_16x16x32_bf16 v[44:47], v[128:131], v[200:203], v[44:47]
	v_mfma_f32_16x16x32_bf16 v[32:35], v[136:139], v[200:203], v[32:35]
	v_mfma_f32_16x16x32_bf16 v[20:23], v[128:131], v[208:211], v[20:23]
	v_mfma_f32_16x16x32_bf16 v[8:11], v[136:139], v[208:211], v[8:11]
	v_mfma_f32_16x16x32_bf16 v[60:63], v[132:135], v[188:191], v[60:63]
	v_mfma_f32_16x16x32_bf16 v[56:59], v[140:143], v[188:191], v[56:59]
	v_mfma_f32_16x16x32_bf16 v[52:55], v[132:135], v[196:199], v[52:55]
	v_mfma_f32_16x16x32_bf16 v[48:51], v[140:143], v[196:199], v[48:51]
	v_mfma_f32_16x16x32_bf16 v[44:47], v[132:135], v[204:207], v[44:47]
	v_mfma_f32_16x16x32_bf16 v[32:35], v[140:143], v[204:207], v[32:35]
	v_mfma_f32_16x16x32_bf16 v[20:23], v[132:135], v[214:217], v[20:23]
	v_mfma_f32_16x16x32_bf16 v[8:11], v[140:143], v[214:217], v[8:11]
	v_mfma_f32_16x16x32_bf16 v[40:43], v[160:163], v[184:187], v[40:43]
	v_mfma_f32_16x16x32_bf16 v[36:39], v[176:179], v[184:187], v[36:39]
	v_mfma_f32_16x16x32_bf16 v[28:31], v[160:163], v[192:195], v[28:31]
	v_mfma_f32_16x16x32_bf16 v[24:27], v[176:179], v[192:195], v[24:27]
	v_mfma_f32_16x16x32_bf16 v[16:19], v[160:163], v[200:203], v[16:19]
	v_mfma_f32_16x16x32_bf16 v[12:15], v[176:179], v[200:203], v[12:15]
	v_mfma_f32_16x16x32_bf16 v[4:7], v[160:163], v[208:211], v[4:7]
	v_mfma_f32_16x16x32_bf16 v[0:3], v[176:179], v[208:211], v[0:3]
	v_mfma_f32_16x16x32_bf16 v[40:43], v[172:175], v[188:191], v[40:43]
	v_mfma_f32_16x16x32_bf16 v[36:39], v[180:183], v[188:191], v[36:39]
	v_mfma_f32_16x16x32_bf16 v[28:31], v[172:175], v[196:199], v[28:31]
	v_mfma_f32_16x16x32_bf16 v[24:27], v[180:183], v[196:199], v[24:27]
	v_mfma_f32_16x16x32_bf16 v[16:19], v[172:175], v[204:207], v[16:19]
	v_mfma_f32_16x16x32_bf16 v[12:15], v[180:183], v[204:207], v[12:15]
	v_mfma_f32_16x16x32_bf16 v[4:7], v[172:175], v[214:217], v[4:7]
	v_mfma_f32_16x16x32_bf16 v[0:3], v[180:183], v[214:217], v[0:3]
	s_barrier
	s_add_i32 s71, s71, 2
	s_add_u32 s46, s46, 0x100
	s_addc_u32 s47, s47, 0
	s_add_u32 s69, s69, 0x100
	s_addc_u32 s70, s70, 0
	s_cmp_gt_u32 s71, 29
.LBB0_827:
	ds_read_b128 v[128:131], v169
	ds_read_b128 v[132:135], v169 offset:1024
	ds_read_b128 v[136:139], v169 offset:2048
	ds_read_b128 v[140:143], v169 offset:3072
	ds_read_b128 v[160:163], v170
	ds_read_b128 v[172:175], v170 offset:1024
	ds_read_b128 v[176:179], v170 offset:2048
	ds_read_b128 v[180:183], v170 offset:3072
	s_add_u32 s48, s46, 0xfff80080
	s_addc_u32 s49, s47, -1
	s_cmp_eq_u32 s71, 28
	s_cselect_b32 s51, s39, s49
	s_cselect_b32 s50, s67, s48
	s_cselect_b32 s49, s37, s70
	s_cselect_b32 s48, s68, s69
	s_add_i32 m0, s45, 0xc000
	ds_read_b128 v[184:187], v171
	ds_read_b128 v[188:191], v171 offset:1024
	ds_read_b128 v[192:195], v171 offset:2048
	ds_read_b128 v[196:199], v171 offset:3072
	ds_read_b128 v[200:203], v171 offset:4096
	ds_read_b128 v[204:207], v171 offset:5120
	ds_read_b128 v[208:211], v171 offset:6144
	ds_read_b128 v[214:217], v171 offset:7168
	global_load_lds_dwordx4 v152, s[46:47]
	s_add_i32 m0, s45, 0xe000
	s_nop 0
	global_load_lds_dwordx4 v154, s[46:47]
	s_waitcnt vmcnt(8)
	s_waitcnt lgkmcnt(0)
	s_barrier
	v_mfma_f32_16x16x32_bf16 v[124:127], v[128:131], v[184:187], v[124:127]
	v_mfma_f32_16x16x32_bf16 v[120:123], v[136:139], v[184:187], v[120:123]
	v_mfma_f32_16x16x32_bf16 v[116:119], v[128:131], v[192:195], v[116:119]
	v_mfma_f32_16x16x32_bf16 v[112:115], v[136:139], v[192:195], v[112:115]
	v_mfma_f32_16x16x32_bf16 v[108:111], v[128:131], v[200:203], v[108:111]
	v_mfma_f32_16x16x32_bf16 v[96:99], v[136:139], v[200:203], v[96:99]
	v_mfma_f32_16x16x32_bf16 v[80:83], v[128:131], v[208:211], v[80:83]
	v_mfma_f32_16x16x32_bf16 v[72:75], v[136:139], v[208:211], v[72:75]
	v_mfma_f32_16x16x32_bf16 v[124:127], v[132:135], v[188:191], v[124:127]
	v_mfma_f32_16x16x32_bf16 v[120:123], v[140:143], v[188:191], v[120:123]
	v_mfma_f32_16x16x32_bf16 v[116:119], v[132:135], v[196:199], v[116:119]
	v_mfma_f32_16x16x32_bf16 v[112:115], v[140:143], v[196:199], v[112:115]
	v_mfma_f32_16x16x32_bf16 v[108:111], v[132:135], v[204:207], v[108:111]
	v_mfma_f32_16x16x32_bf16 v[96:99], v[140:143], v[204:207], v[96:99]
	v_mfma_f32_16x16x32_bf16 v[80:83], v[132:135], v[214:217], v[80:83]
	v_mfma_f32_16x16x32_bf16 v[72:75], v[140:143], v[214:217], v[72:75]
	v_mfma_f32_16x16x32_bf16 v[104:107], v[160:163], v[184:187], v[104:107]
	v_mfma_f32_16x16x32_bf16 v[100:103], v[176:179], v[184:187], v[100:103]
	v_mfma_f32_16x16x32_bf16 v[92:95], v[160:163], v[192:195], v[92:95]
	v_mfma_f32_16x16x32_bf16 v[88:91], v[176:179], v[192:195], v[88:91]
	v_mfma_f32_16x16x32_bf16 v[84:87], v[160:163], v[200:203], v[84:87]
	v_mfma_f32_16x16x32_bf16 v[76:79], v[176:179], v[200:203], v[76:79]
	v_mfma_f32_16x16x32_bf16 v[68:71], v[160:163], v[208:211], v[68:71]
	v_mfma_f32_16x16x32_bf16 v[64:67], v[176:179], v[208:211], v[64:67]
	v_mfma_f32_16x16x32_bf16 v[104:107], v[172:175], v[188:191], v[104:107]
	v_mfma_f32_16x16x32_bf16 v[100:103], v[180:183], v[188:191], v[100:103]
	v_mfma_f32_16x16x32_bf16 v[92:95], v[172:175], v[196:199], v[92:95]
	v_mfma_f32_16x16x32_bf16 v[88:91], v[180:183], v[196:199], v[88:91]
	v_mfma_f32_16x16x32_bf16 v[84:87], v[172:175], v[204:207], v[84:87]
	v_mfma_f32_16x16x32_bf16 v[76:79], v[180:183], v[204:207], v[76:79]
	v_mfma_f32_16x16x32_bf16 v[68:71], v[172:175], v[214:217], v[68:71]
	v_mfma_f32_16x16x32_bf16 v[64:67], v[180:183], v[214:217], v[64:67]
	s_barrier
; #define PG8_STAGE(bufoff, gbase, voff) do { _Pragma("unroll") for (int _i = 0; _i < 2; ++_i) \
;         __builtin_amdgcn_global_load_lds((const unsigned*)((const char*)(gbase) + (voff)[_i]), (PG8_LAS unsigned*)(lds + (bufoff) + ldsw + _i * 8192), 16, 0, 0); } while (0)
; #define PG8_LDA(dst, b, h) do { _Pragma("unroll") for (int m = 0; m < 4; ++m) _Pragma("unroll") for (int k = 0; k < 2; ++k) dst[m][k] = *(const PG8_LAS bf16x8*)(lds + PG8_SA(b, h) + aoff + m * 2048 + k * 1024); } while (0)
; #define PG8_LDB(dst, b, h) do { _Pragma("unroll") for (int n = 0; n < 2; ++n) _Pragma("unroll") for (int k = 0; k < 2; ++k) dst[n][k] = *(const PG8_LAS bf16x8*)(lds + PG8_SB(b, h) + boff + n * 2048 + k * 1024); } while (0)
; #define PG8_MMA(ai, bj, At, Bt) do { __builtin_amdgcn_s_setprio(1); _Pragma("unroll") for (int m = 0; m < 4; ++m) _Pragma("unroll") for (int n = 0; n < 2; ++n) _Pragma("unroll") for (int k = 0; k < 2; ++k) \
;         acc[ai][bj][m][n] = __builtin_amdgcn_mfma_f32_16x16x32_bf16(Bt[n][k], At[m][k], acc[ai][bj][m][n], 0, 0, 0); __builtin_amdgcn_s_setprio(0); } while (0)
; #define PG8_WAIT_V(n) asm volatile("s_waitcnt vmcnt(" #n ")" ::: "memory")
; template <class Epi, class Sched, bool ALIGN_EPI = false, bool SP2 = false>
; __device__ __forceinline__ void gemm_phase(PG8_LAS unsigned char* lds, const Gemm g, const Sched& S, const Epi& E) {
;     ...
;             PG8_LDB(B0, 0, 0); PG8_LDB(B1, 0, 1); PG8_SCHED; PG8_LDA(At, 0, 0); PG8_STAGE(PG8_SA(1, 1), a1 + hstep, voffA);
;             PG8_WAIT_V(8); PG8_WAIT_L(0); PG8_BAR; PG8_MMA(0, 0, At, B0); PG8_MMA(0, 1, At, B1); PG8_BAR; PG8_SCHED;
;             PG8_LDA(At, 0, 1); PG8_STAGE(PG8_SB(0, 0), b2, voffB); PG8_STAGE(PG8_SB(0, 1), b2 + hstep, voffB); PG8_STAGE(PG8_SA(0, 0), a2, voffA);
;             PG8_WAIT_V(8); PG8_WAIT_L(0); PG8_BAR; PG8_MMA(1, 0, At, B0); PG8_MMA(1, 1, At, B1); PG8_BAR; PG8_SCHED;
;             PG8_LDB(B0, 1, 0); PG8_LDB(B1, 1, 1); PG8_SCHED; PG8_LDA(At, 1, 0); PG8_STAGE(PG8_SA(0, 1), a2 + hstep, voffA);
;             PG8_WAIT_V(8); PG8_WAIT_L(0); PG8_BAR; PG8_MMA(0, 0, At, B0); PG8_MMA(0, 1, At, B1); PG8_BAR; PG8_SCHED;
;             PG8_LDA(At, 1, 1); PG8_STAGE(PG8_SB(1, 0), b3, voffB); PG8_STAGE(PG8_SB(1, 1), b3 + hstep, voffB); PG8_STAGE(PG8_SA(1, 0), a3, voffA);
;             PG8_WAIT_V(8); PG8_WAIT_L(0); PG8_BAR; PG8_MMA(1, 0, At, B0); PG8_MMA(1, 1, At, B1); PG8_BAR; PG8_SCHED;
	s_add_i32 s72, s64, s53
	s_mov_b32 m0, s72
	ds_read_b128 v[184:187], v171 offset:16384
	ds_read_b128 v[188:191], v171 offset:17408
	ds_read_b128 v[192:195], v171 offset:18432
	ds_read_b128 v[196:199], v171 offset:19456
	ds_read_b128 v[200:203], v171 offset:20480
	ds_read_b128 v[204:207], v171 offset:21504
	ds_read_b128 v[208:211], v171 offset:22528
	ds_read_b128 v[214:217], v171 offset:23552
	global_load_lds_dwordx4 v146, s[48:49]
	s_add_i32 m0, s72, 0x2000
	s_add_u32 s72, s48, 0x80000
	s_addc_u32 s73, s49, 0
	s_add_i32 s74, s65, s53
	global_load_lds_dwordx4 v150, s[48:49]
	s_mov_b32 m0, s74
	s_nop 0
	global_load_lds_dwordx4 v146, s[72:73]
	s_add_i32 m0, s74, 0x2000
	s_nop 0
	global_load_lds_dwordx4 v150, s[72:73]
	s_mov_b32 m0, s45
	s_nop 0
	global_load_lds_dwordx4 v144, s[50:51]
	s_mov_b32 m0, s54
	s_nop 0
	global_load_lds_dwordx4 v148, s[50:51]
	s_waitcnt vmcnt(8)
	s_waitcnt lgkmcnt(0)
	s_barrier
	v_mfma_f32_16x16x32_bf16 v[60:63], v[128:131], v[184:187], v[60:63]
	v_mfma_f32_16x16x32_bf16 v[56:59], v[136:139], v[184:187], v[56:59]
	v_mfma_f32_16x16x32_bf16 v[52:55], v[128:131], v[192:195], v[52:55]
	v_mfma_f32_16x16x32_bf16 v[48:51], v[136:139], v[192:195], v[48:51]
	v_mfma_f32_16x16x32_bf16 v[44:47], v[128:131], v[200:203], v[44:47]
	v_mfma_f32_16x16x32_bf16 v[32:35], v[136:139], v[200:203], v[32:35]
	v_mfma_f32_16x16x32_bf16 v[20:23], v[128:131], v[208:211], v[20:23]
	v_mfma_f32_16x16x32_bf16 v[8:11], v[136:139], v[208:211], v[8:11]
	v_mfma_f32_16x16x32_bf16 v[60:63], v[132:135], v[188:191], v[60:63]
	v_mfma_f32_16x16x32_bf16 v[56:59], v[140:143], v[188:191], v[56:59]
	v_mfma_f32_16x16x32_bf16 v[52:55], v[132:135], v[196:199], v[52:55]
	v_mfma_f32_16x16x32_bf16 v[48:51], v[140:143], v[196:199], v[48:51]
	v_mfma_f32_16x16x32_bf16 v[44:47], v[132:135], v[204:207], v[44:47]
	v_mfma_f32_16x16x32_bf16 v[32:35], v[140:143], v[204:207], v[32:35]
	v_mfma_f32_16x16x32_bf16 v[20:23], v[132:135], v[214:217], v[20:23]
	v_mfma_f32_16x16x32_bf16 v[8:11], v[140:143], v[214:217], v[8:11]
	v_mfma_f32_16x16x32_bf16 v[40:43], v[160:163], v[184:187], v[40:43]
	v_mfma_f32_16x16x32_bf16 v[36:39], v[176:179], v[184:187], v[36:39]
	v_mfma_f32_16x16x32_bf16 v[28:31], v[160:163], v[192:195], v[28:31]
	v_mfma_f32_16x16x32_bf16 v[24:27], v[176:179], v[192:195], v[24:27]
	v_mfma_f32_16x16x32_bf16 v[16:19], v[160:163], v[200:203], v[16:19]
	v_mfma_f32_16x16x32_bf16 v[12:15], v[176:179], v[200:203], v[12:15]
	v_mfma_f32_16x16x32_bf16 v[4:7], v[160:163], v[208:211], v[4:7]
	v_mfma_f32_16x16x32_bf16 v[0:3], v[176:179], v[208:211], v[0:3]
	v_mfma_f32_16x16x32_bf16 v[40:43], v[172:175], v[188:191], v[40:43]
	v_mfma_f32_16x16x32_bf16 v[36:39], v[180:183], v[188:191], v[36:39]
	v_mfma_f32_16x16x32_bf16 v[28:31], v[172:175], v[196:199], v[28:31]
	v_mfma_f32_16x16x32_bf16 v[24:27], v[180:183], v[196:199], v[24:27]
	v_mfma_f32_16x16x32_bf16 v[16:19], v[172:175], v[204:207], v[16:19]
	v_mfma_f32_16x16x32_bf16 v[12:15], v[180:183], v[204:207], v[12:15]
	v_mfma_f32_16x16x32_bf16 v[4:7], v[172:175], v[214:217], v[4:7]
	v_mfma_f32_16x16x32_bf16 v[0:3], v[180:183], v[214:217], v[0:3]
	s_barrier
	s_add_i32 s72, 0, 0x18000
	s_add_i32 s73, 0, 0x1c000
	v_add_u32_e32 v140, s72, v167
	v_add_u32_e32 v180, s73, v167
	ds_read_b128 v[128:131], v140
	ds_read_b128 v[132:135], v140 offset:1024
	ds_read_b128 v[136:139], v140 offset:2048
	ds_read_b128 v[140:143], v140 offset:3072
	ds_read_b128 v[160:163], v180
	ds_read_b128 v[172:175], v180 offset:1024
	ds_read_b128 v[176:179], v180 offset:2048
	ds_read_b128 v[180:183], v180 offset:3072
	s_add_u32 s84, s50, 0x80
	s_addc_u32 s85, s51, 0
	s_add_u32 s50, s50, 0x80000
	s_addc_u32 s51, s51, 0
	s_mov_b32 m0, s55
	ds_read_b128 v[184:187], v171 offset:32768
	ds_read_b128 v[188:191], v171 offset:33792
	ds_read_b128 v[192:195], v171 offset:34816
	ds_read_b128 v[196:199], v171 offset:35840
	ds_read_b128 v[200:203], v171 offset:36864
	ds_read_b128 v[204:207], v171 offset:37888
	ds_read_b128 v[208:211], v171 offset:38912
	ds_read_b128 v[214:217], v171 offset:39936
	global_load_lds_dwordx4 v144, s[50:51]
	s_mov_b32 m0, s56
	s_nop 0
	global_load_lds_dwordx4 v148, s[50:51]
	s_waitcnt vmcnt(8)
	s_waitcnt lgkmcnt(0)
	s_barrier
	v_mfma_f32_16x16x32_bf16 v[124:127], v[128:131], v[184:187], v[124:127]
	v_mfma_f32_16x16x32_bf16 v[120:123], v[136:139], v[184:187], v[120:123]
	v_mfma_f32_16x16x32_bf16 v[116:119], v[128:131], v[192:195], v[116:119]
	v_mfma_f32_16x16x32_bf16 v[112:115], v[136:139], v[192:195], v[112:115]
	v_mfma_f32_16x16x32_bf16 v[108:111], v[128:131], v[200:203], v[108:111]
	v_mfma_f32_16x16x32_bf16 v[96:99], v[136:139], v[200:203], v[96:99]
	v_mfma_f32_16x16x32_bf16 v[80:83], v[128:131], v[208:211], v[80:83]
	v_mfma_f32_16x16x32_bf16 v[72:75], v[136:139], v[208:211], v[72:75]
	v_mfma_f32_16x16x32_bf16 v[124:127], v[132:135], v[188:191], v[124:127]
	v_mfma_f32_16x16x32_bf16 v[120:123], v[140:143], v[188:191], v[120:123]
	v_mfma_f32_16x16x32_bf16 v[116:119], v[132:135], v[196:199], v[116:119]
	v_mfma_f32_16x16x32_bf16 v[112:115], v[140:143], v[196:199], v[112:115]
	v_mfma_f32_16x16x32_bf16 v[108:111], v[132:135], v[204:207], v[108:111]
	v_mfma_f32_16x16x32_bf16 v[96:99], v[140:143], v[204:207], v[96:99]
	v_mfma_f32_16x16x32_bf16 v[80:83], v[132:135], v[214:217], v[80:83]
	v_mfma_f32_16x16x32_bf16 v[72:75], v[140:143], v[214:217], v[72:75]
	v_mfma_f32_16x16x32_bf16 v[104:107], v[160:163], v[184:187], v[104:107]
	v_mfma_f32_16x16x32_bf16 v[100:103], v[176:179], v[184:187], v[100:103]
	v_mfma_f32_16x16x32_bf16 v[92:95], v[160:163], v[192:195], v[92:95]
	v_mfma_f32_16x16x32_bf16 v[88:91], v[176:179], v[192:195], v[88:91]
	v_mfma_f32_16x16x32_bf16 v[84:87], v[160:163], v[200:203], v[84:87]
	v_mfma_f32_16x16x32_bf16 v[76:79], v[176:179], v[200:203], v[76:79]
	v_mfma_f32_16x16x32_bf16 v[68:71], v[160:163], v[208:211], v[68:71]
	v_mfma_f32_16x16x32_bf16 v[64:67], v[176:179], v[208:211], v[64:67]
	v_mfma_f32_16x16x32_bf16 v[104:107], v[172:175], v[188:191], v[104:107]
	v_mfma_f32_16x16x32_bf16 v[100:103], v[180:183], v[188:191], v[100:103]
	v_mfma_f32_16x16x32_bf16 v[92:95], v[172:175], v[196:199], v[92:95]
	v_mfma_f32_16x16x32_bf16 v[88:91], v[180:183], v[196:199], v[88:91]
	v_mfma_f32_16x16x32_bf16 v[84:87], v[172:175], v[204:207], v[84:87]
	v_mfma_f32_16x16x32_bf16 v[76:79], v[180:183], v[204:207], v[76:79]
	v_mfma_f32_16x16x32_bf16 v[68:71], v[172:175], v[214:217], v[68:71]
	v_mfma_f32_16x16x32_bf16 v[64:67], v[180:183], v[214:217], v[64:67]
	s_barrier
; #define PG8_BAR __builtin_amdgcn_s_barrier()
;     __device__ __forceinline__ void operator()(const f32x4 (&acc)[2][2][4][2], const Unit& u, int wr, int wc, int fr, int fq) const {
;         const int row0 = u.pm * BM + wr * 64 + fr, col0 = u.pn * BM + wc * 32 + 8 * fq;
;         const float* gp = gate + (u.pm >> 5) * 18432 + col0;
;         f32x4 gv[2][2];
; #pragma unroll
;         for (int bj = 0; bj < 2; ++bj)
; #pragma unroll
;             for (int n = 0; n < 2; ++n) gv[bj][n] = *(const f32x4*)(gp + bj * HALF + 4 * n) * scale;
; #pragma unroll
;         for (int ai = 0; ai < 2; ++ai) { f32x4 r[4][2][2];
; #pragma unroll
;             for (int m = 0; m < 4; ++m) { const size_t off = (size_t)(row0 + ai * HALF + m * 16) * 2048 + col0;
; #pragma unroll
;                 for (int bj = 0; bj < 2; ++bj)
; #pragma unroll
;                     for (int n = 0; n < 2; ++n) r[m][bj][n] = *(const f32x4*)(res + off + bj * HALF + 4 * n); }
; #pragma unroll
;             for (int m = 0; m < 4; ++m) { const size_t off = (size_t)(row0 + ai * HALF + m * 16) * 2048 + col0;
; #pragma unroll
;                 for (int bj = 0; bj < 2; ++bj)
; #pragma unroll
; template <class Epi, class Sched, bool ALIGN_EPI = false, bool SP2 = false>
; __device__ __forceinline__ void gemm_phase(PG8_LAS unsigned char* lds, const Gemm g, const Sched& S, const Epi& E) {
;     ...
;             PG8_LDB(B0, 0, 0); PG8_LDB(B1, 0, 1); PG8_SCHED; PG8_LDA(At, 0, 0); PG8_STAGE(PG8_SA(1, 1), a1 + hstep, voffA);
;             PG8_WAIT_V(8); PG8_WAIT_L(0); PG8_BAR; PG8_MMA(0, 0, At, B0); PG8_MMA(0, 1, At, B1); PG8_BAR; PG8_SCHED;
;             PG8_LDA(At, 0, 1); PG8_STAGE(PG8_SB(0, 0), b2, voffB); PG8_STAGE(PG8_SB(0, 1), b2 + hstep, voffB); PG8_STAGE(PG8_SA(0, 0), a2, voffA);
;             PG8_WAIT_V(8); PG8_WAIT_L(0); PG8_BAR; PG8_MMA(1, 0, At, B0); PG8_MMA(1, 1, At, B1); PG8_BAR; PG8_SCHED;
;             PG8_LDB(B0, 1, 0); PG8_LDB(B1, 1, 1); PG8_SCHED; PG8_LDA(At, 1, 0); PG8_STAGE(PG8_SA(0, 1), a2 + hstep, voffA);
;             PG8_WAIT_V(8); PG8_WAIT_L(0); PG8_BAR; PG8_MMA(0, 0, At, B0); PG8_MMA(0, 1, At, B1); PG8_BAR; PG8_SCHED;
;             PG8_LDA(At, 1, 1); PG8_STAGE(PG8_SB(1, 0), b3, voffB); PG8_STAGE(PG8_SB(1, 1), b3 + hstep, voffB); PG8_STAGE(PG8_SA(1, 0), a3, voffA);
;             PG8_WAIT_V(8); PG8_WAIT_L(0); PG8_BAR; PG8_MMA(1, 0, At, B0); PG8_MMA(1, 1, At, B1); PG8_BAR; PG8_SCHED;
	s_add_i32 s50, s72, s53
	s_add_u32 s86, s48, 0x80
	s_addc_u32 s87, s49, 0
	s_mov_b32 m0, s50
	ds_read_b128 v[184:187], v171 offset:49152
	ds_read_b128 v[188:191], v171 offset:50176
	ds_read_b128 v[192:195], v171 offset:51200
	ds_read_b128 v[196:199], v171 offset:52224
	ds_read_b128 v[200:203], v171 offset:53248
	ds_read_b128 v[204:207], v171 offset:54272
	ds_read_b128 v[208:211], v171 offset:55296
	ds_read_b128 v[214:217], v171 offset:56320
	global_load_lds_dwordx4 v146, s[86:87]
	s_add_i32 m0, s50, 0x2000
	s_add_u32 s48, s48, 0x80080
	s_addc_u32 s49, s49, 0
	s_add_i32 s50, s73, s53
	global_load_lds_dwordx4 v150, s[86:87]
	s_mov_b32 m0, s50
	s_nop 0
	global_load_lds_dwordx4 v146, s[48:49]
	s_add_i32 m0, s50, 0x2000
	s_nop 0
	global_load_lds_dwordx4 v150, s[48:49]
	s_mov_b32 m0, s60
	s_nop 0
	global_load_lds_dwordx4 v144, s[84:85]
	s_mov_b32 m0, s61
	s_nop 0
	global_load_lds_dwordx4 v148, s[84:85]
	s_waitcnt vmcnt(8)
	s_waitcnt lgkmcnt(0)
	s_barrier
	v_mfma_f32_16x16x32_bf16 v[60:63], v[128:131], v[184:187], v[60:63]
	v_mfma_f32_16x16x32_bf16 v[56:59], v[136:139], v[184:187], v[56:59]
	v_mfma_f32_16x16x32_bf16 v[52:55], v[128:131], v[192:195], v[52:55]
	v_mfma_f32_16x16x32_bf16 v[48:51], v[136:139], v[192:195], v[48:51]
	v_mfma_f32_16x16x32_bf16 v[44:47], v[128:131], v[200:203], v[44:47]
	v_mfma_f32_16x16x32_bf16 v[32:35], v[136:139], v[200:203], v[32:35]
	v_mfma_f32_16x16x32_bf16 v[20:23], v[128:131], v[208:211], v[20:23]
	v_mfma_f32_16x16x32_bf16 v[8:11], v[136:139], v[208:211], v[8:11]
	v_mfma_f32_16x16x32_bf16 v[60:63], v[132:135], v[188:191], v[60:63]
	v_mfma_f32_16x16x32_bf16 v[56:59], v[140:143], v[188:191], v[56:59]
	v_mfma_f32_16x16x32_bf16 v[52:55], v[132:135], v[196:199], v[52:55]
	v_mfma_f32_16x16x32_bf16 v[48:51], v[140:143], v[196:199], v[48:51]
	v_mfma_f32_16x16x32_bf16 v[44:47], v[132:135], v[204:207], v[44:47]
	v_mfma_f32_16x16x32_bf16 v[32:35], v[140:143], v[204:207], v[32:35]
	v_mfma_f32_16x16x32_bf16 v[20:23], v[132:135], v[214:217], v[20:23]
	v_mfma_f32_16x16x32_bf16 v[8:11], v[140:143], v[214:217], v[8:11]
	v_mfma_f32_16x16x32_bf16 v[40:43], v[160:163], v[184:187], v[40:43]
	v_mfma_f32_16x16x32_bf16 v[36:39], v[176:179], v[184:187], v[36:39]
	v_mfma_f32_16x16x32_bf16 v[28:31], v[160:163], v[192:195], v[28:31]
	v_mfma_f32_16x16x32_bf16 v[24:27], v[176:179], v[192:195], v[24:27]
	v_mfma_f32_16x16x32_bf16 v[16:19], v[160:163], v[200:203], v[16:19]
	v_mfma_f32_16x16x32_bf16 v[12:15], v[176:179], v[200:203], v[12:15]
	v_mfma_f32_16x16x32_bf16 v[4:7], v[160:163], v[208:211], v[4:7]
	v_mfma_f32_16x16x32_bf16 v[0:3], v[176:179], v[208:211], v[0:3]
	v_mfma_f32_16x16x32_bf16 v[40:43], v[172:175], v[188:191], v[40:43]
	v_mfma_f32_16x16x32_bf16 v[36:39], v[180:183], v[188:191], v[36:39]
	v_mfma_f32_16x16x32_bf16 v[28:31], v[172:175], v[196:199], v[28:31]
	v_mfma_f32_16x16x32_bf16 v[24:27], v[180:183], v[196:199], v[24:27]
	v_mfma_f32_16x16x32_bf16 v[16:19], v[172:175], v[204:207], v[16:19]
	v_mfma_f32_16x16x32_bf16 v[12:15], v[180:183], v[204:207], v[12:15]
	v_mfma_f32_16x16x32_bf16 v[4:7], v[172:175], v[214:217], v[4:7]
	v_mfma_f32_16x16x32_bf16 v[0:3], v[180:183], v[214:217], v[0:3]
	s_barrier
	s_add_i32 s71, s71, 2
	s_add_u32 s46, s46, 0x100
	s_addc_u32 s47, s47, 0
	s_add_u32 s69, s69, 0x100
	s_addc_u32 s70, s70, 0
	s_cmp_gt_u32 s71, 29
	s_cbranch_scc0 .LBB0_827
	s_lshr_b32 s37, s44, 5
	s_mul_i32 s46, s37, 0x4800
	v_lshl_or_b32 v128, s66, 8, v168
	s_ashr_i32 s47, s46, 31
	v_lshl_add_u32 v212, s44, 8, v166
	s_lshl_b64 s[46:47], s[46:47], 2
	v_ashrrev_i32_e32 v129, 31, v128
	v_or_b32_e32 v188, 16, v212
	v_or_b32_e32 v204, 32, v212
	s_add_u32 s46, s58, s46
	v_lshlrev_b64 v[160:161], 2, v[128:129]
	v_ashrrev_i32_e32 v213, 31, v212
	v_ashrrev_i32_e32 v189, 31, v188
	v_ashrrev_i32_e32 v205, 31, v204
	s_addc_u32 s47, s59, s47
	v_lshl_add_u64 v[162:163], s[12:13], 0, v[160:161]
	v_lshlrev_b64 v[164:165], 13, v[212:213]
	v_lshlrev_b64 v[218:219], 13, v[188:189]
	v_lshlrev_b64 v[230:231], 13, v[204:205]
	v_or_b32_e32 v212, 48, v212
	v_lshl_add_u64 v[136:137], s[46:47], 0, v[160:161]
	v_lshl_add_u64 v[184:185], v[162:163], 0, v[164:165]
	v_lshl_add_u64 v[200:201], v[162:163], 0, v[218:219]
	v_lshl_add_u64 v[222:223], v[162:163], 0, v[230:231]
	v_ashrrev_i32_e32 v213, 31, v212
	global_load_dwordx4 v[132:135], v[136:137], off offset:16
	global_load_dwordx4 v[140:143], v[136:137], off
	global_load_dwordx4 v[172:175], v[184:185], off offset:16
	global_load_dwordx4 v[176:179], v[184:185], off
	global_load_dwordx4 v[128:131], v[136:137], off offset:528
	s_nop 0
	global_load_dwordx4 v[136:139], v[136:137], off offset:512
	s_nop 0
	global_load_dwordx4 v[180:183], v[184:185], off offset:528
	s_nop 0
	global_load_dwordx4 v[184:187], v[184:185], off offset:512
	s_nop 0
	global_load_dwordx4 v[188:191], v[200:201], off
	global_load_dwordx4 v[192:195], v[200:201], off offset:16
	global_load_dwordx4 v[196:199], v[200:201], off offset:528
	s_nop 0
	global_load_dwordx4 v[200:203], v[200:201], off offset:512
	s_nop 0
	global_load_dwordx4 v[204:207], v[222:223], off
	global_load_dwordx4 v[208:211], v[222:223], off offset:16
	global_load_dwordx4 v[214:217], v[222:223], off offset:512
	s_nop 0
	global_load_dwordx4 v[222:225], v[222:223], off offset:528
	v_lshlrev_b64 v[212:213], 13, v[212:213]
	v_lshl_add_u64 v[244:245], v[162:163], 0, v[212:213]
	global_load_dwordx4 v[232:235], v[244:245], off
	global_load_dwordx4 v[236:239], v[244:245], off offset:16
	global_load_dwordx4 v[240:243], v[244:245], off offset:512
	s_nop 0
	global_load_dwordx4 v[244:247], v[244:245], off offset:528
	v_lshl_add_u64 v[248:249], s[14:15], 0, v[164:165]
	v_lshl_add_u64 v[248:249], v[248:249], 0, v[160:161]
	v_lshl_add_u64 v[218:219], s[14:15], 0, v[218:219]
	v_lshl_add_u64 v[230:231], s[14:15], 0, v[230:231]
	v_lshl_add_u64 v[218:219], v[218:219], 0, v[160:161]
	v_lshl_add_u64 v[230:231], v[230:231], 0, v[160:161]
	s_and_b64 vcc, exec, s[10:11]
	s_mov_b32 s66, s36
	s_mov_b32 s44, s38
	s_mov_b64 s[48:49], s[42:43]
	s_mov_b64 s[46:47], s[40:41]
	s_waitcnt vmcnt(0)
;     __device__ __forceinline__ void operator()(const f32x4 (&acc)[2][2][4][2], const Unit& u, int wr, int wc, int fr, int fq) const {
;     ...
;         for (int ai = 0; ai < 2; ++ai) { f32x4 r[4][2][2];
; #pragma unroll
;             for (int m = 0; m < 4; ++m) { const size_t off = (size_t)(row0 + ai * HALF + m * 16) * 2048 + col0;
; #pragma unroll
;                 for (int bj = 0; bj < 2; ++bj)
; #pragma unroll
;                     for (int n = 0; n < 2; ++n) r[m][bj][n] = *(const f32x4*)(res + off + bj * HALF + 4 * n); }
; #pragma unroll
;             for (int m = 0; m < 4; ++m) { const size_t off = (size_t)(row0 + ai * HALF + m * 16) * 2048 + col0;
; #pragma unroll
;                 for (int bj = 0; bj < 2; ++bj)
; #pragma unroll
;                     for (int n = 0; n < 2; ++n) *(f32x4*)(out + off + bj * HALF + 4 * n) = r[m][bj][n] + gv[bj][n] * acc[ai][bj][m][n]; } }
	v_pk_fma_f32 v[122:123], v[122:123], v[134:135], v[174:175]
	v_pk_fma_f32 v[126:127], v[126:127], v[142:143], v[178:179]
	v_pk_fma_f32 v[124:125], v[124:125], v[140:141], v[176:177]
	v_pk_fma_f32 v[120:121], v[120:121], v[132:133], v[172:173]
	v_pk_fma_f32 v[76:77], v[76:77], v[128:129], v[222:223]
	v_pk_fma_f32 v[106:107], v[106:107], v[138:139], v[186:187]
	v_pk_fma_f32 v[104:105], v[104:105], v[136:137], v[184:185]
	v_pk_fma_f32 v[102:103], v[102:103], v[130:131], v[182:183]
	v_pk_fma_f32 v[100:101], v[100:101], v[128:129], v[180:181]
	v_pk_fma_f32 v[118:119], v[118:119], v[142:143], v[190:191]
	v_pk_fma_f32 v[116:117], v[116:117], v[140:141], v[188:189]
	v_pk_fma_f32 v[114:115], v[114:115], v[134:135], v[194:195]
	v_pk_fma_f32 v[112:113], v[112:113], v[132:133], v[192:193]
	v_pk_fma_f32 v[94:95], v[94:95], v[138:139], v[202:203]
	v_pk_fma_f32 v[92:93], v[92:93], v[136:137], v[200:201]
	v_pk_fma_f32 v[90:91], v[90:91], v[130:131], v[198:199]
	v_pk_fma_f32 v[88:89], v[88:89], v[128:129], v[196:197]
	v_pk_fma_f32 v[110:111], v[110:111], v[142:143], v[206:207]
	v_pk_fma_f32 v[108:109], v[108:109], v[140:141], v[204:205]
	v_pk_fma_f32 v[98:99], v[98:99], v[134:135], v[210:211]
	v_pk_fma_f32 v[96:97], v[96:97], v[132:133], v[208:209]
	v_pk_fma_f32 v[86:87], v[86:87], v[138:139], v[216:217]
	v_pk_fma_f32 v[84:85], v[84:85], v[136:137], v[214:215]
	v_pk_fma_f32 v[78:79], v[78:79], v[130:131], v[224:225]
	global_store_dwordx4 v[248:249], v[124:127], off
	global_store_dwordx4 v[248:249], v[120:123], off offset:16
	global_store_dwordx4 v[248:249], v[104:107], off offset:512
	global_store_dwordx4 v[248:249], v[100:103], off offset:528
	global_store_dwordx4 v[218:219], v[116:119], off
	global_store_dwordx4 v[218:219], v[112:115], off offset:16
	global_store_dwordx4 v[218:219], v[92:95], off offset:512
	global_store_dwordx4 v[218:219], v[88:91], off offset:528
	global_store_dwordx4 v[230:231], v[108:111], off
	global_store_dwordx4 v[230:231], v[96:99], off offset:16
	global_store_dwordx4 v[230:231], v[84:87], off offset:512
	global_store_dwordx4 v[230:231], v[76:79], off offset:528
	v_pk_fma_f32 v[74:75], v[74:75], v[134:135], v[238:239]
	v_pk_fma_f32 v[72:73], v[72:73], v[132:133], v[236:237]
	v_pk_fma_f32 v[76:77], v[80:81], v[140:141], v[232:233]
	v_lshl_add_u64 v[80:81], s[14:15], 0, v[212:213]
	v_pk_fma_f32 v[78:79], v[82:83], v[142:143], v[234:235]
	v_lshl_add_u64 v[80:81], v[80:81], 0, v[160:161]
	v_pk_fma_f32 v[70:71], v[70:71], v[138:139], v[242:243]
	v_pk_fma_f32 v[68:69], v[68:69], v[136:137], v[240:241]
	v_pk_fma_f32 v[66:67], v[66:67], v[130:131], v[246:247]
	v_pk_fma_f32 v[64:65], v[64:65], v[128:129], v[244:245]
	v_lshl_add_u64 v[172:173], v[164:165], 0, s[26:27]
	v_lshl_add_u64 v[174:175], v[164:165], 0, s[28:29]
	v_lshl_add_u64 v[176:177], v[164:165], 0, s[30:31]
	global_store_dwordx4 v[80:81], v[76:79], off
	global_store_dwordx4 v[80:81], v[72:75], off offset:16
	global_store_dwordx4 v[80:81], v[68:71], off offset:512
	global_store_dwordx4 v[80:81], v[64:67], off offset:528
	v_lshl_add_u64 v[76:77], v[162:163], 0, v[172:173]
	v_lshl_add_u64 v[92:93], v[162:163], 0, v[174:175]
	v_lshl_add_u64 v[108:109], v[162:163], 0, v[176:177]
	global_load_dwordx4 v[64:67], v[76:77], off
	global_load_dwordx4 v[68:71], v[76:77], off offset:16
	global_load_dwordx4 v[72:75], v[76:77], off offset:512
	s_nop 0
	global_load_dwordx4 v[76:79], v[76:77], off offset:528
	s_nop 0
	global_load_dwordx4 v[80:83], v[92:93], off
	global_load_dwordx4 v[84:87], v[92:93], off offset:16
	global_load_dwordx4 v[88:91], v[92:93], off offset:512
	s_nop 0
	global_load_dwordx4 v[92:95], v[92:93], off offset:528
	s_nop 0
	global_load_dwordx4 v[96:99], v[108:109], off
	global_load_dwordx4 v[100:103], v[108:109], off offset:16
	global_load_dwordx4 v[104:107], v[108:109], off offset:512
	s_nop 0
	global_load_dwordx4 v[108:111], v[108:109], off offset:528
	v_lshl_add_u64 v[164:165], v[164:165], 0, s[34:35]
	v_lshl_add_u64 v[124:125], v[162:163], 0, v[164:165]
	global_load_dwordx4 v[112:115], v[124:125], off
	global_load_dwordx4 v[116:119], v[124:125], off offset:16
	global_load_dwordx4 v[120:123], v[124:125], off offset:512
	s_nop 0
	global_load_dwordx4 v[124:127], v[124:125], off offset:528
	v_lshl_add_u64 v[162:163], s[14:15], 0, v[172:173]
	v_lshl_add_u64 v[172:173], s[14:15], 0, v[174:175]
	v_lshl_add_u64 v[174:175], s[14:15], 0, v[176:177]
	v_lshl_add_u64 v[162:163], v[162:163], 0, v[160:161]
	v_lshl_add_u64 v[172:173], v[172:173], 0, v[160:161]
	v_lshl_add_u64 v[174:175], v[174:175], 0, v[160:161]
	s_waitcnt vmcnt(15)
;     __device__ __forceinline__ void operator()(const f32x4 (&acc)[2][2][4][2], const Unit& u, int wr, int wc, int fr, int fq) const {
;     ...
;         for (int ai = 0; ai < 2; ++ai) { f32x4 r[4][2][2];
; #pragma unroll
;             for (int m = 0; m < 4; ++m) { const size_t off = (size_t)(row0 + ai * HALF + m * 16) * 2048 + col0;
; #pragma unroll
;                 for (int bj = 0; bj < 2; ++bj)
; #pragma unroll
;                     for (int n = 0; n < 2; ++n) r[m][bj][n] = *(const f32x4*)(res + off + bj * HALF + 4 * n); }
; #pragma unroll
;             for (int m = 0; m < 4; ++m) { const size_t off = (size_t)(row0 + ai * HALF + m * 16) * 2048 + col0;
; #pragma unroll
;                 for (int bj = 0; bj < 2; ++bj)
; #pragma unroll
;                     for (int n = 0; n < 2; ++n) *(f32x4*)(out + off + bj * HALF + 4 * n) = r[m][bj][n] + gv[bj][n] * acc[ai][bj][m][n]; } }
	v_pk_fma_f32 v[62:63], v[62:63], v[142:143], v[66:67]
	v_pk_fma_f32 v[60:61], v[60:61], v[140:141], v[64:65]
	s_waitcnt vmcnt(14)
	v_pk_fma_f32 v[58:59], v[58:59], v[134:135], v[70:71]
	v_pk_fma_f32 v[56:57], v[56:57], v[132:133], v[68:69]
	s_waitcnt vmcnt(13)
	v_pk_fma_f32 v[42:43], v[42:43], v[138:139], v[74:75]
	s_waitcnt vmcnt(4)
	v_pk_fma_f32 v[12:13], v[12:13], v[128:129], v[108:109]
	v_pk_fma_f32 v[40:41], v[40:41], v[136:137], v[72:73]
	v_pk_fma_f32 v[38:39], v[38:39], v[130:131], v[78:79]
	v_pk_fma_f32 v[36:37], v[36:37], v[128:129], v[76:77]
	v_pk_fma_f32 v[54:55], v[54:55], v[142:143], v[82:83]
	v_pk_fma_f32 v[52:53], v[52:53], v[140:141], v[80:81]
	v_pk_fma_f32 v[50:51], v[50:51], v[134:135], v[86:87]
	v_pk_fma_f32 v[48:49], v[48:49], v[132:133], v[84:85]
	v_pk_fma_f32 v[30:31], v[30:31], v[138:139], v[90:91]
	v_pk_fma_f32 v[28:29], v[28:29], v[136:137], v[88:89]
	v_pk_fma_f32 v[26:27], v[26:27], v[130:131], v[94:95]
	v_pk_fma_f32 v[24:25], v[24:25], v[128:129], v[92:93]
	v_pk_fma_f32 v[46:47], v[46:47], v[142:143], v[98:99]
	v_pk_fma_f32 v[44:45], v[44:45], v[140:141], v[96:97]
	v_pk_fma_f32 v[34:35], v[34:35], v[134:135], v[102:103]
	v_pk_fma_f32 v[32:33], v[32:33], v[132:133], v[100:101]
	v_pk_fma_f32 v[18:19], v[18:19], v[138:139], v[106:107]
	v_pk_fma_f32 v[16:17], v[16:17], v[136:137], v[104:105]
	v_pk_fma_f32 v[14:15], v[14:15], v[130:131], v[110:111]
	global_store_dwordx4 v[162:163], v[60:63], off
	global_store_dwordx4 v[162:163], v[56:59], off offset:16
	global_store_dwordx4 v[162:163], v[40:43], off offset:512
	global_store_dwordx4 v[162:163], v[36:39], off offset:528
	global_store_dwordx4 v[172:173], v[52:55], off
	global_store_dwordx4 v[172:173], v[48:51], off offset:16
	global_store_dwordx4 v[172:173], v[28:31], off offset:512
	global_store_dwordx4 v[172:173], v[24:27], off offset:528
	global_store_dwordx4 v[174:175], v[44:47], off
	global_store_dwordx4 v[174:175], v[32:35], off offset:16
	global_store_dwordx4 v[174:175], v[16:19], off offset:512
	global_store_dwordx4 v[174:175], v[12:15], off offset:528
	s_waitcnt vmcnt(15)
	v_pk_fma_f32 v[22:23], v[22:23], v[142:143], v[114:115]
	v_pk_fma_f32 v[20:21], v[20:21], v[140:141], v[112:113]
	v_lshl_add_u64 v[12:13], s[14:15], 0, v[164:165]
	v_lshl_add_u64 v[12:13], v[12:13], 0, v[160:161]
	s_waitcnt vmcnt(14)
	v_pk_fma_f32 v[10:11], v[10:11], v[134:135], v[118:119]
	v_pk_fma_f32 v[8:9], v[8:9], v[132:133], v[116:117]
	s_waitcnt vmcnt(13)
	v_pk_fma_f32 v[6:7], v[6:7], v[138:139], v[122:123]
	v_pk_fma_f32 v[4:5], v[4:5], v[136:137], v[120:121]
	s_waitcnt vmcnt(12)
	v_pk_fma_f32 v[2:3], v[2:3], v[130:131], v[126:127]
	v_pk_fma_f32 v[0:1], v[0:1], v[128:129], v[124:125]
	global_store_dwordx4 v[12:13], v[20:23], off
	global_store_dwordx4 v[12:13], v[8:11], off offset:16
	global_store_dwordx4 v[12:13], v[4:7], off offset:512
	global_store_dwordx4 v[12:13], v[0:3], off offset:528
	s_cbranch_vccz .LBB0_820
	s_waitcnt vmcnt(0)
	s_cmpk_gt_u32 s3, 0xff
	s_cbranch_scc1 .LBB0_831
	s_barrier

; #define PG8_STAGE(bufoff, gbase, voff) do { _Pragma("unroll") for (int _i = 0; _i < 2; ++_i) \
;         __builtin_amdgcn_global_load_lds((const unsigned*)((const char*)(gbase) + (voff)[_i]), (PG8_LAS unsigned*)(lds + (bufoff) + ldsw + _i * 8192), 16, 0, 0); } while (0)
; #define PG8_LDA(dst, b, h) do { _Pragma("unroll") for (int m = 0; m < 4; ++m) _Pragma("unroll") for (int k = 0; k < 2; ++k) dst[m][k] = *(const PG8_LAS bf16x8*)(lds + PG8_SA(b, h) + aoff + m * 2048 + k * 1024); } while (0)
; #define PG8_LDB(dst, b, h) do { _Pragma("unroll") for (int n = 0; n < 2; ++n) _Pragma("unroll") for (int k = 0; k < 2; ++k) dst[n][k] = *(const PG8_LAS bf16x8*)(lds + PG8_SB(b, h) + boff + n * 2048 + k * 1024); } while (0)
; #define PG8_WAIT_V(n) asm volatile("s_waitcnt vmcnt(" #n ")" ::: "memory")
; #define PG8_WAIT_L(n) asm volatile("s_waitcnt lgkmcnt(" #n ")" ::: "memory")
; #define PG8_BAR __builtin_amdgcn_s_barrier()
; #define PG8_SCHED __builtin_amdgcn_sched_barrier(0)
; template <class Epi, class Sched, bool ALIGN_EPI = false, bool SP2 = false>
; __device__ __forceinline__ void gemm_phase(PG8_LAS unsigned char* lds, const Gemm g, const Sched& S, const Epi& E) {
;     ...
;         const bool has_next = S.next(ui + 1, nxt);
;         const char* nA = has_next ? (const char*)g.A + (size_t)nxt.pm * tstep : cA; const char* nB = has_next ? (const char*)g.Bt + (size_t)nxt.pn * tstep : cB;
;         for (int t = 0; t < nt; t += 2) {
;             const bool last = (t == nt - 2);
;             const char* a1 = cA + (size_t)(t + 1) * kstep;
;             const char* a2 = last ? nA : cA + (size_t)(t + 2) * kstep; const char* b2 = last ? nB : cB + (size_t)(t + 2) * kstep;
;             const char* a3 = a2 + kstep; const char* b3 = b2 + kstep;
;             if (last && has_next) S.a_ready(nxt);
;             if constexpr (SP2) {
;             PG8_LDB(B0, 0, 0); PG8_LDB(B1, 0, 1); PG8_SCHED; PG8_LDA(At, 0, 0); PG8_STAGE(PG8_SA(1, 1), a1 + hstep, voffA);
;             PG8_WAIT_V(8); PG8_WAIT_L(0); PG8_BAR; PG8_MMA(0, 0, At, B0); PG8_MMA(0, 1, At, B1); PG8_BAR; PG8_SCHED;
;             PG8_LDA(At, 0, 1); PG8_STAGE(PG8_SB(0, 0), b2, voffB); PG8_STAGE(PG8_SB(0, 1), b2 + hstep, voffB); PG8_STAGE(PG8_SA(0, 0), a2, voffA);
;             PG8_WAIT_V(8); PG8_WAIT_L(0); PG8_BAR; PG8_MMA(1, 0, At, B0); PG8_MMA(1, 1, At, B1); PG8_BAR; PG8_SCHED;
.LBB0_944:
	s_ashr_i32 s23, s22, 31
	v_cmp_lt_i64_e32 vcc, s[24:25], v[140:141]
	s_lshl_b64 s[24:25], s[22:23], 20
	s_add_u32 s24, s38, s24
	s_addc_u32 s25, s39, s25
	s_and_b64 s[26:27], vcc, exec
	s_cselect_b32 s23, s25, s31
	s_cselect_b32 s57, s24, s30
	s_ashr_i32 s15, s14, 31
	s_lshl_b64 s[26:27], s[14:15], 20
	s_add_u32 s26, s40, s26
	s_addc_u32 s27, s41, s27
	s_and_b64 s[36:37], vcc, exec
	s_cselect_b32 s15, s27, s35
	s_cselect_b32 s58, s26, s34
	s_add_u32 s30, s30, 0x80080
	s_addc_u32 s31, s31, 0
	s_add_u32 s59, s34, 0x100
	s_addc_u32 s60, s35, 0
	s_mov_b32 s61, -2
	ds_read_b128 v[152:155], v149
	ds_read_b128 v[156:159], v149 offset:1024
	ds_read_b128 v[160:163], v149 offset:2048
	ds_read_b128 v[164:167], v149 offset:3072
	ds_read_b128 v[168:171], v150
	ds_read_b128 v[172:175], v150 offset:1024
	ds_read_b128 v[176:179], v150 offset:2048
	ds_read_b128 v[180:183], v150 offset:3072
	s_add_u32 s34, s30, 0xfff80080
	s_addc_u32 s35, s31, -1
	s_cmp_eq_u32 s61, 28
	s_cselect_b32 s37, s23, s35
	s_cselect_b32 s36, s57, s34
	s_cselect_b32 s35, s15, s60
	s_cselect_b32 s34, s58, s59
	s_add_i32 m0, s29, 0xc000
	ds_read_b128 v[184:187], v151
	ds_read_b128 v[188:191], v151 offset:1024
	ds_read_b128 v[192:195], v151 offset:2048
	ds_read_b128 v[196:199], v151 offset:3072
	ds_read_b128 v[200:203], v151 offset:4096
	ds_read_b128 v[204:207], v151 offset:5120
	ds_read_b128 v[208:211], v151 offset:6144
	ds_read_b128 v[212:215], v151 offset:7168
	global_load_lds_dwordx4 v136, s[30:31]
	s_add_i32 m0, s29, 0xe000
	s_nop 0
	global_load_lds_dwordx4 v138, s[30:31]
	s_waitcnt vmcnt(8)
	s_waitcnt lgkmcnt(0)
	s_barrier
	v_mfma_f32_16x16x32_bf16 v[124:127], v[152:155], v[184:187], 0
	v_mfma_f32_16x16x32_bf16 v[120:123], v[160:163], v[184:187], 0
	v_mfma_f32_16x16x32_bf16 v[108:111], v[152:155], v[192:195], 0
	v_mfma_f32_16x16x32_bf16 v[104:107], v[160:163], v[192:195], 0
	v_mfma_f32_16x16x32_bf16 v[92:95], v[152:155], v[200:203], 0
	v_mfma_f32_16x16x32_bf16 v[88:91], v[160:163], v[200:203], 0
	v_mfma_f32_16x16x32_bf16 v[76:79], v[152:155], v[208:211], 0
	v_mfma_f32_16x16x32_bf16 v[72:75], v[160:163], v[208:211], 0
	v_mfma_f32_16x16x32_bf16 v[124:127], v[156:159], v[188:191], v[124:127]
	v_mfma_f32_16x16x32_bf16 v[120:123], v[164:167], v[188:191], v[120:123]
	v_mfma_f32_16x16x32_bf16 v[108:111], v[156:159], v[196:199], v[108:111]
	v_mfma_f32_16x16x32_bf16 v[104:107], v[164:167], v[196:199], v[104:107]
	v_mfma_f32_16x16x32_bf16 v[92:95], v[156:159], v[204:207], v[92:95]
	v_mfma_f32_16x16x32_bf16 v[88:91], v[164:167], v[204:207], v[88:91]
	v_mfma_f32_16x16x32_bf16 v[76:79], v[156:159], v[212:215], v[76:79]
	v_mfma_f32_16x16x32_bf16 v[72:75], v[164:167], v[212:215], v[72:75]
	v_mfma_f32_16x16x32_bf16 v[116:119], v[168:171], v[184:187], 0
	v_mfma_f32_16x16x32_bf16 v[112:115], v[176:179], v[184:187], 0
	v_mfma_f32_16x16x32_bf16 v[100:103], v[168:171], v[192:195], 0
	v_mfma_f32_16x16x32_bf16 v[96:99], v[176:179], v[192:195], 0
	v_mfma_f32_16x16x32_bf16 v[84:87], v[168:171], v[200:203], 0
	v_mfma_f32_16x16x32_bf16 v[80:83], v[176:179], v[200:203], 0
	v_mfma_f32_16x16x32_bf16 v[68:71], v[168:171], v[208:211], 0
	v_mfma_f32_16x16x32_bf16 v[64:67], v[176:179], v[208:211], 0
	v_mfma_f32_16x16x32_bf16 v[116:119], v[172:175], v[188:191], v[116:119]
	v_mfma_f32_16x16x32_bf16 v[112:115], v[180:183], v[188:191], v[112:115]
	v_mfma_f32_16x16x32_bf16 v[100:103], v[172:175], v[196:199], v[100:103]
	v_mfma_f32_16x16x32_bf16 v[96:99], v[180:183], v[196:199], v[96:99]
	v_mfma_f32_16x16x32_bf16 v[84:87], v[172:175], v[204:207], v[84:87]
	v_mfma_f32_16x16x32_bf16 v[80:83], v[180:183], v[204:207], v[80:83]
	v_mfma_f32_16x16x32_bf16 v[68:71], v[172:175], v[212:215], v[68:71]
	v_mfma_f32_16x16x32_bf16 v[64:67], v[180:183], v[212:215], v[64:67]
	s_barrier
	s_add_i32 s62, s53, s42
	s_mov_b32 m0, s62
	ds_read_b128 v[184:187], v151 offset:16384
	ds_read_b128 v[188:191], v151 offset:17408
	ds_read_b128 v[192:195], v151 offset:18432
	ds_read_b128 v[196:199], v151 offset:19456
	ds_read_b128 v[200:203], v151 offset:20480
	ds_read_b128 v[204:207], v151 offset:21504
	ds_read_b128 v[208:211], v151 offset:22528
	ds_read_b128 v[212:215], v151 offset:23552
	global_load_lds_dwordx4 v132, s[34:35]
	s_add_i32 m0, s62, 0x2000
	s_add_u32 s62, s34, 0x80000
	s_addc_u32 s63, s35, 0
	s_add_i32 s64, s54, s42
	global_load_lds_dwordx4 v128, s[34:35]
	s_mov_b32 m0, s64
	s_nop 0
	global_load_lds_dwordx4 v132, s[62:63]
	s_add_i32 m0, s64, 0x2000
	s_nop 0
	global_load_lds_dwordx4 v128, s[62:63]
	s_mov_b32 m0, s29
	s_nop 0
	global_load_lds_dwordx4 v134, s[36:37]
	s_mov_b32 m0, s45
	s_nop 0
	global_load_lds_dwordx4 v130, s[36:37]
	s_waitcnt vmcnt(8)
	s_waitcnt lgkmcnt(0)
	s_barrier
; #define PG8_STAGE(bufoff, gbase, voff) do { _Pragma("unroll") for (int _i = 0; _i < 2; ++_i) \
;         __builtin_amdgcn_global_load_lds((const unsigned*)((const char*)(gbase) + (voff)[_i]), (PG8_LAS unsigned*)(lds + (bufoff) + ldsw + _i * 8192), 16, 0, 0); } while (0)
; #define PG8_LDA(dst, b, h) do { _Pragma("unroll") for (int m = 0; m < 4; ++m) _Pragma("unroll") for (int k = 0; k < 2; ++k) dst[m][k] = *(const PG8_LAS bf16x8*)(lds + PG8_SA(b, h) + aoff + m * 2048 + k * 1024); } while (0)
; #define PG8_LDB(dst, b, h) do { _Pragma("unroll") for (int n = 0; n < 2; ++n) _Pragma("unroll") for (int k = 0; k < 2; ++k) dst[n][k] = *(const PG8_LAS bf16x8*)(lds + PG8_SB(b, h) + boff + n * 2048 + k * 1024); } while (0)
; #define PG8_MMA(ai, bj, At, Bt) do { __builtin_amdgcn_s_setprio(1); _Pragma("unroll") for (int m = 0; m < 4; ++m) _Pragma("unroll") for (int n = 0; n < 2; ++n) _Pragma("unroll") for (int k = 0; k < 2; ++k) \
;         acc[ai][bj][m][n] = __builtin_amdgcn_mfma_f32_16x16x32_bf16(Bt[n][k], At[m][k], acc[ai][bj][m][n], 0, 0, 0); __builtin_amdgcn_s_setprio(0); } while (0)
; #define PG8_WAIT_V(n) asm volatile("s_waitcnt vmcnt(" #n ")" ::: "memory")
; template <class Epi, class Sched, bool ALIGN_EPI = false, bool SP2 = false>
; __device__ __forceinline__ void gemm_phase(PG8_LAS unsigned char* lds, const Gemm g, const Sched& S, const Epi& E) {
;     ...
;             PG8_LDB(B0, 0, 0); PG8_LDB(B1, 0, 1); PG8_SCHED; PG8_LDA(At, 0, 0); PG8_STAGE(PG8_SA(1, 1), a1 + hstep, voffA);
;             PG8_WAIT_V(8); PG8_WAIT_L(0); PG8_BAR; PG8_MMA(0, 0, At, B0); PG8_MMA(0, 1, At, B1); PG8_BAR; PG8_SCHED;
;             PG8_LDA(At, 0, 1); PG8_STAGE(PG8_SB(0, 0), b2, voffB); PG8_STAGE(PG8_SB(0, 1), b2 + hstep, voffB); PG8_STAGE(PG8_SA(0, 0), a2, voffA);
;             PG8_WAIT_V(8); PG8_WAIT_L(0); PG8_BAR; PG8_MMA(1, 0, At, B0); PG8_MMA(1, 1, At, B1); PG8_BAR; PG8_SCHED;
;             PG8_LDB(B0, 1, 0); PG8_LDB(B1, 1, 1); PG8_SCHED; PG8_LDA(At, 1, 0); PG8_STAGE(PG8_SA(0, 1), a2 + hstep, voffA);
;             PG8_WAIT_V(8); PG8_WAIT_L(0); PG8_BAR; PG8_MMA(0, 0, At, B0); PG8_MMA(0, 1, At, B1); PG8_BAR; PG8_SCHED;
;             PG8_LDA(At, 1, 1); PG8_STAGE(PG8_SB(1, 0), b3, voffB); PG8_STAGE(PG8_SB(1, 1), b3 + hstep, voffB); PG8_STAGE(PG8_SA(1, 0), a3, voffA);
;             PG8_WAIT_V(8); PG8_WAIT_L(0); PG8_BAR; PG8_MMA(1, 0, At, B0); PG8_MMA(1, 1, At, B1); PG8_BAR; PG8_SCHED;
	v_mfma_f32_16x16x32_bf16 v[60:63], v[152:155], v[184:187], 0
	v_mfma_f32_16x16x32_bf16 v[56:59], v[160:163], v[184:187], 0
	v_mfma_f32_16x16x32_bf16 v[44:47], v[152:155], v[192:195], 0
	v_mfma_f32_16x16x32_bf16 v[40:43], v[160:163], v[192:195], 0
	v_mfma_f32_16x16x32_bf16 v[28:31], v[152:155], v[200:203], 0
	v_mfma_f32_16x16x32_bf16 v[24:27], v[160:163], v[200:203], 0
	v_mfma_f32_16x16x32_bf16 v[12:15], v[152:155], v[208:211], 0
	v_mfma_f32_16x16x32_bf16 v[8:11], v[160:163], v[208:211], 0
	v_mfma_f32_16x16x32_bf16 v[60:63], v[156:159], v[188:191], v[60:63]
	v_mfma_f32_16x16x32_bf16 v[56:59], v[164:167], v[188:191], v[56:59]
	v_mfma_f32_16x16x32_bf16 v[44:47], v[156:159], v[196:199], v[44:47]
	v_mfma_f32_16x16x32_bf16 v[40:43], v[164:167], v[196:199], v[40:43]
	v_mfma_f32_16x16x32_bf16 v[28:31], v[156:159], v[204:207], v[28:31]
	v_mfma_f32_16x16x32_bf16 v[24:27], v[164:167], v[204:207], v[24:27]
	v_mfma_f32_16x16x32_bf16 v[12:15], v[156:159], v[212:215], v[12:15]
	v_mfma_f32_16x16x32_bf16 v[8:11], v[164:167], v[212:215], v[8:11]
	v_mfma_f32_16x16x32_bf16 v[52:55], v[168:171], v[184:187], 0
	v_mfma_f32_16x16x32_bf16 v[48:51], v[176:179], v[184:187], 0
	v_mfma_f32_16x16x32_bf16 v[36:39], v[168:171], v[192:195], 0
	v_mfma_f32_16x16x32_bf16 v[32:35], v[176:179], v[192:195], 0
	v_mfma_f32_16x16x32_bf16 v[20:23], v[168:171], v[200:203], 0
	v_mfma_f32_16x16x32_bf16 v[16:19], v[176:179], v[200:203], 0
	v_mfma_f32_16x16x32_bf16 v[4:7], v[168:171], v[208:211], 0
	v_mfma_f32_16x16x32_bf16 v[0:3], v[176:179], v[208:211], 0
	v_mfma_f32_16x16x32_bf16 v[52:55], v[172:175], v[188:191], v[52:55]
	v_mfma_f32_16x16x32_bf16 v[48:51], v[180:183], v[188:191], v[48:51]
	v_mfma_f32_16x16x32_bf16 v[36:39], v[172:175], v[196:199], v[36:39]
	v_mfma_f32_16x16x32_bf16 v[32:35], v[180:183], v[196:199], v[32:35]
	v_mfma_f32_16x16x32_bf16 v[20:23], v[172:175], v[204:207], v[20:23]
	v_mfma_f32_16x16x32_bf16 v[16:19], v[180:183], v[204:207], v[16:19]
	v_mfma_f32_16x16x32_bf16 v[4:7], v[172:175], v[212:215], v[4:7]
	v_mfma_f32_16x16x32_bf16 v[0:3], v[180:183], v[212:215], v[0:3]
	s_barrier
	s_add_i32 s62, 0, 0x18000
	s_add_i32 s63, 0, 0x1c000
	v_add_u32_e32 v164, s62, v147
	v_add_u32_e32 v180, s63, v147
	ds_read_b128 v[152:155], v164
	ds_read_b128 v[156:159], v164 offset:1024
	ds_read_b128 v[160:163], v164 offset:2048
	ds_read_b128 v[164:167], v164 offset:3072
	ds_read_b128 v[168:171], v180
	ds_read_b128 v[172:175], v180 offset:1024
	ds_read_b128 v[176:179], v180 offset:2048
	ds_read_b128 v[180:183], v180 offset:3072
	s_add_u32 s84, s36, 0x80
	s_addc_u32 s85, s37, 0
	s_add_u32 s36, s36, 0x80000
	s_addc_u32 s37, s37, 0
	s_mov_b32 m0, s46
	ds_read_b128 v[184:187], v151 offset:32768
	ds_read_b128 v[188:191], v151 offset:33792
	ds_read_b128 v[192:195], v151 offset:34816
	ds_read_b128 v[196:199], v151 offset:35840
	ds_read_b128 v[200:203], v151 offset:36864
	ds_read_b128 v[204:207], v151 offset:37888
	ds_read_b128 v[208:211], v151 offset:38912
	ds_read_b128 v[212:215], v151 offset:39936
	global_load_lds_dwordx4 v134, s[36:37]
	s_mov_b32 m0, s47
	s_nop 0
	global_load_lds_dwordx4 v130, s[36:37]
	s_waitcnt vmcnt(8)
	s_waitcnt lgkmcnt(0)
	s_barrier
	v_mfma_f32_16x16x32_bf16 v[124:127], v[152:155], v[184:187], v[124:127]
	v_mfma_f32_16x16x32_bf16 v[120:123], v[160:163], v[184:187], v[120:123]
	v_mfma_f32_16x16x32_bf16 v[108:111], v[152:155], v[192:195], v[108:111]
	v_mfma_f32_16x16x32_bf16 v[104:107], v[160:163], v[192:195], v[104:107]
	v_mfma_f32_16x16x32_bf16 v[92:95], v[152:155], v[200:203], v[92:95]
	v_mfma_f32_16x16x32_bf16 v[88:91], v[160:163], v[200:203], v[88:91]
	v_mfma_f32_16x16x32_bf16 v[76:79], v[152:155], v[208:211], v[76:79]
	v_mfma_f32_16x16x32_bf16 v[72:75], v[160:163], v[208:211], v[72:75]
	v_mfma_f32_16x16x32_bf16 v[124:127], v[156:159], v[188:191], v[124:127]
	v_mfma_f32_16x16x32_bf16 v[120:123], v[164:167], v[188:191], v[120:123]
	v_mfma_f32_16x16x32_bf16 v[108:111], v[156:159], v[196:199], v[108:111]
	v_mfma_f32_16x16x32_bf16 v[104:107], v[164:167], v[196:199], v[104:107]
	v_mfma_f32_16x16x32_bf16 v[92:95], v[156:159], v[204:207], v[92:95]
	v_mfma_f32_16x16x32_bf16 v[88:91], v[164:167], v[204:207], v[88:91]
	v_mfma_f32_16x16x32_bf16 v[76:79], v[156:159], v[212:215], v[76:79]
	v_mfma_f32_16x16x32_bf16 v[72:75], v[164:167], v[212:215], v[72:75]
	v_mfma_f32_16x16x32_bf16 v[116:119], v[168:171], v[184:187], v[116:119]
	v_mfma_f32_16x16x32_bf16 v[112:115], v[176:179], v[184:187], v[112:115]
	v_mfma_f32_16x16x32_bf16 v[100:103], v[168:171], v[192:195], v[100:103]
	v_mfma_f32_16x16x32_bf16 v[96:99], v[176:179], v[192:195], v[96:99]
	v_mfma_f32_16x16x32_bf16 v[84:87], v[168:171], v[200:203], v[84:87]
	v_mfma_f32_16x16x32_bf16 v[80:83], v[176:179], v[200:203], v[80:83]
	v_mfma_f32_16x16x32_bf16 v[68:71], v[168:171], v[208:211], v[68:71]
	v_mfma_f32_16x16x32_bf16 v[64:67], v[176:179], v[208:211], v[64:67]
	v_mfma_f32_16x16x32_bf16 v[116:119], v[172:175], v[188:191], v[116:119]
	v_mfma_f32_16x16x32_bf16 v[112:115], v[180:183], v[188:191], v[112:115]
	v_mfma_f32_16x16x32_bf16 v[100:103], v[172:175], v[196:199], v[100:103]
	v_mfma_f32_16x16x32_bf16 v[96:99], v[180:183], v[196:199], v[96:99]
	v_mfma_f32_16x16x32_bf16 v[84:87], v[172:175], v[204:207], v[84:87]
	v_mfma_f32_16x16x32_bf16 v[80:83], v[180:183], v[204:207], v[80:83]
	v_mfma_f32_16x16x32_bf16 v[68:71], v[172:175], v[212:215], v[68:71]
	v_mfma_f32_16x16x32_bf16 v[64:67], v[180:183], v[212:215], v[64:67]
	s_barrier
; #define PG8_STAGE(bufoff, gbase, voff) do { _Pragma("unroll") for (int _i = 0; _i < 2; ++_i) \
;         __builtin_amdgcn_global_load_lds((const unsigned*)((const char*)(gbase) + (voff)[_i]), (PG8_LAS unsigned*)(lds + (bufoff) + ldsw + _i * 8192), 16, 0, 0); } while (0)
; #define PG8_LDA(dst, b, h) do { _Pragma("unroll") for (int m = 0; m < 4; ++m) _Pragma("unroll") for (int k = 0; k < 2; ++k) dst[m][k] = *(const PG8_LAS bf16x8*)(lds + PG8_SA(b, h) + aoff + m * 2048 + k * 1024); } while (0)
; #define PG8_LDB(dst, b, h) do { _Pragma("unroll") for (int n = 0; n < 2; ++n) _Pragma("unroll") for (int k = 0; k < 2; ++k) dst[n][k] = *(const PG8_LAS bf16x8*)(lds + PG8_SB(b, h) + boff + n * 2048 + k * 1024); } while (0)
; #define PG8_MMA(ai, bj, At, Bt) do { __builtin_amdgcn_s_setprio(1); _Pragma("unroll") for (int m = 0; m < 4; ++m) _Pragma("unroll") for (int n = 0; n < 2; ++n) _Pragma("unroll") for (int k = 0; k < 2; ++k) \
;         acc[ai][bj][m][n] = __builtin_amdgcn_mfma_f32_16x16x32_bf16(Bt[n][k], At[m][k], acc[ai][bj][m][n], 0, 0, 0); __builtin_amdgcn_s_setprio(0); } while (0)
; #define PG8_WAIT_V(n) asm volatile("s_waitcnt vmcnt(" #n ")" ::: "memory")
; template <class Epi, class Sched, bool ALIGN_EPI = false, bool SP2 = false>
; __device__ __forceinline__ void gemm_phase(PG8_LAS unsigned char* lds, const Gemm g, const Sched& S, const Epi& E) {
;     ...
;             PG8_LDB(B0, 0, 0); PG8_LDB(B1, 0, 1); PG8_SCHED; PG8_LDA(At, 0, 0); PG8_STAGE(PG8_SA(1, 1), a1 + hstep, voffA);
;             PG8_WAIT_V(8); PG8_WAIT_L(0); PG8_BAR; PG8_MMA(0, 0, At, B0); PG8_MMA(0, 1, At, B1); PG8_BAR; PG8_SCHED;
;             PG8_LDA(At, 0, 1); PG8_STAGE(PG8_SB(0, 0), b2, voffB); PG8_STAGE(PG8_SB(0, 1), b2 + hstep, voffB); PG8_STAGE(PG8_SA(0, 0), a2, voffA);
;             PG8_WAIT_V(8); PG8_WAIT_L(0); PG8_BAR; PG8_MMA(1, 0, At, B0); PG8_MMA(1, 1, At, B1); PG8_BAR; PG8_SCHED;
;             PG8_LDB(B0, 1, 0); PG8_LDB(B1, 1, 1); PG8_SCHED; PG8_LDA(At, 1, 0); PG8_STAGE(PG8_SA(0, 1), a2 + hstep, voffA);
;             PG8_WAIT_V(8); PG8_WAIT_L(0); PG8_BAR; PG8_MMA(0, 0, At, B0); PG8_MMA(0, 1, At, B1); PG8_BAR; PG8_SCHED;
;             PG8_LDA(At, 1, 1); PG8_STAGE(PG8_SB(1, 0), b3, voffB); PG8_STAGE(PG8_SB(1, 1), b3 + hstep, voffB); PG8_STAGE(PG8_SA(1, 0), a3, voffA);
;             PG8_WAIT_V(8); PG8_WAIT_L(0); PG8_BAR; PG8_MMA(1, 0, At, B0); PG8_MMA(1, 1, At, B1); PG8_BAR; PG8_SCHED;
	s_add_i32 s36, s62, s42
	s_add_u32 s86, s34, 0x80
	s_addc_u32 s87, s35, 0
	s_mov_b32 m0, s36
	ds_read_b128 v[184:187], v151 offset:49152
	ds_read_b128 v[188:191], v151 offset:50176
	ds_read_b128 v[192:195], v151 offset:51200
	ds_read_b128 v[196:199], v151 offset:52224
	ds_read_b128 v[200:203], v151 offset:53248
	ds_read_b128 v[204:207], v151 offset:54272
	ds_read_b128 v[208:211], v151 offset:55296
	ds_read_b128 v[212:215], v151 offset:56320
	global_load_lds_dwordx4 v132, s[86:87]
	s_add_i32 m0, s36, 0x2000
	s_add_u32 s34, s34, 0x80080
	s_addc_u32 s35, s35, 0
	s_add_i32 s36, s63, s42
	global_load_lds_dwordx4 v128, s[86:87]
	s_mov_b32 m0, s36
	s_nop 0
	global_load_lds_dwordx4 v132, s[34:35]
	s_add_i32 m0, s36, 0x2000
	s_nop 0
	global_load_lds_dwordx4 v128, s[34:35]
	s_mov_b32 m0, s49
	s_nop 0
	global_load_lds_dwordx4 v134, s[84:85]
	s_mov_b32 m0, s50
	s_nop 0
	global_load_lds_dwordx4 v130, s[84:85]
	s_waitcnt vmcnt(8)
	s_waitcnt lgkmcnt(0)
	s_barrier
	v_mfma_f32_16x16x32_bf16 v[60:63], v[152:155], v[184:187], v[60:63]
	v_mfma_f32_16x16x32_bf16 v[56:59], v[160:163], v[184:187], v[56:59]
	v_mfma_f32_16x16x32_bf16 v[44:47], v[152:155], v[192:195], v[44:47]
	v_mfma_f32_16x16x32_bf16 v[40:43], v[160:163], v[192:195], v[40:43]
	v_mfma_f32_16x16x32_bf16 v[28:31], v[152:155], v[200:203], v[28:31]
	v_mfma_f32_16x16x32_bf16 v[24:27], v[160:163], v[200:203], v[24:27]
	v_mfma_f32_16x16x32_bf16 v[12:15], v[152:155], v[208:211], v[12:15]
	v_mfma_f32_16x16x32_bf16 v[8:11], v[160:163], v[208:211], v[8:11]
	v_mfma_f32_16x16x32_bf16 v[60:63], v[156:159], v[188:191], v[60:63]
	v_mfma_f32_16x16x32_bf16 v[56:59], v[164:167], v[188:191], v[56:59]
	v_mfma_f32_16x16x32_bf16 v[44:47], v[156:159], v[196:199], v[44:47]
	v_mfma_f32_16x16x32_bf16 v[40:43], v[164:167], v[196:199], v[40:43]
	v_mfma_f32_16x16x32_bf16 v[28:31], v[156:159], v[204:207], v[28:31]
	v_mfma_f32_16x16x32_bf16 v[24:27], v[164:167], v[204:207], v[24:27]
	v_mfma_f32_16x16x32_bf16 v[12:15], v[156:159], v[212:215], v[12:15]
	v_mfma_f32_16x16x32_bf16 v[8:11], v[164:167], v[212:215], v[8:11]
	v_mfma_f32_16x16x32_bf16 v[52:55], v[168:171], v[184:187], v[52:55]
	v_mfma_f32_16x16x32_bf16 v[48:51], v[176:179], v[184:187], v[48:51]
	v_mfma_f32_16x16x32_bf16 v[36:39], v[168:171], v[192:195], v[36:39]
	v_mfma_f32_16x16x32_bf16 v[32:35], v[176:179], v[192:195], v[32:35]
	v_mfma_f32_16x16x32_bf16 v[20:23], v[168:171], v[200:203], v[20:23]
	v_mfma_f32_16x16x32_bf16 v[16:19], v[176:179], v[200:203], v[16:19]
	v_mfma_f32_16x16x32_bf16 v[4:7], v[168:171], v[208:211], v[4:7]
	v_mfma_f32_16x16x32_bf16 v[0:3], v[176:179], v[208:211], v[0:3]
	v_mfma_f32_16x16x32_bf16 v[52:55], v[172:175], v[188:191], v[52:55]
	v_mfma_f32_16x16x32_bf16 v[48:51], v[180:183], v[188:191], v[48:51]
	v_mfma_f32_16x16x32_bf16 v[36:39], v[172:175], v[196:199], v[36:39]
	v_mfma_f32_16x16x32_bf16 v[32:35], v[180:183], v[196:199], v[32:35]
	v_mfma_f32_16x16x32_bf16 v[20:23], v[172:175], v[204:207], v[20:23]
	v_mfma_f32_16x16x32_bf16 v[16:19], v[180:183], v[204:207], v[16:19]
	v_mfma_f32_16x16x32_bf16 v[4:7], v[172:175], v[212:215], v[4:7]
	v_mfma_f32_16x16x32_bf16 v[0:3], v[180:183], v[212:215], v[0:3]
	s_barrier
	s_add_i32 s61, s61, 2
	s_add_u32 s30, s30, 0x100
	s_addc_u32 s31, s31, 0
	s_add_u32 s59, s59, 0x100
	s_addc_u32 s60, s60, 0
	s_cmp_gt_u32 s61, 29
.LBB0_945:
	ds_read_b128 v[152:155], v149
	ds_read_b128 v[156:159], v149 offset:1024
	ds_read_b128 v[160:163], v149 offset:2048
	ds_read_b128 v[164:167], v149 offset:3072
	ds_read_b128 v[168:171], v150
	ds_read_b128 v[172:175], v150 offset:1024
	ds_read_b128 v[176:179], v150 offset:2048
	ds_read_b128 v[180:183], v150 offset:3072
	s_add_u32 s34, s30, 0xfff80080
	s_addc_u32 s35, s31, -1
	s_cmp_eq_u32 s61, 28
	s_cselect_b32 s37, s23, s35
	s_cselect_b32 s36, s57, s34
	s_cselect_b32 s35, s15, s60
	s_cselect_b32 s34, s58, s59
	s_add_i32 m0, s29, 0xc000
	ds_read_b128 v[184:187], v151
	ds_read_b128 v[188:191], v151 offset:1024
	ds_read_b128 v[192:195], v151 offset:2048
	ds_read_b128 v[196:199], v151 offset:3072
	ds_read_b128 v[200:203], v151 offset:4096
	ds_read_b128 v[204:207], v151 offset:5120
	ds_read_b128 v[208:211], v151 offset:6144
	ds_read_b128 v[212:215], v151 offset:7168
	global_load_lds_dwordx4 v136, s[30:31]
	s_add_i32 m0, s29, 0xe000
	s_nop 0
	global_load_lds_dwordx4 v138, s[30:31]
	s_waitcnt vmcnt(8)
	s_waitcnt lgkmcnt(0)
	s_barrier
	v_mfma_f32_16x16x32_bf16 v[124:127], v[152:155], v[184:187], v[124:127]
	v_mfma_f32_16x16x32_bf16 v[120:123], v[160:163], v[184:187], v[120:123]
	v_mfma_f32_16x16x32_bf16 v[108:111], v[152:155], v[192:195], v[108:111]
	v_mfma_f32_16x16x32_bf16 v[104:107], v[160:163], v[192:195], v[104:107]
	v_mfma_f32_16x16x32_bf16 v[92:95], v[152:155], v[200:203], v[92:95]
	v_mfma_f32_16x16x32_bf16 v[88:91], v[160:163], v[200:203], v[88:91]
	v_mfma_f32_16x16x32_bf16 v[76:79], v[152:155], v[208:211], v[76:79]
	v_mfma_f32_16x16x32_bf16 v[72:75], v[160:163], v[208:211], v[72:75]
	v_mfma_f32_16x16x32_bf16 v[124:127], v[156:159], v[188:191], v[124:127]
	v_mfma_f32_16x16x32_bf16 v[120:123], v[164:167], v[188:191], v[120:123]
	v_mfma_f32_16x16x32_bf16 v[108:111], v[156:159], v[196:199], v[108:111]
	v_mfma_f32_16x16x32_bf16 v[104:107], v[164:167], v[196:199], v[104:107]
	v_mfma_f32_16x16x32_bf16 v[92:95], v[156:159], v[204:207], v[92:95]
	v_mfma_f32_16x16x32_bf16 v[88:91], v[164:167], v[204:207], v[88:91]
	v_mfma_f32_16x16x32_bf16 v[76:79], v[156:159], v[212:215], v[76:79]
	v_mfma_f32_16x16x32_bf16 v[72:75], v[164:167], v[212:215], v[72:75]
	v_mfma_f32_16x16x32_bf16 v[116:119], v[168:171], v[184:187], v[116:119]
	v_mfma_f32_16x16x32_bf16 v[112:115], v[176:179], v[184:187], v[112:115]
	v_mfma_f32_16x16x32_bf16 v[100:103], v[168:171], v[192:195], v[100:103]
	v_mfma_f32_16x16x32_bf16 v[96:99], v[176:179], v[192:195], v[96:99]
	v_mfma_f32_16x16x32_bf16 v[84:87], v[168:171], v[200:203], v[84:87]
	v_mfma_f32_16x16x32_bf16 v[80:83], v[176:179], v[200:203], v[80:83]
	v_mfma_f32_16x16x32_bf16 v[68:71], v[168:171], v[208:211], v[68:71]
	v_mfma_f32_16x16x32_bf16 v[64:67], v[176:179], v[208:211], v[64:67]
	v_mfma_f32_16x16x32_bf16 v[116:119], v[172:175], v[188:191], v[116:119]
	v_mfma_f32_16x16x32_bf16 v[112:115], v[180:183], v[188:191], v[112:115]
	v_mfma_f32_16x16x32_bf16 v[100:103], v[172:175], v[196:199], v[100:103]
	v_mfma_f32_16x16x32_bf16 v[96:99], v[180:183], v[196:199], v[96:99]
	v_mfma_f32_16x16x32_bf16 v[84:87], v[172:175], v[204:207], v[84:87]
	v_mfma_f32_16x16x32_bf16 v[80:83], v[180:183], v[204:207], v[80:83]
	v_mfma_f32_16x16x32_bf16 v[68:71], v[172:175], v[212:215], v[68:71]
	v_mfma_f32_16x16x32_bf16 v[64:67], v[180:183], v[212:215], v[64:67]
	s_barrier
; #define PG8_STAGE(bufoff, gbase, voff) do { _Pragma("unroll") for (int _i = 0; _i < 2; ++_i) \
;         __builtin_amdgcn_global_load_lds((const unsigned*)((const char*)(gbase) + (voff)[_i]), (PG8_LAS unsigned*)(lds + (bufoff) + ldsw + _i * 8192), 16, 0, 0); } while (0)
; #define PG8_LDA(dst, b, h) do { _Pragma("unroll") for (int m = 0; m < 4; ++m) _Pragma("unroll") for (int k = 0; k < 2; ++k) dst[m][k] = *(const PG8_LAS bf16x8*)(lds + PG8_SA(b, h) + aoff + m * 2048 + k * 1024); } while (0)
; #define PG8_LDB(dst, b, h) do { _Pragma("unroll") for (int n = 0; n < 2; ++n) _Pragma("unroll") for (int k = 0; k < 2; ++k) dst[n][k] = *(const PG8_LAS bf16x8*)(lds + PG8_SB(b, h) + boff + n * 2048 + k * 1024); } while (0)
; #define PG8_MMA(ai, bj, At, Bt) do { __builtin_amdgcn_s_setprio(1); _Pragma("unroll") for (int m = 0; m < 4; ++m) _Pragma("unroll") for (int n = 0; n < 2; ++n) _Pragma("unroll") for (int k = 0; k < 2; ++k) \
;         acc[ai][bj][m][n] = __builtin_amdgcn_mfma_f32_16x16x32_bf16(Bt[n][k], At[m][k], acc[ai][bj][m][n], 0, 0, 0); __builtin_amdgcn_s_setprio(0); } while (0)
; #define PG8_WAIT_V(n) asm volatile("s_waitcnt vmcnt(" #n ")" ::: "memory")
; template <class Epi, class Sched, bool ALIGN_EPI = false, bool SP2 = false>
; __device__ __forceinline__ void gemm_phase(PG8_LAS unsigned char* lds, const Gemm g, const Sched& S, const Epi& E) {
;     ...
;             PG8_LDB(B0, 0, 0); PG8_LDB(B1, 0, 1); PG8_SCHED; PG8_LDA(At, 0, 0); PG8_STAGE(PG8_SA(1, 1), a1 + hstep, voffA);
;             PG8_WAIT_V(8); PG8_WAIT_L(0); PG8_BAR; PG8_MMA(0, 0, At, B0); PG8_MMA(0, 1, At, B1); PG8_BAR; PG8_SCHED;
;             PG8_LDA(At, 0, 1); PG8_STAGE(PG8_SB(0, 0), b2, voffB); PG8_STAGE(PG8_SB(0, 1), b2 + hstep, voffB); PG8_STAGE(PG8_SA(0, 0), a2, voffA);
;             PG8_WAIT_V(8); PG8_WAIT_L(0); PG8_BAR; PG8_MMA(1, 0, At, B0); PG8_MMA(1, 1, At, B1); PG8_BAR; PG8_SCHED;
;             PG8_LDB(B0, 1, 0); PG8_LDB(B1, 1, 1); PG8_SCHED; PG8_LDA(At, 1, 0); PG8_STAGE(PG8_SA(0, 1), a2 + hstep, voffA);
;             PG8_WAIT_V(8); PG8_WAIT_L(0); PG8_BAR; PG8_MMA(0, 0, At, B0); PG8_MMA(0, 1, At, B1); PG8_BAR; PG8_SCHED;
;             PG8_LDA(At, 1, 1); PG8_STAGE(PG8_SB(1, 0), b3, voffB); PG8_STAGE(PG8_SB(1, 1), b3 + hstep, voffB); PG8_STAGE(PG8_SA(1, 0), a3, voffA);
;             PG8_WAIT_V(8); PG8_WAIT_L(0); PG8_BAR; PG8_MMA(1, 0, At, B0); PG8_MMA(1, 1, At, B1); PG8_BAR; PG8_SCHED;
	s_add_i32 s62, s53, s42
	s_mov_b32 m0, s62
	ds_read_b128 v[184:187], v151 offset:16384
	ds_read_b128 v[188:191], v151 offset:17408
	ds_read_b128 v[192:195], v151 offset:18432
	ds_read_b128 v[196:199], v151 offset:19456
	ds_read_b128 v[200:203], v151 offset:20480
	ds_read_b128 v[204:207], v151 offset:21504
	ds_read_b128 v[208:211], v151 offset:22528
	ds_read_b128 v[212:215], v151 offset:23552
	global_load_lds_dwordx4 v132, s[34:35]
	s_add_i32 m0, s62, 0x2000
	s_add_u32 s62, s34, 0x80000
	s_addc_u32 s63, s35, 0
	s_add_i32 s64, s54, s42
	global_load_lds_dwordx4 v128, s[34:35]
	s_mov_b32 m0, s64
	s_nop 0
	global_load_lds_dwordx4 v132, s[62:63]
	s_add_i32 m0, s64, 0x2000
	s_nop 0
	global_load_lds_dwordx4 v128, s[62:63]
	s_mov_b32 m0, s29
	s_nop 0
	global_load_lds_dwordx4 v134, s[36:37]
	s_mov_b32 m0, s45
	s_nop 0
	global_load_lds_dwordx4 v130, s[36:37]
	s_waitcnt vmcnt(8)
	s_waitcnt lgkmcnt(0)
	s_barrier
	v_mfma_f32_16x16x32_bf16 v[60:63], v[152:155], v[184:187], v[60:63]
	v_mfma_f32_16x16x32_bf16 v[56:59], v[160:163], v[184:187], v[56:59]
	v_mfma_f32_16x16x32_bf16 v[44:47], v[152:155], v[192:195], v[44:47]
	v_mfma_f32_16x16x32_bf16 v[40:43], v[160:163], v[192:195], v[40:43]
	v_mfma_f32_16x16x32_bf16 v[28:31], v[152:155], v[200:203], v[28:31]
	v_mfma_f32_16x16x32_bf16 v[24:27], v[160:163], v[200:203], v[24:27]
	v_mfma_f32_16x16x32_bf16 v[12:15], v[152:155], v[208:211], v[12:15]
	v_mfma_f32_16x16x32_bf16 v[8:11], v[160:163], v[208:211], v[8:11]
	v_mfma_f32_16x16x32_bf16 v[60:63], v[156:159], v[188:191], v[60:63]
	v_mfma_f32_16x16x32_bf16 v[56:59], v[164:167], v[188:191], v[56:59]
	v_mfma_f32_16x16x32_bf16 v[44:47], v[156:159], v[196:199], v[44:47]
	v_mfma_f32_16x16x32_bf16 v[40:43], v[164:167], v[196:199], v[40:43]
	v_mfma_f32_16x16x32_bf16 v[28:31], v[156:159], v[204:207], v[28:31]
	v_mfma_f32_16x16x32_bf16 v[24:27], v[164:167], v[204:207], v[24:27]
	v_mfma_f32_16x16x32_bf16 v[12:15], v[156:159], v[212:215], v[12:15]
	v_mfma_f32_16x16x32_bf16 v[8:11], v[164:167], v[212:215], v[8:11]
	v_mfma_f32_16x16x32_bf16 v[52:55], v[168:171], v[184:187], v[52:55]
	v_mfma_f32_16x16x32_bf16 v[48:51], v[176:179], v[184:187], v[48:51]
	v_mfma_f32_16x16x32_bf16 v[36:39], v[168:171], v[192:195], v[36:39]
	v_mfma_f32_16x16x32_bf16 v[32:35], v[176:179], v[192:195], v[32:35]
	v_mfma_f32_16x16x32_bf16 v[20:23], v[168:171], v[200:203], v[20:23]
	v_mfma_f32_16x16x32_bf16 v[16:19], v[176:179], v[200:203], v[16:19]
	v_mfma_f32_16x16x32_bf16 v[4:7], v[168:171], v[208:211], v[4:7]
	v_mfma_f32_16x16x32_bf16 v[0:3], v[176:179], v[208:211], v[0:3]
	v_mfma_f32_16x16x32_bf16 v[52:55], v[172:175], v[188:191], v[52:55]
	v_mfma_f32_16x16x32_bf16 v[48:51], v[180:183], v[188:191], v[48:51]
	v_mfma_f32_16x16x32_bf16 v[36:39], v[172:175], v[196:199], v[36:39]
	v_mfma_f32_16x16x32_bf16 v[32:35], v[180:183], v[196:199], v[32:35]
	v_mfma_f32_16x16x32_bf16 v[20:23], v[172:175], v[204:207], v[20:23]
	v_mfma_f32_16x16x32_bf16 v[16:19], v[180:183], v[204:207], v[16:19]
	v_mfma_f32_16x16x32_bf16 v[4:7], v[172:175], v[212:215], v[4:7]
	v_mfma_f32_16x16x32_bf16 v[0:3], v[180:183], v[212:215], v[0:3]
	s_barrier
	s_add_i32 s62, 0, 0x18000
	s_add_i32 s63, 0, 0x1c000
	v_add_u32_e32 v164, s62, v147
	v_add_u32_e32 v180, s63, v147
	ds_read_b128 v[152:155], v164
	ds_read_b128 v[156:159], v164 offset:1024
	ds_read_b128 v[160:163], v164 offset:2048
	ds_read_b128 v[164:167], v164 offset:3072
	ds_read_b128 v[168:171], v180
	ds_read_b128 v[172:175], v180 offset:1024
	ds_read_b128 v[176:179], v180 offset:2048
	ds_read_b128 v[180:183], v180 offset:3072
	s_add_u32 s84, s36, 0x80
	s_addc_u32 s85, s37, 0
	s_add_u32 s36, s36, 0x80000
	s_addc_u32 s37, s37, 0
	s_mov_b32 m0, s46
	ds_read_b128 v[184:187], v151 offset:32768
	ds_read_b128 v[188:191], v151 offset:33792
	ds_read_b128 v[192:195], v151 offset:34816
	ds_read_b128 v[196:199], v151 offset:35840
	ds_read_b128 v[200:203], v151 offset:36864
	ds_read_b128 v[204:207], v151 offset:37888
	ds_read_b128 v[208:211], v151 offset:38912
	ds_read_b128 v[212:215], v151 offset:39936
	global_load_lds_dwordx4 v134, s[36:37]
	s_mov_b32 m0, s47
	s_nop 0
	global_load_lds_dwordx4 v130, s[36:37]
	s_waitcnt vmcnt(8)
	s_waitcnt lgkmcnt(0)
	s_barrier
	v_mfma_f32_16x16x32_bf16 v[124:127], v[152:155], v[184:187], v[124:127]
	v_mfma_f32_16x16x32_bf16 v[120:123], v[160:163], v[184:187], v[120:123]
	v_mfma_f32_16x16x32_bf16 v[108:111], v[152:155], v[192:195], v[108:111]
	v_mfma_f32_16x16x32_bf16 v[104:107], v[160:163], v[192:195], v[104:107]
	v_mfma_f32_16x16x32_bf16 v[92:95], v[152:155], v[200:203], v[92:95]
	v_mfma_f32_16x16x32_bf16 v[88:91], v[160:163], v[200:203], v[88:91]
	v_mfma_f32_16x16x32_bf16 v[76:79], v[152:155], v[208:211], v[76:79]
	v_mfma_f32_16x16x32_bf16 v[72:75], v[160:163], v[208:211], v[72:75]
	v_mfma_f32_16x16x32_bf16 v[124:127], v[156:159], v[188:191], v[124:127]
	v_mfma_f32_16x16x32_bf16 v[120:123], v[164:167], v[188:191], v[120:123]
	v_mfma_f32_16x16x32_bf16 v[108:111], v[156:159], v[196:199], v[108:111]
	v_mfma_f32_16x16x32_bf16 v[104:107], v[164:167], v[196:199], v[104:107]
	v_mfma_f32_16x16x32_bf16 v[92:95], v[156:159], v[204:207], v[92:95]
	v_mfma_f32_16x16x32_bf16 v[88:91], v[164:167], v[204:207], v[88:91]
	v_mfma_f32_16x16x32_bf16 v[76:79], v[156:159], v[212:215], v[76:79]
	v_mfma_f32_16x16x32_bf16 v[72:75], v[164:167], v[212:215], v[72:75]
	v_mfma_f32_16x16x32_bf16 v[116:119], v[168:171], v[184:187], v[116:119]
	v_mfma_f32_16x16x32_bf16 v[112:115], v[176:179], v[184:187], v[112:115]
	v_mfma_f32_16x16x32_bf16 v[100:103], v[168:171], v[192:195], v[100:103]
	v_mfma_f32_16x16x32_bf16 v[96:99], v[176:179], v[192:195], v[96:99]
	v_mfma_f32_16x16x32_bf16 v[84:87], v[168:171], v[200:203], v[84:87]
	v_mfma_f32_16x16x32_bf16 v[80:83], v[176:179], v[200:203], v[80:83]
	v_mfma_f32_16x16x32_bf16 v[68:71], v[168:171], v[208:211], v[68:71]
	v_mfma_f32_16x16x32_bf16 v[64:67], v[176:179], v[208:211], v[64:67]
	v_mfma_f32_16x16x32_bf16 v[116:119], v[172:175], v[188:191], v[116:119]
	v_mfma_f32_16x16x32_bf16 v[112:115], v[180:183], v[188:191], v[112:115]
	v_mfma_f32_16x16x32_bf16 v[100:103], v[172:175], v[196:199], v[100:103]
	v_mfma_f32_16x16x32_bf16 v[96:99], v[180:183], v[196:199], v[96:99]
	v_mfma_f32_16x16x32_bf16 v[84:87], v[172:175], v[204:207], v[84:87]
	v_mfma_f32_16x16x32_bf16 v[80:83], v[180:183], v[204:207], v[80:83]
	v_mfma_f32_16x16x32_bf16 v[68:71], v[172:175], v[212:215], v[68:71]
	v_mfma_f32_16x16x32_bf16 v[64:67], v[180:183], v[212:215], v[64:67]
	s_barrier
; __device__ __forceinline__ float fsilu(float v) { return v * fsigmoid(v); }
; __device__ __forceinline__ u32x4 pack8(const f32x4 a, const f32x4 b) { u32x4 w; w.x = cvt_pk_bf16(a[0], a[1]); w.y = cvt_pk_bf16(a[2], a[3]); w.z = cvt_pk_bf16(b[0], b[1]); w.w = cvt_pk_bf16(b[2], b[3]); return w; }
; #define PG8_WAIT_V(n) asm volatile("s_waitcnt vmcnt(" #n ")" ::: "memory")
; #define PG8_WAIT_L(n) asm volatile("s_waitcnt lgkmcnt(" #n ")" ::: "memory")
;     __device__ __forceinline__ void operator()(const f32x4 (&acc)[2][2][4][2], const Unit& u, int wr, int wc, int fr, int fq) const {
;         const int row0 = u.pm * BM + wr * 64 + fr, col0 = u.pn * 128 + wc * 32 + 8 * fq;
; #pragma unroll
;         for (int ai = 0; ai < 2; ++ai)
; #pragma unroll
;             for (int m = 0; m < 4; ++m) {
;                 bf16_t* rowp = O + (size_t)(row0 + ai * HALF + m * 16) * ldc + col0;
;                 f32x4 h0, h1;
; #pragma unroll
;                 for (int j = 0; j < 4; ++j) { h0[j] = fsilu(acc[ai][0][m][0][j]) * acc[ai][1][m][0][j]; h1[j] = fsilu(acc[ai][0][m][1][j]) * acc[ai][1][m][1][j]; }
;                 *(u32x4*)rowp = pack8(h0, h1);
; template <class Epi, class Sched, bool ALIGN_EPI = false, bool SP2 = false>
; __device__ __forceinline__ void gemm_phase(PG8_LAS unsigned char* lds, const Gemm g, const Sched& S, const Epi& E) {
;     ...
;             PG8_LDB(B0, 0, 0); PG8_LDB(B1, 0, 1); PG8_SCHED; PG8_LDA(At, 0, 0); PG8_STAGE(PG8_SA(1, 1), a1 + hstep, voffA);
;             PG8_WAIT_V(8); PG8_WAIT_L(0); PG8_BAR; PG8_MMA(0, 0, At, B0); PG8_MMA(0, 1, At, B1); PG8_BAR; PG8_SCHED;
;             PG8_LDA(At, 0, 1); PG8_STAGE(PG8_SB(0, 0), b2, voffB); PG8_STAGE(PG8_SB(0, 1), b2 + hstep, voffB); PG8_STAGE(PG8_SA(0, 0), a2, voffA);
;             PG8_WAIT_V(8); PG8_WAIT_L(0); PG8_BAR; PG8_MMA(1, 0, At, B0); PG8_MMA(1, 1, At, B1); PG8_BAR; PG8_SCHED;
;             PG8_LDB(B0, 1, 0); PG8_LDB(B1, 1, 1); PG8_SCHED; PG8_LDA(At, 1, 0); PG8_STAGE(PG8_SA(0, 1), a2 + hstep, voffA);
;             PG8_WAIT_V(8); PG8_WAIT_L(0); PG8_BAR; PG8_MMA(0, 0, At, B0); PG8_MMA(0, 1, At, B1); PG8_BAR; PG8_SCHED;
;             PG8_LDA(At, 1, 1); PG8_STAGE(PG8_SB(1, 0), b3, voffB); PG8_STAGE(PG8_SB(1, 1), b3 + hstep, voffB); PG8_STAGE(PG8_SA(1, 0), a3, voffA);
;             PG8_WAIT_V(8); PG8_WAIT_L(0); PG8_BAR; PG8_MMA(1, 0, At, B0); PG8_MMA(1, 1, At, B1); PG8_BAR; PG8_SCHED;
	s_add_i32 s36, s62, s42
	s_add_u32 s86, s34, 0x80
	s_addc_u32 s87, s35, 0
	s_mov_b32 m0, s36
	ds_read_b128 v[184:187], v151 offset:49152
	ds_read_b128 v[188:191], v151 offset:50176
	ds_read_b128 v[192:195], v151 offset:51200
	ds_read_b128 v[196:199], v151 offset:52224
	ds_read_b128 v[200:203], v151 offset:53248
	ds_read_b128 v[204:207], v151 offset:54272
	ds_read_b128 v[208:211], v151 offset:55296
	ds_read_b128 v[212:215], v151 offset:56320
	global_load_lds_dwordx4 v132, s[86:87]
	s_add_i32 m0, s36, 0x2000
	s_add_u32 s34, s34, 0x80080
	s_addc_u32 s35, s35, 0
	s_add_i32 s36, s63, s42
	global_load_lds_dwordx4 v128, s[86:87]
	s_mov_b32 m0, s36
	s_nop 0
	global_load_lds_dwordx4 v132, s[34:35]
	s_add_i32 m0, s36, 0x2000
	s_nop 0
	global_load_lds_dwordx4 v128, s[34:35]
	s_mov_b32 m0, s49
	s_nop 0
	global_load_lds_dwordx4 v134, s[84:85]
	s_mov_b32 m0, s50
	s_nop 0
	global_load_lds_dwordx4 v130, s[84:85]
	s_waitcnt vmcnt(8)
	s_waitcnt lgkmcnt(0)
	s_barrier
	v_mfma_f32_16x16x32_bf16 v[60:63], v[152:155], v[184:187], v[60:63]
	v_mfma_f32_16x16x32_bf16 v[56:59], v[160:163], v[184:187], v[56:59]
	v_mfma_f32_16x16x32_bf16 v[44:47], v[152:155], v[192:195], v[44:47]
	v_mfma_f32_16x16x32_bf16 v[40:43], v[160:163], v[192:195], v[40:43]
	v_mfma_f32_16x16x32_bf16 v[28:31], v[152:155], v[200:203], v[28:31]
	v_mfma_f32_16x16x32_bf16 v[24:27], v[160:163], v[200:203], v[24:27]
	v_mfma_f32_16x16x32_bf16 v[12:15], v[152:155], v[208:211], v[12:15]
	v_mfma_f32_16x16x32_bf16 v[8:11], v[160:163], v[208:211], v[8:11]
	v_mfma_f32_16x16x32_bf16 v[60:63], v[156:159], v[188:191], v[60:63]
	v_mfma_f32_16x16x32_bf16 v[56:59], v[164:167], v[188:191], v[56:59]
	v_mfma_f32_16x16x32_bf16 v[44:47], v[156:159], v[196:199], v[44:47]
	v_mfma_f32_16x16x32_bf16 v[40:43], v[164:167], v[196:199], v[40:43]
	v_mfma_f32_16x16x32_bf16 v[28:31], v[156:159], v[204:207], v[28:31]
	v_mfma_f32_16x16x32_bf16 v[24:27], v[164:167], v[204:207], v[24:27]
	v_mfma_f32_16x16x32_bf16 v[12:15], v[156:159], v[212:215], v[12:15]
	v_mfma_f32_16x16x32_bf16 v[8:11], v[164:167], v[212:215], v[8:11]
	v_mfma_f32_16x16x32_bf16 v[52:55], v[168:171], v[184:187], v[52:55]
	v_mfma_f32_16x16x32_bf16 v[48:51], v[176:179], v[184:187], v[48:51]
	v_mfma_f32_16x16x32_bf16 v[36:39], v[168:171], v[192:195], v[36:39]
	v_mfma_f32_16x16x32_bf16 v[32:35], v[176:179], v[192:195], v[32:35]
	v_mfma_f32_16x16x32_bf16 v[20:23], v[168:171], v[200:203], v[20:23]
	v_mfma_f32_16x16x32_bf16 v[16:19], v[176:179], v[200:203], v[16:19]
	v_mfma_f32_16x16x32_bf16 v[4:7], v[168:171], v[208:211], v[4:7]
	v_mfma_f32_16x16x32_bf16 v[0:3], v[176:179], v[208:211], v[0:3]
	v_mfma_f32_16x16x32_bf16 v[52:55], v[172:175], v[188:191], v[52:55]
	v_mfma_f32_16x16x32_bf16 v[48:51], v[180:183], v[188:191], v[48:51]
	v_mfma_f32_16x16x32_bf16 v[36:39], v[172:175], v[196:199], v[36:39]
	v_mfma_f32_16x16x32_bf16 v[32:35], v[180:183], v[196:199], v[32:35]
	v_mfma_f32_16x16x32_bf16 v[20:23], v[172:175], v[204:207], v[20:23]
	v_mfma_f32_16x16x32_bf16 v[16:19], v[180:183], v[204:207], v[16:19]
	v_mfma_f32_16x16x32_bf16 v[4:7], v[172:175], v[212:215], v[4:7]
	v_mfma_f32_16x16x32_bf16 v[0:3], v[180:183], v[212:215], v[0:3]
	s_barrier
	s_add_i32 s61, s61, 2
	s_add_u32 s30, s30, 0x100
	s_addc_u32 s31, s31, 0
	s_add_u32 s59, s59, 0x100
	s_addc_u32 s60, s60, 0
	s_cmp_gt_u32 s61, 29
	s_cbranch_scc0 .LBB0_945
	v_mul_f32_e32 v153, 0xbfb8aa3b, v124
	v_mul_f32_e32 v158, 0xbfb8aa3b, v120
	v_exp_f32_e32 v153, v153
	v_exp_f32_e32 v159, v158
	v_mul_f32_e32 v158, 0xbfb8aa3b, v125
	v_exp_f32_e32 v160, v158
	v_add_f32_e32 v153, 1.0, v153
	v_rcp_f32_e32 v158, v153
	v_add_f32_e32 v153, 1.0, v159
	v_add_f32_e32 v159, 1.0, v160
	v_rcp_f32_e32 v159, v159
	v_mul_f32_e32 v160, 0xbfb8aa3b, v121
	v_exp_f32_e32 v161, v160
	v_rcp_f32_e32 v160, v153
	v_pk_mul_f32 v[124:125], v[124:125], v[158:159]
	v_mul_f32_e32 v153, 0xbfb8aa3b, v127
	v_pk_mul_f32 v[116:117], v[124:125], v[116:117]
	v_add_f32_e32 v124, 1.0, v161
	v_mul_f32_e32 v125, 0xbfb8aa3b, v122
	v_rcp_f32_e32 v161, v124
	v_mul_f32_e32 v124, 0xbfb8aa3b, v126
	v_exp_f32_e32 v125, v125
	v_exp_f32_e32 v124, v124
	v_exp_f32_e32 v153, v153
	v_mul_f32_e32 v158, 0xbfb8aa3b, v123
	v_exp_f32_e32 v159, v158
	v_add_f32_e32 v125, 1.0, v125
	v_add_f32_e32 v124, 1.0, v124
	v_rcp_f32_e32 v158, v125
	v_add_f32_e32 v125, 1.0, v153
	v_rcp_f32_e32 v124, v124
	v_rcp_f32_e32 v125, v125
	v_add_f32_e32 v153, 1.0, v159
	v_rcp_f32_e32 v159, v153
	v_pk_mul_f32 v[120:121], v[120:121], v[160:161]
	v_lshl_or_b32 v154, s56, 7, v148
	v_pk_mul_f32 v[120:121], v[120:121], v[112:113]
	v_pk_mul_f32 v[112:113], v[126:127], v[124:125]
	v_lshl_add_u32 v152, s28, 8, v146
	v_ashrrev_i32_e32 v155, 31, v154
	v_mov_b64_e32 v[144:145], s[10:11]
	v_pk_mul_f32 v[118:119], v[112:113], v[118:119]
	v_pk_mul_f32 v[112:113], v[122:123], v[158:159]
	v_mad_i64_i32 v[156:157], s[30:31], v152, s55, v[144:145]
	v_pk_mul_f32 v[122:123], v[112:113], v[114:115]
	v_lshlrev_b64 v[112:113], 1, v[154:155]
	v_lshl_add_u64 v[124:125], v[156:157], 0, v[112:113]
	v_cvt_pk_bf16_f32 v114, v116, v117
	v_cvt_pk_bf16_f32 v115, v118, v119
	v_cvt_pk_bf16_f32 v116, v120, v121
	v_cvt_pk_bf16_f32 v117, v122, v123
	global_store_dwordx4 v[124:125], v[114:117], off
	v_mul_f32_e32 v118, 0xbfb8aa3b, v109
	v_exp_f32_e32 v118, v118
	v_mul_f32_e32 v116, 0xbfb8aa3b, v108
	v_mul_f32_e32 v117, 0xbfb8aa3b, v104
	v_exp_f32_e32 v116, v116
	v_exp_f32_e32 v117, v117
	v_or_b32_e32 v114, 16, v152
	v_mad_i64_i32 v[114:115], s[30:31], v114, s55, v[144:145]
	v_add_f32_e32 v116, 1.0, v116
	v_add_f32_e32 v119, 1.0, v117
	v_add_f32_e32 v117, 1.0, v118
	v_rcp_f32_e32 v116, v116
	v_rcp_f32_e32 v117, v117
	v_mul_f32_e32 v118, 0xbfb8aa3b, v105
; __device__ __forceinline__ float fsilu(float v) { return v * fsigmoid(v); }
; __device__ __forceinline__ u32x4 pack8(const f32x4 a, const f32x4 b) { u32x4 w; w.x = cvt_pk_bf16(a[0], a[1]); w.y = cvt_pk_bf16(a[2], a[3]); w.z = cvt_pk_bf16(b[0], b[1]); w.w = cvt_pk_bf16(b[2], b[3]); return w; }
;     __device__ __forceinline__ void operator()(const f32x4 (&acc)[2][2][4][2], const Unit& u, int wr, int wc, int fr, int fq) const {
;         const int row0 = u.pm * BM + wr * 64 + fr, col0 = u.pn * 128 + wc * 32 + 8 * fq;
; #pragma unroll
;         for (int ai = 0; ai < 2; ++ai)
; #pragma unroll
;             for (int m = 0; m < 4; ++m) {
;                 bf16_t* rowp = O + (size_t)(row0 + ai * HALF + m * 16) * ldc + col0;
;                 f32x4 h0, h1;
; #pragma unroll
;                 for (int j = 0; j < 4; ++j) { h0[j] = fsilu(acc[ai][0][m][0][j]) * acc[ai][1][m][0][j]; h1[j] = fsilu(acc[ai][0][m][1][j]) * acc[ai][1][m][1][j]; }
;                 *(u32x4*)rowp = pack8(h0, h1);
	v_exp_f32_e32 v120, v118
	v_rcp_f32_e32 v118, v119
	v_pk_mul_f32 v[108:109], v[108:109], v[116:117]
	v_mul_f32_e32 v116, 0xbfb8aa3b, v111
	v_pk_mul_f32 v[100:101], v[108:109], v[100:101]
	v_add_f32_e32 v108, 1.0, v120
	v_rcp_f32_e32 v119, v108
	v_mul_f32_e32 v109, 0xbfb8aa3b, v106
	v_mul_f32_e32 v108, 0xbfb8aa3b, v110
	v_exp_f32_e32 v109, v109
	v_exp_f32_e32 v108, v108
	v_exp_f32_e32 v117, v116
	v_mul_f32_e32 v116, 0xbfb8aa3b, v107
	v_pk_mul_f32 v[104:105], v[104:105], v[118:119]
	v_exp_f32_e32 v118, v116
	v_add_f32_e32 v109, 1.0, v109
	v_add_f32_e32 v108, 1.0, v108
	v_rcp_f32_e32 v116, v109
	v_add_f32_e32 v109, 1.0, v117
	v_rcp_f32_e32 v108, v108
	v_rcp_f32_e32 v109, v109
	v_add_f32_e32 v117, 1.0, v118
	v_rcp_f32_e32 v117, v117
	v_pk_mul_f32 v[104:105], v[104:105], v[96:97]
	v_pk_mul_f32 v[96:97], v[110:111], v[108:109]
	v_lshl_add_u64 v[108:109], v[114:115], 0, v[112:113]
	v_pk_mul_f32 v[102:103], v[96:97], v[102:103]
	v_pk_mul_f32 v[96:97], v[106:107], v[116:117]
	s_and_b64 vcc, exec, s[8:9]
	v_pk_mul_f32 v[106:107], v[96:97], v[98:99]
	v_cvt_pk_bf16_f32 v96, v100, v101
	v_cvt_pk_bf16_f32 v97, v102, v103
	v_cvt_pk_bf16_f32 v98, v104, v105
	v_cvt_pk_bf16_f32 v99, v106, v107
	global_store_dwordx4 v[108:109], v[96:99], off
	v_mul_f32_e32 v100, 0xbfb8aa3b, v93
	v_exp_f32_e32 v100, v100
	v_mul_f32_e32 v98, 0xbfb8aa3b, v92
	v_mul_f32_e32 v99, 0xbfb8aa3b, v88
	v_exp_f32_e32 v98, v98
	v_exp_f32_e32 v99, v99
	v_or_b32_e32 v96, 32, v152
	v_mad_i64_i32 v[96:97], s[30:31], v96, s55, v[144:145]
	v_add_f32_e32 v98, 1.0, v98
	v_add_f32_e32 v101, 1.0, v99
	v_add_f32_e32 v99, 1.0, v100
	v_rcp_f32_e32 v98, v98
	v_rcp_f32_e32 v99, v99
	v_mul_f32_e32 v100, 0xbfb8aa3b, v89
	v_exp_f32_e32 v102, v100
	v_rcp_f32_e32 v100, v101
	v_pk_mul_f32 v[92:93], v[92:93], v[98:99]
	v_mul_f32_e32 v98, 0xbfb8aa3b, v95
	v_pk_mul_f32 v[84:85], v[92:93], v[84:85]
	v_add_f32_e32 v92, 1.0, v102
	v_rcp_f32_e32 v101, v92
	v_mul_f32_e32 v93, 0xbfb8aa3b, v90
	v_mul_f32_e32 v92, 0xbfb8aa3b, v94
	v_exp_f32_e32 v93, v93
	v_exp_f32_e32 v92, v92
	v_exp_f32_e32 v99, v98
	v_mul_f32_e32 v98, 0xbfb8aa3b, v91
	v_pk_mul_f32 v[88:89], v[88:89], v[100:101]
	v_exp_f32_e32 v100, v98
	v_add_f32_e32 v93, 1.0, v93
	v_add_f32_e32 v92, 1.0, v92
	v_rcp_f32_e32 v98, v93
	v_add_f32_e32 v93, 1.0, v99
	v_rcp_f32_e32 v92, v92
	v_rcp_f32_e32 v93, v93
	v_add_f32_e32 v99, 1.0, v100
	v_rcp_f32_e32 v99, v99
	v_pk_mul_f32 v[88:89], v[88:89], v[80:81]
	v_pk_mul_f32 v[80:81], v[94:95], v[92:93]
	v_lshl_add_u64 v[92:93], v[96:97], 0, v[112:113]
	v_pk_mul_f32 v[86:87], v[80:81], v[86:87]
	v_pk_mul_f32 v[80:81], v[90:91], v[98:99]
	s_mov_b32 s56, s14
	v_pk_mul_f32 v[90:91], v[80:81], v[82:83]
	v_cvt_pk_bf16_f32 v80, v84, v85
	v_cvt_pk_bf16_f32 v81, v86, v87
	v_cvt_pk_bf16_f32 v82, v88, v89
	v_cvt_pk_bf16_f32 v83, v90, v91
	global_store_dwordx4 v[92:93], v[80:83], off
	v_mul_f32_e32 v84, 0xbfb8aa3b, v77
	v_exp_f32_e32 v84, v84
	v_mul_f32_e32 v82, 0xbfb8aa3b, v76
	v_mul_f32_e32 v83, 0xbfb8aa3b, v72
	v_exp_f32_e32 v82, v82
	v_exp_f32_e32 v83, v83
	v_or_b32_e32 v80, 48, v152
	v_mad_i64_i32 v[80:81], s[30:31], v80, s55, v[144:145]
	v_add_f32_e32 v82, 1.0, v82
	v_add_f32_e32 v85, 1.0, v83
	v_add_f32_e32 v83, 1.0, v84
	v_rcp_f32_e32 v82, v82
	v_rcp_f32_e32 v83, v83
	v_mul_f32_e32 v84, 0xbfb8aa3b, v73
	v_exp_f32_e32 v86, v84
	v_rcp_f32_e32 v84, v85
	v_pk_mul_f32 v[76:77], v[76:77], v[82:83]
	v_mul_f32_e32 v82, 0xbfb8aa3b, v79
	v_pk_mul_f32 v[68:69], v[76:77], v[68:69]
	v_add_f32_e32 v76, 1.0, v86
	v_rcp_f32_e32 v85, v76
	v_mul_f32_e32 v77, 0xbfb8aa3b, v74
	v_mul_f32_e32 v76, 0xbfb8aa3b, v78
	v_exp_f32_e32 v77, v77
	v_exp_f32_e32 v76, v76
	v_exp_f32_e32 v83, v82
	v_mul_f32_e32 v82, 0xbfb8aa3b, v75
	v_pk_mul_f32 v[72:73], v[72:73], v[84:85]
	v_exp_f32_e32 v84, v82
	v_add_f32_e32 v77, 1.0, v77
	v_add_f32_e32 v76, 1.0, v76
	v_rcp_f32_e32 v82, v77
	v_add_f32_e32 v77, 1.0, v83
	v_rcp_f32_e32 v76, v76
	v_rcp_f32_e32 v77, v77
	v_add_f32_e32 v83, 1.0, v84
	v_rcp_f32_e32 v83, v83
	v_pk_mul_f32 v[72:73], v[72:73], v[64:65]
	v_pk_mul_f32 v[64:65], v[78:79], v[76:77]
	v_lshl_add_u64 v[76:77], v[80:81], 0, v[112:113]
	v_pk_mul_f32 v[70:71], v[64:65], v[70:71]
	v_pk_mul_f32 v[64:65], v[74:75], v[82:83]
	s_mov_b32 s28, s22
	v_pk_mul_f32 v[74:75], v[64:65], v[66:67]
	v_cvt_pk_bf16_f32 v64, v68, v69
	v_cvt_pk_bf16_f32 v65, v70, v71
	v_cvt_pk_bf16_f32 v66, v72, v73
	v_cvt_pk_bf16_f32 v67, v74, v75
	global_store_dwordx4 v[76:77], v[64:67], off
	v_mul_f32_e32 v68, 0xbfb8aa3b, v61
	v_exp_f32_e32 v68, v68
	v_mul_f32_e32 v66, 0xbfb8aa3b, v60
	v_mul_f32_e32 v67, 0xbfb8aa3b, v56
	v_exp_f32_e32 v66, v66
	v_exp_f32_e32 v67, v67
	v_add_u32_e32 v64, 0x80, v152
	v_mad_i64_i32 v[64:65], s[30:31], v64, s55, v[144:145]
	v_add_f32_e32 v66, 1.0, v66
	v_add_f32_e32 v69, 1.0, v67
	v_add_f32_e32 v67, 1.0, v68
	v_rcp_f32_e32 v66, v66
	v_rcp_f32_e32 v67, v67
	v_mul_f32_e32 v68, 0xbfb8aa3b, v57
	v_exp_f32_e32 v70, v68
	v_rcp_f32_e32 v68, v69
	v_pk_mul_f32 v[60:61], v[60:61], v[66:67]
	v_mul_f32_e32 v66, 0xbfb8aa3b, v63
	v_pk_mul_f32 v[52:53], v[60:61], v[52:53]
	v_add_f32_e32 v60, 1.0, v70
	v_rcp_f32_e32 v69, v60
	v_mul_f32_e32 v61, 0xbfb8aa3b, v58
	v_mul_f32_e32 v60, 0xbfb8aa3b, v62
	v_exp_f32_e32 v61, v61
	v_exp_f32_e32 v60, v60
	v_exp_f32_e32 v67, v66
	v_mul_f32_e32 v66, 0xbfb8aa3b, v59
	v_pk_mul_f32 v[56:57], v[56:57], v[68:69]
	v_exp_f32_e32 v68, v66
	v_add_f32_e32 v61, 1.0, v61
	v_add_f32_e32 v60, 1.0, v60
	v_rcp_f32_e32 v66, v61
; __device__ __forceinline__ float fsilu(float v) { return v * fsigmoid(v); }
; __device__ __forceinline__ u32x4 pack8(const f32x4 a, const f32x4 b) { u32x4 w; w.x = cvt_pk_bf16(a[0], a[1]); w.y = cvt_pk_bf16(a[2], a[3]); w.z = cvt_pk_bf16(b[0], b[1]); w.w = cvt_pk_bf16(b[2], b[3]); return w; }
;     __device__ __forceinline__ void operator()(const f32x4 (&acc)[2][2][4][2], const Unit& u, int wr, int wc, int fr, int fq) const {
;         const int row0 = u.pm * BM + wr * 64 + fr, col0 = u.pn * 128 + wc * 32 + 8 * fq;
; #pragma unroll
;         for (int ai = 0; ai < 2; ++ai)
; #pragma unroll
;             for (int m = 0; m < 4; ++m) {
;                 bf16_t* rowp = O + (size_t)(row0 + ai * HALF + m * 16) * ldc + col0;
;                 f32x4 h0, h1;
; #pragma unroll
;                 for (int j = 0; j < 4; ++j) { h0[j] = fsilu(acc[ai][0][m][0][j]) * acc[ai][1][m][0][j]; h1[j] = fsilu(acc[ai][0][m][1][j]) * acc[ai][1][m][1][j]; }
;                 *(u32x4*)rowp = pack8(h0, h1);
	v_add_f32_e32 v61, 1.0, v67
	v_rcp_f32_e32 v60, v60
	v_rcp_f32_e32 v61, v61
	v_add_f32_e32 v67, 1.0, v68
	v_rcp_f32_e32 v67, v67
	v_pk_mul_f32 v[56:57], v[56:57], v[48:49]
	v_pk_mul_f32 v[48:49], v[62:63], v[60:61]
	v_lshl_add_u64 v[60:61], v[64:65], 0, v[112:113]
	v_pk_mul_f32 v[54:55], v[48:49], v[54:55]
	v_pk_mul_f32 v[48:49], v[58:59], v[66:67]
	s_mov_b64 s[34:35], s[26:27]
	v_pk_mul_f32 v[58:59], v[48:49], v[50:51]
	v_cvt_pk_bf16_f32 v48, v52, v53
	v_cvt_pk_bf16_f32 v49, v54, v55
	v_cvt_pk_bf16_f32 v50, v56, v57
	v_cvt_pk_bf16_f32 v51, v58, v59
	global_store_dwordx4 v[60:61], v[48:51], off
	v_mul_f32_e32 v52, 0xbfb8aa3b, v45
	v_exp_f32_e32 v52, v52
	v_mul_f32_e32 v50, 0xbfb8aa3b, v44
	v_mul_f32_e32 v51, 0xbfb8aa3b, v40
	v_exp_f32_e32 v50, v50
	v_exp_f32_e32 v51, v51
	v_add_u32_e32 v48, 0x90, v152
	v_mad_i64_i32 v[48:49], s[30:31], v48, s55, v[144:145]
	v_add_f32_e32 v50, 1.0, v50
	v_add_f32_e32 v53, 1.0, v51
	v_add_f32_e32 v51, 1.0, v52
	v_rcp_f32_e32 v50, v50
	v_rcp_f32_e32 v51, v51
	v_mul_f32_e32 v52, 0xbfb8aa3b, v41
	v_exp_f32_e32 v54, v52
	v_rcp_f32_e32 v52, v53
	v_pk_mul_f32 v[44:45], v[44:45], v[50:51]
	v_mul_f32_e32 v50, 0xbfb8aa3b, v47
	v_pk_mul_f32 v[36:37], v[44:45], v[36:37]
	v_add_f32_e32 v44, 1.0, v54
	v_rcp_f32_e32 v53, v44
	v_mul_f32_e32 v45, 0xbfb8aa3b, v42
	v_mul_f32_e32 v44, 0xbfb8aa3b, v46
	v_exp_f32_e32 v45, v45
	v_exp_f32_e32 v44, v44
	v_exp_f32_e32 v51, v50
	v_mul_f32_e32 v50, 0xbfb8aa3b, v43
	v_pk_mul_f32 v[40:41], v[40:41], v[52:53]
	v_exp_f32_e32 v52, v50
	v_add_f32_e32 v45, 1.0, v45
	v_add_f32_e32 v44, 1.0, v44
	v_rcp_f32_e32 v50, v45
	v_add_f32_e32 v45, 1.0, v51
	v_rcp_f32_e32 v44, v44
	v_rcp_f32_e32 v45, v45
	v_add_f32_e32 v51, 1.0, v52
	v_rcp_f32_e32 v51, v51
	v_pk_mul_f32 v[40:41], v[40:41], v[32:33]
	v_pk_mul_f32 v[32:33], v[46:47], v[44:45]
	v_lshl_add_u64 v[44:45], v[48:49], 0, v[112:113]
	v_pk_mul_f32 v[38:39], v[32:33], v[38:39]
	v_pk_mul_f32 v[32:33], v[42:43], v[50:51]
	s_nop 0
	v_pk_mul_f32 v[42:43], v[32:33], v[34:35]
	v_cvt_pk_bf16_f32 v32, v36, v37
	v_cvt_pk_bf16_f32 v33, v38, v39
	v_cvt_pk_bf16_f32 v34, v40, v41
	v_cvt_pk_bf16_f32 v35, v42, v43
	global_store_dwordx4 v[44:45], v[32:35], off
	v_mul_f32_e32 v36, 0xbfb8aa3b, v29
	v_exp_f32_e32 v36, v36
	v_mul_f32_e32 v34, 0xbfb8aa3b, v28
	v_mul_f32_e32 v35, 0xbfb8aa3b, v24
	v_exp_f32_e32 v34, v34
	v_exp_f32_e32 v35, v35
	v_add_u32_e32 v32, 0xa0, v152
	v_mad_i64_i32 v[32:33], s[30:31], v32, s55, v[144:145]
	v_add_f32_e32 v34, 1.0, v34
	v_add_f32_e32 v37, 1.0, v35
	v_add_f32_e32 v35, 1.0, v36
	v_rcp_f32_e32 v34, v34
	v_rcp_f32_e32 v35, v35
	v_mul_f32_e32 v36, 0xbfb8aa3b, v25
	v_exp_f32_e32 v38, v36
	v_rcp_f32_e32 v36, v37
	v_pk_mul_f32 v[28:29], v[28:29], v[34:35]
	v_mul_f32_e32 v34, 0xbfb8aa3b, v31
	v_pk_mul_f32 v[20:21], v[28:29], v[20:21]
	v_add_f32_e32 v28, 1.0, v38
	v_rcp_f32_e32 v37, v28
	v_mul_f32_e32 v29, 0xbfb8aa3b, v26
	v_mul_f32_e32 v28, 0xbfb8aa3b, v30
	v_exp_f32_e32 v29, v29
	v_exp_f32_e32 v28, v28
	v_exp_f32_e32 v35, v34
	v_mul_f32_e32 v34, 0xbfb8aa3b, v27
	v_pk_mul_f32 v[24:25], v[24:25], v[36:37]
	v_exp_f32_e32 v36, v34
	v_add_f32_e32 v29, 1.0, v29
	v_add_f32_e32 v28, 1.0, v28
	v_rcp_f32_e32 v34, v29
	v_add_f32_e32 v29, 1.0, v35
	v_rcp_f32_e32 v28, v28
	v_rcp_f32_e32 v29, v29
	v_add_f32_e32 v35, 1.0, v36
	v_rcp_f32_e32 v35, v35
	v_pk_mul_f32 v[24:25], v[24:25], v[16:17]
	v_pk_mul_f32 v[16:17], v[30:31], v[28:29]
	v_lshl_add_u64 v[28:29], v[32:33], 0, v[112:113]
	v_pk_mul_f32 v[22:23], v[16:17], v[22:23]
	v_pk_mul_f32 v[16:17], v[26:27], v[34:35]
	s_nop 0
	v_pk_mul_f32 v[26:27], v[16:17], v[18:19]
	v_cvt_pk_bf16_f32 v16, v20, v21
	v_cvt_pk_bf16_f32 v17, v22, v23
	v_cvt_pk_bf16_f32 v18, v24, v25
	v_cvt_pk_bf16_f32 v19, v26, v27
	global_store_dwordx4 v[28:29], v[16:19], off
	v_mul_f32_e32 v20, 0xbfb8aa3b, v13
	v_exp_f32_e32 v20, v20
	v_mul_f32_e32 v18, 0xbfb8aa3b, v12
	v_mul_f32_e32 v19, 0xbfb8aa3b, v8
	v_exp_f32_e32 v18, v18
	v_exp_f32_e32 v19, v19
	v_add_u32_e32 v16, 0xb0, v152
	v_mad_i64_i32 v[16:17], s[30:31], v16, s55, v[144:145]
	v_add_f32_e32 v18, 1.0, v18
	v_add_f32_e32 v21, 1.0, v19
	v_add_f32_e32 v19, 1.0, v20
	v_rcp_f32_e32 v18, v18
	v_rcp_f32_e32 v19, v19
	v_mul_f32_e32 v20, 0xbfb8aa3b, v9
	v_exp_f32_e32 v22, v20
	v_rcp_f32_e32 v20, v21
	v_pk_mul_f32 v[12:13], v[12:13], v[18:19]
	v_mul_f32_e32 v18, 0xbfb8aa3b, v15
	v_pk_mul_f32 v[4:5], v[12:13], v[4:5]
	v_add_f32_e32 v12, 1.0, v22
	v_rcp_f32_e32 v21, v12
	v_mul_f32_e32 v13, 0xbfb8aa3b, v10
	v_mul_f32_e32 v12, 0xbfb8aa3b, v14
	v_exp_f32_e32 v13, v13
	v_exp_f32_e32 v12, v12
	v_exp_f32_e32 v19, v18
	v_mul_f32_e32 v18, 0xbfb8aa3b, v11
	v_pk_mul_f32 v[8:9], v[8:9], v[20:21]
	v_exp_f32_e32 v20, v18
	v_add_f32_e32 v13, 1.0, v13
	v_add_f32_e32 v12, 1.0, v12
	v_rcp_f32_e32 v18, v13
	v_add_f32_e32 v13, 1.0, v19
	v_rcp_f32_e32 v12, v12
	v_rcp_f32_e32 v13, v13
	v_add_f32_e32 v19, 1.0, v20
	v_rcp_f32_e32 v19, v19
	v_pk_mul_f32 v[8:9], v[8:9], v[0:1]
	v_pk_mul_f32 v[0:1], v[14:15], v[12:13]
	v_lshl_add_u64 v[12:13], v[16:17], 0, v[112:113]
	v_pk_mul_f32 v[6:7], v[0:1], v[6:7]
	v_pk_mul_f32 v[0:1], v[10:11], v[18:19]
	s_mov_b64 s[30:31], s[24:25]
	v_pk_mul_f32 v[10:11], v[0:1], v[2:3]
	v_cvt_pk_bf16_f32 v0, v4, v5
	v_cvt_pk_bf16_f32 v1, v6, v7
	v_cvt_pk_bf16_f32 v2, v8, v9
	v_cvt_pk_bf16_f32 v3, v10, v11
	global_store_dwordx4 v[12:13], v[0:3], off
	s_cbranch_vccz .LBB0_942
	s_waitcnt vmcnt(0)
	s_cmpk_gt_u32 s3, 0xff
	s_cbranch_scc1 .LBB0_949
	s_barrier

; #define PG8_STAGE(bufoff, gbase, voff) do { _Pragma("unroll") for (int _i = 0; _i < 2; ++_i) \
;         __builtin_amdgcn_global_load_lds((const unsigned*)((const char*)(gbase) + (voff)[_i]), (PG8_LAS unsigned*)(lds + (bufoff) + ldsw + _i * 8192), 16, 0, 0); } while (0)
; #define PG8_LDA(dst, b, h) do { _Pragma("unroll") for (int m = 0; m < 4; ++m) _Pragma("unroll") for (int k = 0; k < 2; ++k) dst[m][k] = *(const PG8_LAS bf16x8*)(lds + PG8_SA(b, h) + aoff + m * 2048 + k * 1024); } while (0)
; #define PG8_LDB(dst, b, h) do { _Pragma("unroll") for (int n = 0; n < 2; ++n) _Pragma("unroll") for (int k = 0; k < 2; ++k) dst[n][k] = *(const PG8_LAS bf16x8*)(lds + PG8_SB(b, h) + boff + n * 2048 + k * 1024); } while (0)
; #define PG8_WAIT_V(n) asm volatile("s_waitcnt vmcnt(" #n ")" ::: "memory")
; #define PG8_WAIT_L(n) asm volatile("s_waitcnt lgkmcnt(" #n ")" ::: "memory")
; #define PG8_BAR __builtin_amdgcn_s_barrier()
; #define PG8_SCHED __builtin_amdgcn_sched_barrier(0)
; template <class Epi, class Sched, bool ALIGN_EPI = false, bool SP2 = false>
; __device__ __forceinline__ void gemm_phase(PG8_LAS unsigned char* lds, const Gemm g, const Sched& S, const Epi& E) {
;     ...
;         const bool has_next = S.next(ui + 1, nxt);
;         const char* nA = has_next ? (const char*)g.A + (size_t)nxt.pm * tstep : cA; const char* nB = has_next ? (const char*)g.Bt + (size_t)nxt.pn * tstep : cB;
;         for (int t = 0; t < nt; t += 2) {
;             const bool last = (t == nt - 2);
;             const char* a1 = cA + (size_t)(t + 1) * kstep;
;             const char* a2 = last ? nA : cA + (size_t)(t + 2) * kstep; const char* b2 = last ? nB : cB + (size_t)(t + 2) * kstep;
;             const char* a3 = a2 + kstep; const char* b3 = b2 + kstep;
;             if (last && has_next) S.a_ready(nxt);
;             if constexpr (SP2) {
;             PG8_LDB(B0, 0, 0); PG8_LDB(B1, 0, 1); PG8_SCHED; PG8_LDA(At, 0, 0); PG8_STAGE(PG8_SA(1, 1), a1 + hstep, voffA);
;             PG8_WAIT_V(8); PG8_WAIT_L(0); PG8_BAR; PG8_MMA(0, 0, At, B0); PG8_MMA(0, 1, At, B1); PG8_BAR; PG8_SCHED;
;             PG8_LDA(At, 0, 1); PG8_STAGE(PG8_SB(0, 0), b2, voffB); PG8_STAGE(PG8_SB(0, 1), b2 + hstep, voffB); PG8_STAGE(PG8_SA(0, 0), a2, voffA);
;             PG8_WAIT_V(8); PG8_WAIT_L(0); PG8_BAR; PG8_MMA(1, 0, At, B0); PG8_MMA(1, 1, At, B1); PG8_BAR; PG8_SCHED;
.LBB0_1020:
	s_add_u32 s54, s26, 0x100
	s_addc_u32 s55, s27, 0
	s_mov_b32 s56, -2
	ds_read_b128 v[144:147], v169
	ds_read_b128 v[148:151], v169 offset:1024
	ds_read_b128 v[152:155], v169 offset:2048
	ds_read_b128 v[156:159], v169 offset:3072
	ds_read_b128 v[160:163], v170
	ds_read_b128 v[172:175], v170 offset:1024
	ds_read_b128 v[176:179], v170 offset:2048
	ds_read_b128 v[180:183], v170 offset:3072
	s_add_u32 s26, s24, 0x100
	s_addc_u32 s27, s25, 0
	s_cmpk_eq_i32 s56, 0x54
	s_cselect_b32 s31, s5, s27
	s_cselect_b32 s30, s4, s26
	s_cselect_b32 s29, s7, s55
	s_cselect_b32 s28, s6, s54
	s_add_i32 m0, s38, 0xc000
	ds_read_b128 v[184:187], v171
	ds_read_b128 v[188:191], v171 offset:1024
	ds_read_b128 v[192:195], v171 offset:2048
	ds_read_b128 v[196:199], v171 offset:3072
	ds_read_b128 v[200:203], v171 offset:4096
	ds_read_b128 v[204:207], v171 offset:5120
	ds_read_b128 v[208:211], v171 offset:6144
	ds_read_b128 v[212:215], v171 offset:7168
	global_load_lds_dwordx4 v136, s[24:25]
	s_add_i32 m0, s38, 0xe000
	s_nop 0
	global_load_lds_dwordx4 v138, s[24:25]
	s_waitcnt vmcnt(8)
	s_waitcnt lgkmcnt(0)
	s_barrier
	v_mfma_f32_16x16x32_bf16 v[124:127], v[144:147], v[184:187], 0
	v_mfma_f32_16x16x32_bf16 v[120:123], v[152:155], v[184:187], 0
	v_mfma_f32_16x16x32_bf16 v[116:119], v[144:147], v[192:195], 0
	v_mfma_f32_16x16x32_bf16 v[112:115], v[152:155], v[192:195], 0
	v_mfma_f32_16x16x32_bf16 v[108:111], v[144:147], v[200:203], 0
	v_mfma_f32_16x16x32_bf16 v[96:99], v[152:155], v[200:203], 0
	v_mfma_f32_16x16x32_bf16 v[84:87], v[144:147], v[208:211], 0
	v_mfma_f32_16x16x32_bf16 v[76:79], v[152:155], v[208:211], 0
	v_mfma_f32_16x16x32_bf16 v[124:127], v[148:151], v[188:191], v[124:127]
	v_mfma_f32_16x16x32_bf16 v[120:123], v[156:159], v[188:191], v[120:123]
	v_mfma_f32_16x16x32_bf16 v[116:119], v[148:151], v[196:199], v[116:119]
	v_mfma_f32_16x16x32_bf16 v[112:115], v[156:159], v[196:199], v[112:115]
	v_mfma_f32_16x16x32_bf16 v[108:111], v[148:151], v[204:207], v[108:111]
	v_mfma_f32_16x16x32_bf16 v[96:99], v[156:159], v[204:207], v[96:99]
	v_mfma_f32_16x16x32_bf16 v[84:87], v[148:151], v[212:215], v[84:87]
	v_mfma_f32_16x16x32_bf16 v[76:79], v[156:159], v[212:215], v[76:79]
	v_mfma_f32_16x16x32_bf16 v[104:107], v[160:163], v[184:187], 0
	v_mfma_f32_16x16x32_bf16 v[100:103], v[176:179], v[184:187], 0
	v_mfma_f32_16x16x32_bf16 v[92:95], v[160:163], v[192:195], 0
	v_mfma_f32_16x16x32_bf16 v[88:91], v[176:179], v[192:195], 0
	v_mfma_f32_16x16x32_bf16 v[80:83], v[160:163], v[200:203], 0
	v_mfma_f32_16x16x32_bf16 v[72:75], v[176:179], v[200:203], 0
	v_mfma_f32_16x16x32_bf16 v[68:71], v[160:163], v[208:211], 0
	v_mfma_f32_16x16x32_bf16 v[64:67], v[176:179], v[208:211], 0
	v_mfma_f32_16x16x32_bf16 v[104:107], v[172:175], v[188:191], v[104:107]
	v_mfma_f32_16x16x32_bf16 v[100:103], v[180:183], v[188:191], v[100:103]
	v_mfma_f32_16x16x32_bf16 v[92:95], v[172:175], v[196:199], v[92:95]
	v_mfma_f32_16x16x32_bf16 v[88:91], v[180:183], v[196:199], v[88:91]
	v_mfma_f32_16x16x32_bf16 v[80:83], v[172:175], v[204:207], v[80:83]
	v_mfma_f32_16x16x32_bf16 v[72:75], v[180:183], v[204:207], v[72:75]
	v_mfma_f32_16x16x32_bf16 v[68:71], v[172:175], v[212:215], v[68:71]
	v_mfma_f32_16x16x32_bf16 v[64:67], v[180:183], v[212:215], v[64:67]
	s_barrier
	s_add_i32 s24, s48, s37
	s_mov_b32 m0, s24
	ds_read_b128 v[184:187], v171 offset:16384
	ds_read_b128 v[188:191], v171 offset:17408
	ds_read_b128 v[192:195], v171 offset:18432
	ds_read_b128 v[196:199], v171 offset:19456
	ds_read_b128 v[200:203], v171 offset:20480
	ds_read_b128 v[204:207], v171 offset:21504
	ds_read_b128 v[208:211], v171 offset:22528
	ds_read_b128 v[212:215], v171 offset:23552
	global_load_lds_dwordx4 v130, s[28:29]
	s_add_i32 m0, s24, 0x2000
	s_add_u32 s24, s28, 0x160000
	s_addc_u32 s25, s29, 0
	s_add_i32 s57, s49, s37
	global_load_lds_dwordx4 v134, s[28:29]
	s_mov_b32 m0, s57
	s_nop 0
	global_load_lds_dwordx4 v130, s[24:25]
	s_add_i32 m0, s57, 0x2000
	s_nop 0
	global_load_lds_dwordx4 v134, s[24:25]
	s_mov_b32 m0, s38
	s_nop 0
	global_load_lds_dwordx4 v128, s[30:31]
	s_mov_b32 m0, s39
	s_nop 0
	global_load_lds_dwordx4 v132, s[30:31]
	s_waitcnt vmcnt(8)
	s_waitcnt lgkmcnt(0)
	s_barrier
	v_mfma_f32_16x16x32_bf16 v[60:63], v[144:147], v[184:187], 0
	v_mfma_f32_16x16x32_bf16 v[56:59], v[152:155], v[184:187], 0
	v_mfma_f32_16x16x32_bf16 v[52:55], v[144:147], v[192:195], 0
	v_mfma_f32_16x16x32_bf16 v[48:51], v[152:155], v[192:195], 0
	v_mfma_f32_16x16x32_bf16 v[44:47], v[144:147], v[200:203], 0
	v_mfma_f32_16x16x32_bf16 v[32:35], v[152:155], v[200:203], 0
	v_mfma_f32_16x16x32_bf16 v[20:23], v[144:147], v[208:211], 0
	v_mfma_f32_16x16x32_bf16 v[12:15], v[152:155], v[208:211], 0
	v_mfma_f32_16x16x32_bf16 v[60:63], v[148:151], v[188:191], v[60:63]
	v_mfma_f32_16x16x32_bf16 v[56:59], v[156:159], v[188:191], v[56:59]
	v_mfma_f32_16x16x32_bf16 v[52:55], v[148:151], v[196:199], v[52:55]
	v_mfma_f32_16x16x32_bf16 v[48:51], v[156:159], v[196:199], v[48:51]
	v_mfma_f32_16x16x32_bf16 v[44:47], v[148:151], v[204:207], v[44:47]
	v_mfma_f32_16x16x32_bf16 v[32:35], v[156:159], v[204:207], v[32:35]
	v_mfma_f32_16x16x32_bf16 v[20:23], v[148:151], v[212:215], v[20:23]
	v_mfma_f32_16x16x32_bf16 v[12:15], v[156:159], v[212:215], v[12:15]
	v_mfma_f32_16x16x32_bf16 v[40:43], v[160:163], v[184:187], 0
	v_mfma_f32_16x16x32_bf16 v[36:39], v[176:179], v[184:187], 0
	v_mfma_f32_16x16x32_bf16 v[28:31], v[160:163], v[192:195], 0
	v_mfma_f32_16x16x32_bf16 v[24:27], v[176:179], v[192:195], 0
	v_mfma_f32_16x16x32_bf16 v[16:19], v[160:163], v[200:203], 0
	v_mfma_f32_16x16x32_bf16 v[8:11], v[176:179], v[200:203], 0
	v_mfma_f32_16x16x32_bf16 v[4:7], v[160:163], v[208:211], 0
	v_mfma_f32_16x16x32_bf16 v[0:3], v[176:179], v[208:211], 0
	v_mfma_f32_16x16x32_bf16 v[40:43], v[172:175], v[188:191], v[40:43]
	v_mfma_f32_16x16x32_bf16 v[36:39], v[180:183], v[188:191], v[36:39]
	v_mfma_f32_16x16x32_bf16 v[28:31], v[172:175], v[196:199], v[28:31]
	v_mfma_f32_16x16x32_bf16 v[24:27], v[180:183], v[196:199], v[24:27]
	v_mfma_f32_16x16x32_bf16 v[16:19], v[172:175], v[204:207], v[16:19]
	v_mfma_f32_16x16x32_bf16 v[8:11], v[180:183], v[204:207], v[8:11]
	v_mfma_f32_16x16x32_bf16 v[4:7], v[172:175], v[212:215], v[4:7]
	v_mfma_f32_16x16x32_bf16 v[0:3], v[180:183], v[212:215], v[0:3]
	s_barrier
; #define PG8_STAGE(bufoff, gbase, voff) do { _Pragma("unroll") for (int _i = 0; _i < 2; ++_i) \
;         __builtin_amdgcn_global_load_lds((const unsigned*)((const char*)(gbase) + (voff)[_i]), (PG8_LAS unsigned*)(lds + (bufoff) + ldsw + _i * 8192), 16, 0, 0); } while (0)
; #define PG8_LDA(dst, b, h) do { _Pragma("unroll") for (int m = 0; m < 4; ++m) _Pragma("unroll") for (int k = 0; k < 2; ++k) dst[m][k] = *(const PG8_LAS bf16x8*)(lds + PG8_SA(b, h) + aoff + m * 2048 + k * 1024); } while (0)
; #define PG8_LDB(dst, b, h) do { _Pragma("unroll") for (int n = 0; n < 2; ++n) _Pragma("unroll") for (int k = 0; k < 2; ++k) dst[n][k] = *(const PG8_LAS bf16x8*)(lds + PG8_SB(b, h) + boff + n * 2048 + k * 1024); } while (0)
; #define PG8_MMA(ai, bj, At, Bt) do { __builtin_amdgcn_s_setprio(1); _Pragma("unroll") for (int m = 0; m < 4; ++m) _Pragma("unroll") for (int n = 0; n < 2; ++n) _Pragma("unroll") for (int k = 0; k < 2; ++k) \
;         acc[ai][bj][m][n] = __builtin_amdgcn_mfma_f32_16x16x32_bf16(Bt[n][k], At[m][k], acc[ai][bj][m][n], 0, 0, 0); __builtin_amdgcn_s_setprio(0); } while (0)
; #define PG8_WAIT_V(n) asm volatile("s_waitcnt vmcnt(" #n ")" ::: "memory")
; #define PG8_WAIT_L(n) asm volatile("s_waitcnt lgkmcnt(" #n ")" ::: "memory")
; #define PG8_BAR __builtin_amdgcn_s_barrier()
; #define PG8_SCHED __builtin_amdgcn_sched_barrier(0)
; template <class Epi, class Sched, bool ALIGN_EPI = false, bool SP2 = false>
; __device__ __forceinline__ void gemm_phase(PG8_LAS unsigned char* lds, const Gemm g, const Sched& S, const Epi& E) {
;     ...
;         for (int t = 0; t < nt; t += 2) {
;     ...
;             PG8_LDB(B0, 1, 0); PG8_LDB(B1, 1, 1); PG8_SCHED; PG8_LDA(At, 1, 0); PG8_STAGE(PG8_SA(0, 1), a2 + hstep, voffA);
;             PG8_WAIT_V(8); PG8_WAIT_L(0); PG8_BAR; PG8_MMA(0, 0, At, B0); PG8_MMA(0, 1, At, B1); PG8_BAR; PG8_SCHED;
;             PG8_LDA(At, 1, 1); PG8_STAGE(PG8_SB(1, 0), b3, voffB); PG8_STAGE(PG8_SB(1, 1), b3 + hstep, voffB); PG8_STAGE(PG8_SA(1, 0), a3, voffA);
;             PG8_WAIT_V(8); PG8_WAIT_L(0); PG8_BAR; PG8_MMA(1, 0, At, B0); PG8_MMA(1, 1, At, B1); PG8_BAR; PG8_SCHED;
	s_add_i32 s57, 0, 0x18000
	s_add_i32 s58, 0, 0x1c000
	v_add_u32_e32 v156, s57, v167
	v_add_u32_e32 v180, s58, v167
	ds_read_b128 v[144:147], v156
	ds_read_b128 v[148:151], v156 offset:1024
	ds_read_b128 v[152:155], v156 offset:2048
	ds_read_b128 v[156:159], v156 offset:3072
	ds_read_b128 v[160:163], v180
	ds_read_b128 v[172:175], v180 offset:1024
	ds_read_b128 v[176:179], v180 offset:2048
	ds_read_b128 v[180:183], v180 offset:3072
	s_add_u32 s24, s30, 0x160000
	s_addc_u32 s25, s31, 0
	s_mov_b32 m0, s40
	ds_read_b128 v[184:187], v171 offset:32768
	ds_read_b128 v[188:191], v171 offset:33792
	ds_read_b128 v[192:195], v171 offset:34816
	ds_read_b128 v[196:199], v171 offset:35840
	ds_read_b128 v[200:203], v171 offset:36864
	ds_read_b128 v[204:207], v171 offset:37888
	ds_read_b128 v[208:211], v171 offset:38912
	ds_read_b128 v[212:215], v171 offset:39936
	global_load_lds_dwordx4 v128, s[24:25]
	s_mov_b32 m0, s41
	s_nop 0
	global_load_lds_dwordx4 v132, s[24:25]
	s_waitcnt vmcnt(8)
	s_waitcnt lgkmcnt(0)
	s_barrier
	v_mfma_f32_16x16x32_bf16 v[124:127], v[144:147], v[184:187], v[124:127]
	v_mfma_f32_16x16x32_bf16 v[120:123], v[152:155], v[184:187], v[120:123]
	v_mfma_f32_16x16x32_bf16 v[116:119], v[144:147], v[192:195], v[116:119]
	v_mfma_f32_16x16x32_bf16 v[112:115], v[152:155], v[192:195], v[112:115]
	v_mfma_f32_16x16x32_bf16 v[108:111], v[144:147], v[200:203], v[108:111]
	v_mfma_f32_16x16x32_bf16 v[96:99], v[152:155], v[200:203], v[96:99]
	v_mfma_f32_16x16x32_bf16 v[84:87], v[144:147], v[208:211], v[84:87]
	v_mfma_f32_16x16x32_bf16 v[76:79], v[152:155], v[208:211], v[76:79]
	v_mfma_f32_16x16x32_bf16 v[124:127], v[148:151], v[188:191], v[124:127]
	v_mfma_f32_16x16x32_bf16 v[120:123], v[156:159], v[188:191], v[120:123]
	v_mfma_f32_16x16x32_bf16 v[116:119], v[148:151], v[196:199], v[116:119]
	v_mfma_f32_16x16x32_bf16 v[112:115], v[156:159], v[196:199], v[112:115]
	v_mfma_f32_16x16x32_bf16 v[108:111], v[148:151], v[204:207], v[108:111]
	v_mfma_f32_16x16x32_bf16 v[96:99], v[156:159], v[204:207], v[96:99]
	v_mfma_f32_16x16x32_bf16 v[84:87], v[148:151], v[212:215], v[84:87]
	v_mfma_f32_16x16x32_bf16 v[76:79], v[156:159], v[212:215], v[76:79]
	v_mfma_f32_16x16x32_bf16 v[104:107], v[160:163], v[184:187], v[104:107]
	v_mfma_f32_16x16x32_bf16 v[100:103], v[176:179], v[184:187], v[100:103]
	v_mfma_f32_16x16x32_bf16 v[92:95], v[160:163], v[192:195], v[92:95]
	v_mfma_f32_16x16x32_bf16 v[88:91], v[176:179], v[192:195], v[88:91]
	v_mfma_f32_16x16x32_bf16 v[80:83], v[160:163], v[200:203], v[80:83]
	v_mfma_f32_16x16x32_bf16 v[72:75], v[176:179], v[200:203], v[72:75]
	v_mfma_f32_16x16x32_bf16 v[68:71], v[160:163], v[208:211], v[68:71]
	v_mfma_f32_16x16x32_bf16 v[64:67], v[176:179], v[208:211], v[64:67]
	v_mfma_f32_16x16x32_bf16 v[104:107], v[172:175], v[188:191], v[104:107]
	v_mfma_f32_16x16x32_bf16 v[100:103], v[180:183], v[188:191], v[100:103]
	v_mfma_f32_16x16x32_bf16 v[92:95], v[172:175], v[196:199], v[92:95]
	v_mfma_f32_16x16x32_bf16 v[88:91], v[180:183], v[196:199], v[88:91]
	v_mfma_f32_16x16x32_bf16 v[80:83], v[172:175], v[204:207], v[80:83]
	v_mfma_f32_16x16x32_bf16 v[72:75], v[180:183], v[204:207], v[72:75]
	v_mfma_f32_16x16x32_bf16 v[68:71], v[172:175], v[212:215], v[68:71]
	v_mfma_f32_16x16x32_bf16 v[64:67], v[180:183], v[212:215], v[64:67]
	s_barrier
	s_add_i32 s24, s57, s37
	s_add_u32 s86, s28, 0x80
	s_addc_u32 s87, s29, 0
	s_mov_b32 m0, s24
	ds_read_b128 v[184:187], v171 offset:49152
	ds_read_b128 v[188:191], v171 offset:50176
	ds_read_b128 v[192:195], v171 offset:51200
	ds_read_b128 v[196:199], v171 offset:52224
	ds_read_b128 v[200:203], v171 offset:53248
	ds_read_b128 v[204:207], v171 offset:54272
	ds_read_b128 v[208:211], v171 offset:55296
	ds_read_b128 v[212:215], v171 offset:56320
	global_load_lds_dwordx4 v130, s[86:87]
	s_add_i32 m0, s24, 0x2000
	s_add_u32 s24, s28, 0x160080
	s_addc_u32 s25, s29, 0
	s_add_i32 s28, s58, s37
	global_load_lds_dwordx4 v134, s[86:87]
	s_mov_b32 m0, s28
	s_nop 0
	global_load_lds_dwordx4 v130, s[24:25]
	s_add_i32 m0, s28, 0x2000
	s_nop 0
	global_load_lds_dwordx4 v134, s[24:25]
	s_add_u32 s84, s30, 0x80
	s_addc_u32 s85, s31, 0
	s_mov_b32 m0, s45
	s_nop 0
	global_load_lds_dwordx4 v128, s[84:85]
	s_mov_b32 m0, s46
	s_nop 0
	global_load_lds_dwordx4 v132, s[84:85]
	s_waitcnt vmcnt(8)
	s_waitcnt lgkmcnt(0)
	s_barrier
	v_mfma_f32_16x16x32_bf16 v[60:63], v[144:147], v[184:187], v[60:63]
	v_mfma_f32_16x16x32_bf16 v[56:59], v[152:155], v[184:187], v[56:59]
	v_mfma_f32_16x16x32_bf16 v[52:55], v[144:147], v[192:195], v[52:55]
	v_mfma_f32_16x16x32_bf16 v[48:51], v[152:155], v[192:195], v[48:51]
	v_mfma_f32_16x16x32_bf16 v[44:47], v[144:147], v[200:203], v[44:47]
	v_mfma_f32_16x16x32_bf16 v[32:35], v[152:155], v[200:203], v[32:35]
	v_mfma_f32_16x16x32_bf16 v[20:23], v[144:147], v[208:211], v[20:23]
	v_mfma_f32_16x16x32_bf16 v[12:15], v[152:155], v[208:211], v[12:15]
	v_mfma_f32_16x16x32_bf16 v[60:63], v[148:151], v[188:191], v[60:63]
	v_mfma_f32_16x16x32_bf16 v[56:59], v[156:159], v[188:191], v[56:59]
	v_mfma_f32_16x16x32_bf16 v[52:55], v[148:151], v[196:199], v[52:55]
	v_mfma_f32_16x16x32_bf16 v[48:51], v[156:159], v[196:199], v[48:51]
	v_mfma_f32_16x16x32_bf16 v[44:47], v[148:151], v[204:207], v[44:47]
	v_mfma_f32_16x16x32_bf16 v[32:35], v[156:159], v[204:207], v[32:35]
	v_mfma_f32_16x16x32_bf16 v[20:23], v[148:151], v[212:215], v[20:23]
	v_mfma_f32_16x16x32_bf16 v[12:15], v[156:159], v[212:215], v[12:15]
	v_mfma_f32_16x16x32_bf16 v[40:43], v[160:163], v[184:187], v[40:43]
	v_mfma_f32_16x16x32_bf16 v[36:39], v[176:179], v[184:187], v[36:39]
	v_mfma_f32_16x16x32_bf16 v[28:31], v[160:163], v[192:195], v[28:31]
	v_mfma_f32_16x16x32_bf16 v[24:27], v[176:179], v[192:195], v[24:27]
	v_mfma_f32_16x16x32_bf16 v[16:19], v[160:163], v[200:203], v[16:19]
	v_mfma_f32_16x16x32_bf16 v[8:11], v[176:179], v[200:203], v[8:11]
	v_mfma_f32_16x16x32_bf16 v[4:7], v[160:163], v[208:211], v[4:7]
	v_mfma_f32_16x16x32_bf16 v[0:3], v[176:179], v[208:211], v[0:3]
	v_mfma_f32_16x16x32_bf16 v[40:43], v[172:175], v[188:191], v[40:43]
	v_mfma_f32_16x16x32_bf16 v[36:39], v[180:183], v[188:191], v[36:39]
	v_mfma_f32_16x16x32_bf16 v[28:31], v[172:175], v[196:199], v[28:31]
	v_mfma_f32_16x16x32_bf16 v[24:27], v[180:183], v[196:199], v[24:27]
	v_mfma_f32_16x16x32_bf16 v[16:19], v[172:175], v[204:207], v[16:19]
	v_mfma_f32_16x16x32_bf16 v[8:11], v[180:183], v[204:207], v[8:11]
	v_mfma_f32_16x16x32_bf16 v[4:7], v[172:175], v[212:215], v[4:7]
	v_mfma_f32_16x16x32_bf16 v[0:3], v[180:183], v[212:215], v[0:3]
	s_barrier
	s_add_i32 s56, s56, 2
	s_add_u32 s54, s54, 0x100
	s_addc_u32 s55, s55, 0
	s_cmpk_gt_u32 s56, 0x55
	s_mov_b64 s[24:25], s[26:27]
; #define PG8_STAGE(bufoff, gbase, voff) do { _Pragma("unroll") for (int _i = 0; _i < 2; ++_i) \
;         __builtin_amdgcn_global_load_lds((const unsigned*)((const char*)(gbase) + (voff)[_i]), (PG8_LAS unsigned*)(lds + (bufoff) + ldsw + _i * 8192), 16, 0, 0); } while (0)
; #define PG8_LDA(dst, b, h) do { _Pragma("unroll") for (int m = 0; m < 4; ++m) _Pragma("unroll") for (int k = 0; k < 2; ++k) dst[m][k] = *(const PG8_LAS bf16x8*)(lds + PG8_SA(b, h) + aoff + m * 2048 + k * 1024); } while (0)
; #define PG8_LDB(dst, b, h) do { _Pragma("unroll") for (int n = 0; n < 2; ++n) _Pragma("unroll") for (int k = 0; k < 2; ++k) dst[n][k] = *(const PG8_LAS bf16x8*)(lds + PG8_SB(b, h) + boff + n * 2048 + k * 1024); } while (0)
; #define PG8_MMA(ai, bj, At, Bt) do { __builtin_amdgcn_s_setprio(1); _Pragma("unroll") for (int m = 0; m < 4; ++m) _Pragma("unroll") for (int n = 0; n < 2; ++n) _Pragma("unroll") for (int k = 0; k < 2; ++k) \
;         acc[ai][bj][m][n] = __builtin_amdgcn_mfma_f32_16x16x32_bf16(Bt[n][k], At[m][k], acc[ai][bj][m][n], 0, 0, 0); __builtin_amdgcn_s_setprio(0); } while (0)
; #define PG8_WAIT_V(n) asm volatile("s_waitcnt vmcnt(" #n ")" ::: "memory")
; #define PG8_WAIT_L(n) asm volatile("s_waitcnt lgkmcnt(" #n ")" ::: "memory")
; #define PG8_BAR __builtin_amdgcn_s_barrier()
; #define PG8_SCHED __builtin_amdgcn_sched_barrier(0)
; template <class Epi, class Sched, bool ALIGN_EPI = false, bool SP2 = false>
; __device__ __forceinline__ void gemm_phase(PG8_LAS unsigned char* lds, const Gemm g, const Sched& S, const Epi& E) {
;     ...
;             PG8_LDB(B0, 0, 0); PG8_LDB(B1, 0, 1); PG8_SCHED; PG8_LDA(At, 0, 0); PG8_STAGE(PG8_SA(1, 1), a1 + hstep, voffA);
;             PG8_WAIT_V(8); PG8_WAIT_L(0); PG8_BAR; PG8_MMA(0, 0, At, B0); PG8_MMA(0, 1, At, B1); PG8_BAR; PG8_SCHED;
;             PG8_LDA(At, 0, 1); PG8_STAGE(PG8_SB(0, 0), b2, voffB); PG8_STAGE(PG8_SB(0, 1), b2 + hstep, voffB); PG8_STAGE(PG8_SA(0, 0), a2, voffA);
;             PG8_WAIT_V(8); PG8_WAIT_L(0); PG8_BAR; PG8_MMA(1, 0, At, B0); PG8_MMA(1, 1, At, B1); PG8_BAR; PG8_SCHED;
.LBB0_1021:
	ds_read_b128 v[144:147], v169
	ds_read_b128 v[148:151], v169 offset:1024
	ds_read_b128 v[152:155], v169 offset:2048
	ds_read_b128 v[156:159], v169 offset:3072
	ds_read_b128 v[160:163], v170
	ds_read_b128 v[172:175], v170 offset:1024
	ds_read_b128 v[176:179], v170 offset:2048
	ds_read_b128 v[180:183], v170 offset:3072
	s_add_u32 s26, s24, 0x100
	s_addc_u32 s27, s25, 0
	s_cmpk_eq_i32 s56, 0x54
	s_cselect_b32 s31, s5, s27
	s_cselect_b32 s30, s4, s26
	s_cselect_b32 s29, s7, s55
	s_cselect_b32 s28, s6, s54
	s_add_i32 m0, s38, 0xc000
	ds_read_b128 v[184:187], v171
	ds_read_b128 v[188:191], v171 offset:1024
	ds_read_b128 v[192:195], v171 offset:2048
	ds_read_b128 v[196:199], v171 offset:3072
	ds_read_b128 v[200:203], v171 offset:4096
	ds_read_b128 v[204:207], v171 offset:5120
	ds_read_b128 v[208:211], v171 offset:6144
	ds_read_b128 v[212:215], v171 offset:7168
	global_load_lds_dwordx4 v136, s[24:25]
	s_add_i32 m0, s38, 0xe000
	s_nop 0
	global_load_lds_dwordx4 v138, s[24:25]
	s_waitcnt vmcnt(8)
	s_waitcnt lgkmcnt(0)
	s_barrier
	v_mfma_f32_16x16x32_bf16 v[124:127], v[144:147], v[184:187], v[124:127]
	v_mfma_f32_16x16x32_bf16 v[120:123], v[152:155], v[184:187], v[120:123]
	v_mfma_f32_16x16x32_bf16 v[116:119], v[144:147], v[192:195], v[116:119]
	v_mfma_f32_16x16x32_bf16 v[112:115], v[152:155], v[192:195], v[112:115]
	v_mfma_f32_16x16x32_bf16 v[108:111], v[144:147], v[200:203], v[108:111]
	v_mfma_f32_16x16x32_bf16 v[96:99], v[152:155], v[200:203], v[96:99]
	v_mfma_f32_16x16x32_bf16 v[84:87], v[144:147], v[208:211], v[84:87]
	v_mfma_f32_16x16x32_bf16 v[76:79], v[152:155], v[208:211], v[76:79]
	v_mfma_f32_16x16x32_bf16 v[124:127], v[148:151], v[188:191], v[124:127]
	v_mfma_f32_16x16x32_bf16 v[120:123], v[156:159], v[188:191], v[120:123]
	v_mfma_f32_16x16x32_bf16 v[116:119], v[148:151], v[196:199], v[116:119]
	v_mfma_f32_16x16x32_bf16 v[112:115], v[156:159], v[196:199], v[112:115]
	v_mfma_f32_16x16x32_bf16 v[108:111], v[148:151], v[204:207], v[108:111]
	v_mfma_f32_16x16x32_bf16 v[96:99], v[156:159], v[204:207], v[96:99]
	v_mfma_f32_16x16x32_bf16 v[84:87], v[148:151], v[212:215], v[84:87]
	v_mfma_f32_16x16x32_bf16 v[76:79], v[156:159], v[212:215], v[76:79]
	v_mfma_f32_16x16x32_bf16 v[104:107], v[160:163], v[184:187], v[104:107]
	v_mfma_f32_16x16x32_bf16 v[100:103], v[176:179], v[184:187], v[100:103]
	v_mfma_f32_16x16x32_bf16 v[92:95], v[160:163], v[192:195], v[92:95]
	v_mfma_f32_16x16x32_bf16 v[88:91], v[176:179], v[192:195], v[88:91]
	v_mfma_f32_16x16x32_bf16 v[80:83], v[160:163], v[200:203], v[80:83]
	v_mfma_f32_16x16x32_bf16 v[72:75], v[176:179], v[200:203], v[72:75]
	v_mfma_f32_16x16x32_bf16 v[68:71], v[160:163], v[208:211], v[68:71]
	v_mfma_f32_16x16x32_bf16 v[64:67], v[176:179], v[208:211], v[64:67]
	v_mfma_f32_16x16x32_bf16 v[104:107], v[172:175], v[188:191], v[104:107]
	v_mfma_f32_16x16x32_bf16 v[100:103], v[180:183], v[188:191], v[100:103]
	v_mfma_f32_16x16x32_bf16 v[92:95], v[172:175], v[196:199], v[92:95]
	v_mfma_f32_16x16x32_bf16 v[88:91], v[180:183], v[196:199], v[88:91]
	v_mfma_f32_16x16x32_bf16 v[80:83], v[172:175], v[204:207], v[80:83]
	v_mfma_f32_16x16x32_bf16 v[72:75], v[180:183], v[204:207], v[72:75]
	v_mfma_f32_16x16x32_bf16 v[68:71], v[172:175], v[212:215], v[68:71]
	v_mfma_f32_16x16x32_bf16 v[64:67], v[180:183], v[212:215], v[64:67]
	s_barrier
	s_add_i32 s24, s48, s37
	s_mov_b32 m0, s24
	ds_read_b128 v[184:187], v171 offset:16384
	ds_read_b128 v[188:191], v171 offset:17408
	ds_read_b128 v[192:195], v171 offset:18432
	ds_read_b128 v[196:199], v171 offset:19456
	ds_read_b128 v[200:203], v171 offset:20480
	ds_read_b128 v[204:207], v171 offset:21504
	ds_read_b128 v[208:211], v171 offset:22528
	ds_read_b128 v[212:215], v171 offset:23552
	global_load_lds_dwordx4 v130, s[28:29]
	s_add_i32 m0, s24, 0x2000
	s_add_u32 s24, s28, 0x160000
	s_addc_u32 s25, s29, 0
	s_add_i32 s57, s49, s37
	global_load_lds_dwordx4 v134, s[28:29]
	s_mov_b32 m0, s57
	s_nop 0
	global_load_lds_dwordx4 v130, s[24:25]
	s_add_i32 m0, s57, 0x2000
	s_nop 0
	global_load_lds_dwordx4 v134, s[24:25]
	s_mov_b32 m0, s38
	s_nop 0
	global_load_lds_dwordx4 v128, s[30:31]
	s_mov_b32 m0, s39
	s_nop 0
	global_load_lds_dwordx4 v132, s[30:31]
	s_waitcnt vmcnt(8)
	s_waitcnt lgkmcnt(0)
	s_barrier
	v_mfma_f32_16x16x32_bf16 v[60:63], v[144:147], v[184:187], v[60:63]
	v_mfma_f32_16x16x32_bf16 v[56:59], v[152:155], v[184:187], v[56:59]
	v_mfma_f32_16x16x32_bf16 v[52:55], v[144:147], v[192:195], v[52:55]
	v_mfma_f32_16x16x32_bf16 v[48:51], v[152:155], v[192:195], v[48:51]
	v_mfma_f32_16x16x32_bf16 v[44:47], v[144:147], v[200:203], v[44:47]
	v_mfma_f32_16x16x32_bf16 v[32:35], v[152:155], v[200:203], v[32:35]
	v_mfma_f32_16x16x32_bf16 v[20:23], v[144:147], v[208:211], v[20:23]
	v_mfma_f32_16x16x32_bf16 v[12:15], v[152:155], v[208:211], v[12:15]
	v_mfma_f32_16x16x32_bf16 v[60:63], v[148:151], v[188:191], v[60:63]
	v_mfma_f32_16x16x32_bf16 v[56:59], v[156:159], v[188:191], v[56:59]
	v_mfma_f32_16x16x32_bf16 v[52:55], v[148:151], v[196:199], v[52:55]
	v_mfma_f32_16x16x32_bf16 v[48:51], v[156:159], v[196:199], v[48:51]
	v_mfma_f32_16x16x32_bf16 v[44:47], v[148:151], v[204:207], v[44:47]
	v_mfma_f32_16x16x32_bf16 v[32:35], v[156:159], v[204:207], v[32:35]
	v_mfma_f32_16x16x32_bf16 v[20:23], v[148:151], v[212:215], v[20:23]
	v_mfma_f32_16x16x32_bf16 v[12:15], v[156:159], v[212:215], v[12:15]
	v_mfma_f32_16x16x32_bf16 v[40:43], v[160:163], v[184:187], v[40:43]
	v_mfma_f32_16x16x32_bf16 v[36:39], v[176:179], v[184:187], v[36:39]
	v_mfma_f32_16x16x32_bf16 v[28:31], v[160:163], v[192:195], v[28:31]
	v_mfma_f32_16x16x32_bf16 v[24:27], v[176:179], v[192:195], v[24:27]
	v_mfma_f32_16x16x32_bf16 v[16:19], v[160:163], v[200:203], v[16:19]
	v_mfma_f32_16x16x32_bf16 v[8:11], v[176:179], v[200:203], v[8:11]
	v_mfma_f32_16x16x32_bf16 v[4:7], v[160:163], v[208:211], v[4:7]
	v_mfma_f32_16x16x32_bf16 v[0:3], v[176:179], v[208:211], v[0:3]
	v_mfma_f32_16x16x32_bf16 v[40:43], v[172:175], v[188:191], v[40:43]
	v_mfma_f32_16x16x32_bf16 v[36:39], v[180:183], v[188:191], v[36:39]
	v_mfma_f32_16x16x32_bf16 v[28:31], v[172:175], v[196:199], v[28:31]
	v_mfma_f32_16x16x32_bf16 v[24:27], v[180:183], v[196:199], v[24:27]
	v_mfma_f32_16x16x32_bf16 v[16:19], v[172:175], v[204:207], v[16:19]
	v_mfma_f32_16x16x32_bf16 v[8:11], v[180:183], v[204:207], v[8:11]
	v_mfma_f32_16x16x32_bf16 v[4:7], v[172:175], v[212:215], v[4:7]
	v_mfma_f32_16x16x32_bf16 v[0:3], v[180:183], v[212:215], v[0:3]
	s_barrier
; #define PG8_STAGE(bufoff, gbase, voff) do { _Pragma("unroll") for (int _i = 0; _i < 2; ++_i) \
;         __builtin_amdgcn_global_load_lds((const unsigned*)((const char*)(gbase) + (voff)[_i]), (PG8_LAS unsigned*)(lds + (bufoff) + ldsw + _i * 8192), 16, 0, 0); } while (0)
; #define PG8_LDA(dst, b, h) do { _Pragma("unroll") for (int m = 0; m < 4; ++m) _Pragma("unroll") for (int k = 0; k < 2; ++k) dst[m][k] = *(const PG8_LAS bf16x8*)(lds + PG8_SA(b, h) + aoff + m * 2048 + k * 1024); } while (0)
; #define PG8_LDB(dst, b, h) do { _Pragma("unroll") for (int n = 0; n < 2; ++n) _Pragma("unroll") for (int k = 0; k < 2; ++k) dst[n][k] = *(const PG8_LAS bf16x8*)(lds + PG8_SB(b, h) + boff + n * 2048 + k * 1024); } while (0)
; #define PG8_MMA(ai, bj, At, Bt) do { __builtin_amdgcn_s_setprio(1); _Pragma("unroll") for (int m = 0; m < 4; ++m) _Pragma("unroll") for (int n = 0; n < 2; ++n) _Pragma("unroll") for (int k = 0; k < 2; ++k) \
;         acc[ai][bj][m][n] = __builtin_amdgcn_mfma_f32_16x16x32_bf16(Bt[n][k], At[m][k], acc[ai][bj][m][n], 0, 0, 0); __builtin_amdgcn_s_setprio(0); } while (0)
; #define PG8_WAIT_V(n) asm volatile("s_waitcnt vmcnt(" #n ")" ::: "memory")
; #define PG8_WAIT_L(n) asm volatile("s_waitcnt lgkmcnt(" #n ")" ::: "memory")
; #define PG8_BAR __builtin_amdgcn_s_barrier()
; #define PG8_SCHED __builtin_amdgcn_sched_barrier(0)
; template <class Epi, class Sched, bool ALIGN_EPI = false, bool SP2 = false>
; __device__ __forceinline__ void gemm_phase(PG8_LAS unsigned char* lds, const Gemm g, const Sched& S, const Epi& E) {
;     ...
;             PG8_LDB(B0, 1, 0); PG8_LDB(B1, 1, 1); PG8_SCHED; PG8_LDA(At, 1, 0); PG8_STAGE(PG8_SA(0, 1), a2 + hstep, voffA);
;             PG8_WAIT_V(8); PG8_WAIT_L(0); PG8_BAR; PG8_MMA(0, 0, At, B0); PG8_MMA(0, 1, At, B1); PG8_BAR; PG8_SCHED;
;             PG8_LDA(At, 1, 1); PG8_STAGE(PG8_SB(1, 0), b3, voffB); PG8_STAGE(PG8_SB(1, 1), b3 + hstep, voffB); PG8_STAGE(PG8_SA(1, 0), a3, voffA);
;             PG8_WAIT_V(8); PG8_WAIT_L(0); PG8_BAR; PG8_MMA(1, 0, At, B0); PG8_MMA(1, 1, At, B1); PG8_BAR; PG8_SCHED;
	s_add_i32 s57, 0, 0x18000
	s_add_i32 s58, 0, 0x1c000
	v_add_u32_e32 v156, s57, v167
	v_add_u32_e32 v180, s58, v167
	ds_read_b128 v[144:147], v156
	ds_read_b128 v[148:151], v156 offset:1024
	ds_read_b128 v[152:155], v156 offset:2048
	ds_read_b128 v[156:159], v156 offset:3072
	ds_read_b128 v[160:163], v180
	ds_read_b128 v[172:175], v180 offset:1024
	ds_read_b128 v[176:179], v180 offset:2048
	ds_read_b128 v[180:183], v180 offset:3072
	s_add_u32 s24, s30, 0x160000
	s_addc_u32 s25, s31, 0
	s_mov_b32 m0, s40
	ds_read_b128 v[184:187], v171 offset:32768
	ds_read_b128 v[188:191], v171 offset:33792
	ds_read_b128 v[192:195], v171 offset:34816
	ds_read_b128 v[196:199], v171 offset:35840
	ds_read_b128 v[200:203], v171 offset:36864
	ds_read_b128 v[204:207], v171 offset:37888
	ds_read_b128 v[208:211], v171 offset:38912
	ds_read_b128 v[212:215], v171 offset:39936
	global_load_lds_dwordx4 v128, s[24:25]
	s_mov_b32 m0, s41
	s_nop 0
	global_load_lds_dwordx4 v132, s[24:25]
	s_waitcnt vmcnt(8)
	s_waitcnt lgkmcnt(0)
	s_barrier
	v_mfma_f32_16x16x32_bf16 v[124:127], v[144:147], v[184:187], v[124:127]
	v_mfma_f32_16x16x32_bf16 v[120:123], v[152:155], v[184:187], v[120:123]
	v_mfma_f32_16x16x32_bf16 v[116:119], v[144:147], v[192:195], v[116:119]
	v_mfma_f32_16x16x32_bf16 v[112:115], v[152:155], v[192:195], v[112:115]
	v_mfma_f32_16x16x32_bf16 v[108:111], v[144:147], v[200:203], v[108:111]
	v_mfma_f32_16x16x32_bf16 v[96:99], v[152:155], v[200:203], v[96:99]
	v_mfma_f32_16x16x32_bf16 v[84:87], v[144:147], v[208:211], v[84:87]
	v_mfma_f32_16x16x32_bf16 v[76:79], v[152:155], v[208:211], v[76:79]
	v_mfma_f32_16x16x32_bf16 v[124:127], v[148:151], v[188:191], v[124:127]
	v_mfma_f32_16x16x32_bf16 v[120:123], v[156:159], v[188:191], v[120:123]
	v_mfma_f32_16x16x32_bf16 v[116:119], v[148:151], v[196:199], v[116:119]
	v_mfma_f32_16x16x32_bf16 v[112:115], v[156:159], v[196:199], v[112:115]
	v_mfma_f32_16x16x32_bf16 v[108:111], v[148:151], v[204:207], v[108:111]
	v_mfma_f32_16x16x32_bf16 v[96:99], v[156:159], v[204:207], v[96:99]
	v_mfma_f32_16x16x32_bf16 v[84:87], v[148:151], v[212:215], v[84:87]
	v_mfma_f32_16x16x32_bf16 v[76:79], v[156:159], v[212:215], v[76:79]
	v_mfma_f32_16x16x32_bf16 v[104:107], v[160:163], v[184:187], v[104:107]
	v_mfma_f32_16x16x32_bf16 v[100:103], v[176:179], v[184:187], v[100:103]
	v_mfma_f32_16x16x32_bf16 v[92:95], v[160:163], v[192:195], v[92:95]
	v_mfma_f32_16x16x32_bf16 v[88:91], v[176:179], v[192:195], v[88:91]
	v_mfma_f32_16x16x32_bf16 v[80:83], v[160:163], v[200:203], v[80:83]
	v_mfma_f32_16x16x32_bf16 v[72:75], v[176:179], v[200:203], v[72:75]
	v_mfma_f32_16x16x32_bf16 v[68:71], v[160:163], v[208:211], v[68:71]
	v_mfma_f32_16x16x32_bf16 v[64:67], v[176:179], v[208:211], v[64:67]
	v_mfma_f32_16x16x32_bf16 v[104:107], v[172:175], v[188:191], v[104:107]
	v_mfma_f32_16x16x32_bf16 v[100:103], v[180:183], v[188:191], v[100:103]
	v_mfma_f32_16x16x32_bf16 v[92:95], v[172:175], v[196:199], v[92:95]
	v_mfma_f32_16x16x32_bf16 v[88:91], v[180:183], v[196:199], v[88:91]
	v_mfma_f32_16x16x32_bf16 v[80:83], v[172:175], v[204:207], v[80:83]
	v_mfma_f32_16x16x32_bf16 v[72:75], v[180:183], v[204:207], v[72:75]
	v_mfma_f32_16x16x32_bf16 v[68:71], v[172:175], v[212:215], v[68:71]
	v_mfma_f32_16x16x32_bf16 v[64:67], v[180:183], v[212:215], v[64:67]
	s_barrier
	s_add_i32 s24, s57, s37
	s_add_u32 s86, s28, 0x80
	s_addc_u32 s87, s29, 0
	s_mov_b32 m0, s24
	ds_read_b128 v[184:187], v171 offset:49152
	ds_read_b128 v[188:191], v171 offset:50176
	ds_read_b128 v[192:195], v171 offset:51200
	ds_read_b128 v[196:199], v171 offset:52224
	ds_read_b128 v[200:203], v171 offset:53248
	ds_read_b128 v[204:207], v171 offset:54272
	ds_read_b128 v[208:211], v171 offset:55296
	ds_read_b128 v[212:215], v171 offset:56320
	global_load_lds_dwordx4 v130, s[86:87]
	s_add_i32 m0, s24, 0x2000
	s_add_u32 s24, s28, 0x160080
	s_addc_u32 s25, s29, 0
	s_add_i32 s28, s58, s37
	global_load_lds_dwordx4 v134, s[86:87]
	s_mov_b32 m0, s28
	s_nop 0
	global_load_lds_dwordx4 v130, s[24:25]
	s_add_i32 m0, s28, 0x2000
	s_nop 0
	global_load_lds_dwordx4 v134, s[24:25]
	s_add_u32 s84, s30, 0x80
	s_addc_u32 s85, s31, 0
	s_mov_b32 m0, s45
	s_nop 0
	global_load_lds_dwordx4 v128, s[84:85]
	s_mov_b32 m0, s46
	s_nop 0
	global_load_lds_dwordx4 v132, s[84:85]
	s_waitcnt vmcnt(8)
	s_waitcnt lgkmcnt(0)
	s_barrier
	v_mfma_f32_16x16x32_bf16 v[60:63], v[144:147], v[184:187], v[60:63]
	v_mfma_f32_16x16x32_bf16 v[56:59], v[152:155], v[184:187], v[56:59]
	v_mfma_f32_16x16x32_bf16 v[52:55], v[144:147], v[192:195], v[52:55]
	v_mfma_f32_16x16x32_bf16 v[48:51], v[152:155], v[192:195], v[48:51]
	v_mfma_f32_16x16x32_bf16 v[44:47], v[144:147], v[200:203], v[44:47]
	v_mfma_f32_16x16x32_bf16 v[32:35], v[152:155], v[200:203], v[32:35]
	v_mfma_f32_16x16x32_bf16 v[20:23], v[144:147], v[208:211], v[20:23]
	v_mfma_f32_16x16x32_bf16 v[12:15], v[152:155], v[208:211], v[12:15]
	v_mfma_f32_16x16x32_bf16 v[60:63], v[148:151], v[188:191], v[60:63]
	v_mfma_f32_16x16x32_bf16 v[56:59], v[156:159], v[188:191], v[56:59]
	v_mfma_f32_16x16x32_bf16 v[52:55], v[148:151], v[196:199], v[52:55]
	v_mfma_f32_16x16x32_bf16 v[48:51], v[156:159], v[196:199], v[48:51]
	v_mfma_f32_16x16x32_bf16 v[44:47], v[148:151], v[204:207], v[44:47]
	v_mfma_f32_16x16x32_bf16 v[32:35], v[156:159], v[204:207], v[32:35]
	v_mfma_f32_16x16x32_bf16 v[20:23], v[148:151], v[212:215], v[20:23]
	v_mfma_f32_16x16x32_bf16 v[12:15], v[156:159], v[212:215], v[12:15]
	v_mfma_f32_16x16x32_bf16 v[40:43], v[160:163], v[184:187], v[40:43]
	v_mfma_f32_16x16x32_bf16 v[36:39], v[176:179], v[184:187], v[36:39]
	v_mfma_f32_16x16x32_bf16 v[28:31], v[160:163], v[192:195], v[28:31]
	v_mfma_f32_16x16x32_bf16 v[24:27], v[176:179], v[192:195], v[24:27]
	v_mfma_f32_16x16x32_bf16 v[16:19], v[160:163], v[200:203], v[16:19]
	v_mfma_f32_16x16x32_bf16 v[8:11], v[176:179], v[200:203], v[8:11]
	v_mfma_f32_16x16x32_bf16 v[4:7], v[160:163], v[208:211], v[4:7]
	v_mfma_f32_16x16x32_bf16 v[0:3], v[176:179], v[208:211], v[0:3]
	v_mfma_f32_16x16x32_bf16 v[40:43], v[172:175], v[188:191], v[40:43]
	v_mfma_f32_16x16x32_bf16 v[36:39], v[180:183], v[188:191], v[36:39]
	v_mfma_f32_16x16x32_bf16 v[28:31], v[172:175], v[196:199], v[28:31]
	v_mfma_f32_16x16x32_bf16 v[24:27], v[180:183], v[196:199], v[24:27]
	v_mfma_f32_16x16x32_bf16 v[16:19], v[172:175], v[204:207], v[16:19]
	v_mfma_f32_16x16x32_bf16 v[8:11], v[180:183], v[204:207], v[8:11]
	v_mfma_f32_16x16x32_bf16 v[4:7], v[172:175], v[212:215], v[4:7]
	v_mfma_f32_16x16x32_bf16 v[0:3], v[180:183], v[212:215], v[0:3]
	s_barrier
;     __device__ __forceinline__ void operator()(const f32x4 (&acc)[2][2][4][2], const Unit& u, int wr, int wc, int fr, int fq) const {
;         const int row0 = u.pm * BM + wr * 64 + fr, col0 = u.pn * BM + wc * 32 + 8 * fq;
;         const float* gp = gate + (u.pm >> 5) * 18432 + col0;
;         f32x4 gv[2][2];
; #pragma unroll
;         for (int bj = 0; bj < 2; ++bj)
; #pragma unroll
;             for (int n = 0; n < 2; ++n) gv[bj][n] = *(const f32x4*)(gp + bj * HALF + 4 * n) * scale;
; #pragma unroll
;         for (int ai = 0; ai < 2; ++ai) { f32x4 r[4][2][2];
; #pragma unroll
;             for (int m = 0; m < 4; ++m) { const size_t off = (size_t)(row0 + ai * HALF + m * 16) * 2048 + col0;
; #pragma unroll
;                 for (int bj = 0; bj < 2; ++bj)
; #pragma unroll
;                     for (int n = 0; n < 2; ++n) r[m][bj][n] = *(const f32x4*)(res + off + bj * HALF + 4 * n); }
; #pragma unroll
;             for (int m = 0; m < 4; ++m) { const size_t off = (size_t)(row0 + ai * HALF + m * 16) * 2048 + col0;
; #pragma unroll
;                 for (int bj = 0; bj < 2; ++bj)
; #pragma unroll
;                     for (int n = 0; n < 2; ++n) *(f32x4*)(out + off + bj * HALF + 4 * n) = r[m][bj][n] + gv[bj][n] * acc[ai][bj][m][n]; } }
; template <class Epi, class Sched, bool ALIGN_EPI = false, bool SP2 = false>
; __device__ __forceinline__ void gemm_phase(PG8_LAS unsigned char* lds, const Gemm g, const Sched& S, const Epi& E) {
;     ...
;         for (int t = 0; t < nt; t += 2) {
	s_add_i32 s56, s56, 2
	s_add_u32 s54, s54, 0x100
	s_addc_u32 s55, s55, 0
	s_cmpk_gt_u32 s56, 0x55
	s_mov_b64 s[24:25], s[26:27]
	s_cbranch_scc0 .LBB0_1021
	s_lshr_b32 s24, s52, 5
	s_mulk_i32 s24, 0x4800
	s_ashr_i32 s25, s24, 31
	v_lshl_or_b32 v144, s53, 8, v168
	s_lshl_b64 s[24:25], s[24:25], 2
	s_add_u32 s24, s43, s24
	v_ashrrev_i32_e32 v145, 31, v144
	s_addc_u32 s25, s44, s25
	v_lshlrev_b64 v[144:145], 2, v[144:145]
	v_lshl_add_u64 v[154:155], s[24:25], 0, v[144:145]
	global_load_dwordx4 v[146:149], v[154:155], off offset:16
	global_load_dwordx4 v[150:153], v[154:155], off
	global_load_dwordx4 v[172:175], v[154:155], off offset:528
	global_load_dwordx4 v[176:179], v[154:155], off offset:512
	v_lshl_add_u32 v154, s52, 8, v166
	v_ashrrev_i32_e32 v155, 31, v154
	v_lshl_add_u64 v[162:163], s[8:9], 0, v[144:145]
	v_lshlrev_b64 v[164:165], 13, v[154:155]
	v_lshl_add_u64 v[156:157], v[162:163], 0, v[164:165]
	global_load_dwordx4 v[180:183], v[156:157], off
	global_load_dwordx4 v[184:187], v[156:157], off offset:16
	global_load_dwordx4 v[188:191], v[156:157], off offset:528
	global_load_dwordx4 v[192:195], v[156:157], off offset:512
	v_or_b32_e32 v156, 16, v154
	v_ashrrev_i32_e32 v157, 31, v156
	v_lshlrev_b64 v[156:157], 13, v[156:157]
	v_lshl_add_u64 v[158:159], v[162:163], 0, v[156:157]
	global_load_dwordx4 v[196:199], v[158:159], off
	global_load_dwordx4 v[200:203], v[158:159], off offset:16
	global_load_dwordx4 v[204:207], v[158:159], off offset:528
	global_load_dwordx4 v[208:211], v[158:159], off offset:512
	v_or_b32_e32 v158, 32, v154
	v_ashrrev_i32_e32 v159, 31, v158
	v_lshlrev_b64 v[158:159], 13, v[158:159]
	v_or_b32_e32 v154, 48, v154
	v_lshl_add_u64 v[160:161], v[162:163], 0, v[158:159]
	v_ashrrev_i32_e32 v155, 31, v154
	global_load_dwordx4 v[212:215], v[160:161], off
	global_load_dwordx4 v[216:219], v[160:161], off offset:16
	global_load_dwordx4 v[220:223], v[160:161], off offset:512
	global_load_dwordx4 v[224:227], v[160:161], off offset:528
	v_lshlrev_b64 v[244:245], 13, v[154:155]
	v_lshl_add_u64 v[154:155], v[162:163], 0, v[244:245]
	global_load_dwordx4 v[228:231], v[154:155], off
	global_load_dwordx4 v[232:235], v[154:155], off offset:16
	global_load_dwordx4 v[236:239], v[154:155], off offset:512
	global_load_dwordx4 v[240:243], v[154:155], off offset:528
	v_lshl_add_u64 v[154:155], s[10:11], 0, v[164:165]
	v_lshl_add_u64 v[246:247], v[154:155], 0, v[144:145]
	v_lshl_add_u64 v[154:155], s[10:11], 0, v[156:157]
	v_lshl_add_u64 v[156:157], s[10:11], 0, v[158:159]
	v_lshl_add_u64 v[248:249], v[154:155], 0, v[144:145]
	v_lshl_add_u64 v[250:251], v[156:157], 0, v[144:145]
	s_and_b64 vcc, exec, s[0:1]
	s_mov_b32 s53, s50
	s_mov_b32 s52, s51
	s_mov_b64 s[26:27], s[6:7]
	s_mov_b64 s[24:25], s[4:5]
	s_waitcnt vmcnt(0)
	v_pk_mul_f32 v[154:155], v[148:149], 0.5 op_sel_hi:[1,0]
	v_pk_mul_f32 v[158:159], v[152:153], 0.5 op_sel_hi:[1,0]
	v_pk_mul_f32 v[160:161], v[150:151], 0.5 op_sel_hi:[1,0]
	v_pk_mul_f32 v[150:151], v[178:179], 0.5 op_sel_hi:[1,0]
	v_pk_mul_f32 v[152:153], v[176:177], 0.5 op_sel_hi:[1,0]
	v_pk_mul_f32 v[156:157], v[146:147], 0.5 op_sel_hi:[1,0]
	v_pk_mul_f32 v[146:147], v[174:175], 0.5 op_sel_hi:[1,0]
	v_pk_mul_f32 v[148:149], v[172:173], 0.5 op_sel_hi:[1,0]
	v_pk_fma_f32 v[126:127], v[126:127], v[158:159], v[182:183]
	v_pk_fma_f32 v[124:125], v[124:125], v[160:161], v[180:181]
	v_pk_fma_f32 v[122:123], v[122:123], v[154:155], v[186:187]
	v_pk_fma_f32 v[120:121], v[120:121], v[156:157], v[184:185]
	v_pk_fma_f32 v[106:107], v[106:107], v[150:151], v[194:195]
	v_pk_fma_f32 v[104:105], v[104:105], v[152:153], v[192:193]
	v_pk_fma_f32 v[102:103], v[102:103], v[146:147], v[190:191]
	v_pk_fma_f32 v[100:101], v[100:101], v[148:149], v[188:189]
	v_pk_fma_f32 v[118:119], v[118:119], v[158:159], v[198:199]
	v_pk_fma_f32 v[116:117], v[116:117], v[160:161], v[196:197]
	v_pk_fma_f32 v[114:115], v[114:115], v[154:155], v[202:203]
	v_pk_fma_f32 v[112:113], v[112:113], v[156:157], v[200:201]
	v_pk_fma_f32 v[82:83], v[82:83], v[150:151], v[222:223]
	v_pk_fma_f32 v[80:81], v[80:81], v[152:153], v[220:221]
	v_pk_fma_f32 v[94:95], v[94:95], v[150:151], v[210:211]
	v_pk_fma_f32 v[92:93], v[92:93], v[152:153], v[208:209]
	v_pk_fma_f32 v[90:91], v[90:91], v[146:147], v[206:207]
	v_pk_fma_f32 v[88:89], v[88:89], v[148:149], v[204:205]
	v_pk_fma_f32 v[110:111], v[110:111], v[158:159], v[214:215]
	v_pk_fma_f32 v[108:109], v[108:109], v[160:161], v[212:213]
	v_pk_fma_f32 v[98:99], v[98:99], v[154:155], v[218:219]
	v_pk_fma_f32 v[96:97], v[96:97], v[156:157], v[216:217]
	global_store_dwordx4 v[246:247], v[124:127], off
	global_store_dwordx4 v[246:247], v[120:123], off offset:16
	global_store_dwordx4 v[246:247], v[104:107], off offset:512
	global_store_dwordx4 v[246:247], v[100:103], off offset:528
	global_store_dwordx4 v[248:249], v[116:119], off
	global_store_dwordx4 v[248:249], v[112:115], off offset:16
	global_store_dwordx4 v[248:249], v[92:95], off offset:512
	global_store_dwordx4 v[248:249], v[88:91], off offset:528
	global_store_dwordx4 v[250:251], v[108:111], off
	global_store_dwordx4 v[250:251], v[96:99], off offset:16
	global_store_dwordx4 v[250:251], v[80:83], off offset:512
	v_pk_fma_f32 v[74:75], v[74:75], v[146:147], v[226:227]
	v_pk_fma_f32 v[72:73], v[72:73], v[148:149], v[224:225]
	v_lshl_add_u64 v[80:81], s[10:11], 0, v[244:245]
	global_store_dwordx4 v[250:251], v[72:75], off offset:528
; #define PG8_WAIT_V(n) asm volatile("s_waitcnt vmcnt(" #n ")" ::: "memory")
; #define PG8_BAR __builtin_amdgcn_s_barrier()
;     __device__ __forceinline__ void operator()(const f32x4 (&acc)[2][2][4][2], const Unit& u, int wr, int wc, int fr, int fq) const {
;     ...
;         for (int ai = 0; ai < 2; ++ai) { f32x4 r[4][2][2];
; #pragma unroll
;             for (int m = 0; m < 4; ++m) { const size_t off = (size_t)(row0 + ai * HALF + m * 16) * 2048 + col0;
; #pragma unroll
;                 for (int bj = 0; bj < 2; ++bj)
; #pragma unroll
;                     for (int n = 0; n < 2; ++n) r[m][bj][n] = *(const f32x4*)(res + off + bj * HALF + 4 * n); }
; #pragma unroll
;             for (int m = 0; m < 4; ++m) { const size_t off = (size_t)(row0 + ai * HALF + m * 16) * 2048 + col0;
; #pragma unroll
;                 for (int bj = 0; bj < 2; ++bj)
; #pragma unroll
;                     for (int n = 0; n < 2; ++n) *(f32x4*)(out + off + bj * HALF + 4 * n) = r[m][bj][n] + gv[bj][n] * acc[ai][bj][m][n]; } }
; template <class Epi, class Sched, bool ALIGN_EPI = false, bool SP2 = false>
; __device__ __forceinline__ void gemm_phase(PG8_LAS unsigned char* lds, const Gemm g, const Sched& S, const Epi& E) {
;     ...
;         if (!has_next) break;
; #pragma unroll
;         for (int a = 0; a < 2; ++a)
; #pragma unroll
;             for (int b = 0; b < 2; ++b)
; #pragma unroll
;                 for (int m = 0; m < 4; ++m)
; #pragma unroll
;                     for (int n = 0; n < 2; ++n) acc[a][b][m][n] = (f32x4){0.f, 0.f, 0.f, 0.f};
;         cur = nxt; cA = nA; cB = nB; ++ui;
;         if constexpr (ALIGN_EPI) { if (wr == 1) PG8_BAR; }
;     }
;     PG8_WAIT_V(0);
;     if constexpr (!ALIGN_EPI) { if (wr == 0) PG8_BAR; }
;     PG8_BAR;
	v_lshl_add_u64 v[80:81], v[80:81], 0, v[144:145]
	v_pk_fma_f32 v[70:71], v[70:71], v[150:151], v[238:239]
	v_pk_fma_f32 v[74:75], v[86:87], v[158:159], v[230:231]
	v_pk_fma_f32 v[72:73], v[84:85], v[160:161], v[228:229]
	global_store_dwordx4 v[80:81], v[72:75], off
	v_pk_fma_f32 v[68:69], v[68:69], v[152:153], v[236:237]
	v_pk_fma_f32 v[66:67], v[66:67], v[146:147], v[242:243]
	v_pk_fma_f32 v[74:75], v[78:79], v[154:155], v[234:235]
	v_pk_fma_f32 v[72:73], v[76:77], v[156:157], v[232:233]
	v_pk_fma_f32 v[64:65], v[64:65], v[148:149], v[240:241]
	v_lshl_add_u64 v[172:173], v[164:165], 0, s[18:19]
	v_lshl_add_u64 v[174:175], v[164:165], 0, s[20:21]
	v_lshl_add_u64 v[176:177], v[164:165], 0, s[22:23]
	global_store_dwordx4 v[80:81], v[72:75], off offset:16
	global_store_dwordx4 v[80:81], v[68:71], off offset:512
	global_store_dwordx4 v[80:81], v[64:67], off offset:528
	v_lshl_add_u64 v[80:81], v[162:163], 0, v[172:173]
	v_lshl_add_u64 v[92:93], v[162:163], 0, v[174:175]
	v_lshl_add_u64 v[108:109], v[162:163], 0, v[176:177]
	global_load_dwordx4 v[64:67], v[80:81], off
	global_load_dwordx4 v[68:71], v[80:81], off offset:16
	global_load_dwordx4 v[72:75], v[80:81], off offset:512
	global_load_dwordx4 v[76:79], v[80:81], off offset:528
	s_nop 0
	global_load_dwordx4 v[80:83], v[92:93], off
	global_load_dwordx4 v[84:87], v[92:93], off offset:16
	global_load_dwordx4 v[88:91], v[92:93], off offset:512
	s_nop 0
	global_load_dwordx4 v[92:95], v[92:93], off offset:528
	s_nop 0
	global_load_dwordx4 v[96:99], v[108:109], off
	global_load_dwordx4 v[100:103], v[108:109], off offset:16
	global_load_dwordx4 v[104:107], v[108:109], off offset:512
	s_nop 0
	global_load_dwordx4 v[108:111], v[108:109], off offset:528
	v_lshl_add_u64 v[164:165], v[164:165], 0, s[12:13]
	v_lshl_add_u64 v[124:125], v[162:163], 0, v[164:165]
	global_load_dwordx4 v[112:115], v[124:125], off
	global_load_dwordx4 v[116:119], v[124:125], off offset:16
	global_load_dwordx4 v[120:123], v[124:125], off offset:512
	s_nop 0
	global_load_dwordx4 v[124:127], v[124:125], off offset:528
	v_lshl_add_u64 v[162:163], s[10:11], 0, v[172:173]
	v_lshl_add_u64 v[172:173], s[10:11], 0, v[174:175]
	v_lshl_add_u64 v[174:175], s[10:11], 0, v[176:177]
	v_lshl_add_u64 v[162:163], v[162:163], 0, v[144:145]
	v_lshl_add_u64 v[174:175], v[174:175], 0, v[144:145]
	v_lshl_add_u64 v[172:173], v[172:173], 0, v[144:145]
	s_waitcnt vmcnt(15)
	v_pk_fma_f32 v[62:63], v[62:63], v[158:159], v[66:67]
	v_pk_fma_f32 v[60:61], v[60:61], v[160:161], v[64:65]
	s_waitcnt vmcnt(14)
	v_pk_fma_f32 v[58:59], v[58:59], v[154:155], v[70:71]
	v_pk_fma_f32 v[56:57], v[56:57], v[156:157], v[68:69]
	s_waitcnt vmcnt(5)
	v_pk_fma_f32 v[18:19], v[18:19], v[150:151], v[106:107]
	v_pk_fma_f32 v[16:17], v[16:17], v[152:153], v[104:105]
	v_pk_fma_f32 v[42:43], v[42:43], v[150:151], v[74:75]
	v_pk_fma_f32 v[40:41], v[40:41], v[152:153], v[72:73]
	v_pk_fma_f32 v[38:39], v[38:39], v[146:147], v[78:79]
	v_pk_fma_f32 v[36:37], v[36:37], v[148:149], v[76:77]
	v_pk_fma_f32 v[54:55], v[54:55], v[158:159], v[82:83]
	v_pk_fma_f32 v[52:53], v[52:53], v[160:161], v[80:81]
	v_pk_fma_f32 v[50:51], v[50:51], v[154:155], v[86:87]
	v_pk_fma_f32 v[48:49], v[48:49], v[156:157], v[84:85]
	v_pk_fma_f32 v[30:31], v[30:31], v[150:151], v[90:91]
	v_pk_fma_f32 v[28:29], v[28:29], v[152:153], v[88:89]
	v_pk_fma_f32 v[26:27], v[26:27], v[146:147], v[94:95]
	v_pk_fma_f32 v[24:25], v[24:25], v[148:149], v[92:93]
	v_pk_fma_f32 v[46:47], v[46:47], v[158:159], v[98:99]
	v_pk_fma_f32 v[44:45], v[44:45], v[160:161], v[96:97]
	v_pk_fma_f32 v[34:35], v[34:35], v[154:155], v[102:103]
	v_pk_fma_f32 v[32:33], v[32:33], v[156:157], v[100:101]
	global_store_dwordx4 v[162:163], v[60:63], off
	global_store_dwordx4 v[162:163], v[56:59], off offset:16
	global_store_dwordx4 v[162:163], v[40:43], off offset:512
	global_store_dwordx4 v[162:163], v[36:39], off offset:528
	global_store_dwordx4 v[172:173], v[52:55], off
	global_store_dwordx4 v[172:173], v[48:51], off offset:16
	global_store_dwordx4 v[172:173], v[28:31], off offset:512
	global_store_dwordx4 v[172:173], v[24:27], off offset:528
	global_store_dwordx4 v[174:175], v[44:47], off
	global_store_dwordx4 v[174:175], v[32:35], off offset:16
	global_store_dwordx4 v[174:175], v[16:19], off offset:512
	s_waitcnt vmcnt(15)
	v_pk_fma_f32 v[10:11], v[10:11], v[146:147], v[110:111]
	v_pk_fma_f32 v[8:9], v[8:9], v[148:149], v[108:109]
	v_lshl_add_u64 v[16:17], s[10:11], 0, v[164:165]
	global_store_dwordx4 v[174:175], v[8:11], off offset:528
	v_lshl_add_u64 v[16:17], v[16:17], 0, v[144:145]
	s_waitcnt vmcnt(13)
	v_pk_fma_f32 v[6:7], v[6:7], v[150:151], v[122:123]
	v_pk_fma_f32 v[10:11], v[22:23], v[158:159], v[114:115]
	v_pk_fma_f32 v[8:9], v[20:21], v[160:161], v[112:113]
	global_store_dwordx4 v[16:17], v[8:11], off
	v_pk_fma_f32 v[4:5], v[4:5], v[152:153], v[120:121]
	s_waitcnt vmcnt(13)
	v_pk_fma_f32 v[2:3], v[2:3], v[146:147], v[126:127]
	v_pk_fma_f32 v[10:11], v[14:15], v[154:155], v[118:119]
	v_pk_fma_f32 v[8:9], v[12:13], v[156:157], v[116:117]
	v_pk_fma_f32 v[0:1], v[0:1], v[148:149], v[124:125]
	global_store_dwordx4 v[16:17], v[8:11], off offset:16
	global_store_dwordx4 v[16:17], v[4:7], off offset:512
	global_store_dwordx4 v[16:17], v[0:3], off offset:528
	s_cbranch_vccz .LBB0_1010
	s_waitcnt vmcnt(0)
	s_cmpk_gt_u32 s3, 0xff
	s_cbranch_scc1 .LBB0_1025
	s_barrier
